# k27: GEMM K-loops drop mid-block s_setprio 0/1 toggle and duplicate lgkmcnt(0) after the phase barrier
# baseline (speedup 1.0000x reference)
;     __host__ __device__ bool next(int i, Unit& u) const { const int L = i * G + c; if (L >= 16 * nkc) return false; u.kc = L % nkc; const int t = L / nkc; u.pn = t & 3; u.pm = 33 * (t >> 2); return true; }
; #define PG8_STAGE(bufoff, gbase, voff) do { _Pragma("unroll") for (int _i = 0; _i < 2; ++_i) \
;         __builtin_amdgcn_global_load_lds((const unsigned*)((const char*)(gbase) + (voff)[_i]), (PG8_LAS unsigned*)(lds + (bufoff) + ldsw + _i * 8192), 16, 0, 0); } while (0)
; #define PG8_LDA(dst, b, h) do { _Pragma("unroll") for (int m = 0; m < 4; ++m) _Pragma("unroll") for (int k = 0; k < 2; ++k) dst[m][k] = *(const PG8_LAS bf16x8*)(lds + PG8_SA(b, h) + aoff + m * 2048 + k * 1024); } while (0)
; #define PG8_LDB(dst, b, h) do { _Pragma("unroll") for (int n = 0; n < 2; ++n) _Pragma("unroll") for (int k = 0; k < 2; ++k) dst[n][k] = *(const PG8_LAS bf16x8*)(lds + PG8_SB(b, h) + boff + n * 2048 + k * 1024); } while (0)
; #define PG8_BAR __builtin_amdgcn_s_barrier()
; template <class Epi, class Sched, bool ALIGN_EPI = false, bool SP2 = false>
; __device__ __forceinline__ void gemm_phase(PG8_LAS unsigned char* lds, const Gemm g, const Sched& S, const Epi& E) {
;     ...
;         const bool has_next = S.next(ui + 1, nxt);
;         const char* nA = has_next ? (const char*)g.A + (size_t)nxt.pm * tstep + (size_t)nxt.kc * cstep : cA; const char* nB = has_next ? (const char*)g.Bt + (size_t)nxt.pn * tstep + (size_t)nxt.kc * cstep : cB;
;         for (int t = 0; t < nt; t += 2) {
;             const bool last = (t == nt - 2);
;             const char* a1 = cA + (size_t)(t + 1) * kstep;
;             const char* a2 = last ? nA : cA + (size_t)(t + 2) * kstep; const char* b2 = last ? nB : cB + (size_t)(t + 2) * kstep;
;             const char* a3 = a2 + kstep; const char* b3 = b2 + kstep;
;             if (last && has_next) S.a_ready(nxt);
;             if constexpr (SP2) {
;             PG8_LDB(B0, 0, 0); PG8_LDB(B1, 0, 1); PG8_SCHED; PG8_LDA(At, 0, 0); PG8_STAGE(PG8_SA(1, 1), a1 + hstep, voffA);
;             PG8_WAIT_V(8); PG8_WAIT_L(0); PG8_BAR; PG8_MMA(0, 0, At, B0); PG8_MMA(0, 1, At, B1); PG8_BAR; PG8_SCHED;
;             PG8_LDA(At, 0, 1); PG8_STAGE(PG8_SB(0, 0), b2, voffB); PG8_STAGE(PG8_SB(0, 1), b2 + hstep, voffB); PG8_STAGE(PG8_SA(0, 0), a2, voffA);
;             PG8_WAIT_V(8); PG8_WAIT_L(0); PG8_BAR; PG8_MMA(1, 0, At, B0); PG8_MMA(1, 1, At, B1); PG8_BAR; PG8_SCHED;
.LBB0_188:
	s_ashr_i32 s51, s50, 31
	s_lshl_b64 s[52:53], s[50:51], 19
	s_add_u32 s52, s46, s52
	s_addc_u32 s53, s47, s53
	s_and_b64 s[54:55], s[4:5], exec
	s_cselect_b32 s51, s53, s59
	s_cselect_b32 s83, s52, s58
	s_ashr_i32 s49, s48, 31
	s_lshl_b64 s[54:55], s[48:49], 19
	s_add_u32 s54, s30, s54
	s_addc_u32 s55, s31, s55
	s_and_b64 s[66:67], s[4:5], exec
	s_cselect_b32 s49, s55, s65
	s_cselect_b32 s84, s54, s64
	s_add_u32 s58, s58, 0x40080
	s_addc_u32 s59, s59, 0
	s_add_u32 s85, s64, 0x100
	s_addc_u32 s86, s65, 0
	s_mov_b32 s87, -2
	ds_read_b128 v[168:171], v150
	ds_read_b128 v[172:175], v151
	ds_read_b128 v[176:179], v152
	ds_read_b128 v[180:183], v153
	ds_read_b128 v[184:187], v154
	ds_read_b128 v[188:191], v155
	ds_read_b128 v[192:195], v156
	ds_read_b128 v[196:199], v157
	s_add_u32 s64, s58, 0xfffc0080
	s_addc_u32 s65, s59, -1
	s_cmp_eq_u32 s87, 12
	s_cselect_b32 s67, s51, s65
	s_cselect_b32 s66, s83, s64
	s_cselect_b32 s65, s49, s86
	s_cselect_b32 s64, s84, s85
	s_mov_b32 m0, s79
	v_lshl_add_u64 v[146:147], s[58:59], 0, v[136:137]
	ds_read_b128 v[200:203], v148
	ds_read_b128 v[204:207], v148 offset:1024
	ds_read_b128 v[208:211], v148 offset:2048
	ds_read_b128 v[212:215], v148 offset:3072
	ds_read_b128 v[216:219], v148 offset:4096
	ds_read_b128 v[224:227], v148 offset:5120
	ds_read_b128 v[228:231], v148 offset:6144
	ds_read_b128 v[232:235], v148 offset:7168
	global_load_lds_dwordx4 v[146:147], off
	v_lshl_add_u64 v[146:147], s[58:59], 0, v[138:139]
	s_mov_b32 m0, s80
	s_nop 0
	global_load_lds_dwordx4 v[146:147], off
	s_waitcnt vmcnt(8)
	s_waitcnt lgkmcnt(0)
	s_barrier
	s_setprio 1
	v_mfma_f32_16x16x32_bf16 v[124:127], v[168:171], v[200:203], 0
	v_mfma_f32_16x16x32_bf16 v[120:123], v[176:179], v[200:203], 0
	v_mfma_f32_16x16x32_bf16 v[112:115], v[168:171], v[208:211], 0
	v_mfma_f32_16x16x32_bf16 v[104:107], v[176:179], v[208:211], 0
	v_mfma_f32_16x16x32_bf16 v[96:99], v[168:171], v[216:219], 0
	v_mfma_f32_16x16x32_bf16 v[88:91], v[176:179], v[216:219], 0
	v_mfma_f32_16x16x32_bf16 v[80:83], v[168:171], v[228:231], 0
	v_mfma_f32_16x16x32_bf16 v[72:75], v[176:179], v[228:231], 0
	v_mfma_f32_16x16x32_bf16 v[124:127], v[172:175], v[204:207], v[124:127]
	v_mfma_f32_16x16x32_bf16 v[120:123], v[180:183], v[204:207], v[120:123]
	v_mfma_f32_16x16x32_bf16 v[112:115], v[172:175], v[212:215], v[112:115]
	v_mfma_f32_16x16x32_bf16 v[104:107], v[180:183], v[212:215], v[104:107]
	v_mfma_f32_16x16x32_bf16 v[96:99], v[172:175], v[224:227], v[96:99]
	v_mfma_f32_16x16x32_bf16 v[88:91], v[180:183], v[224:227], v[88:91]
	v_mfma_f32_16x16x32_bf16 v[80:83], v[172:175], v[232:235], v[80:83]
	v_mfma_f32_16x16x32_bf16 v[72:75], v[180:183], v[232:235], v[72:75]
	v_mfma_f32_16x16x32_bf16 v[116:119], v[184:187], v[200:203], 0
	v_mfma_f32_16x16x32_bf16 v[108:111], v[192:195], v[200:203], 0
	v_mfma_f32_16x16x32_bf16 v[100:103], v[184:187], v[208:211], 0
	v_mfma_f32_16x16x32_bf16 v[92:95], v[192:195], v[208:211], 0
	v_mfma_f32_16x16x32_bf16 v[84:87], v[184:187], v[216:219], 0
	v_mfma_f32_16x16x32_bf16 v[76:79], v[192:195], v[216:219], 0
	v_mfma_f32_16x16x32_bf16 v[68:71], v[184:187], v[228:231], 0
	v_mfma_f32_16x16x32_bf16 v[64:67], v[192:195], v[228:231], 0
	v_mfma_f32_16x16x32_bf16 v[116:119], v[188:191], v[204:207], v[116:119]
	v_mfma_f32_16x16x32_bf16 v[108:111], v[196:199], v[204:207], v[108:111]
	v_mfma_f32_16x16x32_bf16 v[100:103], v[188:191], v[212:215], v[100:103]
	v_mfma_f32_16x16x32_bf16 v[92:95], v[196:199], v[212:215], v[92:95]
	v_mfma_f32_16x16x32_bf16 v[84:87], v[188:191], v[224:227], v[84:87]
	v_mfma_f32_16x16x32_bf16 v[76:79], v[196:199], v[224:227], v[76:79]
	v_mfma_f32_16x16x32_bf16 v[68:71], v[188:191], v[232:235], v[68:71]
	v_mfma_f32_16x16x32_bf16 v[64:67], v[196:199], v[232:235], v[64:67]
	s_setprio 0
	s_barrier
	s_mov_b32 m0, s3
	v_lshl_add_u64 v[146:147], s[64:65], 0, v[130:131]
	s_add_u32 s88, s64, 0x40000
	ds_read_b128 v[200:203], v148 offset:16384
	ds_read_b128 v[204:207], v148 offset:17408
	ds_read_b128 v[208:211], v148 offset:18432
	ds_read_b128 v[212:215], v148 offset:19456
	ds_read_b128 v[216:219], v148 offset:20480
	ds_read_b128 v[224:227], v148 offset:21504
	ds_read_b128 v[228:231], v148 offset:22528
	ds_read_b128 v[232:235], v148 offset:23552
	global_load_lds_dwordx4 v[146:147], off
	v_lshl_add_u64 v[220:221], s[64:65], 0, v[134:135]
	s_mov_b32 m0, s14
	s_addc_u32 s89, s65, 0
	global_load_lds_dwordx4 v[220:221], off
	v_lshl_add_u64 v[236:237], s[88:89], 0, v[130:131]
	s_mov_b32 m0, s15
	v_lshl_add_u64 v[238:239], s[66:67], 0, v[132:133]
	global_load_lds_dwordx4 v[236:237], off
	v_lshl_add_u64 v[236:237], s[88:89], 0, v[134:135]
	s_mov_b32 m0, s33
	s_nop 0
	global_load_lds_dwordx4 v[236:237], off
	v_lshl_add_u64 v[236:237], s[66:67], 0, v[128:129]
	s_mov_b32 m0, s1
	s_nop 0
	global_load_lds_dwordx4 v[236:237], off
	s_mov_b32 m0, s39
	s_nop 0
	global_load_lds_dwordx4 v[238:239], off
	s_waitcnt vmcnt(8)
	s_waitcnt lgkmcnt(0)
	s_barrier
; #define PG8_STAGE(bufoff, gbase, voff) do { _Pragma("unroll") for (int _i = 0; _i < 2; ++_i) \
;         __builtin_amdgcn_global_load_lds((const unsigned*)((const char*)(gbase) + (voff)[_i]), (PG8_LAS unsigned*)(lds + (bufoff) + ldsw + _i * 8192), 16, 0, 0); } while (0)
; #define PG8_LDA(dst, b, h) do { _Pragma("unroll") for (int m = 0; m < 4; ++m) _Pragma("unroll") for (int k = 0; k < 2; ++k) dst[m][k] = *(const PG8_LAS bf16x8*)(lds + PG8_SA(b, h) + aoff + m * 2048 + k * 1024); } while (0)
; #define PG8_LDB(dst, b, h) do { _Pragma("unroll") for (int n = 0; n < 2; ++n) _Pragma("unroll") for (int k = 0; k < 2; ++k) dst[n][k] = *(const PG8_LAS bf16x8*)(lds + PG8_SB(b, h) + boff + n * 2048 + k * 1024); } while (0)
; #define PG8_MMA(ai, bj, At, Bt) do { __builtin_amdgcn_s_setprio(1); _Pragma("unroll") for (int m = 0; m < 4; ++m) _Pragma("unroll") for (int n = 0; n < 2; ++n) _Pragma("unroll") for (int k = 0; k < 2; ++k) \
;         acc[ai][bj][m][n] = __builtin_amdgcn_mfma_f32_16x16x32_bf16(Bt[n][k], At[m][k], acc[ai][bj][m][n], 0, 0, 0); __builtin_amdgcn_s_setprio(0); } while (0)
; #define PG8_WAIT_V(n) asm volatile("s_waitcnt vmcnt(" #n ")" ::: "memory")
; #define PG8_WAIT_L(n) asm volatile("s_waitcnt lgkmcnt(" #n ")" ::: "memory")
; #define PG8_BAR __builtin_amdgcn_s_barrier()
; #define PG8_SCHED __builtin_amdgcn_sched_barrier(0)
; template <class Epi, class Sched, bool ALIGN_EPI = false, bool SP2 = false>
; __device__ __forceinline__ void gemm_phase(PG8_LAS unsigned char* lds, const Gemm g, const Sched& S, const Epi& E) {
;     ...
;             PG8_WAIT_V(8); PG8_WAIT_L(0); PG8_BAR; PG8_MMA(1, 0, At, B0); PG8_MMA(1, 1, At, B1); PG8_BAR; PG8_SCHED;
;             PG8_LDB(B0, 1, 0); PG8_LDB(B1, 1, 1); PG8_SCHED; PG8_LDA(At, 1, 0); PG8_STAGE(PG8_SA(0, 1), a2 + hstep, voffA);
;             PG8_WAIT_V(8); PG8_WAIT_L(0); PG8_BAR; PG8_MMA(0, 0, At, B0); PG8_MMA(0, 1, At, B1); PG8_BAR; PG8_SCHED;
	s_setprio 1
	v_mfma_f32_16x16x32_bf16 v[60:63], v[168:171], v[200:203], 0
	v_mfma_f32_16x16x32_bf16 v[56:59], v[176:179], v[200:203], 0
	v_mfma_f32_16x16x32_bf16 v[48:51], v[168:171], v[208:211], 0
	v_mfma_f32_16x16x32_bf16 v[40:43], v[176:179], v[208:211], 0
	v_mfma_f32_16x16x32_bf16 v[32:35], v[168:171], v[216:219], 0
	v_mfma_f32_16x16x32_bf16 v[24:27], v[176:179], v[216:219], 0
	v_mfma_f32_16x16x32_bf16 v[16:19], v[168:171], v[228:231], 0
	v_mfma_f32_16x16x32_bf16 v[8:11], v[176:179], v[228:231], 0
	v_mfma_f32_16x16x32_bf16 v[60:63], v[172:175], v[204:207], v[60:63]
	v_mfma_f32_16x16x32_bf16 v[56:59], v[180:183], v[204:207], v[56:59]
	v_mfma_f32_16x16x32_bf16 v[48:51], v[172:175], v[212:215], v[48:51]
	v_mfma_f32_16x16x32_bf16 v[40:43], v[180:183], v[212:215], v[40:43]
	v_mfma_f32_16x16x32_bf16 v[32:35], v[172:175], v[224:227], v[32:35]
	v_mfma_f32_16x16x32_bf16 v[24:27], v[180:183], v[224:227], v[24:27]
	v_mfma_f32_16x16x32_bf16 v[16:19], v[172:175], v[232:235], v[16:19]
	v_mfma_f32_16x16x32_bf16 v[8:11], v[180:183], v[232:235], v[8:11]
	v_mfma_f32_16x16x32_bf16 v[52:55], v[184:187], v[200:203], 0
	v_mfma_f32_16x16x32_bf16 v[44:47], v[192:195], v[200:203], 0
	v_mfma_f32_16x16x32_bf16 v[36:39], v[184:187], v[208:211], 0
	v_mfma_f32_16x16x32_bf16 v[28:31], v[192:195], v[208:211], 0
	v_mfma_f32_16x16x32_bf16 v[20:23], v[184:187], v[216:219], 0
	v_mfma_f32_16x16x32_bf16 v[12:15], v[192:195], v[216:219], 0
	v_mfma_f32_16x16x32_bf16 v[4:7], v[184:187], v[228:231], 0
	v_mfma_f32_16x16x32_bf16 v[0:3], v[192:195], v[228:231], 0
	v_mfma_f32_16x16x32_bf16 v[52:55], v[188:191], v[204:207], v[52:55]
	v_mfma_f32_16x16x32_bf16 v[44:47], v[196:199], v[204:207], v[44:47]
	v_mfma_f32_16x16x32_bf16 v[36:39], v[188:191], v[212:215], v[36:39]
	v_mfma_f32_16x16x32_bf16 v[28:31], v[196:199], v[212:215], v[28:31]
	v_mfma_f32_16x16x32_bf16 v[20:23], v[188:191], v[224:227], v[20:23]
	v_mfma_f32_16x16x32_bf16 v[12:15], v[196:199], v[224:227], v[12:15]
	v_mfma_f32_16x16x32_bf16 v[4:7], v[188:191], v[232:235], v[4:7]
	v_mfma_f32_16x16x32_bf16 v[0:3], v[196:199], v[232:235], v[0:3]
	s_setprio 0
	s_barrier
	ds_read_b128 v[168:171], v158
	ds_read_b128 v[172:175], v159
	ds_read_b128 v[176:179], v160
	ds_read_b128 v[180:183], v161
	ds_read_b128 v[184:187], v162
	ds_read_b128 v[188:191], v163
	ds_read_b128 v[192:195], v164
	ds_read_b128 v[196:199], v165
	s_add_u32 s66, s66, 0x40000
	s_addc_u32 s67, s67, 0
	s_mov_b32 m0, s43
	v_lshl_add_u64 v[240:241], s[66:67], 0, v[128:129]
	ds_read_b128 v[200:203], v148 offset:32768
	ds_read_b128 v[204:207], v148 offset:33792
	ds_read_b128 v[208:211], v148 offset:34816
	ds_read_b128 v[212:215], v148 offset:35840
	ds_read_b128 v[216:219], v148 offset:36864
	ds_read_b128 v[224:227], v148 offset:37888
	ds_read_b128 v[228:231], v148 offset:38912
	ds_read_b128 v[232:235], v148 offset:39936
	global_load_lds_dwordx4 v[240:241], off
	v_lshl_add_u64 v[240:241], s[66:67], 0, v[132:133]
	s_mov_b32 m0, s57
	s_nop 0
	global_load_lds_dwordx4 v[240:241], off
	s_waitcnt vmcnt(8)
	s_waitcnt lgkmcnt(0)
	s_barrier
	s_setprio 1
	v_mfma_f32_16x16x32_bf16 v[124:127], v[168:171], v[200:203], v[124:127]
	v_mfma_f32_16x16x32_bf16 v[120:123], v[176:179], v[200:203], v[120:123]
	v_mfma_f32_16x16x32_bf16 v[112:115], v[168:171], v[208:211], v[112:115]
	v_mfma_f32_16x16x32_bf16 v[104:107], v[176:179], v[208:211], v[104:107]
	v_mfma_f32_16x16x32_bf16 v[96:99], v[168:171], v[216:219], v[96:99]
	v_mfma_f32_16x16x32_bf16 v[88:91], v[176:179], v[216:219], v[88:91]
	v_mfma_f32_16x16x32_bf16 v[80:83], v[168:171], v[228:231], v[80:83]
	v_mfma_f32_16x16x32_bf16 v[72:75], v[176:179], v[228:231], v[72:75]
	v_mfma_f32_16x16x32_bf16 v[124:127], v[172:175], v[204:207], v[124:127]
	v_mfma_f32_16x16x32_bf16 v[120:123], v[180:183], v[204:207], v[120:123]
	v_mfma_f32_16x16x32_bf16 v[112:115], v[172:175], v[212:215], v[112:115]
	v_mfma_f32_16x16x32_bf16 v[104:107], v[180:183], v[212:215], v[104:107]
	v_mfma_f32_16x16x32_bf16 v[96:99], v[172:175], v[224:227], v[96:99]
	v_mfma_f32_16x16x32_bf16 v[88:91], v[180:183], v[224:227], v[88:91]
	v_mfma_f32_16x16x32_bf16 v[80:83], v[172:175], v[232:235], v[80:83]
	v_mfma_f32_16x16x32_bf16 v[72:75], v[180:183], v[232:235], v[72:75]
	v_mfma_f32_16x16x32_bf16 v[116:119], v[184:187], v[200:203], v[116:119]
	v_mfma_f32_16x16x32_bf16 v[108:111], v[192:195], v[200:203], v[108:111]
	v_mfma_f32_16x16x32_bf16 v[100:103], v[184:187], v[208:211], v[100:103]
	v_mfma_f32_16x16x32_bf16 v[92:95], v[192:195], v[208:211], v[92:95]
	v_mfma_f32_16x16x32_bf16 v[84:87], v[184:187], v[216:219], v[84:87]
	v_mfma_f32_16x16x32_bf16 v[76:79], v[192:195], v[216:219], v[76:79]
	v_mfma_f32_16x16x32_bf16 v[68:71], v[184:187], v[228:231], v[68:71]
	v_mfma_f32_16x16x32_bf16 v[64:67], v[192:195], v[228:231], v[64:67]
	v_mfma_f32_16x16x32_bf16 v[116:119], v[188:191], v[204:207], v[116:119]
	v_mfma_f32_16x16x32_bf16 v[108:111], v[196:199], v[204:207], v[108:111]
	v_mfma_f32_16x16x32_bf16 v[100:103], v[188:191], v[212:215], v[100:103]
	v_mfma_f32_16x16x32_bf16 v[92:95], v[196:199], v[212:215], v[92:95]
	v_mfma_f32_16x16x32_bf16 v[84:87], v[188:191], v[224:227], v[84:87]
	v_mfma_f32_16x16x32_bf16 v[76:79], v[196:199], v[224:227], v[76:79]
	v_mfma_f32_16x16x32_bf16 v[68:71], v[188:191], v[232:235], v[68:71]
	v_mfma_f32_16x16x32_bf16 v[64:67], v[196:199], v[232:235], v[64:67]
	s_setprio 0
	s_barrier
; #define PG8_STAGE(bufoff, gbase, voff) do { _Pragma("unroll") for (int _i = 0; _i < 2; ++_i) \
;         __builtin_amdgcn_global_load_lds((const unsigned*)((const char*)(gbase) + (voff)[_i]), (PG8_LAS unsigned*)(lds + (bufoff) + ldsw + _i * 8192), 16, 0, 0); } while (0)
; #define PG8_LDA(dst, b, h) do { _Pragma("unroll") for (int m = 0; m < 4; ++m) _Pragma("unroll") for (int k = 0; k < 2; ++k) dst[m][k] = *(const PG8_LAS bf16x8*)(lds + PG8_SA(b, h) + aoff + m * 2048 + k * 1024); } while (0)
; #define PG8_LDB(dst, b, h) do { _Pragma("unroll") for (int n = 0; n < 2; ++n) _Pragma("unroll") for (int k = 0; k < 2; ++k) dst[n][k] = *(const PG8_LAS bf16x8*)(lds + PG8_SB(b, h) + boff + n * 2048 + k * 1024); } while (0)
; #define PG8_MMA(ai, bj, At, Bt) do { __builtin_amdgcn_s_setprio(1); _Pragma("unroll") for (int m = 0; m < 4; ++m) _Pragma("unroll") for (int n = 0; n < 2; ++n) _Pragma("unroll") for (int k = 0; k < 2; ++k) \
;         acc[ai][bj][m][n] = __builtin_amdgcn_mfma_f32_16x16x32_bf16(Bt[n][k], At[m][k], acc[ai][bj][m][n], 0, 0, 0); __builtin_amdgcn_s_setprio(0); } while (0)
; #define PG8_WAIT_V(n) asm volatile("s_waitcnt vmcnt(" #n ")" ::: "memory")
; template <class Epi, class Sched, bool ALIGN_EPI = false, bool SP2 = false>
; __device__ __forceinline__ void gemm_phase(PG8_LAS unsigned char* lds, const Gemm g, const Sched& S, const Epi& E) {
;     ...
;             PG8_LDB(B0, 0, 0); PG8_LDB(B1, 0, 1); PG8_SCHED; PG8_LDA(At, 0, 0); PG8_STAGE(PG8_SA(1, 1), a1 + hstep, voffA);
;             PG8_WAIT_V(8); PG8_WAIT_L(0); PG8_BAR; PG8_MMA(0, 0, At, B0); PG8_MMA(0, 1, At, B1); PG8_BAR; PG8_SCHED;
;             PG8_LDA(At, 0, 1); PG8_STAGE(PG8_SB(0, 0), b2, voffB); PG8_STAGE(PG8_SB(0, 1), b2 + hstep, voffB); PG8_STAGE(PG8_SA(0, 0), a2, voffA);
;             PG8_WAIT_V(8); PG8_WAIT_L(0); PG8_BAR; PG8_MMA(1, 0, At, B0); PG8_MMA(1, 1, At, B1); PG8_BAR; PG8_SCHED;
;             PG8_LDB(B0, 1, 0); PG8_LDB(B1, 1, 1); PG8_SCHED; PG8_LDA(At, 1, 0); PG8_STAGE(PG8_SA(0, 1), a2 + hstep, voffA);
;             PG8_WAIT_V(8); PG8_WAIT_L(0); PG8_BAR; PG8_MMA(0, 0, At, B0); PG8_MMA(0, 1, At, B1); PG8_BAR; PG8_SCHED;
;             PG8_LDA(At, 1, 1); PG8_STAGE(PG8_SB(1, 0), b3, voffB); PG8_STAGE(PG8_SB(1, 1), b3 + hstep, voffB); PG8_STAGE(PG8_SA(1, 0), a3, voffA);
;             PG8_WAIT_V(8); PG8_WAIT_L(0); PG8_BAR; PG8_MMA(1, 0, At, B0); PG8_MMA(1, 1, At, B1); PG8_BAR; PG8_SCHED;
	s_mov_b32 m0, s71
	v_lshl_add_u64 v[146:147], v[146:147], 0, s[10:11]
	s_add_u32 s64, s64, 0x40080
	ds_read_b128 v[200:203], v148 offset:49152
	ds_read_b128 v[204:207], v148 offset:50176
	ds_read_b128 v[208:211], v148 offset:51200
	ds_read_b128 v[212:215], v148 offset:52224
	ds_read_b128 v[216:219], v148 offset:53248
	ds_read_b128 v[224:227], v148 offset:54272
	ds_read_b128 v[228:231], v148 offset:55296
	ds_read_b128 v[232:235], v148 offset:56320
	global_load_lds_dwordx4 v[146:147], off
	v_lshl_add_u64 v[146:147], v[220:221], 0, s[10:11]
	s_mov_b32 m0, s72
	s_addc_u32 s65, s65, 0
	global_load_lds_dwordx4 v[146:147], off
	v_lshl_add_u64 v[146:147], s[64:65], 0, v[130:131]
	s_mov_b32 m0, s75
	s_nop 0
	global_load_lds_dwordx4 v[146:147], off
	v_lshl_add_u64 v[146:147], s[64:65], 0, v[134:135]
	s_mov_b32 m0, s76
	s_nop 0
	global_load_lds_dwordx4 v[146:147], off
	v_lshl_add_u64 v[146:147], v[236:237], 0, s[10:11]
	s_mov_b32 m0, s73
	s_nop 0
	global_load_lds_dwordx4 v[146:147], off
	v_lshl_add_u64 v[146:147], v[238:239], 0, s[10:11]
	s_mov_b32 m0, s74
	s_nop 0
	global_load_lds_dwordx4 v[146:147], off
	s_waitcnt vmcnt(8)
	s_waitcnt lgkmcnt(0)
	s_barrier
	s_setprio 1
	v_mfma_f32_16x16x32_bf16 v[60:63], v[168:171], v[200:203], v[60:63]
	v_mfma_f32_16x16x32_bf16 v[56:59], v[176:179], v[200:203], v[56:59]
	v_mfma_f32_16x16x32_bf16 v[48:51], v[168:171], v[208:211], v[48:51]
	v_mfma_f32_16x16x32_bf16 v[40:43], v[176:179], v[208:211], v[40:43]
	v_mfma_f32_16x16x32_bf16 v[32:35], v[168:171], v[216:219], v[32:35]
	v_mfma_f32_16x16x32_bf16 v[24:27], v[176:179], v[216:219], v[24:27]
	v_mfma_f32_16x16x32_bf16 v[16:19], v[168:171], v[228:231], v[16:19]
	v_mfma_f32_16x16x32_bf16 v[8:11], v[176:179], v[228:231], v[8:11]
	v_mfma_f32_16x16x32_bf16 v[60:63], v[172:175], v[204:207], v[60:63]
	v_mfma_f32_16x16x32_bf16 v[56:59], v[180:183], v[204:207], v[56:59]
	v_mfma_f32_16x16x32_bf16 v[48:51], v[172:175], v[212:215], v[48:51]
	v_mfma_f32_16x16x32_bf16 v[40:43], v[180:183], v[212:215], v[40:43]
	v_mfma_f32_16x16x32_bf16 v[32:35], v[172:175], v[224:227], v[32:35]
	v_mfma_f32_16x16x32_bf16 v[24:27], v[180:183], v[224:227], v[24:27]
	v_mfma_f32_16x16x32_bf16 v[16:19], v[172:175], v[232:235], v[16:19]
	v_mfma_f32_16x16x32_bf16 v[8:11], v[180:183], v[232:235], v[8:11]
	v_mfma_f32_16x16x32_bf16 v[52:55], v[184:187], v[200:203], v[52:55]
	v_mfma_f32_16x16x32_bf16 v[44:47], v[192:195], v[200:203], v[44:47]
	v_mfma_f32_16x16x32_bf16 v[36:39], v[184:187], v[208:211], v[36:39]
	v_mfma_f32_16x16x32_bf16 v[28:31], v[192:195], v[208:211], v[28:31]
	v_mfma_f32_16x16x32_bf16 v[20:23], v[184:187], v[216:219], v[20:23]
	v_mfma_f32_16x16x32_bf16 v[12:15], v[192:195], v[216:219], v[12:15]
	v_mfma_f32_16x16x32_bf16 v[4:7], v[184:187], v[228:231], v[4:7]
	v_mfma_f32_16x16x32_bf16 v[0:3], v[192:195], v[228:231], v[0:3]
	v_mfma_f32_16x16x32_bf16 v[52:55], v[188:191], v[204:207], v[52:55]
	v_mfma_f32_16x16x32_bf16 v[44:47], v[196:199], v[204:207], v[44:47]
	v_mfma_f32_16x16x32_bf16 v[36:39], v[188:191], v[212:215], v[36:39]
	v_mfma_f32_16x16x32_bf16 v[28:31], v[196:199], v[212:215], v[28:31]
	v_mfma_f32_16x16x32_bf16 v[20:23], v[188:191], v[224:227], v[20:23]
	v_mfma_f32_16x16x32_bf16 v[12:15], v[196:199], v[224:227], v[12:15]
	v_mfma_f32_16x16x32_bf16 v[4:7], v[188:191], v[232:235], v[4:7]
	v_mfma_f32_16x16x32_bf16 v[0:3], v[196:199], v[232:235], v[0:3]
	s_setprio 0
	s_barrier
	s_add_i32 s87, s87, 2
	s_add_u32 s58, s58, 0x100
	s_addc_u32 s59, s59, 0
	s_add_u32 s85, s85, 0x100
	s_addc_u32 s86, s86, 0
.LBB0_189:
	ds_read_b128 v[168:171], v150
	ds_read_b128 v[172:175], v151
	ds_read_b128 v[176:179], v152
	ds_read_b128 v[180:183], v153
	ds_read_b128 v[184:187], v154
	ds_read_b128 v[188:191], v155
	ds_read_b128 v[192:195], v156
	ds_read_b128 v[196:199], v157
	s_add_u32 s64, s58, 0xfffc0080
	s_addc_u32 s65, s59, -1
	s_cmp_eq_u32 s87, 12
	s_cselect_b32 s67, s51, s65
	s_cselect_b32 s66, s83, s64
	s_cselect_b32 s65, s49, s86
	s_cselect_b32 s64, s84, s85
	s_mov_b32 m0, s79
	v_lshl_add_u64 v[146:147], s[58:59], 0, v[136:137]
	ds_read_b128 v[200:203], v148
	ds_read_b128 v[204:207], v148 offset:1024
	ds_read_b128 v[208:211], v148 offset:2048
	ds_read_b128 v[212:215], v148 offset:3072
	ds_read_b128 v[216:219], v148 offset:4096
	ds_read_b128 v[224:227], v148 offset:5120
	ds_read_b128 v[228:231], v148 offset:6144
	ds_read_b128 v[232:235], v148 offset:7168
	global_load_lds_dwordx4 v[146:147], off
	v_lshl_add_u64 v[146:147], s[58:59], 0, v[138:139]
	s_mov_b32 m0, s80
	s_nop 0
	global_load_lds_dwordx4 v[146:147], off
	s_waitcnt vmcnt(8)
	s_waitcnt lgkmcnt(0)
	s_barrier
; #define PG8_STAGE(bufoff, gbase, voff) do { _Pragma("unroll") for (int _i = 0; _i < 2; ++_i) \
;         __builtin_amdgcn_global_load_lds((const unsigned*)((const char*)(gbase) + (voff)[_i]), (PG8_LAS unsigned*)(lds + (bufoff) + ldsw + _i * 8192), 16, 0, 0); } while (0)
; #define PG8_LDA(dst, b, h) do { _Pragma("unroll") for (int m = 0; m < 4; ++m) _Pragma("unroll") for (int k = 0; k < 2; ++k) dst[m][k] = *(const PG8_LAS bf16x8*)(lds + PG8_SA(b, h) + aoff + m * 2048 + k * 1024); } while (0)
; #define PG8_MMA(ai, bj, At, Bt) do { __builtin_amdgcn_s_setprio(1); _Pragma("unroll") for (int m = 0; m < 4; ++m) _Pragma("unroll") for (int n = 0; n < 2; ++n) _Pragma("unroll") for (int k = 0; k < 2; ++k) \
;         acc[ai][bj][m][n] = __builtin_amdgcn_mfma_f32_16x16x32_bf16(Bt[n][k], At[m][k], acc[ai][bj][m][n], 0, 0, 0); __builtin_amdgcn_s_setprio(0); } while (0)
; #define PG8_WAIT_V(n) asm volatile("s_waitcnt vmcnt(" #n ")" ::: "memory")
; #define PG8_WAIT_L(n) asm volatile("s_waitcnt lgkmcnt(" #n ")" ::: "memory")
; #define PG8_BAR __builtin_amdgcn_s_barrier()
; #define PG8_SCHED __builtin_amdgcn_sched_barrier(0)
; template <class Epi, class Sched, bool ALIGN_EPI = false, bool SP2 = false>
; __device__ __forceinline__ void gemm_phase(PG8_LAS unsigned char* lds, const Gemm g, const Sched& S, const Epi& E) {
;     ...
;             PG8_WAIT_V(8); PG8_WAIT_L(0); PG8_BAR; PG8_MMA(0, 0, At, B0); PG8_MMA(0, 1, At, B1); PG8_BAR; PG8_SCHED;
;             PG8_LDA(At, 0, 1); PG8_STAGE(PG8_SB(0, 0), b2, voffB); PG8_STAGE(PG8_SB(0, 1), b2 + hstep, voffB); PG8_STAGE(PG8_SA(0, 0), a2, voffA);
;             PG8_WAIT_V(8); PG8_WAIT_L(0); PG8_BAR; PG8_MMA(1, 0, At, B0); PG8_MMA(1, 1, At, B1); PG8_BAR; PG8_SCHED;
	s_setprio 1
	v_mfma_f32_16x16x32_bf16 v[124:127], v[168:171], v[200:203], v[124:127]
	v_mfma_f32_16x16x32_bf16 v[120:123], v[176:179], v[200:203], v[120:123]
	v_mfma_f32_16x16x32_bf16 v[112:115], v[168:171], v[208:211], v[112:115]
	v_mfma_f32_16x16x32_bf16 v[104:107], v[176:179], v[208:211], v[104:107]
	v_mfma_f32_16x16x32_bf16 v[96:99], v[168:171], v[216:219], v[96:99]
	v_mfma_f32_16x16x32_bf16 v[88:91], v[176:179], v[216:219], v[88:91]
	v_mfma_f32_16x16x32_bf16 v[80:83], v[168:171], v[228:231], v[80:83]
	v_mfma_f32_16x16x32_bf16 v[72:75], v[176:179], v[228:231], v[72:75]
	v_mfma_f32_16x16x32_bf16 v[124:127], v[172:175], v[204:207], v[124:127]
	v_mfma_f32_16x16x32_bf16 v[120:123], v[180:183], v[204:207], v[120:123]
	v_mfma_f32_16x16x32_bf16 v[112:115], v[172:175], v[212:215], v[112:115]
	v_mfma_f32_16x16x32_bf16 v[104:107], v[180:183], v[212:215], v[104:107]
	v_mfma_f32_16x16x32_bf16 v[96:99], v[172:175], v[224:227], v[96:99]
	v_mfma_f32_16x16x32_bf16 v[88:91], v[180:183], v[224:227], v[88:91]
	v_mfma_f32_16x16x32_bf16 v[80:83], v[172:175], v[232:235], v[80:83]
	v_mfma_f32_16x16x32_bf16 v[72:75], v[180:183], v[232:235], v[72:75]
	v_mfma_f32_16x16x32_bf16 v[116:119], v[184:187], v[200:203], v[116:119]
	v_mfma_f32_16x16x32_bf16 v[108:111], v[192:195], v[200:203], v[108:111]
	v_mfma_f32_16x16x32_bf16 v[100:103], v[184:187], v[208:211], v[100:103]
	v_mfma_f32_16x16x32_bf16 v[92:95], v[192:195], v[208:211], v[92:95]
	v_mfma_f32_16x16x32_bf16 v[84:87], v[184:187], v[216:219], v[84:87]
	v_mfma_f32_16x16x32_bf16 v[76:79], v[192:195], v[216:219], v[76:79]
	v_mfma_f32_16x16x32_bf16 v[68:71], v[184:187], v[228:231], v[68:71]
	v_mfma_f32_16x16x32_bf16 v[64:67], v[192:195], v[228:231], v[64:67]
	v_mfma_f32_16x16x32_bf16 v[116:119], v[188:191], v[204:207], v[116:119]
	v_mfma_f32_16x16x32_bf16 v[108:111], v[196:199], v[204:207], v[108:111]
	v_mfma_f32_16x16x32_bf16 v[100:103], v[188:191], v[212:215], v[100:103]
	v_mfma_f32_16x16x32_bf16 v[92:95], v[196:199], v[212:215], v[92:95]
	v_mfma_f32_16x16x32_bf16 v[84:87], v[188:191], v[224:227], v[84:87]
	v_mfma_f32_16x16x32_bf16 v[76:79], v[196:199], v[224:227], v[76:79]
	v_mfma_f32_16x16x32_bf16 v[68:71], v[188:191], v[232:235], v[68:71]
	v_mfma_f32_16x16x32_bf16 v[64:67], v[196:199], v[232:235], v[64:67]
	s_setprio 0
	s_barrier
	s_mov_b32 m0, s3
	v_lshl_add_u64 v[146:147], s[64:65], 0, v[130:131]
	s_add_u32 s88, s64, 0x40000
	ds_read_b128 v[200:203], v148 offset:16384
	ds_read_b128 v[204:207], v148 offset:17408
	ds_read_b128 v[208:211], v148 offset:18432
	ds_read_b128 v[212:215], v148 offset:19456
	ds_read_b128 v[216:219], v148 offset:20480
	ds_read_b128 v[224:227], v148 offset:21504
	ds_read_b128 v[228:231], v148 offset:22528
	ds_read_b128 v[232:235], v148 offset:23552
	global_load_lds_dwordx4 v[146:147], off
	v_lshl_add_u64 v[220:221], s[64:65], 0, v[134:135]
	s_mov_b32 m0, s14
	s_addc_u32 s89, s65, 0
	global_load_lds_dwordx4 v[220:221], off
	v_lshl_add_u64 v[236:237], s[88:89], 0, v[130:131]
	s_mov_b32 m0, s15
	v_lshl_add_u64 v[238:239], s[66:67], 0, v[132:133]
	global_load_lds_dwordx4 v[236:237], off
	v_lshl_add_u64 v[236:237], s[88:89], 0, v[134:135]
	s_mov_b32 m0, s33
	s_nop 0
	global_load_lds_dwordx4 v[236:237], off
	v_lshl_add_u64 v[236:237], s[66:67], 0, v[128:129]
	s_mov_b32 m0, s1
	s_nop 0
	global_load_lds_dwordx4 v[236:237], off
	s_mov_b32 m0, s39
	s_nop 0
	global_load_lds_dwordx4 v[238:239], off
	s_waitcnt vmcnt(8)
	s_waitcnt lgkmcnt(0)
	s_barrier
	s_setprio 1
	v_mfma_f32_16x16x32_bf16 v[60:63], v[168:171], v[200:203], v[60:63]
	v_mfma_f32_16x16x32_bf16 v[56:59], v[176:179], v[200:203], v[56:59]
	v_mfma_f32_16x16x32_bf16 v[48:51], v[168:171], v[208:211], v[48:51]
	v_mfma_f32_16x16x32_bf16 v[40:43], v[176:179], v[208:211], v[40:43]
	v_mfma_f32_16x16x32_bf16 v[32:35], v[168:171], v[216:219], v[32:35]
	v_mfma_f32_16x16x32_bf16 v[24:27], v[176:179], v[216:219], v[24:27]
	v_mfma_f32_16x16x32_bf16 v[16:19], v[168:171], v[228:231], v[16:19]
	v_mfma_f32_16x16x32_bf16 v[8:11], v[176:179], v[228:231], v[8:11]
	v_mfma_f32_16x16x32_bf16 v[60:63], v[172:175], v[204:207], v[60:63]
	v_mfma_f32_16x16x32_bf16 v[56:59], v[180:183], v[204:207], v[56:59]
	v_mfma_f32_16x16x32_bf16 v[48:51], v[172:175], v[212:215], v[48:51]
	v_mfma_f32_16x16x32_bf16 v[40:43], v[180:183], v[212:215], v[40:43]
	v_mfma_f32_16x16x32_bf16 v[32:35], v[172:175], v[224:227], v[32:35]
	v_mfma_f32_16x16x32_bf16 v[24:27], v[180:183], v[224:227], v[24:27]
	v_mfma_f32_16x16x32_bf16 v[16:19], v[172:175], v[232:235], v[16:19]
	v_mfma_f32_16x16x32_bf16 v[8:11], v[180:183], v[232:235], v[8:11]
	v_mfma_f32_16x16x32_bf16 v[52:55], v[184:187], v[200:203], v[52:55]
	v_mfma_f32_16x16x32_bf16 v[44:47], v[192:195], v[200:203], v[44:47]
	v_mfma_f32_16x16x32_bf16 v[36:39], v[184:187], v[208:211], v[36:39]
	v_mfma_f32_16x16x32_bf16 v[28:31], v[192:195], v[208:211], v[28:31]
	v_mfma_f32_16x16x32_bf16 v[20:23], v[184:187], v[216:219], v[20:23]
	v_mfma_f32_16x16x32_bf16 v[12:15], v[192:195], v[216:219], v[12:15]
	v_mfma_f32_16x16x32_bf16 v[4:7], v[184:187], v[228:231], v[4:7]
	v_mfma_f32_16x16x32_bf16 v[0:3], v[192:195], v[228:231], v[0:3]
	v_mfma_f32_16x16x32_bf16 v[52:55], v[188:191], v[204:207], v[52:55]
	v_mfma_f32_16x16x32_bf16 v[44:47], v[196:199], v[204:207], v[44:47]
	v_mfma_f32_16x16x32_bf16 v[36:39], v[188:191], v[212:215], v[36:39]
	v_mfma_f32_16x16x32_bf16 v[28:31], v[196:199], v[212:215], v[28:31]
	v_mfma_f32_16x16x32_bf16 v[20:23], v[188:191], v[224:227], v[20:23]
	v_mfma_f32_16x16x32_bf16 v[12:15], v[196:199], v[224:227], v[12:15]
	v_mfma_f32_16x16x32_bf16 v[4:7], v[188:191], v[232:235], v[4:7]
	v_mfma_f32_16x16x32_bf16 v[0:3], v[196:199], v[232:235], v[0:3]
	s_setprio 0
	s_barrier
; #define PG8_STAGE(bufoff, gbase, voff) do { _Pragma("unroll") for (int _i = 0; _i < 2; ++_i) \
;         __builtin_amdgcn_global_load_lds((const unsigned*)((const char*)(gbase) + (voff)[_i]), (PG8_LAS unsigned*)(lds + (bufoff) + ldsw + _i * 8192), 16, 0, 0); } while (0)
; #define PG8_LDA(dst, b, h) do { _Pragma("unroll") for (int m = 0; m < 4; ++m) _Pragma("unroll") for (int k = 0; k < 2; ++k) dst[m][k] = *(const PG8_LAS bf16x8*)(lds + PG8_SA(b, h) + aoff + m * 2048 + k * 1024); } while (0)
; #define PG8_LDB(dst, b, h) do { _Pragma("unroll") for (int n = 0; n < 2; ++n) _Pragma("unroll") for (int k = 0; k < 2; ++k) dst[n][k] = *(const PG8_LAS bf16x8*)(lds + PG8_SB(b, h) + boff + n * 2048 + k * 1024); } while (0)
; #define PG8_MMA(ai, bj, At, Bt) do { __builtin_amdgcn_s_setprio(1); _Pragma("unroll") for (int m = 0; m < 4; ++m) _Pragma("unroll") for (int n = 0; n < 2; ++n) _Pragma("unroll") for (int k = 0; k < 2; ++k) \
;         acc[ai][bj][m][n] = __builtin_amdgcn_mfma_f32_16x16x32_bf16(Bt[n][k], At[m][k], acc[ai][bj][m][n], 0, 0, 0); __builtin_amdgcn_s_setprio(0); } while (0)
; #define PG8_WAIT_V(n) asm volatile("s_waitcnt vmcnt(" #n ")" ::: "memory")
; #define PG8_WAIT_L(n) asm volatile("s_waitcnt lgkmcnt(" #n ")" ::: "memory")
; #define PG8_BAR __builtin_amdgcn_s_barrier()
; #define PG8_SCHED __builtin_amdgcn_sched_barrier(0)
; template <class Epi, class Sched, bool ALIGN_EPI = false, bool SP2 = false>
; __device__ __forceinline__ void gemm_phase(PG8_LAS unsigned char* lds, const Gemm g, const Sched& S, const Epi& E) {
;     ...
;             PG8_LDB(B0, 1, 0); PG8_LDB(B1, 1, 1); PG8_SCHED; PG8_LDA(At, 1, 0); PG8_STAGE(PG8_SA(0, 1), a2 + hstep, voffA);
;             PG8_WAIT_V(8); PG8_WAIT_L(0); PG8_BAR; PG8_MMA(0, 0, At, B0); PG8_MMA(0, 1, At, B1); PG8_BAR; PG8_SCHED;
;             PG8_LDA(At, 1, 1); PG8_STAGE(PG8_SB(1, 0), b3, voffB); PG8_STAGE(PG8_SB(1, 1), b3 + hstep, voffB); PG8_STAGE(PG8_SA(1, 0), a3, voffA);
;             PG8_WAIT_V(8); PG8_WAIT_L(0); PG8_BAR; PG8_MMA(1, 0, At, B0); PG8_MMA(1, 1, At, B1); PG8_BAR; PG8_SCHED;
;     ...
;         if constexpr (ALIGN_EPI) { if (wr == 0) PG8_BAR; }
	ds_read_b128 v[168:171], v158
	ds_read_b128 v[172:175], v159
	ds_read_b128 v[176:179], v160
	ds_read_b128 v[180:183], v161
	ds_read_b128 v[184:187], v162
	ds_read_b128 v[188:191], v163
	ds_read_b128 v[192:195], v164
	ds_read_b128 v[196:199], v165
	s_add_u32 s66, s66, 0x40000
	s_addc_u32 s67, s67, 0
	s_mov_b32 m0, s43
	v_lshl_add_u64 v[240:241], s[66:67], 0, v[128:129]
	ds_read_b128 v[200:203], v148 offset:32768
	ds_read_b128 v[204:207], v148 offset:33792
	ds_read_b128 v[208:211], v148 offset:34816
	ds_read_b128 v[212:215], v148 offset:35840
	ds_read_b128 v[216:219], v148 offset:36864
	ds_read_b128 v[224:227], v148 offset:37888
	ds_read_b128 v[228:231], v148 offset:38912
	ds_read_b128 v[232:235], v148 offset:39936
	global_load_lds_dwordx4 v[240:241], off
	v_lshl_add_u64 v[240:241], s[66:67], 0, v[132:133]
	s_mov_b32 m0, s57
	s_nop 0
	global_load_lds_dwordx4 v[240:241], off
	s_waitcnt vmcnt(8)
	s_waitcnt lgkmcnt(0)
	s_barrier
	s_setprio 1
	v_mfma_f32_16x16x32_bf16 v[124:127], v[168:171], v[200:203], v[124:127]
	v_mfma_f32_16x16x32_bf16 v[120:123], v[176:179], v[200:203], v[120:123]
	v_mfma_f32_16x16x32_bf16 v[112:115], v[168:171], v[208:211], v[112:115]
	v_mfma_f32_16x16x32_bf16 v[104:107], v[176:179], v[208:211], v[104:107]
	v_mfma_f32_16x16x32_bf16 v[96:99], v[168:171], v[216:219], v[96:99]
	v_mfma_f32_16x16x32_bf16 v[88:91], v[176:179], v[216:219], v[88:91]
	v_mfma_f32_16x16x32_bf16 v[80:83], v[168:171], v[228:231], v[80:83]
	v_mfma_f32_16x16x32_bf16 v[72:75], v[176:179], v[228:231], v[72:75]
	v_mfma_f32_16x16x32_bf16 v[124:127], v[172:175], v[204:207], v[124:127]
	v_mfma_f32_16x16x32_bf16 v[120:123], v[180:183], v[204:207], v[120:123]
	v_mfma_f32_16x16x32_bf16 v[112:115], v[172:175], v[212:215], v[112:115]
	v_mfma_f32_16x16x32_bf16 v[104:107], v[180:183], v[212:215], v[104:107]
	v_mfma_f32_16x16x32_bf16 v[96:99], v[172:175], v[224:227], v[96:99]
	v_mfma_f32_16x16x32_bf16 v[88:91], v[180:183], v[224:227], v[88:91]
	v_mfma_f32_16x16x32_bf16 v[80:83], v[172:175], v[232:235], v[80:83]
	v_mfma_f32_16x16x32_bf16 v[72:75], v[180:183], v[232:235], v[72:75]
	v_mfma_f32_16x16x32_bf16 v[116:119], v[184:187], v[200:203], v[116:119]
	v_mfma_f32_16x16x32_bf16 v[108:111], v[192:195], v[200:203], v[108:111]
	v_mfma_f32_16x16x32_bf16 v[100:103], v[184:187], v[208:211], v[100:103]
	v_mfma_f32_16x16x32_bf16 v[92:95], v[192:195], v[208:211], v[92:95]
	v_mfma_f32_16x16x32_bf16 v[84:87], v[184:187], v[216:219], v[84:87]
	v_mfma_f32_16x16x32_bf16 v[76:79], v[192:195], v[216:219], v[76:79]
	v_mfma_f32_16x16x32_bf16 v[68:71], v[184:187], v[228:231], v[68:71]
	v_mfma_f32_16x16x32_bf16 v[64:67], v[192:195], v[228:231], v[64:67]
	v_mfma_f32_16x16x32_bf16 v[116:119], v[188:191], v[204:207], v[116:119]
	v_mfma_f32_16x16x32_bf16 v[108:111], v[196:199], v[204:207], v[108:111]
	v_mfma_f32_16x16x32_bf16 v[100:103], v[188:191], v[212:215], v[100:103]
	v_mfma_f32_16x16x32_bf16 v[92:95], v[196:199], v[212:215], v[92:95]
	v_mfma_f32_16x16x32_bf16 v[84:87], v[188:191], v[224:227], v[84:87]
	v_mfma_f32_16x16x32_bf16 v[76:79], v[196:199], v[224:227], v[76:79]
	v_mfma_f32_16x16x32_bf16 v[68:71], v[188:191], v[232:235], v[68:71]
	v_mfma_f32_16x16x32_bf16 v[64:67], v[196:199], v[232:235], v[64:67]
	s_setprio 0
	s_barrier
	s_mov_b32 m0, s71
	v_lshl_add_u64 v[146:147], v[146:147], 0, s[10:11]
	s_add_u32 s64, s64, 0x40080
	ds_read_b128 v[200:203], v148 offset:49152
	ds_read_b128 v[204:207], v148 offset:50176
	ds_read_b128 v[208:211], v148 offset:51200
	ds_read_b128 v[212:215], v148 offset:52224
	ds_read_b128 v[216:219], v148 offset:53248
	ds_read_b128 v[224:227], v148 offset:54272
	ds_read_b128 v[228:231], v148 offset:55296
	ds_read_b128 v[232:235], v148 offset:56320
	global_load_lds_dwordx4 v[146:147], off
	v_lshl_add_u64 v[146:147], v[220:221], 0, s[10:11]
	s_mov_b32 m0, s72
	s_addc_u32 s65, s65, 0
	global_load_lds_dwordx4 v[146:147], off
	v_lshl_add_u64 v[146:147], s[64:65], 0, v[130:131]
	s_mov_b32 m0, s75
	s_nop 0
	global_load_lds_dwordx4 v[146:147], off
	v_lshl_add_u64 v[146:147], s[64:65], 0, v[134:135]
	s_mov_b32 m0, s76
	s_nop 0
	global_load_lds_dwordx4 v[146:147], off
	v_lshl_add_u64 v[146:147], v[236:237], 0, s[10:11]
	s_mov_b32 m0, s73
	s_nop 0
	global_load_lds_dwordx4 v[146:147], off
	v_lshl_add_u64 v[146:147], v[238:239], 0, s[10:11]
	s_mov_b32 m0, s74
	s_nop 0
	global_load_lds_dwordx4 v[146:147], off
	s_waitcnt vmcnt(8)
	s_waitcnt lgkmcnt(0)
	s_barrier
	s_setprio 1
	v_mfma_f32_16x16x32_bf16 v[60:63], v[168:171], v[200:203], v[60:63]
	v_mfma_f32_16x16x32_bf16 v[56:59], v[176:179], v[200:203], v[56:59]
	v_mfma_f32_16x16x32_bf16 v[48:51], v[168:171], v[208:211], v[48:51]
	v_mfma_f32_16x16x32_bf16 v[40:43], v[176:179], v[208:211], v[40:43]
	v_mfma_f32_16x16x32_bf16 v[32:35], v[168:171], v[216:219], v[32:35]
	v_mfma_f32_16x16x32_bf16 v[24:27], v[176:179], v[216:219], v[24:27]
	v_mfma_f32_16x16x32_bf16 v[16:19], v[168:171], v[228:231], v[16:19]
	v_mfma_f32_16x16x32_bf16 v[8:11], v[176:179], v[228:231], v[8:11]
	v_mfma_f32_16x16x32_bf16 v[60:63], v[172:175], v[204:207], v[60:63]
	v_mfma_f32_16x16x32_bf16 v[56:59], v[180:183], v[204:207], v[56:59]
	v_mfma_f32_16x16x32_bf16 v[48:51], v[172:175], v[212:215], v[48:51]
	v_mfma_f32_16x16x32_bf16 v[40:43], v[180:183], v[212:215], v[40:43]
	v_mfma_f32_16x16x32_bf16 v[32:35], v[172:175], v[224:227], v[32:35]
	v_mfma_f32_16x16x32_bf16 v[24:27], v[180:183], v[224:227], v[24:27]
	v_mfma_f32_16x16x32_bf16 v[16:19], v[172:175], v[232:235], v[16:19]
	v_mfma_f32_16x16x32_bf16 v[8:11], v[180:183], v[232:235], v[8:11]
	v_mfma_f32_16x16x32_bf16 v[52:55], v[184:187], v[200:203], v[52:55]
	v_mfma_f32_16x16x32_bf16 v[44:47], v[192:195], v[200:203], v[44:47]
	v_mfma_f32_16x16x32_bf16 v[36:39], v[184:187], v[208:211], v[36:39]
	v_mfma_f32_16x16x32_bf16 v[28:31], v[192:195], v[208:211], v[28:31]
	v_mfma_f32_16x16x32_bf16 v[20:23], v[184:187], v[216:219], v[20:23]
	v_mfma_f32_16x16x32_bf16 v[12:15], v[192:195], v[216:219], v[12:15]
	v_mfma_f32_16x16x32_bf16 v[4:7], v[184:187], v[228:231], v[4:7]
	v_mfma_f32_16x16x32_bf16 v[0:3], v[192:195], v[228:231], v[0:3]
	v_mfma_f32_16x16x32_bf16 v[52:55], v[188:191], v[204:207], v[52:55]
	v_mfma_f32_16x16x32_bf16 v[44:47], v[196:199], v[204:207], v[44:47]
	v_mfma_f32_16x16x32_bf16 v[36:39], v[188:191], v[212:215], v[36:39]
	v_mfma_f32_16x16x32_bf16 v[28:31], v[196:199], v[212:215], v[28:31]
	v_mfma_f32_16x16x32_bf16 v[20:23], v[188:191], v[224:227], v[20:23]
	v_mfma_f32_16x16x32_bf16 v[12:15], v[196:199], v[224:227], v[12:15]
	v_mfma_f32_16x16x32_bf16 v[4:7], v[188:191], v[232:235], v[4:7]
	v_mfma_f32_16x16x32_bf16 v[0:3], v[196:199], v[232:235], v[0:3]
	s_setprio 0
	s_barrier
	s_add_i32 s87, s87, 2
	s_add_u32 s58, s58, 0x100
	s_addc_u32 s59, s59, 0
	s_add_u32 s85, s85, 0x100
	s_addc_u32 s86, s86, 0
	s_cmp_gt_u32 s87, 13
	s_cbranch_scc0 .LBB0_189
	s_and_b64 vcc, exec, s[12:13]
	s_cbranch_vccz .LBB0_192
	s_barrier

;     __host__ __device__ bool next(int i, Unit& u) const { const int L = i * G + c; if (L >= 16 * nkc) return false; u.kc = L % nkc; const int t = L / nkc; u.pn = t & 3; u.pm = 33 * (t >> 2); return true; }
; #define PG8_STAGE(bufoff, gbase, voff) do { _Pragma("unroll") for (int _i = 0; _i < 2; ++_i) \
;         __builtin_amdgcn_global_load_lds((const unsigned*)((const char*)(gbase) + (voff)[_i]), (PG8_LAS unsigned*)(lds + (bufoff) + ldsw + _i * 8192), 16, 0, 0); } while (0)
; #define PG8_LDA(dst, b, h) do { _Pragma("unroll") for (int m = 0; m < 4; ++m) _Pragma("unroll") for (int k = 0; k < 2; ++k) dst[m][k] = *(const PG8_LAS bf16x8*)(lds + PG8_SA(b, h) + aoff + m * 2048 + k * 1024); } while (0)
; #define PG8_LDB(dst, b, h) do { _Pragma("unroll") for (int n = 0; n < 2; ++n) _Pragma("unroll") for (int k = 0; k < 2; ++k) dst[n][k] = *(const PG8_LAS bf16x8*)(lds + PG8_SB(b, h) + boff + n * 2048 + k * 1024); } while (0)
; #define PG8_BAR __builtin_amdgcn_s_barrier()
; template <class Epi, class Sched, bool ALIGN_EPI = false, bool SP2 = false>
; __device__ __forceinline__ void gemm_phase(PG8_LAS unsigned char* lds, const Gemm g, const Sched& S, const Epi& E) {
;     ...
;         const bool has_next = S.next(ui + 1, nxt);
;         const char* nA = has_next ? (const char*)g.A + (size_t)nxt.pm * tstep + (size_t)nxt.kc * cstep : cA; const char* nB = has_next ? (const char*)g.Bt + (size_t)nxt.pn * tstep + (size_t)nxt.kc * cstep : cB;
;         for (int t = 0; t < nt; t += 2) {
;             const bool last = (t == nt - 2);
;             const char* a1 = cA + (size_t)(t + 1) * kstep;
;             const char* a2 = last ? nA : cA + (size_t)(t + 2) * kstep; const char* b2 = last ? nB : cB + (size_t)(t + 2) * kstep;
;             const char* a3 = a2 + kstep; const char* b3 = b2 + kstep;
;             if (last && has_next) S.a_ready(nxt);
;             if constexpr (SP2) {
;             PG8_LDB(B0, 0, 0); PG8_LDB(B1, 0, 1); PG8_SCHED; PG8_LDA(At, 0, 0); PG8_STAGE(PG8_SA(1, 1), a1 + hstep, voffA);
;             PG8_WAIT_V(8); PG8_WAIT_L(0); PG8_BAR; PG8_MMA(0, 0, At, B0); PG8_MMA(0, 1, At, B1); PG8_BAR; PG8_SCHED;
;             PG8_LDA(At, 0, 1); PG8_STAGE(PG8_SB(0, 0), b2, voffB); PG8_STAGE(PG8_SB(0, 1), b2 + hstep, voffB); PG8_STAGE(PG8_SA(0, 0), a2, voffA);
;             PG8_WAIT_V(8); PG8_WAIT_L(0); PG8_BAR; PG8_MMA(1, 0, At, B0); PG8_MMA(1, 1, At, B1); PG8_BAR; PG8_SCHED;
.LBB0_633:
	s_ashr_i32 s57, s56, 31
	s_lshl_b64 s[6:7], s[56:57], 19
	s_add_u32 s58, s46, s6
	s_addc_u32 s59, s47, s7
	s_and_b64 s[6:7], s[4:5], exec
	s_cselect_b32 s57, s59, s65
	s_cselect_b32 vcc_lo, s58, s64
	s_ashr_i32 s55, s54, 31
	s_lshl_b64 s[6:7], s[54:55], 19
	s_add_u32 s60, s0, s6
	s_addc_u32 s61, s1, s7
	s_and_b64 s[6:7], s[4:5], exec
	s_cselect_b32 s55, s61, s67
	s_cselect_b32 vcc_hi, s60, s66
	s_add_u32 s90, s66, 0x100
	s_addc_u32 s92, s67, 0
	s_mov_b32 s6, -2
	s_waitcnt vmcnt(0)
	ds_read_b128 v[142:145], v174
	ds_read_b128 v[146:149], v175
	ds_read_b128 v[150:153], v176
	ds_read_b128 v[154:157], v177
	ds_read_b128 v[158:161], v178
	ds_read_b128 v[162:165], v179
	ds_read_b128 v[166:169], v180
	ds_read_b128 v[190:193], v181
	s_add_u32 s66, s64, 0x100
	s_addc_u32 s67, s65, 0
	s_cmp_eq_u32 s6, 12
	s_cselect_b32 s73, s57, s67
	s_cselect_b32 s72, vcc_lo, s66
	s_cselect_b32 s71, s55, s92
	s_cselect_b32 s70, vcc_hi, s90
	s_mov_b32 m0, s86
	v_lshl_add_u64 v[170:171], s[64:65], 0, v[134:135]
	ds_read_b128 v[194:197], v172
	ds_read_b128 v[198:201], v172 offset:1024
	ds_read_b128 v[202:205], v172 offset:2048
	ds_read_b128 v[206:209], v172 offset:3072
	ds_read_b128 v[210:213], v172 offset:4096
	ds_read_b128 v[214:217], v172 offset:5120
	ds_read_b128 v[218:221], v172 offset:6144
	ds_read_b128 v[224:227], v172 offset:7168
	global_load_lds_dwordx4 v[170:171], off
	v_lshl_add_u64 v[170:171], s[64:65], 0, v[136:137]
	s_mov_b32 m0, s87
	s_nop 0
	global_load_lds_dwordx4 v[170:171], off
	s_waitcnt vmcnt(8)
	s_waitcnt lgkmcnt(0)
	s_barrier
	s_setprio 1
	v_mfma_f32_16x16x32_bf16 v[124:127], v[142:145], v[194:197], 0
	v_mfma_f32_16x16x32_bf16 v[108:111], v[150:153], v[194:197], 0
	v_mfma_f32_16x16x32_bf16 v[120:123], v[142:145], v[202:205], 0
	v_mfma_f32_16x16x32_bf16 v[96:99], v[150:153], v[202:205], 0
	v_mfma_f32_16x16x32_bf16 v[116:119], v[142:145], v[210:213], 0
	v_mfma_f32_16x16x32_bf16 v[88:91], v[150:153], v[210:213], 0
	v_mfma_f32_16x16x32_bf16 v[112:115], v[142:145], v[218:221], 0
	v_mfma_f32_16x16x32_bf16 v[84:87], v[150:153], v[218:221], 0
	v_mfma_f32_16x16x32_bf16 v[124:127], v[146:149], v[198:201], v[124:127]
	v_mfma_f32_16x16x32_bf16 v[108:111], v[154:157], v[198:201], v[108:111]
	v_mfma_f32_16x16x32_bf16 v[120:123], v[146:149], v[206:209], v[120:123]
	v_mfma_f32_16x16x32_bf16 v[96:99], v[154:157], v[206:209], v[96:99]
	v_mfma_f32_16x16x32_bf16 v[116:119], v[146:149], v[214:217], v[116:119]
	v_mfma_f32_16x16x32_bf16 v[88:91], v[154:157], v[214:217], v[88:91]
	v_mfma_f32_16x16x32_bf16 v[112:115], v[146:149], v[224:227], v[112:115]
	v_mfma_f32_16x16x32_bf16 v[84:87], v[154:157], v[224:227], v[84:87]
	v_mfma_f32_16x16x32_bf16 v[68:71], v[158:161], v[194:197], 0
	v_mfma_f32_16x16x32_bf16 v[40:43], v[166:169], v[194:197], 0
	v_mfma_f32_16x16x32_bf16 v[60:63], v[158:161], v[202:205], 0
	v_mfma_f32_16x16x32_bf16 v[32:35], v[166:169], v[202:205], 0
	v_mfma_f32_16x16x32_bf16 v[52:55], v[158:161], v[210:213], 0
	v_mfma_f32_16x16x32_bf16 v[24:27], v[166:169], v[210:213], 0
	v_mfma_f32_16x16x32_bf16 v[48:51], v[158:161], v[218:221], 0
	v_mfma_f32_16x16x32_bf16 v[16:19], v[166:169], v[218:221], 0
	v_mfma_f32_16x16x32_bf16 v[68:71], v[162:165], v[198:201], v[68:71]
	v_mfma_f32_16x16x32_bf16 v[40:43], v[190:193], v[198:201], v[40:43]
	v_mfma_f32_16x16x32_bf16 v[60:63], v[162:165], v[206:209], v[60:63]
	v_mfma_f32_16x16x32_bf16 v[32:35], v[190:193], v[206:209], v[32:35]
	v_mfma_f32_16x16x32_bf16 v[52:55], v[162:165], v[214:217], v[52:55]
	v_mfma_f32_16x16x32_bf16 v[24:27], v[190:193], v[214:217], v[24:27]
	v_mfma_f32_16x16x32_bf16 v[48:51], v[162:165], v[224:227], v[48:51]
	v_mfma_f32_16x16x32_bf16 v[16:19], v[190:193], v[224:227], v[16:19]
	s_setprio 0
	s_barrier
	s_mov_b32 m0, s13
	v_lshl_add_u64 v[170:171], s[70:71], 0, v[128:129]
	s_add_u32 s64, s70, 0x40000
	ds_read_b128 v[194:197], v172 offset:16384
	ds_read_b128 v[198:201], v172 offset:17408
	ds_read_b128 v[202:205], v172 offset:18432
	ds_read_b128 v[206:209], v172 offset:19456
	ds_read_b128 v[210:213], v172 offset:20480
	ds_read_b128 v[214:217], v172 offset:21504
	ds_read_b128 v[218:221], v172 offset:22528
	ds_read_b128 v[224:227], v172 offset:23552
	global_load_lds_dwordx4 v[170:171], off
	v_lshl_add_u64 v[228:229], s[70:71], 0, v[130:131]
	s_mov_b32 m0, s14
	s_addc_u32 s65, s71, 0
	global_load_lds_dwordx4 v[228:229], off
	v_lshl_add_u64 v[230:231], s[64:65], 0, v[128:129]
	s_mov_b32 m0, s15
	v_lshl_add_u64 v[232:233], s[72:73], 0, v[130:131]
	global_load_lds_dwordx4 v[230:231], off
	v_lshl_add_u64 v[230:231], s[64:65], 0, v[130:131]
	s_mov_b32 m0, s33
	s_nop 0
	global_load_lds_dwordx4 v[230:231], off
	v_lshl_add_u64 v[230:231], s[72:73], 0, v[128:129]
	s_mov_b32 m0, s12
	s_nop 0
	global_load_lds_dwordx4 v[230:231], off
	s_mov_b32 m0, s39
	s_nop 0
	global_load_lds_dwordx4 v[232:233], off
	s_waitcnt vmcnt(8)
	s_waitcnt lgkmcnt(0)
	s_barrier
; #define PG8_STAGE(bufoff, gbase, voff) do { _Pragma("unroll") for (int _i = 0; _i < 2; ++_i) \
;         __builtin_amdgcn_global_load_lds((const unsigned*)((const char*)(gbase) + (voff)[_i]), (PG8_LAS unsigned*)(lds + (bufoff) + ldsw + _i * 8192), 16, 0, 0); } while (0)
; #define PG8_LDA(dst, b, h) do { _Pragma("unroll") for (int m = 0; m < 4; ++m) _Pragma("unroll") for (int k = 0; k < 2; ++k) dst[m][k] = *(const PG8_LAS bf16x8*)(lds + PG8_SA(b, h) + aoff + m * 2048 + k * 1024); } while (0)
; #define PG8_LDB(dst, b, h) do { _Pragma("unroll") for (int n = 0; n < 2; ++n) _Pragma("unroll") for (int k = 0; k < 2; ++k) dst[n][k] = *(const PG8_LAS bf16x8*)(lds + PG8_SB(b, h) + boff + n * 2048 + k * 1024); } while (0)
; #define PG8_MMA(ai, bj, At, Bt) do { __builtin_amdgcn_s_setprio(1); _Pragma("unroll") for (int m = 0; m < 4; ++m) _Pragma("unroll") for (int n = 0; n < 2; ++n) _Pragma("unroll") for (int k = 0; k < 2; ++k) \
;         acc[ai][bj][m][n] = __builtin_amdgcn_mfma_f32_16x16x32_bf16(Bt[n][k], At[m][k], acc[ai][bj][m][n], 0, 0, 0); __builtin_amdgcn_s_setprio(0); } while (0)
; #define PG8_WAIT_V(n) asm volatile("s_waitcnt vmcnt(" #n ")" ::: "memory")
; #define PG8_WAIT_L(n) asm volatile("s_waitcnt lgkmcnt(" #n ")" ::: "memory")
; #define PG8_BAR __builtin_amdgcn_s_barrier()
; #define PG8_SCHED __builtin_amdgcn_sched_barrier(0)
; template <class Epi, class Sched, bool ALIGN_EPI = false, bool SP2 = false>
; __device__ __forceinline__ void gemm_phase(PG8_LAS unsigned char* lds, const Gemm g, const Sched& S, const Epi& E) {
;     ...
;             PG8_WAIT_V(8); PG8_WAIT_L(0); PG8_BAR; PG8_MMA(1, 0, At, B0); PG8_MMA(1, 1, At, B1); PG8_BAR; PG8_SCHED;
;             PG8_LDB(B0, 1, 0); PG8_LDB(B1, 1, 1); PG8_SCHED; PG8_LDA(At, 1, 0); PG8_STAGE(PG8_SA(0, 1), a2 + hstep, voffA);
;             PG8_WAIT_V(8); PG8_WAIT_L(0); PG8_BAR; PG8_MMA(0, 0, At, B0); PG8_MMA(0, 1, At, B1); PG8_BAR; PG8_SCHED;
	s_setprio 1
	v_mfma_f32_16x16x32_bf16 v[104:107], v[142:145], v[194:197], 0
	v_mfma_f32_16x16x32_bf16 v[76:79], v[150:153], v[194:197], 0
	v_mfma_f32_16x16x32_bf16 v[100:103], v[142:145], v[202:205], 0
	v_mfma_f32_16x16x32_bf16 v[72:75], v[150:153], v[202:205], 0
	v_mfma_f32_16x16x32_bf16 v[92:95], v[142:145], v[210:213], 0
	v_mfma_f32_16x16x32_bf16 v[64:67], v[150:153], v[210:213], 0
	v_mfma_f32_16x16x32_bf16 v[80:83], v[142:145], v[218:221], 0
	v_mfma_f32_16x16x32_bf16 v[56:59], v[150:153], v[218:221], 0
	v_mfma_f32_16x16x32_bf16 v[104:107], v[146:149], v[198:201], v[104:107]
	v_mfma_f32_16x16x32_bf16 v[76:79], v[154:157], v[198:201], v[76:79]
	v_mfma_f32_16x16x32_bf16 v[100:103], v[146:149], v[206:209], v[100:103]
	v_mfma_f32_16x16x32_bf16 v[72:75], v[154:157], v[206:209], v[72:75]
	v_mfma_f32_16x16x32_bf16 v[92:95], v[146:149], v[214:217], v[92:95]
	v_mfma_f32_16x16x32_bf16 v[64:67], v[154:157], v[214:217], v[64:67]
	v_mfma_f32_16x16x32_bf16 v[80:83], v[146:149], v[224:227], v[80:83]
	v_mfma_f32_16x16x32_bf16 v[56:59], v[154:157], v[224:227], v[56:59]
	v_mfma_f32_16x16x32_bf16 v[44:47], v[158:161], v[194:197], 0
	v_mfma_f32_16x16x32_bf16 v[12:15], v[166:169], v[194:197], 0
	v_mfma_f32_16x16x32_bf16 v[36:39], v[158:161], v[202:205], 0
	v_mfma_f32_16x16x32_bf16 v[8:11], v[166:169], v[202:205], 0
	v_mfma_f32_16x16x32_bf16 v[28:31], v[158:161], v[210:213], 0
	v_mfma_f32_16x16x32_bf16 v[4:7], v[166:169], v[210:213], 0
	v_mfma_f32_16x16x32_bf16 v[20:23], v[158:161], v[218:221], 0
	v_mfma_f32_16x16x32_bf16 v[0:3], v[166:169], v[218:221], 0
	v_mfma_f32_16x16x32_bf16 v[44:47], v[162:165], v[198:201], v[44:47]
	v_mfma_f32_16x16x32_bf16 v[12:15], v[190:193], v[198:201], v[12:15]
	v_mfma_f32_16x16x32_bf16 v[36:39], v[162:165], v[206:209], v[36:39]
	v_mfma_f32_16x16x32_bf16 v[8:11], v[190:193], v[206:209], v[8:11]
	v_mfma_f32_16x16x32_bf16 v[28:31], v[162:165], v[214:217], v[28:31]
	v_mfma_f32_16x16x32_bf16 v[4:7], v[190:193], v[214:217], v[4:7]
	v_mfma_f32_16x16x32_bf16 v[20:23], v[162:165], v[224:227], v[20:23]
	v_mfma_f32_16x16x32_bf16 v[0:3], v[190:193], v[224:227], v[0:3]
	s_setprio 0
	s_barrier
	ds_read_b128 v[142:145], v182
	ds_read_b128 v[146:149], v183
	ds_read_b128 v[150:153], v184
	ds_read_b128 v[154:157], v185
	ds_read_b128 v[158:161], v186
	ds_read_b128 v[162:165], v187
	ds_read_b128 v[166:169], v188
	ds_read_b128 v[190:193], v189
	s_add_u32 s64, s72, 0x40000
	s_addc_u32 s65, s73, 0
	s_mov_b32 m0, s43
	v_lshl_add_u64 v[234:235], s[64:65], 0, v[128:129]
	ds_read_b128 v[194:197], v172 offset:32768
	ds_read_b128 v[198:201], v172 offset:33792
	ds_read_b128 v[202:205], v172 offset:34816
	ds_read_b128 v[206:209], v172 offset:35840
	ds_read_b128 v[210:213], v172 offset:36864
	ds_read_b128 v[214:217], v172 offset:37888
	ds_read_b128 v[218:221], v172 offset:38912
	ds_read_b128 v[224:227], v172 offset:39936
	global_load_lds_dwordx4 v[234:235], off
	v_lshl_add_u64 v[234:235], s[64:65], 0, v[130:131]
	s_mov_b32 m0, s74
	s_nop 0
	global_load_lds_dwordx4 v[234:235], off
	s_waitcnt vmcnt(8)
	s_waitcnt lgkmcnt(0)
	s_barrier
	s_setprio 1
	v_mfma_f32_16x16x32_bf16 v[124:127], v[142:145], v[194:197], v[124:127]
	v_mfma_f32_16x16x32_bf16 v[108:111], v[150:153], v[194:197], v[108:111]
	v_mfma_f32_16x16x32_bf16 v[120:123], v[142:145], v[202:205], v[120:123]
	v_mfma_f32_16x16x32_bf16 v[96:99], v[150:153], v[202:205], v[96:99]
	v_mfma_f32_16x16x32_bf16 v[116:119], v[142:145], v[210:213], v[116:119]
	v_mfma_f32_16x16x32_bf16 v[88:91], v[150:153], v[210:213], v[88:91]
	v_mfma_f32_16x16x32_bf16 v[112:115], v[142:145], v[218:221], v[112:115]
	v_mfma_f32_16x16x32_bf16 v[84:87], v[150:153], v[218:221], v[84:87]
	v_mfma_f32_16x16x32_bf16 v[124:127], v[146:149], v[198:201], v[124:127]
	v_mfma_f32_16x16x32_bf16 v[108:111], v[154:157], v[198:201], v[108:111]
	v_mfma_f32_16x16x32_bf16 v[120:123], v[146:149], v[206:209], v[120:123]
	v_mfma_f32_16x16x32_bf16 v[96:99], v[154:157], v[206:209], v[96:99]
	v_mfma_f32_16x16x32_bf16 v[116:119], v[146:149], v[214:217], v[116:119]
	v_mfma_f32_16x16x32_bf16 v[88:91], v[154:157], v[214:217], v[88:91]
	v_mfma_f32_16x16x32_bf16 v[112:115], v[146:149], v[224:227], v[112:115]
	v_mfma_f32_16x16x32_bf16 v[84:87], v[154:157], v[224:227], v[84:87]
	v_mfma_f32_16x16x32_bf16 v[68:71], v[158:161], v[194:197], v[68:71]
	v_mfma_f32_16x16x32_bf16 v[40:43], v[166:169], v[194:197], v[40:43]
	v_mfma_f32_16x16x32_bf16 v[60:63], v[158:161], v[202:205], v[60:63]
	v_mfma_f32_16x16x32_bf16 v[32:35], v[166:169], v[202:205], v[32:35]
	v_mfma_f32_16x16x32_bf16 v[52:55], v[158:161], v[210:213], v[52:55]
	v_mfma_f32_16x16x32_bf16 v[24:27], v[166:169], v[210:213], v[24:27]
	v_mfma_f32_16x16x32_bf16 v[48:51], v[158:161], v[218:221], v[48:51]
	v_mfma_f32_16x16x32_bf16 v[16:19], v[166:169], v[218:221], v[16:19]
	v_mfma_f32_16x16x32_bf16 v[68:71], v[162:165], v[198:201], v[68:71]
	v_mfma_f32_16x16x32_bf16 v[40:43], v[190:193], v[198:201], v[40:43]
	v_mfma_f32_16x16x32_bf16 v[60:63], v[162:165], v[206:209], v[60:63]
	v_mfma_f32_16x16x32_bf16 v[32:35], v[190:193], v[206:209], v[32:35]
	v_mfma_f32_16x16x32_bf16 v[52:55], v[162:165], v[214:217], v[52:55]
	v_mfma_f32_16x16x32_bf16 v[24:27], v[190:193], v[214:217], v[24:27]
	v_mfma_f32_16x16x32_bf16 v[48:51], v[162:165], v[224:227], v[48:51]
	v_mfma_f32_16x16x32_bf16 v[16:19], v[190:193], v[224:227], v[16:19]
	s_setprio 0
	s_barrier
; #define PG8_STAGE(bufoff, gbase, voff) do { _Pragma("unroll") for (int _i = 0; _i < 2; ++_i) \
;         __builtin_amdgcn_global_load_lds((const unsigned*)((const char*)(gbase) + (voff)[_i]), (PG8_LAS unsigned*)(lds + (bufoff) + ldsw + _i * 8192), 16, 0, 0); } while (0)
; #define PG8_LDA(dst, b, h) do { _Pragma("unroll") for (int m = 0; m < 4; ++m) _Pragma("unroll") for (int k = 0; k < 2; ++k) dst[m][k] = *(const PG8_LAS bf16x8*)(lds + PG8_SA(b, h) + aoff + m * 2048 + k * 1024); } while (0)
; #define PG8_LDB(dst, b, h) do { _Pragma("unroll") for (int n = 0; n < 2; ++n) _Pragma("unroll") for (int k = 0; k < 2; ++k) dst[n][k] = *(const PG8_LAS bf16x8*)(lds + PG8_SB(b, h) + boff + n * 2048 + k * 1024); } while (0)
; #define PG8_MMA(ai, bj, At, Bt) do { __builtin_amdgcn_s_setprio(1); _Pragma("unroll") for (int m = 0; m < 4; ++m) _Pragma("unroll") for (int n = 0; n < 2; ++n) _Pragma("unroll") for (int k = 0; k < 2; ++k) \
;         acc[ai][bj][m][n] = __builtin_amdgcn_mfma_f32_16x16x32_bf16(Bt[n][k], At[m][k], acc[ai][bj][m][n], 0, 0, 0); __builtin_amdgcn_s_setprio(0); } while (0)
; #define PG8_WAIT_V(n) asm volatile("s_waitcnt vmcnt(" #n ")" ::: "memory")
; template <class Epi, class Sched, bool ALIGN_EPI = false, bool SP2 = false>
; __device__ __forceinline__ void gemm_phase(PG8_LAS unsigned char* lds, const Gemm g, const Sched& S, const Epi& E) {
;     ...
;             PG8_LDB(B0, 0, 0); PG8_LDB(B1, 0, 1); PG8_SCHED; PG8_LDA(At, 0, 0); PG8_STAGE(PG8_SA(1, 1), a1 + hstep, voffA);
;             PG8_WAIT_V(8); PG8_WAIT_L(0); PG8_BAR; PG8_MMA(0, 0, At, B0); PG8_MMA(0, 1, At, B1); PG8_BAR; PG8_SCHED;
;             PG8_LDA(At, 0, 1); PG8_STAGE(PG8_SB(0, 0), b2, voffB); PG8_STAGE(PG8_SB(0, 1), b2 + hstep, voffB); PG8_STAGE(PG8_SA(0, 0), a2, voffA);
;             PG8_WAIT_V(8); PG8_WAIT_L(0); PG8_BAR; PG8_MMA(1, 0, At, B0); PG8_MMA(1, 1, At, B1); PG8_BAR; PG8_SCHED;
;             PG8_LDB(B0, 1, 0); PG8_LDB(B1, 1, 1); PG8_SCHED; PG8_LDA(At, 1, 0); PG8_STAGE(PG8_SA(0, 1), a2 + hstep, voffA);
;             PG8_WAIT_V(8); PG8_WAIT_L(0); PG8_BAR; PG8_MMA(0, 0, At, B0); PG8_MMA(0, 1, At, B1); PG8_BAR; PG8_SCHED;
;             PG8_LDA(At, 1, 1); PG8_STAGE(PG8_SB(1, 0), b3, voffB); PG8_STAGE(PG8_SB(1, 1), b3 + hstep, voffB); PG8_STAGE(PG8_SA(1, 0), a3, voffA);
;             PG8_WAIT_V(8); PG8_WAIT_L(0); PG8_BAR; PG8_MMA(1, 0, At, B0); PG8_MMA(1, 1, At, B1); PG8_BAR; PG8_SCHED;
	s_mov_b32 m0, s78
	v_lshl_add_u64 v[170:171], v[170:171], 0, s[10:11]
	s_add_u32 s64, s70, 0x40080
	ds_read_b128 v[194:197], v172 offset:49152
	ds_read_b128 v[198:201], v172 offset:50176
	ds_read_b128 v[202:205], v172 offset:51200
	ds_read_b128 v[206:209], v172 offset:52224
	ds_read_b128 v[210:213], v172 offset:53248
	ds_read_b128 v[214:217], v172 offset:54272
	ds_read_b128 v[218:221], v172 offset:55296
	ds_read_b128 v[224:227], v172 offset:56320
	global_load_lds_dwordx4 v[170:171], off
	v_lshl_add_u64 v[170:171], v[228:229], 0, s[10:11]
	s_mov_b32 m0, s79
	s_addc_u32 s65, s71, 0
	global_load_lds_dwordx4 v[170:171], off
	v_lshl_add_u64 v[170:171], s[64:65], 0, v[128:129]
	s_mov_b32 m0, s82
	s_nop 0
	global_load_lds_dwordx4 v[170:171], off
	v_lshl_add_u64 v[170:171], s[64:65], 0, v[130:131]
	s_mov_b32 m0, s83
	s_nop 0
	global_load_lds_dwordx4 v[170:171], off
	v_lshl_add_u64 v[170:171], v[230:231], 0, s[10:11]
	s_mov_b32 m0, s80
	s_nop 0
	global_load_lds_dwordx4 v[170:171], off
	v_lshl_add_u64 v[170:171], v[232:233], 0, s[10:11]
	s_mov_b32 m0, s81
	s_nop 0
	global_load_lds_dwordx4 v[170:171], off
	s_waitcnt vmcnt(8)
	s_waitcnt lgkmcnt(0)
	s_barrier
	s_setprio 1
	v_mfma_f32_16x16x32_bf16 v[104:107], v[142:145], v[194:197], v[104:107]
	v_mfma_f32_16x16x32_bf16 v[76:79], v[150:153], v[194:197], v[76:79]
	v_mfma_f32_16x16x32_bf16 v[100:103], v[142:145], v[202:205], v[100:103]
	v_mfma_f32_16x16x32_bf16 v[72:75], v[150:153], v[202:205], v[72:75]
	v_mfma_f32_16x16x32_bf16 v[92:95], v[142:145], v[210:213], v[92:95]
	v_mfma_f32_16x16x32_bf16 v[64:67], v[150:153], v[210:213], v[64:67]
	v_mfma_f32_16x16x32_bf16 v[80:83], v[142:145], v[218:221], v[80:83]
	v_mfma_f32_16x16x32_bf16 v[56:59], v[150:153], v[218:221], v[56:59]
	v_mfma_f32_16x16x32_bf16 v[104:107], v[146:149], v[198:201], v[104:107]
	v_mfma_f32_16x16x32_bf16 v[76:79], v[154:157], v[198:201], v[76:79]
	v_mfma_f32_16x16x32_bf16 v[100:103], v[146:149], v[206:209], v[100:103]
	v_mfma_f32_16x16x32_bf16 v[72:75], v[154:157], v[206:209], v[72:75]
	v_mfma_f32_16x16x32_bf16 v[92:95], v[146:149], v[214:217], v[92:95]
	v_mfma_f32_16x16x32_bf16 v[64:67], v[154:157], v[214:217], v[64:67]
	v_mfma_f32_16x16x32_bf16 v[80:83], v[146:149], v[224:227], v[80:83]
	v_mfma_f32_16x16x32_bf16 v[56:59], v[154:157], v[224:227], v[56:59]
	v_mfma_f32_16x16x32_bf16 v[44:47], v[158:161], v[194:197], v[44:47]
	v_mfma_f32_16x16x32_bf16 v[12:15], v[166:169], v[194:197], v[12:15]
	v_mfma_f32_16x16x32_bf16 v[36:39], v[158:161], v[202:205], v[36:39]
	v_mfma_f32_16x16x32_bf16 v[8:11], v[166:169], v[202:205], v[8:11]
	v_mfma_f32_16x16x32_bf16 v[28:31], v[158:161], v[210:213], v[28:31]
	v_mfma_f32_16x16x32_bf16 v[4:7], v[166:169], v[210:213], v[4:7]
	v_mfma_f32_16x16x32_bf16 v[20:23], v[158:161], v[218:221], v[20:23]
	v_mfma_f32_16x16x32_bf16 v[0:3], v[166:169], v[218:221], v[0:3]
	v_mfma_f32_16x16x32_bf16 v[44:47], v[162:165], v[198:201], v[44:47]
	v_mfma_f32_16x16x32_bf16 v[12:15], v[190:193], v[198:201], v[12:15]
	v_mfma_f32_16x16x32_bf16 v[36:39], v[162:165], v[206:209], v[36:39]
	v_mfma_f32_16x16x32_bf16 v[8:11], v[190:193], v[206:209], v[8:11]
	v_mfma_f32_16x16x32_bf16 v[28:31], v[162:165], v[214:217], v[28:31]
	v_mfma_f32_16x16x32_bf16 v[4:7], v[190:193], v[214:217], v[4:7]
	v_mfma_f32_16x16x32_bf16 v[20:23], v[162:165], v[224:227], v[20:23]
	v_mfma_f32_16x16x32_bf16 v[0:3], v[190:193], v[224:227], v[0:3]
	s_setprio 0
	s_barrier
	s_add_i32 s6, s6, 2
	s_add_u32 s90, s90, 0x100
	s_addc_u32 s92, s92, 0
	s_mov_b64 s[64:65], s[66:67]
.LBB0_634:
	ds_read_b128 v[142:145], v174
	ds_read_b128 v[146:149], v175
	ds_read_b128 v[150:153], v176
	ds_read_b128 v[154:157], v177
	ds_read_b128 v[158:161], v178
	ds_read_b128 v[162:165], v179
	ds_read_b128 v[166:169], v180
	ds_read_b128 v[190:193], v181
	s_add_u32 s66, s64, 0x100
	s_addc_u32 s67, s65, 0
	s_cmp_eq_u32 s6, 12
	s_cselect_b32 s73, s57, s67
	s_cselect_b32 s72, vcc_lo, s66
	s_cselect_b32 s71, s55, s92
	s_cselect_b32 s70, vcc_hi, s90
	s_mov_b32 m0, s86
	v_lshl_add_u64 v[170:171], s[64:65], 0, v[134:135]
	ds_read_b128 v[194:197], v172
	ds_read_b128 v[198:201], v172 offset:1024
	ds_read_b128 v[202:205], v172 offset:2048
	ds_read_b128 v[206:209], v172 offset:3072
	ds_read_b128 v[210:213], v172 offset:4096
	ds_read_b128 v[214:217], v172 offset:5120
	ds_read_b128 v[218:221], v172 offset:6144
	ds_read_b128 v[224:227], v172 offset:7168
	global_load_lds_dwordx4 v[170:171], off
	v_lshl_add_u64 v[170:171], s[64:65], 0, v[136:137]
	s_mov_b32 m0, s87
	s_nop 0
	global_load_lds_dwordx4 v[170:171], off
	s_waitcnt vmcnt(8)
	s_waitcnt lgkmcnt(0)
	s_barrier
; #define PG8_STAGE(bufoff, gbase, voff) do { _Pragma("unroll") for (int _i = 0; _i < 2; ++_i) \
;         __builtin_amdgcn_global_load_lds((const unsigned*)((const char*)(gbase) + (voff)[_i]), (PG8_LAS unsigned*)(lds + (bufoff) + ldsw + _i * 8192), 16, 0, 0); } while (0)
; #define PG8_LDA(dst, b, h) do { _Pragma("unroll") for (int m = 0; m < 4; ++m) _Pragma("unroll") for (int k = 0; k < 2; ++k) dst[m][k] = *(const PG8_LAS bf16x8*)(lds + PG8_SA(b, h) + aoff + m * 2048 + k * 1024); } while (0)
; #define PG8_MMA(ai, bj, At, Bt) do { __builtin_amdgcn_s_setprio(1); _Pragma("unroll") for (int m = 0; m < 4; ++m) _Pragma("unroll") for (int n = 0; n < 2; ++n) _Pragma("unroll") for (int k = 0; k < 2; ++k) \
;         acc[ai][bj][m][n] = __builtin_amdgcn_mfma_f32_16x16x32_bf16(Bt[n][k], At[m][k], acc[ai][bj][m][n], 0, 0, 0); __builtin_amdgcn_s_setprio(0); } while (0)
; #define PG8_WAIT_V(n) asm volatile("s_waitcnt vmcnt(" #n ")" ::: "memory")
; #define PG8_WAIT_L(n) asm volatile("s_waitcnt lgkmcnt(" #n ")" ::: "memory")
; #define PG8_BAR __builtin_amdgcn_s_barrier()
; #define PG8_SCHED __builtin_amdgcn_sched_barrier(0)
; template <class Epi, class Sched, bool ALIGN_EPI = false, bool SP2 = false>
; __device__ __forceinline__ void gemm_phase(PG8_LAS unsigned char* lds, const Gemm g, const Sched& S, const Epi& E) {
;     ...
;             PG8_WAIT_V(8); PG8_WAIT_L(0); PG8_BAR; PG8_MMA(0, 0, At, B0); PG8_MMA(0, 1, At, B1); PG8_BAR; PG8_SCHED;
;             PG8_LDA(At, 0, 1); PG8_STAGE(PG8_SB(0, 0), b2, voffB); PG8_STAGE(PG8_SB(0, 1), b2 + hstep, voffB); PG8_STAGE(PG8_SA(0, 0), a2, voffA);
;             PG8_WAIT_V(8); PG8_WAIT_L(0); PG8_BAR; PG8_MMA(1, 0, At, B0); PG8_MMA(1, 1, At, B1); PG8_BAR; PG8_SCHED;
	s_setprio 1
	v_mfma_f32_16x16x32_bf16 v[124:127], v[142:145], v[194:197], v[124:127]
	v_mfma_f32_16x16x32_bf16 v[108:111], v[150:153], v[194:197], v[108:111]
	v_mfma_f32_16x16x32_bf16 v[120:123], v[142:145], v[202:205], v[120:123]
	v_mfma_f32_16x16x32_bf16 v[96:99], v[150:153], v[202:205], v[96:99]
	v_mfma_f32_16x16x32_bf16 v[116:119], v[142:145], v[210:213], v[116:119]
	v_mfma_f32_16x16x32_bf16 v[88:91], v[150:153], v[210:213], v[88:91]
	v_mfma_f32_16x16x32_bf16 v[112:115], v[142:145], v[218:221], v[112:115]
	v_mfma_f32_16x16x32_bf16 v[84:87], v[150:153], v[218:221], v[84:87]
	v_mfma_f32_16x16x32_bf16 v[124:127], v[146:149], v[198:201], v[124:127]
	v_mfma_f32_16x16x32_bf16 v[108:111], v[154:157], v[198:201], v[108:111]
	v_mfma_f32_16x16x32_bf16 v[120:123], v[146:149], v[206:209], v[120:123]
	v_mfma_f32_16x16x32_bf16 v[96:99], v[154:157], v[206:209], v[96:99]
	v_mfma_f32_16x16x32_bf16 v[116:119], v[146:149], v[214:217], v[116:119]
	v_mfma_f32_16x16x32_bf16 v[88:91], v[154:157], v[214:217], v[88:91]
	v_mfma_f32_16x16x32_bf16 v[112:115], v[146:149], v[224:227], v[112:115]
	v_mfma_f32_16x16x32_bf16 v[84:87], v[154:157], v[224:227], v[84:87]
	v_mfma_f32_16x16x32_bf16 v[68:71], v[158:161], v[194:197], v[68:71]
	v_mfma_f32_16x16x32_bf16 v[40:43], v[166:169], v[194:197], v[40:43]
	v_mfma_f32_16x16x32_bf16 v[60:63], v[158:161], v[202:205], v[60:63]
	v_mfma_f32_16x16x32_bf16 v[32:35], v[166:169], v[202:205], v[32:35]
	v_mfma_f32_16x16x32_bf16 v[52:55], v[158:161], v[210:213], v[52:55]
	v_mfma_f32_16x16x32_bf16 v[24:27], v[166:169], v[210:213], v[24:27]
	v_mfma_f32_16x16x32_bf16 v[48:51], v[158:161], v[218:221], v[48:51]
	v_mfma_f32_16x16x32_bf16 v[16:19], v[166:169], v[218:221], v[16:19]
	v_mfma_f32_16x16x32_bf16 v[68:71], v[162:165], v[198:201], v[68:71]
	v_mfma_f32_16x16x32_bf16 v[40:43], v[190:193], v[198:201], v[40:43]
	v_mfma_f32_16x16x32_bf16 v[60:63], v[162:165], v[206:209], v[60:63]
	v_mfma_f32_16x16x32_bf16 v[32:35], v[190:193], v[206:209], v[32:35]
	v_mfma_f32_16x16x32_bf16 v[52:55], v[162:165], v[214:217], v[52:55]
	v_mfma_f32_16x16x32_bf16 v[24:27], v[190:193], v[214:217], v[24:27]
	v_mfma_f32_16x16x32_bf16 v[48:51], v[162:165], v[224:227], v[48:51]
	v_mfma_f32_16x16x32_bf16 v[16:19], v[190:193], v[224:227], v[16:19]
	s_setprio 0
	s_barrier
	s_mov_b32 m0, s13
	v_lshl_add_u64 v[170:171], s[70:71], 0, v[128:129]
	s_add_u32 s64, s70, 0x40000
	ds_read_b128 v[194:197], v172 offset:16384
	ds_read_b128 v[198:201], v172 offset:17408
	ds_read_b128 v[202:205], v172 offset:18432
	ds_read_b128 v[206:209], v172 offset:19456
	ds_read_b128 v[210:213], v172 offset:20480
	ds_read_b128 v[214:217], v172 offset:21504
	ds_read_b128 v[218:221], v172 offset:22528
	ds_read_b128 v[224:227], v172 offset:23552
	global_load_lds_dwordx4 v[170:171], off
	v_lshl_add_u64 v[228:229], s[70:71], 0, v[130:131]
	s_mov_b32 m0, s14
	s_addc_u32 s65, s71, 0
	global_load_lds_dwordx4 v[228:229], off
	v_lshl_add_u64 v[230:231], s[64:65], 0, v[128:129]
	s_mov_b32 m0, s15
	v_lshl_add_u64 v[232:233], s[72:73], 0, v[130:131]
	global_load_lds_dwordx4 v[230:231], off
	v_lshl_add_u64 v[230:231], s[64:65], 0, v[130:131]
	s_mov_b32 m0, s33
	s_nop 0
	global_load_lds_dwordx4 v[230:231], off
	v_lshl_add_u64 v[230:231], s[72:73], 0, v[128:129]
	s_mov_b32 m0, s12
	s_nop 0
	global_load_lds_dwordx4 v[230:231], off
	s_mov_b32 m0, s39
	s_nop 0
	global_load_lds_dwordx4 v[232:233], off
	s_waitcnt vmcnt(8)
	s_waitcnt lgkmcnt(0)
	s_barrier
	s_setprio 1
	v_mfma_f32_16x16x32_bf16 v[104:107], v[142:145], v[194:197], v[104:107]
	v_mfma_f32_16x16x32_bf16 v[76:79], v[150:153], v[194:197], v[76:79]
	v_mfma_f32_16x16x32_bf16 v[100:103], v[142:145], v[202:205], v[100:103]
	v_mfma_f32_16x16x32_bf16 v[72:75], v[150:153], v[202:205], v[72:75]
	v_mfma_f32_16x16x32_bf16 v[92:95], v[142:145], v[210:213], v[92:95]
	v_mfma_f32_16x16x32_bf16 v[64:67], v[150:153], v[210:213], v[64:67]
	v_mfma_f32_16x16x32_bf16 v[80:83], v[142:145], v[218:221], v[80:83]
	v_mfma_f32_16x16x32_bf16 v[56:59], v[150:153], v[218:221], v[56:59]
	v_mfma_f32_16x16x32_bf16 v[104:107], v[146:149], v[198:201], v[104:107]
	v_mfma_f32_16x16x32_bf16 v[76:79], v[154:157], v[198:201], v[76:79]
	v_mfma_f32_16x16x32_bf16 v[100:103], v[146:149], v[206:209], v[100:103]
	v_mfma_f32_16x16x32_bf16 v[72:75], v[154:157], v[206:209], v[72:75]
	v_mfma_f32_16x16x32_bf16 v[92:95], v[146:149], v[214:217], v[92:95]
	v_mfma_f32_16x16x32_bf16 v[64:67], v[154:157], v[214:217], v[64:67]
	v_mfma_f32_16x16x32_bf16 v[80:83], v[146:149], v[224:227], v[80:83]
	v_mfma_f32_16x16x32_bf16 v[56:59], v[154:157], v[224:227], v[56:59]
	v_mfma_f32_16x16x32_bf16 v[44:47], v[158:161], v[194:197], v[44:47]
	v_mfma_f32_16x16x32_bf16 v[12:15], v[166:169], v[194:197], v[12:15]
	v_mfma_f32_16x16x32_bf16 v[36:39], v[158:161], v[202:205], v[36:39]
	v_mfma_f32_16x16x32_bf16 v[8:11], v[166:169], v[202:205], v[8:11]
	v_mfma_f32_16x16x32_bf16 v[28:31], v[158:161], v[210:213], v[28:31]
	v_mfma_f32_16x16x32_bf16 v[4:7], v[166:169], v[210:213], v[4:7]
	v_mfma_f32_16x16x32_bf16 v[20:23], v[158:161], v[218:221], v[20:23]
	v_mfma_f32_16x16x32_bf16 v[0:3], v[166:169], v[218:221], v[0:3]
	v_mfma_f32_16x16x32_bf16 v[44:47], v[162:165], v[198:201], v[44:47]
	v_mfma_f32_16x16x32_bf16 v[12:15], v[190:193], v[198:201], v[12:15]
	v_mfma_f32_16x16x32_bf16 v[36:39], v[162:165], v[206:209], v[36:39]
	v_mfma_f32_16x16x32_bf16 v[8:11], v[190:193], v[206:209], v[8:11]
	v_mfma_f32_16x16x32_bf16 v[28:31], v[162:165], v[214:217], v[28:31]
	v_mfma_f32_16x16x32_bf16 v[4:7], v[190:193], v[214:217], v[4:7]
	v_mfma_f32_16x16x32_bf16 v[20:23], v[162:165], v[224:227], v[20:23]
	v_mfma_f32_16x16x32_bf16 v[0:3], v[190:193], v[224:227], v[0:3]
	s_setprio 0
	s_barrier
; #define PG8_STAGE(bufoff, gbase, voff) do { _Pragma("unroll") for (int _i = 0; _i < 2; ++_i) \
;         __builtin_amdgcn_global_load_lds((const unsigned*)((const char*)(gbase) + (voff)[_i]), (PG8_LAS unsigned*)(lds + (bufoff) + ldsw + _i * 8192), 16, 0, 0); } while (0)
; #define PG8_LDA(dst, b, h) do { _Pragma("unroll") for (int m = 0; m < 4; ++m) _Pragma("unroll") for (int k = 0; k < 2; ++k) dst[m][k] = *(const PG8_LAS bf16x8*)(lds + PG8_SA(b, h) + aoff + m * 2048 + k * 1024); } while (0)
; #define PG8_LDB(dst, b, h) do { _Pragma("unroll") for (int n = 0; n < 2; ++n) _Pragma("unroll") for (int k = 0; k < 2; ++k) dst[n][k] = *(const PG8_LAS bf16x8*)(lds + PG8_SB(b, h) + boff + n * 2048 + k * 1024); } while (0)
; #define PG8_MMA(ai, bj, At, Bt) do { __builtin_amdgcn_s_setprio(1); _Pragma("unroll") for (int m = 0; m < 4; ++m) _Pragma("unroll") for (int n = 0; n < 2; ++n) _Pragma("unroll") for (int k = 0; k < 2; ++k) \
;         acc[ai][bj][m][n] = __builtin_amdgcn_mfma_f32_16x16x32_bf16(Bt[n][k], At[m][k], acc[ai][bj][m][n], 0, 0, 0); __builtin_amdgcn_s_setprio(0); } while (0)
; #define PG8_WAIT_V(n) asm volatile("s_waitcnt vmcnt(" #n ")" ::: "memory")
; #define PG8_WAIT_L(n) asm volatile("s_waitcnt lgkmcnt(" #n ")" ::: "memory")
; #define PG8_BAR __builtin_amdgcn_s_barrier()
; #define PG8_SCHED __builtin_amdgcn_sched_barrier(0)
; template <class Epi, class Sched, bool ALIGN_EPI = false, bool SP2 = false>
; __device__ __forceinline__ void gemm_phase(PG8_LAS unsigned char* lds, const Gemm g, const Sched& S, const Epi& E) {
;     ...
;             PG8_LDB(B0, 1, 0); PG8_LDB(B1, 1, 1); PG8_SCHED; PG8_LDA(At, 1, 0); PG8_STAGE(PG8_SA(0, 1), a2 + hstep, voffA);
;             PG8_WAIT_V(8); PG8_WAIT_L(0); PG8_BAR; PG8_MMA(0, 0, At, B0); PG8_MMA(0, 1, At, B1); PG8_BAR; PG8_SCHED;
;             PG8_LDA(At, 1, 1); PG8_STAGE(PG8_SB(1, 0), b3, voffB); PG8_STAGE(PG8_SB(1, 1), b3 + hstep, voffB); PG8_STAGE(PG8_SA(1, 0), a3, voffA);
;             PG8_WAIT_V(8); PG8_WAIT_L(0); PG8_BAR; PG8_MMA(1, 0, At, B0); PG8_MMA(1, 1, At, B1); PG8_BAR; PG8_SCHED;
	ds_read_b128 v[142:145], v182
	ds_read_b128 v[146:149], v183
	ds_read_b128 v[150:153], v184
	ds_read_b128 v[154:157], v185
	ds_read_b128 v[158:161], v186
	ds_read_b128 v[162:165], v187
	ds_read_b128 v[166:169], v188
	ds_read_b128 v[190:193], v189
	s_add_u32 s64, s72, 0x40000
	s_addc_u32 s65, s73, 0
	s_mov_b32 m0, s43
	v_lshl_add_u64 v[234:235], s[64:65], 0, v[128:129]
	ds_read_b128 v[194:197], v172 offset:32768
	ds_read_b128 v[198:201], v172 offset:33792
	ds_read_b128 v[202:205], v172 offset:34816
	ds_read_b128 v[206:209], v172 offset:35840
	ds_read_b128 v[210:213], v172 offset:36864
	ds_read_b128 v[214:217], v172 offset:37888
	ds_read_b128 v[218:221], v172 offset:38912
	ds_read_b128 v[224:227], v172 offset:39936
	global_load_lds_dwordx4 v[234:235], off
	v_lshl_add_u64 v[234:235], s[64:65], 0, v[130:131]
	s_mov_b32 m0, s74
	s_nop 0
	global_load_lds_dwordx4 v[234:235], off
	s_waitcnt vmcnt(8)
	s_waitcnt lgkmcnt(0)
	s_barrier
	s_setprio 1
	v_mfma_f32_16x16x32_bf16 v[124:127], v[142:145], v[194:197], v[124:127]
	v_mfma_f32_16x16x32_bf16 v[108:111], v[150:153], v[194:197], v[108:111]
	v_mfma_f32_16x16x32_bf16 v[120:123], v[142:145], v[202:205], v[120:123]
	v_mfma_f32_16x16x32_bf16 v[96:99], v[150:153], v[202:205], v[96:99]
	v_mfma_f32_16x16x32_bf16 v[116:119], v[142:145], v[210:213], v[116:119]
	v_mfma_f32_16x16x32_bf16 v[88:91], v[150:153], v[210:213], v[88:91]
	v_mfma_f32_16x16x32_bf16 v[112:115], v[142:145], v[218:221], v[112:115]
	v_mfma_f32_16x16x32_bf16 v[84:87], v[150:153], v[218:221], v[84:87]
	v_mfma_f32_16x16x32_bf16 v[124:127], v[146:149], v[198:201], v[124:127]
	v_mfma_f32_16x16x32_bf16 v[108:111], v[154:157], v[198:201], v[108:111]
	v_mfma_f32_16x16x32_bf16 v[120:123], v[146:149], v[206:209], v[120:123]
	v_mfma_f32_16x16x32_bf16 v[96:99], v[154:157], v[206:209], v[96:99]
	v_mfma_f32_16x16x32_bf16 v[116:119], v[146:149], v[214:217], v[116:119]
	v_mfma_f32_16x16x32_bf16 v[88:91], v[154:157], v[214:217], v[88:91]
	v_mfma_f32_16x16x32_bf16 v[112:115], v[146:149], v[224:227], v[112:115]
	v_mfma_f32_16x16x32_bf16 v[84:87], v[154:157], v[224:227], v[84:87]
	v_mfma_f32_16x16x32_bf16 v[68:71], v[158:161], v[194:197], v[68:71]
	v_mfma_f32_16x16x32_bf16 v[40:43], v[166:169], v[194:197], v[40:43]
	v_mfma_f32_16x16x32_bf16 v[60:63], v[158:161], v[202:205], v[60:63]
	v_mfma_f32_16x16x32_bf16 v[32:35], v[166:169], v[202:205], v[32:35]
	v_mfma_f32_16x16x32_bf16 v[52:55], v[158:161], v[210:213], v[52:55]
	v_mfma_f32_16x16x32_bf16 v[24:27], v[166:169], v[210:213], v[24:27]
	v_mfma_f32_16x16x32_bf16 v[48:51], v[158:161], v[218:221], v[48:51]
	v_mfma_f32_16x16x32_bf16 v[16:19], v[166:169], v[218:221], v[16:19]
	v_mfma_f32_16x16x32_bf16 v[68:71], v[162:165], v[198:201], v[68:71]
	v_mfma_f32_16x16x32_bf16 v[40:43], v[190:193], v[198:201], v[40:43]
	v_mfma_f32_16x16x32_bf16 v[60:63], v[162:165], v[206:209], v[60:63]
	v_mfma_f32_16x16x32_bf16 v[32:35], v[190:193], v[206:209], v[32:35]
	v_mfma_f32_16x16x32_bf16 v[52:55], v[162:165], v[214:217], v[52:55]
	v_mfma_f32_16x16x32_bf16 v[24:27], v[190:193], v[214:217], v[24:27]
	v_mfma_f32_16x16x32_bf16 v[48:51], v[162:165], v[224:227], v[48:51]
	v_mfma_f32_16x16x32_bf16 v[16:19], v[190:193], v[224:227], v[16:19]
	s_setprio 0
	s_barrier
	s_mov_b32 m0, s78
	v_lshl_add_u64 v[170:171], v[170:171], 0, s[10:11]
	s_add_u32 s64, s70, 0x40080
	ds_read_b128 v[194:197], v172 offset:49152
	ds_read_b128 v[198:201], v172 offset:50176
	ds_read_b128 v[202:205], v172 offset:51200
	ds_read_b128 v[206:209], v172 offset:52224
	ds_read_b128 v[210:213], v172 offset:53248
	ds_read_b128 v[214:217], v172 offset:54272
	ds_read_b128 v[218:221], v172 offset:55296
	ds_read_b128 v[224:227], v172 offset:56320
	global_load_lds_dwordx4 v[170:171], off
	v_lshl_add_u64 v[170:171], v[228:229], 0, s[10:11]
	s_mov_b32 m0, s79
	s_addc_u32 s65, s71, 0
	global_load_lds_dwordx4 v[170:171], off
	v_lshl_add_u64 v[170:171], s[64:65], 0, v[128:129]
	s_mov_b32 m0, s82
	s_nop 0
	global_load_lds_dwordx4 v[170:171], off
	v_lshl_add_u64 v[170:171], s[64:65], 0, v[130:131]
	s_mov_b32 m0, s83
	s_nop 0
	global_load_lds_dwordx4 v[170:171], off
	v_lshl_add_u64 v[170:171], v[230:231], 0, s[10:11]
	s_mov_b32 m0, s80
	s_nop 0
	global_load_lds_dwordx4 v[170:171], off
	v_lshl_add_u64 v[170:171], v[232:233], 0, s[10:11]
	s_mov_b32 m0, s81
	s_nop 0
	global_load_lds_dwordx4 v[170:171], off
	s_waitcnt vmcnt(8)
	s_waitcnt lgkmcnt(0)
	s_barrier
	s_setprio 1
	v_mfma_f32_16x16x32_bf16 v[104:107], v[142:145], v[194:197], v[104:107]
	v_mfma_f32_16x16x32_bf16 v[76:79], v[150:153], v[194:197], v[76:79]
	v_mfma_f32_16x16x32_bf16 v[100:103], v[142:145], v[202:205], v[100:103]
	v_mfma_f32_16x16x32_bf16 v[72:75], v[150:153], v[202:205], v[72:75]
	v_mfma_f32_16x16x32_bf16 v[92:95], v[142:145], v[210:213], v[92:95]
	v_mfma_f32_16x16x32_bf16 v[64:67], v[150:153], v[210:213], v[64:67]
	v_mfma_f32_16x16x32_bf16 v[80:83], v[142:145], v[218:221], v[80:83]
	v_mfma_f32_16x16x32_bf16 v[56:59], v[150:153], v[218:221], v[56:59]
	v_mfma_f32_16x16x32_bf16 v[104:107], v[146:149], v[198:201], v[104:107]
	v_mfma_f32_16x16x32_bf16 v[76:79], v[154:157], v[198:201], v[76:79]
	v_mfma_f32_16x16x32_bf16 v[100:103], v[146:149], v[206:209], v[100:103]
	v_mfma_f32_16x16x32_bf16 v[72:75], v[154:157], v[206:209], v[72:75]
	v_mfma_f32_16x16x32_bf16 v[92:95], v[146:149], v[214:217], v[92:95]
	v_mfma_f32_16x16x32_bf16 v[64:67], v[154:157], v[214:217], v[64:67]
	v_mfma_f32_16x16x32_bf16 v[80:83], v[146:149], v[224:227], v[80:83]
	v_mfma_f32_16x16x32_bf16 v[56:59], v[154:157], v[224:227], v[56:59]
	v_mfma_f32_16x16x32_bf16 v[44:47], v[158:161], v[194:197], v[44:47]
	v_mfma_f32_16x16x32_bf16 v[12:15], v[166:169], v[194:197], v[12:15]
	v_mfma_f32_16x16x32_bf16 v[36:39], v[158:161], v[202:205], v[36:39]
	v_mfma_f32_16x16x32_bf16 v[8:11], v[166:169], v[202:205], v[8:11]
	v_mfma_f32_16x16x32_bf16 v[28:31], v[158:161], v[210:213], v[28:31]
	v_mfma_f32_16x16x32_bf16 v[4:7], v[166:169], v[210:213], v[4:7]
	v_mfma_f32_16x16x32_bf16 v[20:23], v[158:161], v[218:221], v[20:23]
	v_mfma_f32_16x16x32_bf16 v[0:3], v[166:169], v[218:221], v[0:3]
	v_mfma_f32_16x16x32_bf16 v[44:47], v[162:165], v[198:201], v[44:47]
	v_mfma_f32_16x16x32_bf16 v[12:15], v[190:193], v[198:201], v[12:15]
	v_mfma_f32_16x16x32_bf16 v[36:39], v[162:165], v[206:209], v[36:39]
	v_mfma_f32_16x16x32_bf16 v[8:11], v[190:193], v[206:209], v[8:11]
	v_mfma_f32_16x16x32_bf16 v[28:31], v[162:165], v[214:217], v[28:31]
	v_mfma_f32_16x16x32_bf16 v[4:7], v[190:193], v[214:217], v[4:7]
	v_mfma_f32_16x16x32_bf16 v[20:23], v[162:165], v[224:227], v[20:23]
	v_mfma_f32_16x16x32_bf16 v[0:3], v[190:193], v[224:227], v[0:3]
	s_setprio 0
	s_barrier
	s_add_i32 s6, s6, 2
	s_add_u32 s90, s90, 0x100
	s_addc_u32 s92, s92, 0
	s_cmp_gt_u32 s6, 13
	s_mov_b64 s[64:65], s[66:67]
	s_cbranch_scc0 .LBB0_634
	s_and_b64 vcc, exec, s[52:53]
	s_cbranch_vccz .LBB0_637
	s_barrier

;     __host__ __device__ bool next(int i, Unit& u) const { const int L = i * G + c; if (L >= 16 * nkc) return false; u.kc = L % nkc; const int t = L / nkc; u.pn = t & 3; u.pm = 33 * (t >> 2); return true; }
; #define PG8_STAGE(bufoff, gbase, voff) do { _Pragma("unroll") for (int _i = 0; _i < 2; ++_i) \
;         __builtin_amdgcn_global_load_lds((const unsigned*)((const char*)(gbase) + (voff)[_i]), (PG8_LAS unsigned*)(lds + (bufoff) + ldsw + _i * 8192), 16, 0, 0); } while (0)
; #define PG8_LDA(dst, b, h) do { _Pragma("unroll") for (int m = 0; m < 4; ++m) _Pragma("unroll") for (int k = 0; k < 2; ++k) dst[m][k] = *(const PG8_LAS bf16x8*)(lds + PG8_SA(b, h) + aoff + m * 2048 + k * 1024); } while (0)
; #define PG8_LDB(dst, b, h) do { _Pragma("unroll") for (int n = 0; n < 2; ++n) _Pragma("unroll") for (int k = 0; k < 2; ++k) dst[n][k] = *(const PG8_LAS bf16x8*)(lds + PG8_SB(b, h) + boff + n * 2048 + k * 1024); } while (0)
; #define PG8_BAR __builtin_amdgcn_s_barrier()
; template <class Epi, class Sched, bool ALIGN_EPI = false, bool SP2 = false>
; __device__ __forceinline__ void gemm_phase(PG8_LAS unsigned char* lds, const Gemm g, const Sched& S, const Epi& E) {
;     ...
;         const bool has_next = S.next(ui + 1, nxt);
;         const char* nA = has_next ? (const char*)g.A + (size_t)nxt.pm * tstep + (size_t)nxt.kc * cstep : cA; const char* nB = has_next ? (const char*)g.Bt + (size_t)nxt.pn * tstep + (size_t)nxt.kc * cstep : cB;
;         for (int t = 0; t < nt; t += 2) {
;             const bool last = (t == nt - 2);
;             const char* a1 = cA + (size_t)(t + 1) * kstep;
;             const char* a2 = last ? nA : cA + (size_t)(t + 2) * kstep; const char* b2 = last ? nB : cB + (size_t)(t + 2) * kstep;
;             const char* a3 = a2 + kstep; const char* b3 = b2 + kstep;
;             if (last && has_next) S.a_ready(nxt);
;             if constexpr (SP2) {
;             PG8_LDB(B0, 0, 0); PG8_LDB(B1, 0, 1); PG8_SCHED; PG8_LDA(At, 0, 0); PG8_STAGE(PG8_SA(1, 1), a1 + hstep, voffA);
;             PG8_WAIT_V(8); PG8_WAIT_L(0); PG8_BAR; PG8_MMA(0, 0, At, B0); PG8_MMA(0, 1, At, B1); PG8_BAR; PG8_SCHED;
;             PG8_LDA(At, 0, 1); PG8_STAGE(PG8_SB(0, 0), b2, voffB); PG8_STAGE(PG8_SB(0, 1), b2 + hstep, voffB); PG8_STAGE(PG8_SA(0, 0), a2, voffA);
;             PG8_WAIT_V(8); PG8_WAIT_L(0); PG8_BAR; PG8_MMA(1, 0, At, B0); PG8_MMA(1, 1, At, B1); PG8_BAR; PG8_SCHED;
.LBB0_653:
	s_ashr_i32 s59, s58, 31
	s_lshl_b64 s[6:7], s[58:59], 19
	s_add_u32 s57, s46, s6
	s_addc_u32 s59, s47, s7
	s_ashr_i32 s55, s54, 31
	s_lshl_b64 s[6:7], s[54:55], 9
	s_add_u32 s66, s57, s6
	s_addc_u32 s67, s59, s7
	s_ashr_i32 s57, s56, 31
	s_lshl_b64 s[70:71], s[56:57], 19
	s_add_u32 s55, s0, s70
	s_addc_u32 s57, s1, s71
	s_add_u32 s70, s55, s6
	s_addc_u32 s71, s57, s7
	s_and_b64 vcc, exec, s[4:5]
	s_cbranch_vccnz .LBB0_661
	s_and_b64 s[6:7], s[62:63], exec
	s_cselect_b32 s55, s67, s73
	s_cselect_b32 s57, s66, s72
	s_cselect_b32 s59, s71, s75
	s_cselect_b32 s61, s70, s74
	s_add_u32 s90, s74, 0x100
	s_addc_u32 s92, s75, 0
	s_mov_b32 s6, 0
	ds_read_b128 v[156:159], v140
	ds_read_b128 v[160:163], v141
	ds_read_b128 v[164:167], v142
	ds_read_b128 v[168:171], v143
	ds_read_b128 v[172:175], v144
	ds_read_b128 v[176:179], v145
	ds_read_b128 v[180:183], v146
	ds_read_b128 v[184:187], v147
	s_add_i32 s7, s6, 2
	s_add_u32 s74, s72, 0x100
	s_addc_u32 s75, s73, 0
	s_cmp_eq_u32 s87, s6
	s_cselect_b32 s79, s55, s75
	s_cselect_b32 s78, s57, s74
	s_cselect_b32 s77, s59, s92
	s_cselect_b32 s76, s61, s90
	s_mov_b32 m0, s88
	v_lshl_add_u64 v[220:221], s[72:73], 0, v[134:135]
	ds_read_b128 v[188:191], v138
	ds_read_b128 v[192:195], v138 offset:1024
	ds_read_b128 v[196:199], v138 offset:2048
	ds_read_b128 v[200:203], v138 offset:3072
	ds_read_b128 v[204:207], v138 offset:4096
	ds_read_b128 v[208:211], v138 offset:5120
	ds_read_b128 v[212:215], v138 offset:6144
	ds_read_b128 v[216:219], v138 offset:7168
	global_load_lds_dwordx4 v[220:221], off
	v_lshl_add_u64 v[220:221], s[72:73], 0, v[136:137]
	s_mov_b32 m0, s89
	s_nop 0
	global_load_lds_dwordx4 v[220:221], off
	s_waitcnt vmcnt(8)
	s_waitcnt lgkmcnt(0)
	s_barrier
	s_setprio 1
	v_mfma_f32_16x16x32_bf16 v[124:127], v[156:159], v[188:191], 0
	v_mfma_f32_16x16x32_bf16 v[120:123], v[164:167], v[188:191], 0
	v_mfma_f32_16x16x32_bf16 v[108:111], v[156:159], v[196:199], 0
	v_mfma_f32_16x16x32_bf16 v[104:107], v[164:167], v[196:199], 0
	v_mfma_f32_16x16x32_bf16 v[92:95], v[156:159], v[204:207], 0
	v_mfma_f32_16x16x32_bf16 v[88:91], v[164:167], v[204:207], 0
	v_mfma_f32_16x16x32_bf16 v[76:79], v[156:159], v[212:215], 0
	v_mfma_f32_16x16x32_bf16 v[72:75], v[164:167], v[212:215], 0
	v_mfma_f32_16x16x32_bf16 v[124:127], v[160:163], v[192:195], v[124:127]
	v_mfma_f32_16x16x32_bf16 v[120:123], v[168:171], v[192:195], v[120:123]
	v_mfma_f32_16x16x32_bf16 v[108:111], v[160:163], v[200:203], v[108:111]
	v_mfma_f32_16x16x32_bf16 v[104:107], v[168:171], v[200:203], v[104:107]
	v_mfma_f32_16x16x32_bf16 v[92:95], v[160:163], v[208:211], v[92:95]
	v_mfma_f32_16x16x32_bf16 v[88:91], v[168:171], v[208:211], v[88:91]
	v_mfma_f32_16x16x32_bf16 v[76:79], v[160:163], v[216:219], v[76:79]
	v_mfma_f32_16x16x32_bf16 v[72:75], v[168:171], v[216:219], v[72:75]
	v_mfma_f32_16x16x32_bf16 v[116:119], v[172:175], v[188:191], 0
	v_mfma_f32_16x16x32_bf16 v[112:115], v[180:183], v[188:191], 0
	v_mfma_f32_16x16x32_bf16 v[100:103], v[172:175], v[196:199], 0
	v_mfma_f32_16x16x32_bf16 v[96:99], v[180:183], v[196:199], 0
	v_mfma_f32_16x16x32_bf16 v[84:87], v[172:175], v[204:207], 0
	v_mfma_f32_16x16x32_bf16 v[80:83], v[180:183], v[204:207], 0
	v_mfma_f32_16x16x32_bf16 v[68:71], v[172:175], v[212:215], 0
	v_mfma_f32_16x16x32_bf16 v[64:67], v[180:183], v[212:215], 0
	v_mfma_f32_16x16x32_bf16 v[116:119], v[176:179], v[192:195], v[116:119]
	v_mfma_f32_16x16x32_bf16 v[112:115], v[184:187], v[192:195], v[112:115]
	v_mfma_f32_16x16x32_bf16 v[100:103], v[176:179], v[200:203], v[100:103]
	v_mfma_f32_16x16x32_bf16 v[96:99], v[184:187], v[200:203], v[96:99]
	v_mfma_f32_16x16x32_bf16 v[84:87], v[176:179], v[208:211], v[84:87]
	v_mfma_f32_16x16x32_bf16 v[80:83], v[184:187], v[208:211], v[80:83]
	v_mfma_f32_16x16x32_bf16 v[68:71], v[176:179], v[216:219], v[68:71]
	v_mfma_f32_16x16x32_bf16 v[64:67], v[184:187], v[216:219], v[64:67]
	s_setprio 0
	s_barrier
	s_mov_b32 m0, s13
	v_lshl_add_u64 v[220:221], s[76:77], 0, v[130:131]
	s_add_u32 s72, s76, 0x40000
	ds_read_b128 v[188:191], v138 offset:16384
	ds_read_b128 v[192:195], v138 offset:17408
	ds_read_b128 v[196:199], v138 offset:18432
	ds_read_b128 v[200:203], v138 offset:19456
	ds_read_b128 v[204:207], v138 offset:20480
	ds_read_b128 v[208:211], v138 offset:21504
	ds_read_b128 v[212:215], v138 offset:22528
	ds_read_b128 v[216:219], v138 offset:23552
	global_load_lds_dwordx4 v[220:221], off
	v_lshl_add_u64 v[224:225], s[76:77], 0, v[128:129]
	s_mov_b32 m0, s14
	s_addc_u32 s73, s77, 0
	global_load_lds_dwordx4 v[224:225], off
	v_lshl_add_u64 v[226:227], s[72:73], 0, v[130:131]
	s_mov_b32 m0, s15
	v_lshl_add_u64 v[228:229], s[78:79], 0, v[128:129]
	global_load_lds_dwordx4 v[226:227], off
	v_lshl_add_u64 v[226:227], s[72:73], 0, v[128:129]
	s_mov_b32 m0, s33
	s_nop 0
	global_load_lds_dwordx4 v[226:227], off
	v_lshl_add_u64 v[226:227], s[78:79], 0, v[130:131]
	s_mov_b32 m0, s12
	s_nop 0
	global_load_lds_dwordx4 v[226:227], off
	s_mov_b32 m0, s39
	s_nop 0
	global_load_lds_dwordx4 v[228:229], off
	s_waitcnt vmcnt(8)
	s_waitcnt lgkmcnt(0)
	s_barrier
; #define PG8_STAGE(bufoff, gbase, voff) do { _Pragma("unroll") for (int _i = 0; _i < 2; ++_i) \
;         __builtin_amdgcn_global_load_lds((const unsigned*)((const char*)(gbase) + (voff)[_i]), (PG8_LAS unsigned*)(lds + (bufoff) + ldsw + _i * 8192), 16, 0, 0); } while (0)
; #define PG8_LDA(dst, b, h) do { _Pragma("unroll") for (int m = 0; m < 4; ++m) _Pragma("unroll") for (int k = 0; k < 2; ++k) dst[m][k] = *(const PG8_LAS bf16x8*)(lds + PG8_SA(b, h) + aoff + m * 2048 + k * 1024); } while (0)
; #define PG8_LDB(dst, b, h) do { _Pragma("unroll") for (int n = 0; n < 2; ++n) _Pragma("unroll") for (int k = 0; k < 2; ++k) dst[n][k] = *(const PG8_LAS bf16x8*)(lds + PG8_SB(b, h) + boff + n * 2048 + k * 1024); } while (0)
; #define PG8_MMA(ai, bj, At, Bt) do { __builtin_amdgcn_s_setprio(1); _Pragma("unroll") for (int m = 0; m < 4; ++m) _Pragma("unroll") for (int n = 0; n < 2; ++n) _Pragma("unroll") for (int k = 0; k < 2; ++k) \
;         acc[ai][bj][m][n] = __builtin_amdgcn_mfma_f32_16x16x32_bf16(Bt[n][k], At[m][k], acc[ai][bj][m][n], 0, 0, 0); __builtin_amdgcn_s_setprio(0); } while (0)
; #define PG8_WAIT_V(n) asm volatile("s_waitcnt vmcnt(" #n ")" ::: "memory")
; #define PG8_WAIT_L(n) asm volatile("s_waitcnt lgkmcnt(" #n ")" ::: "memory")
; #define PG8_BAR __builtin_amdgcn_s_barrier()
; #define PG8_SCHED __builtin_amdgcn_sched_barrier(0)
; template <class Epi, class Sched, bool ALIGN_EPI = false, bool SP2 = false>
; __device__ __forceinline__ void gemm_phase(PG8_LAS unsigned char* lds, const Gemm g, const Sched& S, const Epi& E) {
;     ...
;             PG8_WAIT_V(8); PG8_WAIT_L(0); PG8_BAR; PG8_MMA(1, 0, At, B0); PG8_MMA(1, 1, At, B1); PG8_BAR; PG8_SCHED;
;             PG8_LDB(B0, 1, 0); PG8_LDB(B1, 1, 1); PG8_SCHED; PG8_LDA(At, 1, 0); PG8_STAGE(PG8_SA(0, 1), a2 + hstep, voffA);
;             PG8_WAIT_V(8); PG8_WAIT_L(0); PG8_BAR; PG8_MMA(0, 0, At, B0); PG8_MMA(0, 1, At, B1); PG8_BAR; PG8_SCHED;
	s_setprio 1
	v_mfma_f32_16x16x32_bf16 v[60:63], v[156:159], v[188:191], 0
	v_mfma_f32_16x16x32_bf16 v[56:59], v[164:167], v[188:191], 0
	v_mfma_f32_16x16x32_bf16 v[44:47], v[156:159], v[196:199], 0
	v_mfma_f32_16x16x32_bf16 v[40:43], v[164:167], v[196:199], 0
	v_mfma_f32_16x16x32_bf16 v[28:31], v[156:159], v[204:207], 0
	v_mfma_f32_16x16x32_bf16 v[24:27], v[164:167], v[204:207], 0
	v_mfma_f32_16x16x32_bf16 v[12:15], v[156:159], v[212:215], 0
	v_mfma_f32_16x16x32_bf16 v[8:11], v[164:167], v[212:215], 0
	v_mfma_f32_16x16x32_bf16 v[60:63], v[160:163], v[192:195], v[60:63]
	v_mfma_f32_16x16x32_bf16 v[56:59], v[168:171], v[192:195], v[56:59]
	v_mfma_f32_16x16x32_bf16 v[44:47], v[160:163], v[200:203], v[44:47]
	v_mfma_f32_16x16x32_bf16 v[40:43], v[168:171], v[200:203], v[40:43]
	v_mfma_f32_16x16x32_bf16 v[28:31], v[160:163], v[208:211], v[28:31]
	v_mfma_f32_16x16x32_bf16 v[24:27], v[168:171], v[208:211], v[24:27]
	v_mfma_f32_16x16x32_bf16 v[12:15], v[160:163], v[216:219], v[12:15]
	v_mfma_f32_16x16x32_bf16 v[8:11], v[168:171], v[216:219], v[8:11]
	v_mfma_f32_16x16x32_bf16 v[52:55], v[172:175], v[188:191], 0
	v_mfma_f32_16x16x32_bf16 v[48:51], v[180:183], v[188:191], 0
	v_mfma_f32_16x16x32_bf16 v[36:39], v[172:175], v[196:199], 0
	v_mfma_f32_16x16x32_bf16 v[32:35], v[180:183], v[196:199], 0
	v_mfma_f32_16x16x32_bf16 v[20:23], v[172:175], v[204:207], 0
	v_mfma_f32_16x16x32_bf16 v[16:19], v[180:183], v[204:207], 0
	v_mfma_f32_16x16x32_bf16 v[4:7], v[172:175], v[212:215], 0
	v_mfma_f32_16x16x32_bf16 v[0:3], v[180:183], v[212:215], 0
	v_mfma_f32_16x16x32_bf16 v[52:55], v[176:179], v[192:195], v[52:55]
	v_mfma_f32_16x16x32_bf16 v[48:51], v[184:187], v[192:195], v[48:51]
	v_mfma_f32_16x16x32_bf16 v[36:39], v[176:179], v[200:203], v[36:39]
	v_mfma_f32_16x16x32_bf16 v[32:35], v[184:187], v[200:203], v[32:35]
	v_mfma_f32_16x16x32_bf16 v[20:23], v[176:179], v[208:211], v[20:23]
	v_mfma_f32_16x16x32_bf16 v[16:19], v[184:187], v[208:211], v[16:19]
	v_mfma_f32_16x16x32_bf16 v[4:7], v[176:179], v[216:219], v[4:7]
	v_mfma_f32_16x16x32_bf16 v[0:3], v[184:187], v[216:219], v[0:3]
	s_setprio 0
	s_barrier
	ds_read_b128 v[156:159], v148
	ds_read_b128 v[160:163], v149
	ds_read_b128 v[164:167], v150
	ds_read_b128 v[168:171], v151
	ds_read_b128 v[172:175], v152
	ds_read_b128 v[176:179], v153
	ds_read_b128 v[180:183], v154
	ds_read_b128 v[184:187], v155
	s_add_u32 s72, s78, 0x40000
	s_addc_u32 s73, s79, 0
	s_mov_b32 m0, s43
	v_lshl_add_u64 v[230:231], s[72:73], 0, v[130:131]
	ds_read_b128 v[188:191], v138 offset:32768
	ds_read_b128 v[192:195], v138 offset:33792
	ds_read_b128 v[196:199], v138 offset:34816
	ds_read_b128 v[200:203], v138 offset:35840
	ds_read_b128 v[204:207], v138 offset:36864
	ds_read_b128 v[208:211], v138 offset:37888
	ds_read_b128 v[212:215], v138 offset:38912
	ds_read_b128 v[216:219], v138 offset:39936
	global_load_lds_dwordx4 v[230:231], off
	v_lshl_add_u64 v[230:231], s[72:73], 0, v[128:129]
	s_mov_b32 m0, s65
	s_nop 0
	global_load_lds_dwordx4 v[230:231], off
	s_waitcnt vmcnt(8)
	s_waitcnt lgkmcnt(0)
	s_barrier
	s_setprio 1
	v_mfma_f32_16x16x32_bf16 v[124:127], v[156:159], v[188:191], v[124:127]
	v_mfma_f32_16x16x32_bf16 v[120:123], v[164:167], v[188:191], v[120:123]
	v_mfma_f32_16x16x32_bf16 v[108:111], v[156:159], v[196:199], v[108:111]
	v_mfma_f32_16x16x32_bf16 v[104:107], v[164:167], v[196:199], v[104:107]
	v_mfma_f32_16x16x32_bf16 v[92:95], v[156:159], v[204:207], v[92:95]
	v_mfma_f32_16x16x32_bf16 v[88:91], v[164:167], v[204:207], v[88:91]
	v_mfma_f32_16x16x32_bf16 v[76:79], v[156:159], v[212:215], v[76:79]
	v_mfma_f32_16x16x32_bf16 v[72:75], v[164:167], v[212:215], v[72:75]
	v_mfma_f32_16x16x32_bf16 v[124:127], v[160:163], v[192:195], v[124:127]
	v_mfma_f32_16x16x32_bf16 v[120:123], v[168:171], v[192:195], v[120:123]
	v_mfma_f32_16x16x32_bf16 v[108:111], v[160:163], v[200:203], v[108:111]
	v_mfma_f32_16x16x32_bf16 v[104:107], v[168:171], v[200:203], v[104:107]
	v_mfma_f32_16x16x32_bf16 v[92:95], v[160:163], v[208:211], v[92:95]
	v_mfma_f32_16x16x32_bf16 v[88:91], v[168:171], v[208:211], v[88:91]
	v_mfma_f32_16x16x32_bf16 v[76:79], v[160:163], v[216:219], v[76:79]
	v_mfma_f32_16x16x32_bf16 v[72:75], v[168:171], v[216:219], v[72:75]
	v_mfma_f32_16x16x32_bf16 v[116:119], v[172:175], v[188:191], v[116:119]
	v_mfma_f32_16x16x32_bf16 v[112:115], v[180:183], v[188:191], v[112:115]
	v_mfma_f32_16x16x32_bf16 v[100:103], v[172:175], v[196:199], v[100:103]
	v_mfma_f32_16x16x32_bf16 v[96:99], v[180:183], v[196:199], v[96:99]
	v_mfma_f32_16x16x32_bf16 v[84:87], v[172:175], v[204:207], v[84:87]
	v_mfma_f32_16x16x32_bf16 v[80:83], v[180:183], v[204:207], v[80:83]
	v_mfma_f32_16x16x32_bf16 v[68:71], v[172:175], v[212:215], v[68:71]
	v_mfma_f32_16x16x32_bf16 v[64:67], v[180:183], v[212:215], v[64:67]
	v_mfma_f32_16x16x32_bf16 v[116:119], v[176:179], v[192:195], v[116:119]
	v_mfma_f32_16x16x32_bf16 v[112:115], v[184:187], v[192:195], v[112:115]
	v_mfma_f32_16x16x32_bf16 v[100:103], v[176:179], v[200:203], v[100:103]
	v_mfma_f32_16x16x32_bf16 v[96:99], v[184:187], v[200:203], v[96:99]
	v_mfma_f32_16x16x32_bf16 v[84:87], v[176:179], v[208:211], v[84:87]
	v_mfma_f32_16x16x32_bf16 v[80:83], v[184:187], v[208:211], v[80:83]
	v_mfma_f32_16x16x32_bf16 v[68:71], v[176:179], v[216:219], v[68:71]
	v_mfma_f32_16x16x32_bf16 v[64:67], v[184:187], v[216:219], v[64:67]
	s_setprio 0
	s_barrier
; #define PG8_STAGE(bufoff, gbase, voff) do { _Pragma("unroll") for (int _i = 0; _i < 2; ++_i) \
;         __builtin_amdgcn_global_load_lds((const unsigned*)((const char*)(gbase) + (voff)[_i]), (PG8_LAS unsigned*)(lds + (bufoff) + ldsw + _i * 8192), 16, 0, 0); } while (0)
; #define PG8_LDA(dst, b, h) do { _Pragma("unroll") for (int m = 0; m < 4; ++m) _Pragma("unroll") for (int k = 0; k < 2; ++k) dst[m][k] = *(const PG8_LAS bf16x8*)(lds + PG8_SA(b, h) + aoff + m * 2048 + k * 1024); } while (0)
; #define PG8_LDB(dst, b, h) do { _Pragma("unroll") for (int n = 0; n < 2; ++n) _Pragma("unroll") for (int k = 0; k < 2; ++k) dst[n][k] = *(const PG8_LAS bf16x8*)(lds + PG8_SB(b, h) + boff + n * 2048 + k * 1024); } while (0)
; #define PG8_MMA(ai, bj, At, Bt) do { __builtin_amdgcn_s_setprio(1); _Pragma("unroll") for (int m = 0; m < 4; ++m) _Pragma("unroll") for (int n = 0; n < 2; ++n) _Pragma("unroll") for (int k = 0; k < 2; ++k) \
;         acc[ai][bj][m][n] = __builtin_amdgcn_mfma_f32_16x16x32_bf16(Bt[n][k], At[m][k], acc[ai][bj][m][n], 0, 0, 0); __builtin_amdgcn_s_setprio(0); } while (0)
; #define PG8_WAIT_V(n) asm volatile("s_waitcnt vmcnt(" #n ")" ::: "memory")
; template <class Epi, class Sched, bool ALIGN_EPI = false, bool SP2 = false>
; __device__ __forceinline__ void gemm_phase(PG8_LAS unsigned char* lds, const Gemm g, const Sched& S, const Epi& E) {
;     ...
;             PG8_LDB(B0, 0, 0); PG8_LDB(B1, 0, 1); PG8_SCHED; PG8_LDA(At, 0, 0); PG8_STAGE(PG8_SA(1, 1), a1 + hstep, voffA);
;             PG8_WAIT_V(8); PG8_WAIT_L(0); PG8_BAR; PG8_MMA(0, 0, At, B0); PG8_MMA(0, 1, At, B1); PG8_BAR; PG8_SCHED;
;             PG8_LDA(At, 0, 1); PG8_STAGE(PG8_SB(0, 0), b2, voffB); PG8_STAGE(PG8_SB(0, 1), b2 + hstep, voffB); PG8_STAGE(PG8_SA(0, 0), a2, voffA);
;             PG8_WAIT_V(8); PG8_WAIT_L(0); PG8_BAR; PG8_MMA(1, 0, At, B0); PG8_MMA(1, 1, At, B1); PG8_BAR; PG8_SCHED;
;             PG8_LDB(B0, 1, 0); PG8_LDB(B1, 1, 1); PG8_SCHED; PG8_LDA(At, 1, 0); PG8_STAGE(PG8_SA(0, 1), a2 + hstep, voffA);
;             PG8_WAIT_V(8); PG8_WAIT_L(0); PG8_BAR; PG8_MMA(0, 0, At, B0); PG8_MMA(0, 1, At, B1); PG8_BAR; PG8_SCHED;
;             PG8_LDA(At, 1, 1); PG8_STAGE(PG8_SB(1, 0), b3, voffB); PG8_STAGE(PG8_SB(1, 1), b3 + hstep, voffB); PG8_STAGE(PG8_SA(1, 0), a3, voffA);
;             PG8_WAIT_V(8); PG8_WAIT_L(0); PG8_BAR; PG8_MMA(1, 0, At, B0); PG8_MMA(1, 1, At, B1); PG8_BAR; PG8_SCHED;
	s_mov_b32 m0, s81
	v_lshl_add_u64 v[220:221], v[220:221], 0, s[36:37]
	s_add_u32 s72, s76, 0x40080
	ds_read_b128 v[188:191], v138 offset:49152
	ds_read_b128 v[192:195], v138 offset:50176
	ds_read_b128 v[196:199], v138 offset:51200
	ds_read_b128 v[200:203], v138 offset:52224
	ds_read_b128 v[204:207], v138 offset:53248
	ds_read_b128 v[208:211], v138 offset:54272
	ds_read_b128 v[212:215], v138 offset:55296
	ds_read_b128 v[216:219], v138 offset:56320
	global_load_lds_dwordx4 v[220:221], off
	v_lshl_add_u64 v[220:221], v[224:225], 0, s[36:37]
	s_mov_b32 m0, s82
	s_addc_u32 s73, s77, 0
	global_load_lds_dwordx4 v[220:221], off
	v_lshl_add_u64 v[220:221], s[72:73], 0, v[130:131]
	s_mov_b32 m0, s85
	s_nop 0
	global_load_lds_dwordx4 v[220:221], off
	v_lshl_add_u64 v[220:221], s[72:73], 0, v[128:129]
	s_mov_b32 m0, s86
	s_nop 0
	global_load_lds_dwordx4 v[220:221], off
	v_lshl_add_u64 v[220:221], v[226:227], 0, s[36:37]
	s_mov_b32 m0, s83
	s_nop 0
	global_load_lds_dwordx4 v[220:221], off
	v_lshl_add_u64 v[220:221], v[228:229], 0, s[36:37]
	s_mov_b32 m0, s84
	s_nop 0
	global_load_lds_dwordx4 v[220:221], off
	s_waitcnt vmcnt(8)
	s_waitcnt lgkmcnt(0)
	s_barrier
	s_setprio 1
	v_mfma_f32_16x16x32_bf16 v[60:63], v[156:159], v[188:191], v[60:63]
	v_mfma_f32_16x16x32_bf16 v[56:59], v[164:167], v[188:191], v[56:59]
	v_mfma_f32_16x16x32_bf16 v[44:47], v[156:159], v[196:199], v[44:47]
	v_mfma_f32_16x16x32_bf16 v[40:43], v[164:167], v[196:199], v[40:43]
	v_mfma_f32_16x16x32_bf16 v[28:31], v[156:159], v[204:207], v[28:31]
	v_mfma_f32_16x16x32_bf16 v[24:27], v[164:167], v[204:207], v[24:27]
	v_mfma_f32_16x16x32_bf16 v[12:15], v[156:159], v[212:215], v[12:15]
	v_mfma_f32_16x16x32_bf16 v[8:11], v[164:167], v[212:215], v[8:11]
	v_mfma_f32_16x16x32_bf16 v[60:63], v[160:163], v[192:195], v[60:63]
	v_mfma_f32_16x16x32_bf16 v[56:59], v[168:171], v[192:195], v[56:59]
	v_mfma_f32_16x16x32_bf16 v[44:47], v[160:163], v[200:203], v[44:47]
	v_mfma_f32_16x16x32_bf16 v[40:43], v[168:171], v[200:203], v[40:43]
	v_mfma_f32_16x16x32_bf16 v[28:31], v[160:163], v[208:211], v[28:31]
	v_mfma_f32_16x16x32_bf16 v[24:27], v[168:171], v[208:211], v[24:27]
	v_mfma_f32_16x16x32_bf16 v[12:15], v[160:163], v[216:219], v[12:15]
	v_mfma_f32_16x16x32_bf16 v[8:11], v[168:171], v[216:219], v[8:11]
	v_mfma_f32_16x16x32_bf16 v[52:55], v[172:175], v[188:191], v[52:55]
	v_mfma_f32_16x16x32_bf16 v[48:51], v[180:183], v[188:191], v[48:51]
	v_mfma_f32_16x16x32_bf16 v[36:39], v[172:175], v[196:199], v[36:39]
	v_mfma_f32_16x16x32_bf16 v[32:35], v[180:183], v[196:199], v[32:35]
	v_mfma_f32_16x16x32_bf16 v[20:23], v[172:175], v[204:207], v[20:23]
	v_mfma_f32_16x16x32_bf16 v[16:19], v[180:183], v[204:207], v[16:19]
	v_mfma_f32_16x16x32_bf16 v[4:7], v[172:175], v[212:215], v[4:7]
	v_mfma_f32_16x16x32_bf16 v[0:3], v[180:183], v[212:215], v[0:3]
	v_mfma_f32_16x16x32_bf16 v[52:55], v[176:179], v[192:195], v[52:55]
	v_mfma_f32_16x16x32_bf16 v[48:51], v[184:187], v[192:195], v[48:51]
	v_mfma_f32_16x16x32_bf16 v[36:39], v[176:179], v[200:203], v[36:39]
	v_mfma_f32_16x16x32_bf16 v[32:35], v[184:187], v[200:203], v[32:35]
	v_mfma_f32_16x16x32_bf16 v[20:23], v[176:179], v[208:211], v[20:23]
	v_mfma_f32_16x16x32_bf16 v[16:19], v[184:187], v[208:211], v[16:19]
	v_mfma_f32_16x16x32_bf16 v[4:7], v[176:179], v[216:219], v[4:7]
	v_mfma_f32_16x16x32_bf16 v[0:3], v[184:187], v[216:219], v[0:3]
	s_setprio 0
	s_barrier
	s_add_u32 s90, s90, 0x100
	s_addc_u32 s92, s92, 0
	s_mov_b64 s[72:73], s[74:75]
	s_mov_b32 s6, s7
.LBB0_655:
	ds_read_b128 v[156:159], v140
	ds_read_b128 v[160:163], v141
	ds_read_b128 v[164:167], v142
	ds_read_b128 v[168:171], v143
	ds_read_b128 v[172:175], v144
	ds_read_b128 v[176:179], v145
	ds_read_b128 v[180:183], v146
	ds_read_b128 v[184:187], v147
	s_add_i32 s7, s6, 2
	s_add_u32 s74, s72, 0x100
	s_addc_u32 s75, s73, 0
	s_cmp_eq_u32 s87, s6
	s_cselect_b32 s79, s55, s75
	s_cselect_b32 s78, s57, s74
	s_cselect_b32 s77, s59, s92
	s_cselect_b32 s76, s61, s90
	s_mov_b32 m0, s88
	v_lshl_add_u64 v[220:221], s[72:73], 0, v[134:135]
	ds_read_b128 v[188:191], v138
	ds_read_b128 v[192:195], v138 offset:1024
	ds_read_b128 v[196:199], v138 offset:2048
	ds_read_b128 v[200:203], v138 offset:3072
	ds_read_b128 v[204:207], v138 offset:4096
	ds_read_b128 v[208:211], v138 offset:5120
	ds_read_b128 v[212:215], v138 offset:6144
	ds_read_b128 v[216:219], v138 offset:7168
	global_load_lds_dwordx4 v[220:221], off
	v_lshl_add_u64 v[220:221], s[72:73], 0, v[136:137]
	s_mov_b32 m0, s89
	s_nop 0
	global_load_lds_dwordx4 v[220:221], off
	s_waitcnt vmcnt(8)
	s_waitcnt lgkmcnt(0)
	s_barrier
; #define PG8_STAGE(bufoff, gbase, voff) do { _Pragma("unroll") for (int _i = 0; _i < 2; ++_i) \
;         __builtin_amdgcn_global_load_lds((const unsigned*)((const char*)(gbase) + (voff)[_i]), (PG8_LAS unsigned*)(lds + (bufoff) + ldsw + _i * 8192), 16, 0, 0); } while (0)
; #define PG8_LDA(dst, b, h) do { _Pragma("unroll") for (int m = 0; m < 4; ++m) _Pragma("unroll") for (int k = 0; k < 2; ++k) dst[m][k] = *(const PG8_LAS bf16x8*)(lds + PG8_SA(b, h) + aoff + m * 2048 + k * 1024); } while (0)
; #define PG8_MMA(ai, bj, At, Bt) do { __builtin_amdgcn_s_setprio(1); _Pragma("unroll") for (int m = 0; m < 4; ++m) _Pragma("unroll") for (int n = 0; n < 2; ++n) _Pragma("unroll") for (int k = 0; k < 2; ++k) \
;         acc[ai][bj][m][n] = __builtin_amdgcn_mfma_f32_16x16x32_bf16(Bt[n][k], At[m][k], acc[ai][bj][m][n], 0, 0, 0); __builtin_amdgcn_s_setprio(0); } while (0)
; #define PG8_WAIT_V(n) asm volatile("s_waitcnt vmcnt(" #n ")" ::: "memory")
; #define PG8_WAIT_L(n) asm volatile("s_waitcnt lgkmcnt(" #n ")" ::: "memory")
; #define PG8_BAR __builtin_amdgcn_s_barrier()
; #define PG8_SCHED __builtin_amdgcn_sched_barrier(0)
; template <class Epi, class Sched, bool ALIGN_EPI = false, bool SP2 = false>
; __device__ __forceinline__ void gemm_phase(PG8_LAS unsigned char* lds, const Gemm g, const Sched& S, const Epi& E) {
;     ...
;             PG8_WAIT_V(8); PG8_WAIT_L(0); PG8_BAR; PG8_MMA(0, 0, At, B0); PG8_MMA(0, 1, At, B1); PG8_BAR; PG8_SCHED;
;             PG8_LDA(At, 0, 1); PG8_STAGE(PG8_SB(0, 0), b2, voffB); PG8_STAGE(PG8_SB(0, 1), b2 + hstep, voffB); PG8_STAGE(PG8_SA(0, 0), a2, voffA);
;             PG8_WAIT_V(8); PG8_WAIT_L(0); PG8_BAR; PG8_MMA(1, 0, At, B0); PG8_MMA(1, 1, At, B1); PG8_BAR; PG8_SCHED;
	s_setprio 1
	v_mfma_f32_16x16x32_bf16 v[124:127], v[156:159], v[188:191], v[124:127]
	v_mfma_f32_16x16x32_bf16 v[120:123], v[164:167], v[188:191], v[120:123]
	v_mfma_f32_16x16x32_bf16 v[108:111], v[156:159], v[196:199], v[108:111]
	v_mfma_f32_16x16x32_bf16 v[104:107], v[164:167], v[196:199], v[104:107]
	v_mfma_f32_16x16x32_bf16 v[92:95], v[156:159], v[204:207], v[92:95]
	v_mfma_f32_16x16x32_bf16 v[88:91], v[164:167], v[204:207], v[88:91]
	v_mfma_f32_16x16x32_bf16 v[76:79], v[156:159], v[212:215], v[76:79]
	v_mfma_f32_16x16x32_bf16 v[72:75], v[164:167], v[212:215], v[72:75]
	v_mfma_f32_16x16x32_bf16 v[124:127], v[160:163], v[192:195], v[124:127]
	v_mfma_f32_16x16x32_bf16 v[120:123], v[168:171], v[192:195], v[120:123]
	v_mfma_f32_16x16x32_bf16 v[108:111], v[160:163], v[200:203], v[108:111]
	v_mfma_f32_16x16x32_bf16 v[104:107], v[168:171], v[200:203], v[104:107]
	v_mfma_f32_16x16x32_bf16 v[92:95], v[160:163], v[208:211], v[92:95]
	v_mfma_f32_16x16x32_bf16 v[88:91], v[168:171], v[208:211], v[88:91]
	v_mfma_f32_16x16x32_bf16 v[76:79], v[160:163], v[216:219], v[76:79]
	v_mfma_f32_16x16x32_bf16 v[72:75], v[168:171], v[216:219], v[72:75]
	v_mfma_f32_16x16x32_bf16 v[116:119], v[172:175], v[188:191], v[116:119]
	v_mfma_f32_16x16x32_bf16 v[112:115], v[180:183], v[188:191], v[112:115]
	v_mfma_f32_16x16x32_bf16 v[100:103], v[172:175], v[196:199], v[100:103]
	v_mfma_f32_16x16x32_bf16 v[96:99], v[180:183], v[196:199], v[96:99]
	v_mfma_f32_16x16x32_bf16 v[84:87], v[172:175], v[204:207], v[84:87]
	v_mfma_f32_16x16x32_bf16 v[80:83], v[180:183], v[204:207], v[80:83]
	v_mfma_f32_16x16x32_bf16 v[68:71], v[172:175], v[212:215], v[68:71]
	v_mfma_f32_16x16x32_bf16 v[64:67], v[180:183], v[212:215], v[64:67]
	v_mfma_f32_16x16x32_bf16 v[116:119], v[176:179], v[192:195], v[116:119]
	v_mfma_f32_16x16x32_bf16 v[112:115], v[184:187], v[192:195], v[112:115]
	v_mfma_f32_16x16x32_bf16 v[100:103], v[176:179], v[200:203], v[100:103]
	v_mfma_f32_16x16x32_bf16 v[96:99], v[184:187], v[200:203], v[96:99]
	v_mfma_f32_16x16x32_bf16 v[84:87], v[176:179], v[208:211], v[84:87]
	v_mfma_f32_16x16x32_bf16 v[80:83], v[184:187], v[208:211], v[80:83]
	v_mfma_f32_16x16x32_bf16 v[68:71], v[176:179], v[216:219], v[68:71]
	v_mfma_f32_16x16x32_bf16 v[64:67], v[184:187], v[216:219], v[64:67]
	s_setprio 0
	s_barrier
	s_mov_b32 m0, s13
	v_lshl_add_u64 v[220:221], s[76:77], 0, v[130:131]
	s_add_u32 s72, s76, 0x40000
	ds_read_b128 v[188:191], v138 offset:16384
	ds_read_b128 v[192:195], v138 offset:17408
	ds_read_b128 v[196:199], v138 offset:18432
	ds_read_b128 v[200:203], v138 offset:19456
	ds_read_b128 v[204:207], v138 offset:20480
	ds_read_b128 v[208:211], v138 offset:21504
	ds_read_b128 v[212:215], v138 offset:22528
	ds_read_b128 v[216:219], v138 offset:23552
	global_load_lds_dwordx4 v[220:221], off
	v_lshl_add_u64 v[224:225], s[76:77], 0, v[128:129]
	s_mov_b32 m0, s14
	s_addc_u32 s73, s77, 0
	global_load_lds_dwordx4 v[224:225], off
	v_lshl_add_u64 v[226:227], s[72:73], 0, v[130:131]
	s_mov_b32 m0, s15
	v_lshl_add_u64 v[228:229], s[78:79], 0, v[128:129]
	global_load_lds_dwordx4 v[226:227], off
	v_lshl_add_u64 v[226:227], s[72:73], 0, v[128:129]
	s_mov_b32 m0, s33
	s_nop 0
	global_load_lds_dwordx4 v[226:227], off
	v_lshl_add_u64 v[226:227], s[78:79], 0, v[130:131]
	s_mov_b32 m0, s12
	s_nop 0
	global_load_lds_dwordx4 v[226:227], off
	s_mov_b32 m0, s39
	s_nop 0
	global_load_lds_dwordx4 v[228:229], off
	s_waitcnt vmcnt(8)
	s_waitcnt lgkmcnt(0)
	s_barrier
	s_setprio 1
	v_mfma_f32_16x16x32_bf16 v[60:63], v[156:159], v[188:191], v[60:63]
	v_mfma_f32_16x16x32_bf16 v[56:59], v[164:167], v[188:191], v[56:59]
	v_mfma_f32_16x16x32_bf16 v[44:47], v[156:159], v[196:199], v[44:47]
	v_mfma_f32_16x16x32_bf16 v[40:43], v[164:167], v[196:199], v[40:43]
	v_mfma_f32_16x16x32_bf16 v[28:31], v[156:159], v[204:207], v[28:31]
	v_mfma_f32_16x16x32_bf16 v[24:27], v[164:167], v[204:207], v[24:27]
	v_mfma_f32_16x16x32_bf16 v[12:15], v[156:159], v[212:215], v[12:15]
	v_mfma_f32_16x16x32_bf16 v[8:11], v[164:167], v[212:215], v[8:11]
	v_mfma_f32_16x16x32_bf16 v[60:63], v[160:163], v[192:195], v[60:63]
	v_mfma_f32_16x16x32_bf16 v[56:59], v[168:171], v[192:195], v[56:59]
	v_mfma_f32_16x16x32_bf16 v[44:47], v[160:163], v[200:203], v[44:47]
	v_mfma_f32_16x16x32_bf16 v[40:43], v[168:171], v[200:203], v[40:43]
	v_mfma_f32_16x16x32_bf16 v[28:31], v[160:163], v[208:211], v[28:31]
	v_mfma_f32_16x16x32_bf16 v[24:27], v[168:171], v[208:211], v[24:27]
	v_mfma_f32_16x16x32_bf16 v[12:15], v[160:163], v[216:219], v[12:15]
	v_mfma_f32_16x16x32_bf16 v[8:11], v[168:171], v[216:219], v[8:11]
	v_mfma_f32_16x16x32_bf16 v[52:55], v[172:175], v[188:191], v[52:55]
	v_mfma_f32_16x16x32_bf16 v[48:51], v[180:183], v[188:191], v[48:51]
	v_mfma_f32_16x16x32_bf16 v[36:39], v[172:175], v[196:199], v[36:39]
	v_mfma_f32_16x16x32_bf16 v[32:35], v[180:183], v[196:199], v[32:35]
	v_mfma_f32_16x16x32_bf16 v[20:23], v[172:175], v[204:207], v[20:23]
	v_mfma_f32_16x16x32_bf16 v[16:19], v[180:183], v[204:207], v[16:19]
	v_mfma_f32_16x16x32_bf16 v[4:7], v[172:175], v[212:215], v[4:7]
	v_mfma_f32_16x16x32_bf16 v[0:3], v[180:183], v[212:215], v[0:3]
	v_mfma_f32_16x16x32_bf16 v[52:55], v[176:179], v[192:195], v[52:55]
	v_mfma_f32_16x16x32_bf16 v[48:51], v[184:187], v[192:195], v[48:51]
	v_mfma_f32_16x16x32_bf16 v[36:39], v[176:179], v[200:203], v[36:39]
	v_mfma_f32_16x16x32_bf16 v[32:35], v[184:187], v[200:203], v[32:35]
	v_mfma_f32_16x16x32_bf16 v[20:23], v[176:179], v[208:211], v[20:23]
	v_mfma_f32_16x16x32_bf16 v[16:19], v[184:187], v[208:211], v[16:19]
	v_mfma_f32_16x16x32_bf16 v[4:7], v[176:179], v[216:219], v[4:7]
	v_mfma_f32_16x16x32_bf16 v[0:3], v[184:187], v[216:219], v[0:3]
	s_setprio 0
	s_barrier
; #define PG8_STAGE(bufoff, gbase, voff) do { _Pragma("unroll") for (int _i = 0; _i < 2; ++_i) \
;         __builtin_amdgcn_global_load_lds((const unsigned*)((const char*)(gbase) + (voff)[_i]), (PG8_LAS unsigned*)(lds + (bufoff) + ldsw + _i * 8192), 16, 0, 0); } while (0)
; #define PG8_LDA(dst, b, h) do { _Pragma("unroll") for (int m = 0; m < 4; ++m) _Pragma("unroll") for (int k = 0; k < 2; ++k) dst[m][k] = *(const PG8_LAS bf16x8*)(lds + PG8_SA(b, h) + aoff + m * 2048 + k * 1024); } while (0)
; #define PG8_LDB(dst, b, h) do { _Pragma("unroll") for (int n = 0; n < 2; ++n) _Pragma("unroll") for (int k = 0; k < 2; ++k) dst[n][k] = *(const PG8_LAS bf16x8*)(lds + PG8_SB(b, h) + boff + n * 2048 + k * 1024); } while (0)
; #define PG8_MMA(ai, bj, At, Bt) do { __builtin_amdgcn_s_setprio(1); _Pragma("unroll") for (int m = 0; m < 4; ++m) _Pragma("unroll") for (int n = 0; n < 2; ++n) _Pragma("unroll") for (int k = 0; k < 2; ++k) \
;         acc[ai][bj][m][n] = __builtin_amdgcn_mfma_f32_16x16x32_bf16(Bt[n][k], At[m][k], acc[ai][bj][m][n], 0, 0, 0); __builtin_amdgcn_s_setprio(0); } while (0)
; #define PG8_WAIT_V(n) asm volatile("s_waitcnt vmcnt(" #n ")" ::: "memory")
; #define PG8_WAIT_L(n) asm volatile("s_waitcnt lgkmcnt(" #n ")" ::: "memory")
; #define PG8_BAR __builtin_amdgcn_s_barrier()
; #define PG8_SCHED __builtin_amdgcn_sched_barrier(0)
; template <class Epi, class Sched, bool ALIGN_EPI = false, bool SP2 = false>
; __device__ __forceinline__ void gemm_phase(PG8_LAS unsigned char* lds, const Gemm g, const Sched& S, const Epi& E) {
;     ...
;             PG8_LDB(B0, 1, 0); PG8_LDB(B1, 1, 1); PG8_SCHED; PG8_LDA(At, 1, 0); PG8_STAGE(PG8_SA(0, 1), a2 + hstep, voffA);
;             PG8_WAIT_V(8); PG8_WAIT_L(0); PG8_BAR; PG8_MMA(0, 0, At, B0); PG8_MMA(0, 1, At, B1); PG8_BAR; PG8_SCHED;
;             PG8_LDA(At, 1, 1); PG8_STAGE(PG8_SB(1, 0), b3, voffB); PG8_STAGE(PG8_SB(1, 1), b3 + hstep, voffB); PG8_STAGE(PG8_SA(1, 0), a3, voffA);
;             PG8_WAIT_V(8); PG8_WAIT_L(0); PG8_BAR; PG8_MMA(1, 0, At, B0); PG8_MMA(1, 1, At, B1); PG8_BAR; PG8_SCHED;
	ds_read_b128 v[156:159], v148
	ds_read_b128 v[160:163], v149
	ds_read_b128 v[164:167], v150
	ds_read_b128 v[168:171], v151
	ds_read_b128 v[172:175], v152
	ds_read_b128 v[176:179], v153
	ds_read_b128 v[180:183], v154
	ds_read_b128 v[184:187], v155
	s_add_u32 s72, s78, 0x40000
	s_addc_u32 s73, s79, 0
	s_mov_b32 m0, s43
	v_lshl_add_u64 v[230:231], s[72:73], 0, v[130:131]
	ds_read_b128 v[188:191], v138 offset:32768
	ds_read_b128 v[192:195], v138 offset:33792
	ds_read_b128 v[196:199], v138 offset:34816
	ds_read_b128 v[200:203], v138 offset:35840
	ds_read_b128 v[204:207], v138 offset:36864
	ds_read_b128 v[208:211], v138 offset:37888
	ds_read_b128 v[212:215], v138 offset:38912
	ds_read_b128 v[216:219], v138 offset:39936
	global_load_lds_dwordx4 v[230:231], off
	v_lshl_add_u64 v[230:231], s[72:73], 0, v[128:129]
	s_mov_b32 m0, s65
	s_nop 0
	global_load_lds_dwordx4 v[230:231], off
	s_waitcnt vmcnt(8)
	s_waitcnt lgkmcnt(0)
	s_barrier
	s_setprio 1
	v_mfma_f32_16x16x32_bf16 v[124:127], v[156:159], v[188:191], v[124:127]
	v_mfma_f32_16x16x32_bf16 v[120:123], v[164:167], v[188:191], v[120:123]
	v_mfma_f32_16x16x32_bf16 v[108:111], v[156:159], v[196:199], v[108:111]
	v_mfma_f32_16x16x32_bf16 v[104:107], v[164:167], v[196:199], v[104:107]
	v_mfma_f32_16x16x32_bf16 v[92:95], v[156:159], v[204:207], v[92:95]
	v_mfma_f32_16x16x32_bf16 v[88:91], v[164:167], v[204:207], v[88:91]
	v_mfma_f32_16x16x32_bf16 v[76:79], v[156:159], v[212:215], v[76:79]
	v_mfma_f32_16x16x32_bf16 v[72:75], v[164:167], v[212:215], v[72:75]
	v_mfma_f32_16x16x32_bf16 v[124:127], v[160:163], v[192:195], v[124:127]
	v_mfma_f32_16x16x32_bf16 v[120:123], v[168:171], v[192:195], v[120:123]
	v_mfma_f32_16x16x32_bf16 v[108:111], v[160:163], v[200:203], v[108:111]
	v_mfma_f32_16x16x32_bf16 v[104:107], v[168:171], v[200:203], v[104:107]
	v_mfma_f32_16x16x32_bf16 v[92:95], v[160:163], v[208:211], v[92:95]
	v_mfma_f32_16x16x32_bf16 v[88:91], v[168:171], v[208:211], v[88:91]
	v_mfma_f32_16x16x32_bf16 v[76:79], v[160:163], v[216:219], v[76:79]
	v_mfma_f32_16x16x32_bf16 v[72:75], v[168:171], v[216:219], v[72:75]
	v_mfma_f32_16x16x32_bf16 v[116:119], v[172:175], v[188:191], v[116:119]
	v_mfma_f32_16x16x32_bf16 v[112:115], v[180:183], v[188:191], v[112:115]
	v_mfma_f32_16x16x32_bf16 v[100:103], v[172:175], v[196:199], v[100:103]
	v_mfma_f32_16x16x32_bf16 v[96:99], v[180:183], v[196:199], v[96:99]
	v_mfma_f32_16x16x32_bf16 v[84:87], v[172:175], v[204:207], v[84:87]
	v_mfma_f32_16x16x32_bf16 v[80:83], v[180:183], v[204:207], v[80:83]
	v_mfma_f32_16x16x32_bf16 v[68:71], v[172:175], v[212:215], v[68:71]
	v_mfma_f32_16x16x32_bf16 v[64:67], v[180:183], v[212:215], v[64:67]
	v_mfma_f32_16x16x32_bf16 v[116:119], v[176:179], v[192:195], v[116:119]
	v_mfma_f32_16x16x32_bf16 v[112:115], v[184:187], v[192:195], v[112:115]
	v_mfma_f32_16x16x32_bf16 v[100:103], v[176:179], v[200:203], v[100:103]
	v_mfma_f32_16x16x32_bf16 v[96:99], v[184:187], v[200:203], v[96:99]
	v_mfma_f32_16x16x32_bf16 v[84:87], v[176:179], v[208:211], v[84:87]
	v_mfma_f32_16x16x32_bf16 v[80:83], v[184:187], v[208:211], v[80:83]
	v_mfma_f32_16x16x32_bf16 v[68:71], v[176:179], v[216:219], v[68:71]
	v_mfma_f32_16x16x32_bf16 v[64:67], v[184:187], v[216:219], v[64:67]
	s_setprio 0
	s_barrier
	s_mov_b32 m0, s81
	v_lshl_add_u64 v[220:221], v[220:221], 0, s[36:37]
	s_add_u32 s72, s76, 0x40080
	ds_read_b128 v[188:191], v138 offset:49152
	ds_read_b128 v[192:195], v138 offset:50176
	ds_read_b128 v[196:199], v138 offset:51200
	ds_read_b128 v[200:203], v138 offset:52224
	ds_read_b128 v[204:207], v138 offset:53248
	ds_read_b128 v[208:211], v138 offset:54272
	ds_read_b128 v[212:215], v138 offset:55296
	ds_read_b128 v[216:219], v138 offset:56320
	global_load_lds_dwordx4 v[220:221], off
	v_lshl_add_u64 v[220:221], v[224:225], 0, s[36:37]
	s_mov_b32 m0, s82
	s_addc_u32 s73, s77, 0
	global_load_lds_dwordx4 v[220:221], off
	v_lshl_add_u64 v[220:221], s[72:73], 0, v[130:131]
	s_mov_b32 m0, s85
	s_nop 0
	global_load_lds_dwordx4 v[220:221], off
	v_lshl_add_u64 v[220:221], s[72:73], 0, v[128:129]
	s_mov_b32 m0, s86
	s_nop 0
	global_load_lds_dwordx4 v[220:221], off
	v_lshl_add_u64 v[220:221], v[226:227], 0, s[36:37]
	s_mov_b32 m0, s83
	s_nop 0
	global_load_lds_dwordx4 v[220:221], off
	v_lshl_add_u64 v[220:221], v[228:229], 0, s[36:37]
	s_mov_b32 m0, s84
	s_nop 0
	global_load_lds_dwordx4 v[220:221], off
	s_waitcnt vmcnt(8)
	s_waitcnt lgkmcnt(0)
	s_barrier
	s_setprio 1
	v_mfma_f32_16x16x32_bf16 v[60:63], v[156:159], v[188:191], v[60:63]
	v_mfma_f32_16x16x32_bf16 v[56:59], v[164:167], v[188:191], v[56:59]
	v_mfma_f32_16x16x32_bf16 v[44:47], v[156:159], v[196:199], v[44:47]
	v_mfma_f32_16x16x32_bf16 v[40:43], v[164:167], v[196:199], v[40:43]
	v_mfma_f32_16x16x32_bf16 v[28:31], v[156:159], v[204:207], v[28:31]
	v_mfma_f32_16x16x32_bf16 v[24:27], v[164:167], v[204:207], v[24:27]
	v_mfma_f32_16x16x32_bf16 v[12:15], v[156:159], v[212:215], v[12:15]
	v_mfma_f32_16x16x32_bf16 v[8:11], v[164:167], v[212:215], v[8:11]
	v_mfma_f32_16x16x32_bf16 v[60:63], v[160:163], v[192:195], v[60:63]
	v_mfma_f32_16x16x32_bf16 v[56:59], v[168:171], v[192:195], v[56:59]
	v_mfma_f32_16x16x32_bf16 v[44:47], v[160:163], v[200:203], v[44:47]
	v_mfma_f32_16x16x32_bf16 v[40:43], v[168:171], v[200:203], v[40:43]
	v_mfma_f32_16x16x32_bf16 v[28:31], v[160:163], v[208:211], v[28:31]
	v_mfma_f32_16x16x32_bf16 v[24:27], v[168:171], v[208:211], v[24:27]
	v_mfma_f32_16x16x32_bf16 v[12:15], v[160:163], v[216:219], v[12:15]
	v_mfma_f32_16x16x32_bf16 v[8:11], v[168:171], v[216:219], v[8:11]
	v_mfma_f32_16x16x32_bf16 v[52:55], v[172:175], v[188:191], v[52:55]
	v_mfma_f32_16x16x32_bf16 v[48:51], v[180:183], v[188:191], v[48:51]
	v_mfma_f32_16x16x32_bf16 v[36:39], v[172:175], v[196:199], v[36:39]
	v_mfma_f32_16x16x32_bf16 v[32:35], v[180:183], v[196:199], v[32:35]
	v_mfma_f32_16x16x32_bf16 v[20:23], v[172:175], v[204:207], v[20:23]
	v_mfma_f32_16x16x32_bf16 v[16:19], v[180:183], v[204:207], v[16:19]
	v_mfma_f32_16x16x32_bf16 v[4:7], v[172:175], v[212:215], v[4:7]
	v_mfma_f32_16x16x32_bf16 v[0:3], v[180:183], v[212:215], v[0:3]
	v_mfma_f32_16x16x32_bf16 v[52:55], v[176:179], v[192:195], v[52:55]
	v_mfma_f32_16x16x32_bf16 v[48:51], v[184:187], v[192:195], v[48:51]
	v_mfma_f32_16x16x32_bf16 v[36:39], v[176:179], v[200:203], v[36:39]
	v_mfma_f32_16x16x32_bf16 v[32:35], v[184:187], v[200:203], v[32:35]
	v_mfma_f32_16x16x32_bf16 v[20:23], v[176:179], v[208:211], v[20:23]
	v_mfma_f32_16x16x32_bf16 v[16:19], v[184:187], v[208:211], v[16:19]
	v_mfma_f32_16x16x32_bf16 v[4:7], v[176:179], v[216:219], v[4:7]
	v_mfma_f32_16x16x32_bf16 v[0:3], v[184:187], v[216:219], v[0:3]
	s_setprio 0
	s_barrier
	s_add_u32 s90, s90, 0x100
	s_addc_u32 s92, s92, 0
	s_cmp_ge_i32 s7, s3
	s_mov_b64 s[72:73], s[74:75]
	s_mov_b32 s6, s7
	s_cbranch_scc0 .LBB0_655
	s_and_b64 vcc, exec, s[52:53]
	s_cbranch_vccz .LBB0_658

;     __host__ __device__ bool next(int i, Unit& u) const { const int L = i * G + c; if (L >= 16 * nkc) return false; u.kc = L % nkc; const int t = L / nkc; u.pn = t & 3; u.pm = 33 * (t >> 2); return true; }
; #define PG8_STAGE(bufoff, gbase, voff) do { _Pragma("unroll") for (int _i = 0; _i < 2; ++_i) \
;         __builtin_amdgcn_global_load_lds((const unsigned*)((const char*)(gbase) + (voff)[_i]), (PG8_LAS unsigned*)(lds + (bufoff) + ldsw + _i * 8192), 16, 0, 0); } while (0)
; #define PG8_LDA(dst, b, h) do { _Pragma("unroll") for (int m = 0; m < 4; ++m) _Pragma("unroll") for (int k = 0; k < 2; ++k) dst[m][k] = *(const PG8_LAS bf16x8*)(lds + PG8_SA(b, h) + aoff + m * 2048 + k * 1024); } while (0)
; #define PG8_LDB(dst, b, h) do { _Pragma("unroll") for (int n = 0; n < 2; ++n) _Pragma("unroll") for (int k = 0; k < 2; ++k) dst[n][k] = *(const PG8_LAS bf16x8*)(lds + PG8_SB(b, h) + boff + n * 2048 + k * 1024); } while (0)
; #define PG8_BAR __builtin_amdgcn_s_barrier()
; template <class Epi, class Sched, bool ALIGN_EPI = false, bool SP2 = false>
; __device__ __forceinline__ void gemm_phase(PG8_LAS unsigned char* lds, const Gemm g, const Sched& S, const Epi& E) {
;     ...
;         const bool has_next = S.next(ui + 1, nxt);
;         const char* nA = has_next ? (const char*)g.A + (size_t)nxt.pm * tstep + (size_t)nxt.kc * cstep : cA; const char* nB = has_next ? (const char*)g.Bt + (size_t)nxt.pn * tstep + (size_t)nxt.kc * cstep : cB;
;         for (int t = 0; t < nt; t += 2) {
;             const bool last = (t == nt - 2);
;             const char* a1 = cA + (size_t)(t + 1) * kstep;
;             const char* a2 = last ? nA : cA + (size_t)(t + 2) * kstep; const char* b2 = last ? nB : cB + (size_t)(t + 2) * kstep;
;             const char* a3 = a2 + kstep; const char* b3 = b2 + kstep;
;             if (last && has_next) S.a_ready(nxt);
;             if constexpr (SP2) {
;             PG8_LDB(B0, 0, 0); PG8_LDB(B1, 0, 1); PG8_SCHED; PG8_LDA(At, 0, 0); PG8_STAGE(PG8_SA(1, 1), a1 + hstep, voffA);
;             PG8_WAIT_V(8); PG8_WAIT_L(0); PG8_BAR; PG8_MMA(0, 0, At, B0); PG8_MMA(0, 1, At, B1); PG8_BAR; PG8_SCHED;
;             PG8_LDA(At, 0, 1); PG8_STAGE(PG8_SB(0, 0), b2, voffB); PG8_STAGE(PG8_SB(0, 1), b2 + hstep, voffB); PG8_STAGE(PG8_SA(0, 0), a2, voffA);
;             PG8_WAIT_V(8); PG8_WAIT_L(0); PG8_BAR; PG8_MMA(1, 0, At, B0); PG8_MMA(1, 1, At, B1); PG8_BAR; PG8_SCHED;
.LBB0_792:
	s_ashr_i32 s55, s54, 31
	s_lshl_b64 s[6:7], s[54:55], 19
	s_add_u32 s56, s46, s6
	s_addc_u32 s57, s47, s7
	s_and_b64 s[6:7], s[4:5], exec
	s_cselect_b32 s55, s57, s63
	s_cselect_b32 s82, s56, s62
	s_ashr_i32 s53, s52, 31
	s_lshl_b64 s[6:7], s[52:53], 19
	s_add_u32 s58, s1, s6
	s_addc_u32 s59, s3, s7
	s_and_b64 s[6:7], s[4:5], exec
	s_cselect_b32 s53, s59, s65
	s_cselect_b32 s83, s58, s64
	s_add_u32 s62, s62, 0x40080
	s_addc_u32 s63, s63, 0
	s_add_u32 s84, s64, 0x100
	s_addc_u32 s85, s65, 0
	s_mov_b32 s86, -2
	ds_read_b128 v[166:169], v149
	ds_read_b128 v[170:173], v150
	ds_read_b128 v[174:177], v151
	ds_read_b128 v[178:181], v152
	ds_read_b128 v[182:185], v153
	ds_read_b128 v[186:189], v154
	ds_read_b128 v[190:193], v155
	ds_read_b128 v[194:197], v156
	s_add_u32 s6, s62, 0xfffc0080
	s_addc_u32 s7, s63, -1
	s_cmp_eq_u32 s86, 12
	s_cselect_b32 s67, s55, s7
	s_cselect_b32 s66, s82, s6
	s_cselect_b32 s65, s53, s85
	s_cselect_b32 s64, s83, s84
	s_mov_b32 m0, s79
	v_lshl_add_u64 v[144:145], s[62:63], 0, v[136:137]
	ds_read_b128 v[198:201], v147
	ds_read_b128 v[202:205], v147 offset:1024
	ds_read_b128 v[206:209], v147 offset:2048
	ds_read_b128 v[210:213], v147 offset:3072
	ds_read_b128 v[214:217], v147 offset:4096
	ds_read_b128 v[218:221], v147 offset:5120
	ds_read_b128 v[224:227], v147 offset:6144
	ds_read_b128 v[228:231], v147 offset:7168
	global_load_lds_dwordx4 v[144:145], off
	v_lshl_add_u64 v[144:145], s[62:63], 0, v[138:139]
	s_mov_b32 m0, s80
	s_nop 0
	global_load_lds_dwordx4 v[144:145], off
	s_waitcnt vmcnt(8)
	s_waitcnt lgkmcnt(0)
	s_barrier
	s_setprio 1
	v_mfma_f32_16x16x32_bf16 v[124:127], v[166:169], v[198:201], 0
	v_mfma_f32_16x16x32_bf16 v[120:123], v[174:177], v[198:201], 0
	v_mfma_f32_16x16x32_bf16 v[108:111], v[166:169], v[206:209], 0
	v_mfma_f32_16x16x32_bf16 v[104:107], v[174:177], v[206:209], 0
	v_mfma_f32_16x16x32_bf16 v[92:95], v[166:169], v[214:217], 0
	v_mfma_f32_16x16x32_bf16 v[88:91], v[174:177], v[214:217], 0
	v_mfma_f32_16x16x32_bf16 v[76:79], v[166:169], v[224:227], 0
	v_mfma_f32_16x16x32_bf16 v[72:75], v[174:177], v[224:227], 0
	v_mfma_f32_16x16x32_bf16 v[124:127], v[170:173], v[202:205], v[124:127]
	v_mfma_f32_16x16x32_bf16 v[120:123], v[178:181], v[202:205], v[120:123]
	v_mfma_f32_16x16x32_bf16 v[108:111], v[170:173], v[210:213], v[108:111]
	v_mfma_f32_16x16x32_bf16 v[104:107], v[178:181], v[210:213], v[104:107]
	v_mfma_f32_16x16x32_bf16 v[92:95], v[170:173], v[218:221], v[92:95]
	v_mfma_f32_16x16x32_bf16 v[88:91], v[178:181], v[218:221], v[88:91]
	v_mfma_f32_16x16x32_bf16 v[76:79], v[170:173], v[228:231], v[76:79]
	v_mfma_f32_16x16x32_bf16 v[72:75], v[178:181], v[228:231], v[72:75]
	v_mfma_f32_16x16x32_bf16 v[116:119], v[182:185], v[198:201], 0
	v_mfma_f32_16x16x32_bf16 v[112:115], v[190:193], v[198:201], 0
	v_mfma_f32_16x16x32_bf16 v[100:103], v[182:185], v[206:209], 0
	v_mfma_f32_16x16x32_bf16 v[96:99], v[190:193], v[206:209], 0
	v_mfma_f32_16x16x32_bf16 v[84:87], v[182:185], v[214:217], 0
	v_mfma_f32_16x16x32_bf16 v[80:83], v[190:193], v[214:217], 0
	v_mfma_f32_16x16x32_bf16 v[68:71], v[182:185], v[224:227], 0
	v_mfma_f32_16x16x32_bf16 v[64:67], v[190:193], v[224:227], 0
	v_mfma_f32_16x16x32_bf16 v[116:119], v[186:189], v[202:205], v[116:119]
	v_mfma_f32_16x16x32_bf16 v[112:115], v[194:197], v[202:205], v[112:115]
	v_mfma_f32_16x16x32_bf16 v[100:103], v[186:189], v[210:213], v[100:103]
	v_mfma_f32_16x16x32_bf16 v[96:99], v[194:197], v[210:213], v[96:99]
	v_mfma_f32_16x16x32_bf16 v[84:87], v[186:189], v[218:221], v[84:87]
	v_mfma_f32_16x16x32_bf16 v[80:83], v[194:197], v[218:221], v[80:83]
	v_mfma_f32_16x16x32_bf16 v[68:71], v[186:189], v[228:231], v[68:71]
	v_mfma_f32_16x16x32_bf16 v[64:67], v[194:197], v[228:231], v[64:67]
	s_setprio 0
	s_barrier
	s_mov_b32 m0, s15
	v_lshl_add_u64 v[144:145], s[64:65], 0, v[132:133]
	s_add_u32 s6, s64, 0x40000
	ds_read_b128 v[198:201], v147 offset:16384
	ds_read_b128 v[202:205], v147 offset:17408
	ds_read_b128 v[206:209], v147 offset:18432
	ds_read_b128 v[210:213], v147 offset:19456
	ds_read_b128 v[214:217], v147 offset:20480
	ds_read_b128 v[218:221], v147 offset:21504
	ds_read_b128 v[224:227], v147 offset:22528
	ds_read_b128 v[228:231], v147 offset:23552
	global_load_lds_dwordx4 v[144:145], off
	v_lshl_add_u64 v[232:233], s[64:65], 0, v[128:129]
	s_mov_b32 m0, s39
	s_addc_u32 s7, s65, 0
	global_load_lds_dwordx4 v[232:233], off
	v_lshl_add_u64 v[234:235], s[6:7], 0, v[132:133]
	s_mov_b32 m0, s43
	v_lshl_add_u64 v[236:237], s[66:67], 0, v[130:131]
	global_load_lds_dwordx4 v[234:235], off
	v_lshl_add_u64 v[234:235], s[6:7], 0, v[128:129]
	s_mov_b32 m0, s61
	s_nop 0
	global_load_lds_dwordx4 v[234:235], off
	v_lshl_add_u64 v[234:235], s[66:67], 0, v[134:135]
	s_mov_b32 m0, s12
	s_nop 0
	global_load_lds_dwordx4 v[234:235], off
	s_mov_b32 m0, s68
	s_nop 0
	global_load_lds_dwordx4 v[236:237], off
	s_waitcnt vmcnt(8)
	s_waitcnt lgkmcnt(0)
	s_barrier
; #define PG8_STAGE(bufoff, gbase, voff) do { _Pragma("unroll") for (int _i = 0; _i < 2; ++_i) \
;         __builtin_amdgcn_global_load_lds((const unsigned*)((const char*)(gbase) + (voff)[_i]), (PG8_LAS unsigned*)(lds + (bufoff) + ldsw + _i * 8192), 16, 0, 0); } while (0)
; #define PG8_LDA(dst, b, h) do { _Pragma("unroll") for (int m = 0; m < 4; ++m) _Pragma("unroll") for (int k = 0; k < 2; ++k) dst[m][k] = *(const PG8_LAS bf16x8*)(lds + PG8_SA(b, h) + aoff + m * 2048 + k * 1024); } while (0)
; #define PG8_LDB(dst, b, h) do { _Pragma("unroll") for (int n = 0; n < 2; ++n) _Pragma("unroll") for (int k = 0; k < 2; ++k) dst[n][k] = *(const PG8_LAS bf16x8*)(lds + PG8_SB(b, h) + boff + n * 2048 + k * 1024); } while (0)
; #define PG8_MMA(ai, bj, At, Bt) do { __builtin_amdgcn_s_setprio(1); _Pragma("unroll") for (int m = 0; m < 4; ++m) _Pragma("unroll") for (int n = 0; n < 2; ++n) _Pragma("unroll") for (int k = 0; k < 2; ++k) \
;         acc[ai][bj][m][n] = __builtin_amdgcn_mfma_f32_16x16x32_bf16(Bt[n][k], At[m][k], acc[ai][bj][m][n], 0, 0, 0); __builtin_amdgcn_s_setprio(0); } while (0)
; #define PG8_WAIT_V(n) asm volatile("s_waitcnt vmcnt(" #n ")" ::: "memory")
; #define PG8_WAIT_L(n) asm volatile("s_waitcnt lgkmcnt(" #n ")" ::: "memory")
; #define PG8_BAR __builtin_amdgcn_s_barrier()
; #define PG8_SCHED __builtin_amdgcn_sched_barrier(0)
; template <class Epi, class Sched, bool ALIGN_EPI = false, bool SP2 = false>
; __device__ __forceinline__ void gemm_phase(PG8_LAS unsigned char* lds, const Gemm g, const Sched& S, const Epi& E) {
;     ...
;             PG8_WAIT_V(8); PG8_WAIT_L(0); PG8_BAR; PG8_MMA(1, 0, At, B0); PG8_MMA(1, 1, At, B1); PG8_BAR; PG8_SCHED;
;             PG8_LDB(B0, 1, 0); PG8_LDB(B1, 1, 1); PG8_SCHED; PG8_LDA(At, 1, 0); PG8_STAGE(PG8_SA(0, 1), a2 + hstep, voffA);
;             PG8_WAIT_V(8); PG8_WAIT_L(0); PG8_BAR; PG8_MMA(0, 0, At, B0); PG8_MMA(0, 1, At, B1); PG8_BAR; PG8_SCHED;
	s_setprio 1
	v_mfma_f32_16x16x32_bf16 v[60:63], v[166:169], v[198:201], 0
	v_mfma_f32_16x16x32_bf16 v[56:59], v[174:177], v[198:201], 0
	v_mfma_f32_16x16x32_bf16 v[44:47], v[166:169], v[206:209], 0
	v_mfma_f32_16x16x32_bf16 v[40:43], v[174:177], v[206:209], 0
	v_mfma_f32_16x16x32_bf16 v[28:31], v[166:169], v[214:217], 0
	v_mfma_f32_16x16x32_bf16 v[24:27], v[174:177], v[214:217], 0
	v_mfma_f32_16x16x32_bf16 v[12:15], v[166:169], v[224:227], 0
	v_mfma_f32_16x16x32_bf16 v[8:11], v[174:177], v[224:227], 0
	v_mfma_f32_16x16x32_bf16 v[60:63], v[170:173], v[202:205], v[60:63]
	v_mfma_f32_16x16x32_bf16 v[56:59], v[178:181], v[202:205], v[56:59]
	v_mfma_f32_16x16x32_bf16 v[44:47], v[170:173], v[210:213], v[44:47]
	v_mfma_f32_16x16x32_bf16 v[40:43], v[178:181], v[210:213], v[40:43]
	v_mfma_f32_16x16x32_bf16 v[28:31], v[170:173], v[218:221], v[28:31]
	v_mfma_f32_16x16x32_bf16 v[24:27], v[178:181], v[218:221], v[24:27]
	v_mfma_f32_16x16x32_bf16 v[12:15], v[170:173], v[228:231], v[12:15]
	v_mfma_f32_16x16x32_bf16 v[8:11], v[178:181], v[228:231], v[8:11]
	v_mfma_f32_16x16x32_bf16 v[52:55], v[182:185], v[198:201], 0
	v_mfma_f32_16x16x32_bf16 v[48:51], v[190:193], v[198:201], 0
	v_mfma_f32_16x16x32_bf16 v[36:39], v[182:185], v[206:209], 0
	v_mfma_f32_16x16x32_bf16 v[32:35], v[190:193], v[206:209], 0
	v_mfma_f32_16x16x32_bf16 v[20:23], v[182:185], v[214:217], 0
	v_mfma_f32_16x16x32_bf16 v[16:19], v[190:193], v[214:217], 0
	v_mfma_f32_16x16x32_bf16 v[4:7], v[182:185], v[224:227], 0
	v_mfma_f32_16x16x32_bf16 v[0:3], v[190:193], v[224:227], 0
	v_mfma_f32_16x16x32_bf16 v[52:55], v[186:189], v[202:205], v[52:55]
	v_mfma_f32_16x16x32_bf16 v[48:51], v[194:197], v[202:205], v[48:51]
	v_mfma_f32_16x16x32_bf16 v[36:39], v[186:189], v[210:213], v[36:39]
	v_mfma_f32_16x16x32_bf16 v[32:35], v[194:197], v[210:213], v[32:35]
	v_mfma_f32_16x16x32_bf16 v[20:23], v[186:189], v[218:221], v[20:23]
	v_mfma_f32_16x16x32_bf16 v[16:19], v[194:197], v[218:221], v[16:19]
	v_mfma_f32_16x16x32_bf16 v[4:7], v[186:189], v[228:231], v[4:7]
	v_mfma_f32_16x16x32_bf16 v[0:3], v[194:197], v[228:231], v[0:3]
	s_setprio 0
	s_barrier
	ds_read_b128 v[166:169], v157
	ds_read_b128 v[170:173], v158
	ds_read_b128 v[174:177], v159
	ds_read_b128 v[178:181], v160
	ds_read_b128 v[182:185], v161
	ds_read_b128 v[186:189], v162
	ds_read_b128 v[190:193], v163
	ds_read_b128 v[194:197], v164
	s_add_u32 s6, s66, 0x40000
	s_addc_u32 s7, s67, 0
	s_mov_b32 m0, s69
	v_lshl_add_u64 v[238:239], s[6:7], 0, v[134:135]
	ds_read_b128 v[198:201], v147 offset:32768
	ds_read_b128 v[202:205], v147 offset:33792
	ds_read_b128 v[206:209], v147 offset:34816
	ds_read_b128 v[210:213], v147 offset:35840
	ds_read_b128 v[214:217], v147 offset:36864
	ds_read_b128 v[218:221], v147 offset:37888
	ds_read_b128 v[224:227], v147 offset:38912
	ds_read_b128 v[228:231], v147 offset:39936
	global_load_lds_dwordx4 v[238:239], off
	v_lshl_add_u64 v[238:239], s[6:7], 0, v[130:131]
	s_mov_b32 m0, s70
	s_nop 0
	global_load_lds_dwordx4 v[238:239], off
	s_waitcnt vmcnt(8)
	s_waitcnt lgkmcnt(0)
	s_barrier
	s_setprio 1
	v_mfma_f32_16x16x32_bf16 v[124:127], v[166:169], v[198:201], v[124:127]
	v_mfma_f32_16x16x32_bf16 v[120:123], v[174:177], v[198:201], v[120:123]
	v_mfma_f32_16x16x32_bf16 v[108:111], v[166:169], v[206:209], v[108:111]
	v_mfma_f32_16x16x32_bf16 v[104:107], v[174:177], v[206:209], v[104:107]
	v_mfma_f32_16x16x32_bf16 v[92:95], v[166:169], v[214:217], v[92:95]
	v_mfma_f32_16x16x32_bf16 v[88:91], v[174:177], v[214:217], v[88:91]
	v_mfma_f32_16x16x32_bf16 v[76:79], v[166:169], v[224:227], v[76:79]
	v_mfma_f32_16x16x32_bf16 v[72:75], v[174:177], v[224:227], v[72:75]
	v_mfma_f32_16x16x32_bf16 v[124:127], v[170:173], v[202:205], v[124:127]
	v_mfma_f32_16x16x32_bf16 v[120:123], v[178:181], v[202:205], v[120:123]
	v_mfma_f32_16x16x32_bf16 v[108:111], v[170:173], v[210:213], v[108:111]
	v_mfma_f32_16x16x32_bf16 v[104:107], v[178:181], v[210:213], v[104:107]
	v_mfma_f32_16x16x32_bf16 v[92:95], v[170:173], v[218:221], v[92:95]
	v_mfma_f32_16x16x32_bf16 v[88:91], v[178:181], v[218:221], v[88:91]
	v_mfma_f32_16x16x32_bf16 v[76:79], v[170:173], v[228:231], v[76:79]
	v_mfma_f32_16x16x32_bf16 v[72:75], v[178:181], v[228:231], v[72:75]
	v_mfma_f32_16x16x32_bf16 v[116:119], v[182:185], v[198:201], v[116:119]
	v_mfma_f32_16x16x32_bf16 v[112:115], v[190:193], v[198:201], v[112:115]
	v_mfma_f32_16x16x32_bf16 v[100:103], v[182:185], v[206:209], v[100:103]
	v_mfma_f32_16x16x32_bf16 v[96:99], v[190:193], v[206:209], v[96:99]
	v_mfma_f32_16x16x32_bf16 v[84:87], v[182:185], v[214:217], v[84:87]
	v_mfma_f32_16x16x32_bf16 v[80:83], v[190:193], v[214:217], v[80:83]
	v_mfma_f32_16x16x32_bf16 v[68:71], v[182:185], v[224:227], v[68:71]
	v_mfma_f32_16x16x32_bf16 v[64:67], v[190:193], v[224:227], v[64:67]
	v_mfma_f32_16x16x32_bf16 v[116:119], v[186:189], v[202:205], v[116:119]
	v_mfma_f32_16x16x32_bf16 v[112:115], v[194:197], v[202:205], v[112:115]
	v_mfma_f32_16x16x32_bf16 v[100:103], v[186:189], v[210:213], v[100:103]
	v_mfma_f32_16x16x32_bf16 v[96:99], v[194:197], v[210:213], v[96:99]
	v_mfma_f32_16x16x32_bf16 v[84:87], v[186:189], v[218:221], v[84:87]
	v_mfma_f32_16x16x32_bf16 v[80:83], v[194:197], v[218:221], v[80:83]
	v_mfma_f32_16x16x32_bf16 v[68:71], v[186:189], v[228:231], v[68:71]
	v_mfma_f32_16x16x32_bf16 v[64:67], v[194:197], v[228:231], v[64:67]
	s_setprio 0
	s_barrier
; #define PG8_STAGE(bufoff, gbase, voff) do { _Pragma("unroll") for (int _i = 0; _i < 2; ++_i) \
;         __builtin_amdgcn_global_load_lds((const unsigned*)((const char*)(gbase) + (voff)[_i]), (PG8_LAS unsigned*)(lds + (bufoff) + ldsw + _i * 8192), 16, 0, 0); } while (0)
; #define PG8_LDA(dst, b, h) do { _Pragma("unroll") for (int m = 0; m < 4; ++m) _Pragma("unroll") for (int k = 0; k < 2; ++k) dst[m][k] = *(const PG8_LAS bf16x8*)(lds + PG8_SA(b, h) + aoff + m * 2048 + k * 1024); } while (0)
; #define PG8_LDB(dst, b, h) do { _Pragma("unroll") for (int n = 0; n < 2; ++n) _Pragma("unroll") for (int k = 0; k < 2; ++k) dst[n][k] = *(const PG8_LAS bf16x8*)(lds + PG8_SB(b, h) + boff + n * 2048 + k * 1024); } while (0)
; #define PG8_MMA(ai, bj, At, Bt) do { __builtin_amdgcn_s_setprio(1); _Pragma("unroll") for (int m = 0; m < 4; ++m) _Pragma("unroll") for (int n = 0; n < 2; ++n) _Pragma("unroll") for (int k = 0; k < 2; ++k) \
;         acc[ai][bj][m][n] = __builtin_amdgcn_mfma_f32_16x16x32_bf16(Bt[n][k], At[m][k], acc[ai][bj][m][n], 0, 0, 0); __builtin_amdgcn_s_setprio(0); } while (0)
; #define PG8_WAIT_V(n) asm volatile("s_waitcnt vmcnt(" #n ")" ::: "memory")
; template <class Epi, class Sched, bool ALIGN_EPI = false, bool SP2 = false>
; __device__ __forceinline__ void gemm_phase(PG8_LAS unsigned char* lds, const Gemm g, const Sched& S, const Epi& E) {
;     ...
;             PG8_LDB(B0, 0, 0); PG8_LDB(B1, 0, 1); PG8_SCHED; PG8_LDA(At, 0, 0); PG8_STAGE(PG8_SA(1, 1), a1 + hstep, voffA);
;             PG8_WAIT_V(8); PG8_WAIT_L(0); PG8_BAR; PG8_MMA(0, 0, At, B0); PG8_MMA(0, 1, At, B1); PG8_BAR; PG8_SCHED;
;             PG8_LDA(At, 0, 1); PG8_STAGE(PG8_SB(0, 0), b2, voffB); PG8_STAGE(PG8_SB(0, 1), b2 + hstep, voffB); PG8_STAGE(PG8_SA(0, 0), a2, voffA);
;             PG8_WAIT_V(8); PG8_WAIT_L(0); PG8_BAR; PG8_MMA(1, 0, At, B0); PG8_MMA(1, 1, At, B1); PG8_BAR; PG8_SCHED;
;             PG8_LDB(B0, 1, 0); PG8_LDB(B1, 1, 1); PG8_SCHED; PG8_LDA(At, 1, 0); PG8_STAGE(PG8_SA(0, 1), a2 + hstep, voffA);
;             PG8_WAIT_V(8); PG8_WAIT_L(0); PG8_BAR; PG8_MMA(0, 0, At, B0); PG8_MMA(0, 1, At, B1); PG8_BAR; PG8_SCHED;
;             PG8_LDA(At, 1, 1); PG8_STAGE(PG8_SB(1, 0), b3, voffB); PG8_STAGE(PG8_SB(1, 1), b3 + hstep, voffB); PG8_STAGE(PG8_SA(1, 0), a3, voffA);
;             PG8_WAIT_V(8); PG8_WAIT_L(0); PG8_BAR; PG8_MMA(1, 0, At, B0); PG8_MMA(1, 1, At, B1); PG8_BAR; PG8_SCHED;
	s_mov_b32 m0, s72
	v_lshl_add_u64 v[144:145], v[144:145], 0, s[36:37]
	s_add_u32 s6, s64, 0x40080
	ds_read_b128 v[198:201], v147 offset:49152
	ds_read_b128 v[202:205], v147 offset:50176
	ds_read_b128 v[206:209], v147 offset:51200
	ds_read_b128 v[210:213], v147 offset:52224
	ds_read_b128 v[214:217], v147 offset:53248
	ds_read_b128 v[218:221], v147 offset:54272
	ds_read_b128 v[224:227], v147 offset:55296
	ds_read_b128 v[228:231], v147 offset:56320
	global_load_lds_dwordx4 v[144:145], off
	v_lshl_add_u64 v[144:145], v[232:233], 0, s[36:37]
	s_mov_b32 m0, s73
	s_addc_u32 s7, s65, 0
	global_load_lds_dwordx4 v[144:145], off
	v_lshl_add_u64 v[144:145], s[6:7], 0, v[132:133]
	s_mov_b32 m0, s76
	s_nop 0
	global_load_lds_dwordx4 v[144:145], off
	v_lshl_add_u64 v[144:145], s[6:7], 0, v[128:129]
	s_mov_b32 m0, s77
	s_nop 0
	global_load_lds_dwordx4 v[144:145], off
	v_lshl_add_u64 v[144:145], v[234:235], 0, s[36:37]
	s_mov_b32 m0, s74
	s_nop 0
	global_load_lds_dwordx4 v[144:145], off
	v_lshl_add_u64 v[144:145], v[236:237], 0, s[36:37]
	s_mov_b32 m0, s75
	s_nop 0
	global_load_lds_dwordx4 v[144:145], off
	s_waitcnt vmcnt(8)
	s_waitcnt lgkmcnt(0)
	s_barrier
	s_setprio 1
	v_mfma_f32_16x16x32_bf16 v[60:63], v[166:169], v[198:201], v[60:63]
	v_mfma_f32_16x16x32_bf16 v[56:59], v[174:177], v[198:201], v[56:59]
	v_mfma_f32_16x16x32_bf16 v[44:47], v[166:169], v[206:209], v[44:47]
	v_mfma_f32_16x16x32_bf16 v[40:43], v[174:177], v[206:209], v[40:43]
	v_mfma_f32_16x16x32_bf16 v[28:31], v[166:169], v[214:217], v[28:31]
	v_mfma_f32_16x16x32_bf16 v[24:27], v[174:177], v[214:217], v[24:27]
	v_mfma_f32_16x16x32_bf16 v[12:15], v[166:169], v[224:227], v[12:15]
	v_mfma_f32_16x16x32_bf16 v[8:11], v[174:177], v[224:227], v[8:11]
	v_mfma_f32_16x16x32_bf16 v[60:63], v[170:173], v[202:205], v[60:63]
	v_mfma_f32_16x16x32_bf16 v[56:59], v[178:181], v[202:205], v[56:59]
	v_mfma_f32_16x16x32_bf16 v[44:47], v[170:173], v[210:213], v[44:47]
	v_mfma_f32_16x16x32_bf16 v[40:43], v[178:181], v[210:213], v[40:43]
	v_mfma_f32_16x16x32_bf16 v[28:31], v[170:173], v[218:221], v[28:31]
	v_mfma_f32_16x16x32_bf16 v[24:27], v[178:181], v[218:221], v[24:27]
	v_mfma_f32_16x16x32_bf16 v[12:15], v[170:173], v[228:231], v[12:15]
	v_mfma_f32_16x16x32_bf16 v[8:11], v[178:181], v[228:231], v[8:11]
	v_mfma_f32_16x16x32_bf16 v[52:55], v[182:185], v[198:201], v[52:55]
	v_mfma_f32_16x16x32_bf16 v[48:51], v[190:193], v[198:201], v[48:51]
	v_mfma_f32_16x16x32_bf16 v[36:39], v[182:185], v[206:209], v[36:39]
	v_mfma_f32_16x16x32_bf16 v[32:35], v[190:193], v[206:209], v[32:35]
	v_mfma_f32_16x16x32_bf16 v[20:23], v[182:185], v[214:217], v[20:23]
	v_mfma_f32_16x16x32_bf16 v[16:19], v[190:193], v[214:217], v[16:19]
	v_mfma_f32_16x16x32_bf16 v[4:7], v[182:185], v[224:227], v[4:7]
	v_mfma_f32_16x16x32_bf16 v[0:3], v[190:193], v[224:227], v[0:3]
	v_mfma_f32_16x16x32_bf16 v[52:55], v[186:189], v[202:205], v[52:55]
	v_mfma_f32_16x16x32_bf16 v[48:51], v[194:197], v[202:205], v[48:51]
	v_mfma_f32_16x16x32_bf16 v[36:39], v[186:189], v[210:213], v[36:39]
	v_mfma_f32_16x16x32_bf16 v[32:35], v[194:197], v[210:213], v[32:35]
	v_mfma_f32_16x16x32_bf16 v[20:23], v[186:189], v[218:221], v[20:23]
	v_mfma_f32_16x16x32_bf16 v[16:19], v[194:197], v[218:221], v[16:19]
	v_mfma_f32_16x16x32_bf16 v[4:7], v[186:189], v[228:231], v[4:7]
	v_mfma_f32_16x16x32_bf16 v[0:3], v[194:197], v[228:231], v[0:3]
	s_setprio 0
	s_barrier
	s_add_i32 s86, s86, 2
	s_add_u32 s62, s62, 0x100
	s_addc_u32 s63, s63, 0
	s_add_u32 s84, s84, 0x100
	s_addc_u32 s85, s85, 0
.LBB0_793:
	ds_read_b128 v[166:169], v149
	ds_read_b128 v[170:173], v150
	ds_read_b128 v[174:177], v151
	ds_read_b128 v[178:181], v152
	ds_read_b128 v[182:185], v153
	ds_read_b128 v[186:189], v154
	ds_read_b128 v[190:193], v155
	ds_read_b128 v[194:197], v156
	s_add_u32 s6, s62, 0xfffc0080
	s_addc_u32 s7, s63, -1
	s_cmp_eq_u32 s86, 12
	s_cselect_b32 s67, s55, s7
	s_cselect_b32 s66, s82, s6
	s_cselect_b32 s65, s53, s85
	s_cselect_b32 s64, s83, s84
	s_mov_b32 m0, s79
	v_lshl_add_u64 v[144:145], s[62:63], 0, v[136:137]
	ds_read_b128 v[198:201], v147
	ds_read_b128 v[202:205], v147 offset:1024
	ds_read_b128 v[206:209], v147 offset:2048
	ds_read_b128 v[210:213], v147 offset:3072
	ds_read_b128 v[214:217], v147 offset:4096
	ds_read_b128 v[218:221], v147 offset:5120
	ds_read_b128 v[224:227], v147 offset:6144
	ds_read_b128 v[228:231], v147 offset:7168
	global_load_lds_dwordx4 v[144:145], off
	v_lshl_add_u64 v[144:145], s[62:63], 0, v[138:139]
	s_mov_b32 m0, s80
	s_nop 0
	global_load_lds_dwordx4 v[144:145], off
	s_waitcnt vmcnt(8)
	s_waitcnt lgkmcnt(0)
	s_barrier
; #define PG8_STAGE(bufoff, gbase, voff) do { _Pragma("unroll") for (int _i = 0; _i < 2; ++_i) \
;         __builtin_amdgcn_global_load_lds((const unsigned*)((const char*)(gbase) + (voff)[_i]), (PG8_LAS unsigned*)(lds + (bufoff) + ldsw + _i * 8192), 16, 0, 0); } while (0)
; #define PG8_LDA(dst, b, h) do { _Pragma("unroll") for (int m = 0; m < 4; ++m) _Pragma("unroll") for (int k = 0; k < 2; ++k) dst[m][k] = *(const PG8_LAS bf16x8*)(lds + PG8_SA(b, h) + aoff + m * 2048 + k * 1024); } while (0)
; #define PG8_MMA(ai, bj, At, Bt) do { __builtin_amdgcn_s_setprio(1); _Pragma("unroll") for (int m = 0; m < 4; ++m) _Pragma("unroll") for (int n = 0; n < 2; ++n) _Pragma("unroll") for (int k = 0; k < 2; ++k) \
;         acc[ai][bj][m][n] = __builtin_amdgcn_mfma_f32_16x16x32_bf16(Bt[n][k], At[m][k], acc[ai][bj][m][n], 0, 0, 0); __builtin_amdgcn_s_setprio(0); } while (0)
; #define PG8_WAIT_V(n) asm volatile("s_waitcnt vmcnt(" #n ")" ::: "memory")
; #define PG8_WAIT_L(n) asm volatile("s_waitcnt lgkmcnt(" #n ")" ::: "memory")
; #define PG8_BAR __builtin_amdgcn_s_barrier()
; #define PG8_SCHED __builtin_amdgcn_sched_barrier(0)
; template <class Epi, class Sched, bool ALIGN_EPI = false, bool SP2 = false>
; __device__ __forceinline__ void gemm_phase(PG8_LAS unsigned char* lds, const Gemm g, const Sched& S, const Epi& E) {
;     ...
;             PG8_WAIT_V(8); PG8_WAIT_L(0); PG8_BAR; PG8_MMA(0, 0, At, B0); PG8_MMA(0, 1, At, B1); PG8_BAR; PG8_SCHED;
;             PG8_LDA(At, 0, 1); PG8_STAGE(PG8_SB(0, 0), b2, voffB); PG8_STAGE(PG8_SB(0, 1), b2 + hstep, voffB); PG8_STAGE(PG8_SA(0, 0), a2, voffA);
;             PG8_WAIT_V(8); PG8_WAIT_L(0); PG8_BAR; PG8_MMA(1, 0, At, B0); PG8_MMA(1, 1, At, B1); PG8_BAR; PG8_SCHED;
	s_setprio 1
	v_mfma_f32_16x16x32_bf16 v[124:127], v[166:169], v[198:201], v[124:127]
	v_mfma_f32_16x16x32_bf16 v[120:123], v[174:177], v[198:201], v[120:123]
	v_mfma_f32_16x16x32_bf16 v[108:111], v[166:169], v[206:209], v[108:111]
	v_mfma_f32_16x16x32_bf16 v[104:107], v[174:177], v[206:209], v[104:107]
	v_mfma_f32_16x16x32_bf16 v[92:95], v[166:169], v[214:217], v[92:95]
	v_mfma_f32_16x16x32_bf16 v[88:91], v[174:177], v[214:217], v[88:91]
	v_mfma_f32_16x16x32_bf16 v[76:79], v[166:169], v[224:227], v[76:79]
	v_mfma_f32_16x16x32_bf16 v[72:75], v[174:177], v[224:227], v[72:75]
	v_mfma_f32_16x16x32_bf16 v[124:127], v[170:173], v[202:205], v[124:127]
	v_mfma_f32_16x16x32_bf16 v[120:123], v[178:181], v[202:205], v[120:123]
	v_mfma_f32_16x16x32_bf16 v[108:111], v[170:173], v[210:213], v[108:111]
	v_mfma_f32_16x16x32_bf16 v[104:107], v[178:181], v[210:213], v[104:107]
	v_mfma_f32_16x16x32_bf16 v[92:95], v[170:173], v[218:221], v[92:95]
	v_mfma_f32_16x16x32_bf16 v[88:91], v[178:181], v[218:221], v[88:91]
	v_mfma_f32_16x16x32_bf16 v[76:79], v[170:173], v[228:231], v[76:79]
	v_mfma_f32_16x16x32_bf16 v[72:75], v[178:181], v[228:231], v[72:75]
	v_mfma_f32_16x16x32_bf16 v[116:119], v[182:185], v[198:201], v[116:119]
	v_mfma_f32_16x16x32_bf16 v[112:115], v[190:193], v[198:201], v[112:115]
	v_mfma_f32_16x16x32_bf16 v[100:103], v[182:185], v[206:209], v[100:103]
	v_mfma_f32_16x16x32_bf16 v[96:99], v[190:193], v[206:209], v[96:99]
	v_mfma_f32_16x16x32_bf16 v[84:87], v[182:185], v[214:217], v[84:87]
	v_mfma_f32_16x16x32_bf16 v[80:83], v[190:193], v[214:217], v[80:83]
	v_mfma_f32_16x16x32_bf16 v[68:71], v[182:185], v[224:227], v[68:71]
	v_mfma_f32_16x16x32_bf16 v[64:67], v[190:193], v[224:227], v[64:67]
	v_mfma_f32_16x16x32_bf16 v[116:119], v[186:189], v[202:205], v[116:119]
	v_mfma_f32_16x16x32_bf16 v[112:115], v[194:197], v[202:205], v[112:115]
	v_mfma_f32_16x16x32_bf16 v[100:103], v[186:189], v[210:213], v[100:103]
	v_mfma_f32_16x16x32_bf16 v[96:99], v[194:197], v[210:213], v[96:99]
	v_mfma_f32_16x16x32_bf16 v[84:87], v[186:189], v[218:221], v[84:87]
	v_mfma_f32_16x16x32_bf16 v[80:83], v[194:197], v[218:221], v[80:83]
	v_mfma_f32_16x16x32_bf16 v[68:71], v[186:189], v[228:231], v[68:71]
	v_mfma_f32_16x16x32_bf16 v[64:67], v[194:197], v[228:231], v[64:67]
	s_setprio 0
	s_barrier
	s_mov_b32 m0, s15
	v_lshl_add_u64 v[144:145], s[64:65], 0, v[132:133]
	s_add_u32 s6, s64, 0x40000
	ds_read_b128 v[198:201], v147 offset:16384
	ds_read_b128 v[202:205], v147 offset:17408
	ds_read_b128 v[206:209], v147 offset:18432
	ds_read_b128 v[210:213], v147 offset:19456
	ds_read_b128 v[214:217], v147 offset:20480
	ds_read_b128 v[218:221], v147 offset:21504
	ds_read_b128 v[224:227], v147 offset:22528
	ds_read_b128 v[228:231], v147 offset:23552
	global_load_lds_dwordx4 v[144:145], off
	v_lshl_add_u64 v[232:233], s[64:65], 0, v[128:129]
	s_mov_b32 m0, s39
	s_addc_u32 s7, s65, 0
	global_load_lds_dwordx4 v[232:233], off
	v_lshl_add_u64 v[234:235], s[6:7], 0, v[132:133]
	s_mov_b32 m0, s43
	v_lshl_add_u64 v[236:237], s[66:67], 0, v[130:131]
	global_load_lds_dwordx4 v[234:235], off
	v_lshl_add_u64 v[234:235], s[6:7], 0, v[128:129]
	s_mov_b32 m0, s61
	s_nop 0
	global_load_lds_dwordx4 v[234:235], off
	v_lshl_add_u64 v[234:235], s[66:67], 0, v[134:135]
	s_mov_b32 m0, s12
	s_nop 0
	global_load_lds_dwordx4 v[234:235], off
	s_mov_b32 m0, s68
	s_nop 0
	global_load_lds_dwordx4 v[236:237], off
	s_waitcnt vmcnt(8)
	s_waitcnt lgkmcnt(0)
	s_barrier
	s_setprio 1
	v_mfma_f32_16x16x32_bf16 v[60:63], v[166:169], v[198:201], v[60:63]
	v_mfma_f32_16x16x32_bf16 v[56:59], v[174:177], v[198:201], v[56:59]
	v_mfma_f32_16x16x32_bf16 v[44:47], v[166:169], v[206:209], v[44:47]
	v_mfma_f32_16x16x32_bf16 v[40:43], v[174:177], v[206:209], v[40:43]
	v_mfma_f32_16x16x32_bf16 v[28:31], v[166:169], v[214:217], v[28:31]
	v_mfma_f32_16x16x32_bf16 v[24:27], v[174:177], v[214:217], v[24:27]
	v_mfma_f32_16x16x32_bf16 v[12:15], v[166:169], v[224:227], v[12:15]
	v_mfma_f32_16x16x32_bf16 v[8:11], v[174:177], v[224:227], v[8:11]
	v_mfma_f32_16x16x32_bf16 v[60:63], v[170:173], v[202:205], v[60:63]
	v_mfma_f32_16x16x32_bf16 v[56:59], v[178:181], v[202:205], v[56:59]
	v_mfma_f32_16x16x32_bf16 v[44:47], v[170:173], v[210:213], v[44:47]
	v_mfma_f32_16x16x32_bf16 v[40:43], v[178:181], v[210:213], v[40:43]
	v_mfma_f32_16x16x32_bf16 v[28:31], v[170:173], v[218:221], v[28:31]
	v_mfma_f32_16x16x32_bf16 v[24:27], v[178:181], v[218:221], v[24:27]
	v_mfma_f32_16x16x32_bf16 v[12:15], v[170:173], v[228:231], v[12:15]
	v_mfma_f32_16x16x32_bf16 v[8:11], v[178:181], v[228:231], v[8:11]
	v_mfma_f32_16x16x32_bf16 v[52:55], v[182:185], v[198:201], v[52:55]
	v_mfma_f32_16x16x32_bf16 v[48:51], v[190:193], v[198:201], v[48:51]
	v_mfma_f32_16x16x32_bf16 v[36:39], v[182:185], v[206:209], v[36:39]
	v_mfma_f32_16x16x32_bf16 v[32:35], v[190:193], v[206:209], v[32:35]
	v_mfma_f32_16x16x32_bf16 v[20:23], v[182:185], v[214:217], v[20:23]
	v_mfma_f32_16x16x32_bf16 v[16:19], v[190:193], v[214:217], v[16:19]
	v_mfma_f32_16x16x32_bf16 v[4:7], v[182:185], v[224:227], v[4:7]
	v_mfma_f32_16x16x32_bf16 v[0:3], v[190:193], v[224:227], v[0:3]
	v_mfma_f32_16x16x32_bf16 v[52:55], v[186:189], v[202:205], v[52:55]
	v_mfma_f32_16x16x32_bf16 v[48:51], v[194:197], v[202:205], v[48:51]
	v_mfma_f32_16x16x32_bf16 v[36:39], v[186:189], v[210:213], v[36:39]
	v_mfma_f32_16x16x32_bf16 v[32:35], v[194:197], v[210:213], v[32:35]
	v_mfma_f32_16x16x32_bf16 v[20:23], v[186:189], v[218:221], v[20:23]
	v_mfma_f32_16x16x32_bf16 v[16:19], v[194:197], v[218:221], v[16:19]
	v_mfma_f32_16x16x32_bf16 v[4:7], v[186:189], v[228:231], v[4:7]
	v_mfma_f32_16x16x32_bf16 v[0:3], v[194:197], v[228:231], v[0:3]
	s_setprio 0
	s_barrier
; #define PG8_STAGE(bufoff, gbase, voff) do { _Pragma("unroll") for (int _i = 0; _i < 2; ++_i) \
;         __builtin_amdgcn_global_load_lds((const unsigned*)((const char*)(gbase) + (voff)[_i]), (PG8_LAS unsigned*)(lds + (bufoff) + ldsw + _i * 8192), 16, 0, 0); } while (0)
; #define PG8_LDA(dst, b, h) do { _Pragma("unroll") for (int m = 0; m < 4; ++m) _Pragma("unroll") for (int k = 0; k < 2; ++k) dst[m][k] = *(const PG8_LAS bf16x8*)(lds + PG8_SA(b, h) + aoff + m * 2048 + k * 1024); } while (0)
; #define PG8_LDB(dst, b, h) do { _Pragma("unroll") for (int n = 0; n < 2; ++n) _Pragma("unroll") for (int k = 0; k < 2; ++k) dst[n][k] = *(const PG8_LAS bf16x8*)(lds + PG8_SB(b, h) + boff + n * 2048 + k * 1024); } while (0)
; #define PG8_MMA(ai, bj, At, Bt) do { __builtin_amdgcn_s_setprio(1); _Pragma("unroll") for (int m = 0; m < 4; ++m) _Pragma("unroll") for (int n = 0; n < 2; ++n) _Pragma("unroll") for (int k = 0; k < 2; ++k) \
;         acc[ai][bj][m][n] = __builtin_amdgcn_mfma_f32_16x16x32_bf16(Bt[n][k], At[m][k], acc[ai][bj][m][n], 0, 0, 0); __builtin_amdgcn_s_setprio(0); } while (0)
; template <class Epi, class Sched, bool ALIGN_EPI = false, bool SP2 = false>
; __device__ __forceinline__ void gemm_phase(PG8_LAS unsigned char* lds, const Gemm g, const Sched& S, const Epi& E) {
;     ...
;             PG8_LDB(B0, 0, 0); PG8_LDB(B1, 0, 1); PG8_SCHED; PG8_LDA(At, 0, 0); PG8_STAGE(PG8_SA(1, 1), a1 + hstep, voffA);
;             PG8_WAIT_V(8); PG8_WAIT_L(0); PG8_BAR; PG8_MMA(0, 0, At, B0); PG8_MMA(0, 1, At, B1); PG8_BAR; PG8_SCHED;
;             PG8_LDA(At, 0, 1); PG8_STAGE(PG8_SB(0, 0), b2, voffB); PG8_STAGE(PG8_SB(0, 1), b2 + hstep, voffB); PG8_STAGE(PG8_SA(0, 0), a2, voffA);
;             PG8_WAIT_V(8); PG8_WAIT_L(0); PG8_BAR; PG8_MMA(1, 0, At, B0); PG8_MMA(1, 1, At, B1); PG8_BAR; PG8_SCHED;
;             PG8_LDB(B0, 1, 0); PG8_LDB(B1, 1, 1); PG8_SCHED; PG8_LDA(At, 1, 0); PG8_STAGE(PG8_SA(0, 1), a2 + hstep, voffA);
;             PG8_WAIT_V(8); PG8_WAIT_L(0); PG8_BAR; PG8_MMA(0, 0, At, B0); PG8_MMA(0, 1, At, B1); PG8_BAR; PG8_SCHED;
;             PG8_LDA(At, 1, 1); PG8_STAGE(PG8_SB(1, 0), b3, voffB); PG8_STAGE(PG8_SB(1, 1), b3 + hstep, voffB); PG8_STAGE(PG8_SA(1, 0), a3, voffA);
;             PG8_WAIT_V(8); PG8_WAIT_L(0); PG8_BAR; PG8_MMA(1, 0, At, B0); PG8_MMA(1, 1, At, B1); PG8_BAR; PG8_SCHED;
;     ...
;         if constexpr (ALIGN_EPI) { if (wr == 0) PG8_BAR; }
	ds_read_b128 v[166:169], v157
	ds_read_b128 v[170:173], v158
	ds_read_b128 v[174:177], v159
	ds_read_b128 v[178:181], v160
	ds_read_b128 v[182:185], v161
	ds_read_b128 v[186:189], v162
	ds_read_b128 v[190:193], v163
	ds_read_b128 v[194:197], v164
	s_add_u32 s6, s66, 0x40000
	s_addc_u32 s7, s67, 0
	s_mov_b32 m0, s69
	v_lshl_add_u64 v[238:239], s[6:7], 0, v[134:135]
	ds_read_b128 v[198:201], v147 offset:32768
	ds_read_b128 v[202:205], v147 offset:33792
	ds_read_b128 v[206:209], v147 offset:34816
	ds_read_b128 v[210:213], v147 offset:35840
	ds_read_b128 v[214:217], v147 offset:36864
	ds_read_b128 v[218:221], v147 offset:37888
	ds_read_b128 v[224:227], v147 offset:38912
	ds_read_b128 v[228:231], v147 offset:39936
	global_load_lds_dwordx4 v[238:239], off
	v_lshl_add_u64 v[238:239], s[6:7], 0, v[130:131]
	s_mov_b32 m0, s70
	s_nop 0
	global_load_lds_dwordx4 v[238:239], off
	s_waitcnt vmcnt(8)
	s_waitcnt lgkmcnt(0)
	s_barrier
	s_setprio 1
	v_mfma_f32_16x16x32_bf16 v[124:127], v[166:169], v[198:201], v[124:127]
	v_mfma_f32_16x16x32_bf16 v[120:123], v[174:177], v[198:201], v[120:123]
	v_mfma_f32_16x16x32_bf16 v[108:111], v[166:169], v[206:209], v[108:111]
	v_mfma_f32_16x16x32_bf16 v[104:107], v[174:177], v[206:209], v[104:107]
	v_mfma_f32_16x16x32_bf16 v[92:95], v[166:169], v[214:217], v[92:95]
	v_mfma_f32_16x16x32_bf16 v[88:91], v[174:177], v[214:217], v[88:91]
	v_mfma_f32_16x16x32_bf16 v[76:79], v[166:169], v[224:227], v[76:79]
	v_mfma_f32_16x16x32_bf16 v[72:75], v[174:177], v[224:227], v[72:75]
	v_mfma_f32_16x16x32_bf16 v[124:127], v[170:173], v[202:205], v[124:127]
	v_mfma_f32_16x16x32_bf16 v[120:123], v[178:181], v[202:205], v[120:123]
	v_mfma_f32_16x16x32_bf16 v[108:111], v[170:173], v[210:213], v[108:111]
	v_mfma_f32_16x16x32_bf16 v[104:107], v[178:181], v[210:213], v[104:107]
	v_mfma_f32_16x16x32_bf16 v[92:95], v[170:173], v[218:221], v[92:95]
	v_mfma_f32_16x16x32_bf16 v[88:91], v[178:181], v[218:221], v[88:91]
	v_mfma_f32_16x16x32_bf16 v[76:79], v[170:173], v[228:231], v[76:79]
	v_mfma_f32_16x16x32_bf16 v[72:75], v[178:181], v[228:231], v[72:75]
	v_mfma_f32_16x16x32_bf16 v[116:119], v[182:185], v[198:201], v[116:119]
	v_mfma_f32_16x16x32_bf16 v[112:115], v[190:193], v[198:201], v[112:115]
	v_mfma_f32_16x16x32_bf16 v[100:103], v[182:185], v[206:209], v[100:103]
	v_mfma_f32_16x16x32_bf16 v[96:99], v[190:193], v[206:209], v[96:99]
	v_mfma_f32_16x16x32_bf16 v[84:87], v[182:185], v[214:217], v[84:87]
	v_mfma_f32_16x16x32_bf16 v[80:83], v[190:193], v[214:217], v[80:83]
	v_mfma_f32_16x16x32_bf16 v[68:71], v[182:185], v[224:227], v[68:71]
	v_mfma_f32_16x16x32_bf16 v[64:67], v[190:193], v[224:227], v[64:67]
	v_mfma_f32_16x16x32_bf16 v[116:119], v[186:189], v[202:205], v[116:119]
	v_mfma_f32_16x16x32_bf16 v[112:115], v[194:197], v[202:205], v[112:115]
	v_mfma_f32_16x16x32_bf16 v[100:103], v[186:189], v[210:213], v[100:103]
	v_mfma_f32_16x16x32_bf16 v[96:99], v[194:197], v[210:213], v[96:99]
	v_mfma_f32_16x16x32_bf16 v[84:87], v[186:189], v[218:221], v[84:87]
	v_mfma_f32_16x16x32_bf16 v[80:83], v[194:197], v[218:221], v[80:83]
	v_mfma_f32_16x16x32_bf16 v[68:71], v[186:189], v[228:231], v[68:71]
	v_mfma_f32_16x16x32_bf16 v[64:67], v[194:197], v[228:231], v[64:67]
	s_setprio 0
	s_barrier
	s_mov_b32 m0, s72
	v_lshl_add_u64 v[144:145], v[144:145], 0, s[36:37]
	s_add_u32 s6, s64, 0x40080
	ds_read_b128 v[198:201], v147 offset:49152
	ds_read_b128 v[202:205], v147 offset:50176
	ds_read_b128 v[206:209], v147 offset:51200
	ds_read_b128 v[210:213], v147 offset:52224
	ds_read_b128 v[214:217], v147 offset:53248
	ds_read_b128 v[218:221], v147 offset:54272
	ds_read_b128 v[224:227], v147 offset:55296
	ds_read_b128 v[228:231], v147 offset:56320
	global_load_lds_dwordx4 v[144:145], off
	v_lshl_add_u64 v[144:145], v[232:233], 0, s[36:37]
	s_mov_b32 m0, s73
	s_addc_u32 s7, s65, 0
	global_load_lds_dwordx4 v[144:145], off
	v_lshl_add_u64 v[144:145], s[6:7], 0, v[132:133]
	s_mov_b32 m0, s76
	s_nop 0
	global_load_lds_dwordx4 v[144:145], off
	v_lshl_add_u64 v[144:145], s[6:7], 0, v[128:129]
	s_mov_b32 m0, s77
	s_nop 0
	global_load_lds_dwordx4 v[144:145], off
	v_lshl_add_u64 v[144:145], v[234:235], 0, s[36:37]
	s_mov_b32 m0, s74
	s_nop 0
	global_load_lds_dwordx4 v[144:145], off
	v_lshl_add_u64 v[144:145], v[236:237], 0, s[36:37]
	s_mov_b32 m0, s75
	s_nop 0
	global_load_lds_dwordx4 v[144:145], off
	s_waitcnt vmcnt(8)
	s_waitcnt lgkmcnt(0)
	s_barrier
	s_setprio 1
	v_mfma_f32_16x16x32_bf16 v[60:63], v[166:169], v[198:201], v[60:63]
	v_mfma_f32_16x16x32_bf16 v[56:59], v[174:177], v[198:201], v[56:59]
	v_mfma_f32_16x16x32_bf16 v[44:47], v[166:169], v[206:209], v[44:47]
	v_mfma_f32_16x16x32_bf16 v[40:43], v[174:177], v[206:209], v[40:43]
	v_mfma_f32_16x16x32_bf16 v[28:31], v[166:169], v[214:217], v[28:31]
	v_mfma_f32_16x16x32_bf16 v[24:27], v[174:177], v[214:217], v[24:27]
	v_mfma_f32_16x16x32_bf16 v[12:15], v[166:169], v[224:227], v[12:15]
	v_mfma_f32_16x16x32_bf16 v[8:11], v[174:177], v[224:227], v[8:11]
	v_mfma_f32_16x16x32_bf16 v[60:63], v[170:173], v[202:205], v[60:63]
	v_mfma_f32_16x16x32_bf16 v[56:59], v[178:181], v[202:205], v[56:59]
	v_mfma_f32_16x16x32_bf16 v[44:47], v[170:173], v[210:213], v[44:47]
	v_mfma_f32_16x16x32_bf16 v[40:43], v[178:181], v[210:213], v[40:43]
	v_mfma_f32_16x16x32_bf16 v[28:31], v[170:173], v[218:221], v[28:31]
	v_mfma_f32_16x16x32_bf16 v[24:27], v[178:181], v[218:221], v[24:27]
	v_mfma_f32_16x16x32_bf16 v[12:15], v[170:173], v[228:231], v[12:15]
	v_mfma_f32_16x16x32_bf16 v[8:11], v[178:181], v[228:231], v[8:11]
	v_mfma_f32_16x16x32_bf16 v[52:55], v[182:185], v[198:201], v[52:55]
	v_mfma_f32_16x16x32_bf16 v[48:51], v[190:193], v[198:201], v[48:51]
	v_mfma_f32_16x16x32_bf16 v[36:39], v[182:185], v[206:209], v[36:39]
	v_mfma_f32_16x16x32_bf16 v[32:35], v[190:193], v[206:209], v[32:35]
	v_mfma_f32_16x16x32_bf16 v[20:23], v[182:185], v[214:217], v[20:23]
	v_mfma_f32_16x16x32_bf16 v[16:19], v[190:193], v[214:217], v[16:19]
	v_mfma_f32_16x16x32_bf16 v[4:7], v[182:185], v[224:227], v[4:7]
	v_mfma_f32_16x16x32_bf16 v[0:3], v[190:193], v[224:227], v[0:3]
	v_mfma_f32_16x16x32_bf16 v[52:55], v[186:189], v[202:205], v[52:55]
	v_mfma_f32_16x16x32_bf16 v[48:51], v[194:197], v[202:205], v[48:51]
	v_mfma_f32_16x16x32_bf16 v[36:39], v[186:189], v[210:213], v[36:39]
	v_mfma_f32_16x16x32_bf16 v[32:35], v[194:197], v[210:213], v[32:35]
	v_mfma_f32_16x16x32_bf16 v[20:23], v[186:189], v[218:221], v[20:23]
	v_mfma_f32_16x16x32_bf16 v[16:19], v[194:197], v[218:221], v[16:19]
	v_mfma_f32_16x16x32_bf16 v[4:7], v[186:189], v[228:231], v[4:7]
	v_mfma_f32_16x16x32_bf16 v[0:3], v[194:197], v[228:231], v[0:3]
	s_setprio 0
	s_barrier
	s_add_i32 s86, s86, 2
	s_add_u32 s62, s62, 0x100
	s_addc_u32 s63, s63, 0
	s_add_u32 s84, s84, 0x100
	s_addc_u32 s85, s85, 0
	s_cmp_gt_u32 s86, 13
	s_cbranch_scc0 .LBB0_793
	s_and_b64 vcc, exec, s[40:41]
	s_cbranch_vccz .LBB0_796
	s_barrier

;     __host__ __device__ bool next(int i, Unit& u) const { const int L = i * G + c; if (L >= 16 * nkc) return false; u.kc = L % nkc; const int t = L / nkc; u.pn = t & 3; u.pm = 33 * (t >> 2); return true; }
; #define PG8_LDA(dst, b, h) do { _Pragma("unroll") for (int m = 0; m < 4; ++m) _Pragma("unroll") for (int k = 0; k < 2; ++k) dst[m][k] = *(const PG8_LAS bf16x8*)(lds + PG8_SA(b, h) + aoff + m * 2048 + k * 1024); } while (0)
; template <class Epi, class Sched, bool ALIGN_EPI = false, bool SP2 = false>
; __device__ __forceinline__ void gemm_phase(PG8_LAS unsigned char* lds, const Gemm g, const Sched& S, const Epi& E) {
;     ...
;         const bool has_next = S.next(ui + 1, nxt);
;         const char* nA = has_next ? (const char*)g.A + (size_t)nxt.pm * tstep + (size_t)nxt.kc * cstep : cA; const char* nB = has_next ? (const char*)g.Bt + (size_t)nxt.pn * tstep + (size_t)nxt.kc * cstep : cB;
;         for (int t = 0; t < nt; t += 2) {
;             const bool last = (t == nt - 2);
;             const char* a1 = cA + (size_t)(t + 1) * kstep;
;             const char* a2 = last ? nA : cA + (size_t)(t + 2) * kstep; const char* b2 = last ? nB : cB + (size_t)(t + 2) * kstep;
;             const char* a3 = a2 + kstep; const char* b3 = b2 + kstep;
;             if (last && has_next) S.a_ready(nxt);
;             if constexpr (SP2) {
;             PG8_LDB(B0, 0, 0); PG8_LDB(B1, 0, 1); PG8_SCHED; PG8_LDA(At, 0, 0); PG8_STAGE(PG8_SA(1, 1), a1 + hstep, voffA);
;             PG8_WAIT_V(8); PG8_WAIT_L(0); PG8_BAR; PG8_MMA(0, 0, At, B0); PG8_MMA(0, 1, At, B1); PG8_BAR; PG8_SCHED;
;             PG8_LDA(At, 0, 1); PG8_STAGE(PG8_SB(0, 0), b2, voffB); PG8_STAGE(PG8_SB(0, 1), b2 + hstep, voffB); PG8_STAGE(PG8_SA(0, 0), a2, voffA);
;             PG8_WAIT_V(8); PG8_WAIT_L(0); PG8_BAR; PG8_MMA(1, 0, At, B0); PG8_MMA(1, 1, At, B1); PG8_BAR; PG8_SCHED;
;             PG8_LDB(B0, 1, 0); PG8_LDB(B1, 1, 1); PG8_SCHED; PG8_LDA(At, 1, 0); PG8_STAGE(PG8_SA(0, 1), a2 + hstep, voffA);
;             PG8_WAIT_V(8); PG8_WAIT_L(0); PG8_BAR; PG8_MMA(0, 0, At, B0); PG8_MMA(0, 1, At, B1); PG8_BAR; PG8_SCHED;
;             PG8_LDA(At, 1, 1); PG8_STAGE(PG8_SB(1, 0), b3, voffB); PG8_STAGE(PG8_SB(1, 1), b3 + hstep, voffB); PG8_STAGE(PG8_SA(1, 0), a3, voffA);
;             PG8_WAIT_V(8); PG8_WAIT_L(0); PG8_BAR; PG8_MMA(1, 0, At, B0); PG8_MMA(1, 1, At, B1); PG8_BAR; PG8_SCHED;
.LBB0_872:
	s_add_u32 s57, s60, 0x100
	s_addc_u32 s88, s61, 0
	s_mov_b32 s89, -2
	ds_read_b128 v[142:145], v174
	ds_read_b128 v[146:149], v175
	ds_read_b128 v[150:153], v176
	ds_read_b128 v[154:157], v177
	ds_read_b128 v[158:161], v178
	ds_read_b128 v[162:165], v179
	ds_read_b128 v[166:169], v180
	ds_read_b128 v[190:193], v181
	s_add_u32 s60, s58, 0x100
	s_addc_u32 s61, s59, 0
	s_cmp_eq_u32 s89, 40
	s_cselect_b32 s65, s9, s61
	s_cselect_b32 s64, s8, s60
	s_cselect_b32 s63, s55, s88
	s_cselect_b32 s62, s54, s57
	s_mov_b32 m0, s78
	v_lshl_add_u64 v[170:171], s[58:59], 0, v[134:135]
	ds_read_b128 v[194:197], v172
	ds_read_b128 v[198:201], v172 offset:1024
	ds_read_b128 v[202:205], v172 offset:2048
	ds_read_b128 v[206:209], v172 offset:3072
	ds_read_b128 v[210:213], v172 offset:4096
	ds_read_b128 v[214:217], v172 offset:5120
	ds_read_b128 v[218:221], v172 offset:6144
	ds_read_b128 v[224:227], v172 offset:7168
	global_load_lds_dwordx4 v[170:171], off
	v_lshl_add_u64 v[170:171], s[58:59], 0, v[136:137]
	s_mov_b32 m0, s79
	s_nop 0
	global_load_lds_dwordx4 v[170:171], off
	s_waitcnt vmcnt(8)
	s_waitcnt lgkmcnt(0)
	s_barrier
	s_setprio 1
	v_mfma_f32_16x16x32_bf16 v[124:127], v[142:145], v[194:197], 0
	v_mfma_f32_16x16x32_bf16 v[108:111], v[150:153], v[194:197], 0
	v_mfma_f32_16x16x32_bf16 v[120:123], v[142:145], v[202:205], 0
	v_mfma_f32_16x16x32_bf16 v[96:99], v[150:153], v[202:205], 0
	v_mfma_f32_16x16x32_bf16 v[116:119], v[142:145], v[210:213], 0
	v_mfma_f32_16x16x32_bf16 v[88:91], v[150:153], v[210:213], 0
	v_mfma_f32_16x16x32_bf16 v[112:115], v[142:145], v[218:221], 0
	v_mfma_f32_16x16x32_bf16 v[84:87], v[150:153], v[218:221], 0
	v_mfma_f32_16x16x32_bf16 v[124:127], v[146:149], v[198:201], v[124:127]
	v_mfma_f32_16x16x32_bf16 v[108:111], v[154:157], v[198:201], v[108:111]
	v_mfma_f32_16x16x32_bf16 v[120:123], v[146:149], v[206:209], v[120:123]
	v_mfma_f32_16x16x32_bf16 v[96:99], v[154:157], v[206:209], v[96:99]
	v_mfma_f32_16x16x32_bf16 v[116:119], v[146:149], v[214:217], v[116:119]
	v_mfma_f32_16x16x32_bf16 v[88:91], v[154:157], v[214:217], v[88:91]
	v_mfma_f32_16x16x32_bf16 v[112:115], v[146:149], v[224:227], v[112:115]
	v_mfma_f32_16x16x32_bf16 v[84:87], v[154:157], v[224:227], v[84:87]
	v_mfma_f32_16x16x32_bf16 v[68:71], v[158:161], v[194:197], 0
	v_mfma_f32_16x16x32_bf16 v[40:43], v[166:169], v[194:197], 0
	v_mfma_f32_16x16x32_bf16 v[60:63], v[158:161], v[202:205], 0
	v_mfma_f32_16x16x32_bf16 v[32:35], v[166:169], v[202:205], 0
	v_mfma_f32_16x16x32_bf16 v[52:55], v[158:161], v[210:213], 0
	v_mfma_f32_16x16x32_bf16 v[24:27], v[166:169], v[210:213], 0
	v_mfma_f32_16x16x32_bf16 v[48:51], v[158:161], v[218:221], 0
	v_mfma_f32_16x16x32_bf16 v[16:19], v[166:169], v[218:221], 0
	v_mfma_f32_16x16x32_bf16 v[68:71], v[162:165], v[198:201], v[68:71]
	v_mfma_f32_16x16x32_bf16 v[40:43], v[190:193], v[198:201], v[40:43]
	v_mfma_f32_16x16x32_bf16 v[60:63], v[162:165], v[206:209], v[60:63]
	v_mfma_f32_16x16x32_bf16 v[32:35], v[190:193], v[206:209], v[32:35]
	v_mfma_f32_16x16x32_bf16 v[52:55], v[162:165], v[214:217], v[52:55]
	v_mfma_f32_16x16x32_bf16 v[24:27], v[190:193], v[214:217], v[24:27]
	v_mfma_f32_16x16x32_bf16 v[48:51], v[162:165], v[224:227], v[48:51]
	v_mfma_f32_16x16x32_bf16 v[16:19], v[190:193], v[224:227], v[16:19]
	s_setprio 0
	s_barrier
	s_mov_b32 m0, s12
	v_lshl_add_u64 v[170:171], s[62:63], 0, v[128:129]
	s_add_u32 s58, s62, 0xb0000
	ds_read_b128 v[194:197], v172 offset:16384
	ds_read_b128 v[198:201], v172 offset:17408
	ds_read_b128 v[202:205], v172 offset:18432
	ds_read_b128 v[206:209], v172 offset:19456
	ds_read_b128 v[210:213], v172 offset:20480
	ds_read_b128 v[214:217], v172 offset:21504
	ds_read_b128 v[218:221], v172 offset:22528
	ds_read_b128 v[224:227], v172 offset:23552
	global_load_lds_dwordx4 v[170:171], off
	v_lshl_add_u64 v[228:229], s[62:63], 0, v[130:131]
	s_mov_b32 m0, s13
	s_addc_u32 s59, s63, 0
	global_load_lds_dwordx4 v[228:229], off
	v_lshl_add_u64 v[230:231], s[58:59], 0, v[128:129]
	s_mov_b32 m0, s14
	v_lshl_add_u64 v[232:233], s[64:65], 0, v[130:131]
	global_load_lds_dwordx4 v[230:231], off
	v_lshl_add_u64 v[230:231], s[58:59], 0, v[130:131]
	s_mov_b32 m0, s15
	s_nop 0
	global_load_lds_dwordx4 v[230:231], off
	v_lshl_add_u64 v[230:231], s[64:65], 0, v[128:129]
	s_mov_b32 m0, s5
	s_nop 0
	global_load_lds_dwordx4 v[230:231], off
	s_mov_b32 m0, s39
	s_nop 0
	global_load_lds_dwordx4 v[232:233], off
	s_waitcnt vmcnt(8)
	s_waitcnt lgkmcnt(0)
	s_barrier
	s_setprio 1
	v_mfma_f32_16x16x32_bf16 v[104:107], v[142:145], v[194:197], 0
	v_mfma_f32_16x16x32_bf16 v[76:79], v[150:153], v[194:197], 0
	v_mfma_f32_16x16x32_bf16 v[100:103], v[142:145], v[202:205], 0
	v_mfma_f32_16x16x32_bf16 v[72:75], v[150:153], v[202:205], 0
	v_mfma_f32_16x16x32_bf16 v[92:95], v[142:145], v[210:213], 0
	v_mfma_f32_16x16x32_bf16 v[64:67], v[150:153], v[210:213], 0
	v_mfma_f32_16x16x32_bf16 v[80:83], v[142:145], v[218:221], 0
	v_mfma_f32_16x16x32_bf16 v[56:59], v[150:153], v[218:221], 0
	v_mfma_f32_16x16x32_bf16 v[104:107], v[146:149], v[198:201], v[104:107]
	v_mfma_f32_16x16x32_bf16 v[76:79], v[154:157], v[198:201], v[76:79]
	v_mfma_f32_16x16x32_bf16 v[100:103], v[146:149], v[206:209], v[100:103]
	v_mfma_f32_16x16x32_bf16 v[72:75], v[154:157], v[206:209], v[72:75]
	v_mfma_f32_16x16x32_bf16 v[92:95], v[146:149], v[214:217], v[92:95]
	v_mfma_f32_16x16x32_bf16 v[64:67], v[154:157], v[214:217], v[64:67]
	v_mfma_f32_16x16x32_bf16 v[80:83], v[146:149], v[224:227], v[80:83]
	v_mfma_f32_16x16x32_bf16 v[56:59], v[154:157], v[224:227], v[56:59]
	v_mfma_f32_16x16x32_bf16 v[44:47], v[158:161], v[194:197], 0
	v_mfma_f32_16x16x32_bf16 v[12:15], v[166:169], v[194:197], 0
	v_mfma_f32_16x16x32_bf16 v[36:39], v[158:161], v[202:205], 0
	v_mfma_f32_16x16x32_bf16 v[8:11], v[166:169], v[202:205], 0
	v_mfma_f32_16x16x32_bf16 v[28:31], v[158:161], v[210:213], 0
	v_mfma_f32_16x16x32_bf16 v[4:7], v[166:169], v[210:213], 0
	v_mfma_f32_16x16x32_bf16 v[20:23], v[158:161], v[218:221], 0
	v_mfma_f32_16x16x32_bf16 v[0:3], v[166:169], v[218:221], 0
	v_mfma_f32_16x16x32_bf16 v[44:47], v[162:165], v[198:201], v[44:47]
	v_mfma_f32_16x16x32_bf16 v[12:15], v[190:193], v[198:201], v[12:15]
	v_mfma_f32_16x16x32_bf16 v[36:39], v[162:165], v[206:209], v[36:39]
	v_mfma_f32_16x16x32_bf16 v[8:11], v[190:193], v[206:209], v[8:11]
	v_mfma_f32_16x16x32_bf16 v[28:31], v[162:165], v[214:217], v[28:31]
	v_mfma_f32_16x16x32_bf16 v[4:7], v[190:193], v[214:217], v[4:7]
	v_mfma_f32_16x16x32_bf16 v[20:23], v[162:165], v[224:227], v[20:23]
	v_mfma_f32_16x16x32_bf16 v[0:3], v[190:193], v[224:227], v[0:3]
	s_setprio 0
	s_barrier
; #define PG8_STAGE(bufoff, gbase, voff) do { _Pragma("unroll") for (int _i = 0; _i < 2; ++_i) \
;         __builtin_amdgcn_global_load_lds((const unsigned*)((const char*)(gbase) + (voff)[_i]), (PG8_LAS unsigned*)(lds + (bufoff) + ldsw + _i * 8192), 16, 0, 0); } while (0)
; #define PG8_LDA(dst, b, h) do { _Pragma("unroll") for (int m = 0; m < 4; ++m) _Pragma("unroll") for (int k = 0; k < 2; ++k) dst[m][k] = *(const PG8_LAS bf16x8*)(lds + PG8_SA(b, h) + aoff + m * 2048 + k * 1024); } while (0)
; #define PG8_LDB(dst, b, h) do { _Pragma("unroll") for (int n = 0; n < 2; ++n) _Pragma("unroll") for (int k = 0; k < 2; ++k) dst[n][k] = *(const PG8_LAS bf16x8*)(lds + PG8_SB(b, h) + boff + n * 2048 + k * 1024); } while (0)
; #define PG8_MMA(ai, bj, At, Bt) do { __builtin_amdgcn_s_setprio(1); _Pragma("unroll") for (int m = 0; m < 4; ++m) _Pragma("unroll") for (int n = 0; n < 2; ++n) _Pragma("unroll") for (int k = 0; k < 2; ++k) \
;         acc[ai][bj][m][n] = __builtin_amdgcn_mfma_f32_16x16x32_bf16(Bt[n][k], At[m][k], acc[ai][bj][m][n], 0, 0, 0); __builtin_amdgcn_s_setprio(0); } while (0)
; #define PG8_WAIT_V(n) asm volatile("s_waitcnt vmcnt(" #n ")" ::: "memory")
; #define PG8_WAIT_L(n) asm volatile("s_waitcnt lgkmcnt(" #n ")" ::: "memory")
; #define PG8_BAR __builtin_amdgcn_s_barrier()
; #define PG8_SCHED __builtin_amdgcn_sched_barrier(0)
; template <class Epi, class Sched, bool ALIGN_EPI = false, bool SP2 = false>
; __device__ __forceinline__ void gemm_phase(PG8_LAS unsigned char* lds, const Gemm g, const Sched& S, const Epi& E) {
;     ...
;             PG8_LDB(B0, 1, 0); PG8_LDB(B1, 1, 1); PG8_SCHED; PG8_LDA(At, 1, 0); PG8_STAGE(PG8_SA(0, 1), a2 + hstep, voffA);
;             PG8_WAIT_V(8); PG8_WAIT_L(0); PG8_BAR; PG8_MMA(0, 0, At, B0); PG8_MMA(0, 1, At, B1); PG8_BAR; PG8_SCHED;
;             PG8_LDA(At, 1, 1); PG8_STAGE(PG8_SB(1, 0), b3, voffB); PG8_STAGE(PG8_SB(1, 1), b3 + hstep, voffB); PG8_STAGE(PG8_SA(1, 0), a3, voffA);
;             PG8_WAIT_V(8); PG8_WAIT_L(0); PG8_BAR; PG8_MMA(1, 0, At, B0); PG8_MMA(1, 1, At, B1); PG8_BAR; PG8_SCHED;
	ds_read_b128 v[142:145], v182
	ds_read_b128 v[146:149], v183
	ds_read_b128 v[150:153], v184
	ds_read_b128 v[154:157], v185
	ds_read_b128 v[158:161], v186
	ds_read_b128 v[162:165], v187
	ds_read_b128 v[166:169], v188
	ds_read_b128 v[190:193], v189
	s_add_u32 s58, s64, 0xb0000
	s_addc_u32 s59, s65, 0
	s_mov_b32 m0, s43
	v_lshl_add_u64 v[234:235], s[58:59], 0, v[128:129]
	ds_read_b128 v[194:197], v172 offset:32768
	ds_read_b128 v[198:201], v172 offset:33792
	ds_read_b128 v[202:205], v172 offset:34816
	ds_read_b128 v[206:209], v172 offset:35840
	ds_read_b128 v[210:213], v172 offset:36864
	ds_read_b128 v[214:217], v172 offset:37888
	ds_read_b128 v[218:221], v172 offset:38912
	ds_read_b128 v[224:227], v172 offset:39936
	global_load_lds_dwordx4 v[234:235], off
	v_lshl_add_u64 v[234:235], s[58:59], 0, v[130:131]
	s_mov_b32 m0, s66
	s_nop 0
	global_load_lds_dwordx4 v[234:235], off
	s_waitcnt vmcnt(8)
	s_waitcnt lgkmcnt(0)
	s_barrier
	s_setprio 1
	v_mfma_f32_16x16x32_bf16 v[124:127], v[142:145], v[194:197], v[124:127]
	v_mfma_f32_16x16x32_bf16 v[108:111], v[150:153], v[194:197], v[108:111]
	v_mfma_f32_16x16x32_bf16 v[120:123], v[142:145], v[202:205], v[120:123]
	v_mfma_f32_16x16x32_bf16 v[96:99], v[150:153], v[202:205], v[96:99]
	v_mfma_f32_16x16x32_bf16 v[116:119], v[142:145], v[210:213], v[116:119]
	v_mfma_f32_16x16x32_bf16 v[88:91], v[150:153], v[210:213], v[88:91]
	v_mfma_f32_16x16x32_bf16 v[112:115], v[142:145], v[218:221], v[112:115]
	v_mfma_f32_16x16x32_bf16 v[84:87], v[150:153], v[218:221], v[84:87]
	v_mfma_f32_16x16x32_bf16 v[124:127], v[146:149], v[198:201], v[124:127]
	v_mfma_f32_16x16x32_bf16 v[108:111], v[154:157], v[198:201], v[108:111]
	v_mfma_f32_16x16x32_bf16 v[120:123], v[146:149], v[206:209], v[120:123]
	v_mfma_f32_16x16x32_bf16 v[96:99], v[154:157], v[206:209], v[96:99]
	v_mfma_f32_16x16x32_bf16 v[116:119], v[146:149], v[214:217], v[116:119]
	v_mfma_f32_16x16x32_bf16 v[88:91], v[154:157], v[214:217], v[88:91]
	v_mfma_f32_16x16x32_bf16 v[112:115], v[146:149], v[224:227], v[112:115]
	v_mfma_f32_16x16x32_bf16 v[84:87], v[154:157], v[224:227], v[84:87]
	v_mfma_f32_16x16x32_bf16 v[68:71], v[158:161], v[194:197], v[68:71]
	v_mfma_f32_16x16x32_bf16 v[40:43], v[166:169], v[194:197], v[40:43]
	v_mfma_f32_16x16x32_bf16 v[60:63], v[158:161], v[202:205], v[60:63]
	v_mfma_f32_16x16x32_bf16 v[32:35], v[166:169], v[202:205], v[32:35]
	v_mfma_f32_16x16x32_bf16 v[52:55], v[158:161], v[210:213], v[52:55]
	v_mfma_f32_16x16x32_bf16 v[24:27], v[166:169], v[210:213], v[24:27]
	v_mfma_f32_16x16x32_bf16 v[48:51], v[158:161], v[218:221], v[48:51]
	v_mfma_f32_16x16x32_bf16 v[16:19], v[166:169], v[218:221], v[16:19]
	v_mfma_f32_16x16x32_bf16 v[68:71], v[162:165], v[198:201], v[68:71]
	v_mfma_f32_16x16x32_bf16 v[40:43], v[190:193], v[198:201], v[40:43]
	v_mfma_f32_16x16x32_bf16 v[60:63], v[162:165], v[206:209], v[60:63]
	v_mfma_f32_16x16x32_bf16 v[32:35], v[190:193], v[206:209], v[32:35]
	v_mfma_f32_16x16x32_bf16 v[52:55], v[162:165], v[214:217], v[52:55]
	v_mfma_f32_16x16x32_bf16 v[24:27], v[190:193], v[214:217], v[24:27]
	v_mfma_f32_16x16x32_bf16 v[48:51], v[162:165], v[224:227], v[48:51]
	v_mfma_f32_16x16x32_bf16 v[16:19], v[190:193], v[224:227], v[16:19]
	s_setprio 0
	s_barrier
	s_mov_b32 m0, s70
	v_lshl_add_u64 v[170:171], v[170:171], 0, s[40:41]
	s_add_u32 s58, s62, 0xb0080
	ds_read_b128 v[194:197], v172 offset:49152
	ds_read_b128 v[198:201], v172 offset:50176
	ds_read_b128 v[202:205], v172 offset:51200
	ds_read_b128 v[206:209], v172 offset:52224
	ds_read_b128 v[210:213], v172 offset:53248
	ds_read_b128 v[214:217], v172 offset:54272
	ds_read_b128 v[218:221], v172 offset:55296
	ds_read_b128 v[224:227], v172 offset:56320
	global_load_lds_dwordx4 v[170:171], off
	v_lshl_add_u64 v[170:171], v[228:229], 0, s[40:41]
	s_mov_b32 m0, s71
	s_addc_u32 s59, s63, 0
	global_load_lds_dwordx4 v[170:171], off
	v_lshl_add_u64 v[170:171], s[58:59], 0, v[128:129]
	s_mov_b32 m0, s74
	s_nop 0
	global_load_lds_dwordx4 v[170:171], off
	v_lshl_add_u64 v[170:171], s[58:59], 0, v[130:131]
	s_mov_b32 m0, s75
	s_nop 0
	global_load_lds_dwordx4 v[170:171], off
	v_lshl_add_u64 v[170:171], v[230:231], 0, s[40:41]
	s_mov_b32 m0, s72
	s_nop 0
	global_load_lds_dwordx4 v[170:171], off
	v_lshl_add_u64 v[170:171], v[232:233], 0, s[40:41]
	s_mov_b32 m0, s73
	s_nop 0
	global_load_lds_dwordx4 v[170:171], off
	s_waitcnt vmcnt(8)
	s_waitcnt lgkmcnt(0)
	s_barrier
	s_setprio 1
	v_mfma_f32_16x16x32_bf16 v[104:107], v[142:145], v[194:197], v[104:107]
	v_mfma_f32_16x16x32_bf16 v[76:79], v[150:153], v[194:197], v[76:79]
	v_mfma_f32_16x16x32_bf16 v[100:103], v[142:145], v[202:205], v[100:103]
	v_mfma_f32_16x16x32_bf16 v[72:75], v[150:153], v[202:205], v[72:75]
	v_mfma_f32_16x16x32_bf16 v[92:95], v[142:145], v[210:213], v[92:95]
	v_mfma_f32_16x16x32_bf16 v[64:67], v[150:153], v[210:213], v[64:67]
	v_mfma_f32_16x16x32_bf16 v[80:83], v[142:145], v[218:221], v[80:83]
	v_mfma_f32_16x16x32_bf16 v[56:59], v[150:153], v[218:221], v[56:59]
	v_mfma_f32_16x16x32_bf16 v[104:107], v[146:149], v[198:201], v[104:107]
	v_mfma_f32_16x16x32_bf16 v[76:79], v[154:157], v[198:201], v[76:79]
	v_mfma_f32_16x16x32_bf16 v[100:103], v[146:149], v[206:209], v[100:103]
	v_mfma_f32_16x16x32_bf16 v[72:75], v[154:157], v[206:209], v[72:75]
	v_mfma_f32_16x16x32_bf16 v[92:95], v[146:149], v[214:217], v[92:95]
	v_mfma_f32_16x16x32_bf16 v[64:67], v[154:157], v[214:217], v[64:67]
	v_mfma_f32_16x16x32_bf16 v[80:83], v[146:149], v[224:227], v[80:83]
	v_mfma_f32_16x16x32_bf16 v[56:59], v[154:157], v[224:227], v[56:59]
	v_mfma_f32_16x16x32_bf16 v[44:47], v[158:161], v[194:197], v[44:47]
	v_mfma_f32_16x16x32_bf16 v[12:15], v[166:169], v[194:197], v[12:15]
	v_mfma_f32_16x16x32_bf16 v[36:39], v[158:161], v[202:205], v[36:39]
	v_mfma_f32_16x16x32_bf16 v[8:11], v[166:169], v[202:205], v[8:11]
	v_mfma_f32_16x16x32_bf16 v[28:31], v[158:161], v[210:213], v[28:31]
	v_mfma_f32_16x16x32_bf16 v[4:7], v[166:169], v[210:213], v[4:7]
	v_mfma_f32_16x16x32_bf16 v[20:23], v[158:161], v[218:221], v[20:23]
	v_mfma_f32_16x16x32_bf16 v[0:3], v[166:169], v[218:221], v[0:3]
	v_mfma_f32_16x16x32_bf16 v[44:47], v[162:165], v[198:201], v[44:47]
	v_mfma_f32_16x16x32_bf16 v[12:15], v[190:193], v[198:201], v[12:15]
	v_mfma_f32_16x16x32_bf16 v[36:39], v[162:165], v[206:209], v[36:39]
	v_mfma_f32_16x16x32_bf16 v[8:11], v[190:193], v[206:209], v[8:11]
	v_mfma_f32_16x16x32_bf16 v[28:31], v[162:165], v[214:217], v[28:31]
	v_mfma_f32_16x16x32_bf16 v[4:7], v[190:193], v[214:217], v[4:7]
	v_mfma_f32_16x16x32_bf16 v[20:23], v[162:165], v[224:227], v[20:23]
	v_mfma_f32_16x16x32_bf16 v[0:3], v[190:193], v[224:227], v[0:3]
	s_setprio 0
	s_barrier
	s_add_i32 s89, s89, 2
	s_add_u32 s57, s57, 0x100
	s_addc_u32 s88, s88, 0
	s_mov_b64 s[58:59], s[60:61]
; #define PG8_STAGE(bufoff, gbase, voff) do { _Pragma("unroll") for (int _i = 0; _i < 2; ++_i) \
;         __builtin_amdgcn_global_load_lds((const unsigned*)((const char*)(gbase) + (voff)[_i]), (PG8_LAS unsigned*)(lds + (bufoff) + ldsw + _i * 8192), 16, 0, 0); } while (0)
; #define PG8_LDA(dst, b, h) do { _Pragma("unroll") for (int m = 0; m < 4; ++m) _Pragma("unroll") for (int k = 0; k < 2; ++k) dst[m][k] = *(const PG8_LAS bf16x8*)(lds + PG8_SA(b, h) + aoff + m * 2048 + k * 1024); } while (0)
; #define PG8_LDB(dst, b, h) do { _Pragma("unroll") for (int n = 0; n < 2; ++n) _Pragma("unroll") for (int k = 0; k < 2; ++k) dst[n][k] = *(const PG8_LAS bf16x8*)(lds + PG8_SB(b, h) + boff + n * 2048 + k * 1024); } while (0)
; #define PG8_MMA(ai, bj, At, Bt) do { __builtin_amdgcn_s_setprio(1); _Pragma("unroll") for (int m = 0; m < 4; ++m) _Pragma("unroll") for (int n = 0; n < 2; ++n) _Pragma("unroll") for (int k = 0; k < 2; ++k) \
;         acc[ai][bj][m][n] = __builtin_amdgcn_mfma_f32_16x16x32_bf16(Bt[n][k], At[m][k], acc[ai][bj][m][n], 0, 0, 0); __builtin_amdgcn_s_setprio(0); } while (0)
; #define PG8_WAIT_V(n) asm volatile("s_waitcnt vmcnt(" #n ")" ::: "memory")
; #define PG8_BAR __builtin_amdgcn_s_barrier()
; template <class Epi, class Sched, bool ALIGN_EPI = false, bool SP2 = false>
; __device__ __forceinline__ void gemm_phase(PG8_LAS unsigned char* lds, const Gemm g, const Sched& S, const Epi& E) {
;     ...
;         for (int t = 0; t < nt; t += 2) {
;             const bool last = (t == nt - 2);
;             const char* a1 = cA + (size_t)(t + 1) * kstep;
;             const char* a2 = last ? nA : cA + (size_t)(t + 2) * kstep; const char* b2 = last ? nB : cB + (size_t)(t + 2) * kstep;
;             const char* a3 = a2 + kstep; const char* b3 = b2 + kstep;
;             if (last && has_next) S.a_ready(nxt);
;             if constexpr (SP2) {
;             PG8_LDB(B0, 0, 0); PG8_LDB(B1, 0, 1); PG8_SCHED; PG8_LDA(At, 0, 0); PG8_STAGE(PG8_SA(1, 1), a1 + hstep, voffA);
;             PG8_WAIT_V(8); PG8_WAIT_L(0); PG8_BAR; PG8_MMA(0, 0, At, B0); PG8_MMA(0, 1, At, B1); PG8_BAR; PG8_SCHED;
;             PG8_LDA(At, 0, 1); PG8_STAGE(PG8_SB(0, 0), b2, voffB); PG8_STAGE(PG8_SB(0, 1), b2 + hstep, voffB); PG8_STAGE(PG8_SA(0, 0), a2, voffA);
;             PG8_WAIT_V(8); PG8_WAIT_L(0); PG8_BAR; PG8_MMA(1, 0, At, B0); PG8_MMA(1, 1, At, B1); PG8_BAR; PG8_SCHED;
.LBB0_873:
	ds_read_b128 v[142:145], v174
	ds_read_b128 v[146:149], v175
	ds_read_b128 v[150:153], v176
	ds_read_b128 v[154:157], v177
	ds_read_b128 v[158:161], v178
	ds_read_b128 v[162:165], v179
	ds_read_b128 v[166:169], v180
	ds_read_b128 v[190:193], v181
	s_add_u32 s60, s58, 0x100
	s_addc_u32 s61, s59, 0
	s_cmp_eq_u32 s89, 40
	s_cselect_b32 s65, s9, s61
	s_cselect_b32 s64, s8, s60
	s_cselect_b32 s63, s55, s88
	s_cselect_b32 s62, s54, s57
	s_mov_b32 m0, s78
	v_lshl_add_u64 v[170:171], s[58:59], 0, v[134:135]
	ds_read_b128 v[194:197], v172
	ds_read_b128 v[198:201], v172 offset:1024
	ds_read_b128 v[202:205], v172 offset:2048
	ds_read_b128 v[206:209], v172 offset:3072
	ds_read_b128 v[210:213], v172 offset:4096
	ds_read_b128 v[214:217], v172 offset:5120
	ds_read_b128 v[218:221], v172 offset:6144
	ds_read_b128 v[224:227], v172 offset:7168
	global_load_lds_dwordx4 v[170:171], off
	v_lshl_add_u64 v[170:171], s[58:59], 0, v[136:137]
	s_mov_b32 m0, s79
	s_nop 0
	global_load_lds_dwordx4 v[170:171], off
	s_waitcnt vmcnt(8)
	s_waitcnt lgkmcnt(0)
	s_barrier
	s_setprio 1
	v_mfma_f32_16x16x32_bf16 v[124:127], v[142:145], v[194:197], v[124:127]
	v_mfma_f32_16x16x32_bf16 v[108:111], v[150:153], v[194:197], v[108:111]
	v_mfma_f32_16x16x32_bf16 v[120:123], v[142:145], v[202:205], v[120:123]
	v_mfma_f32_16x16x32_bf16 v[96:99], v[150:153], v[202:205], v[96:99]
	v_mfma_f32_16x16x32_bf16 v[116:119], v[142:145], v[210:213], v[116:119]
	v_mfma_f32_16x16x32_bf16 v[88:91], v[150:153], v[210:213], v[88:91]
	v_mfma_f32_16x16x32_bf16 v[112:115], v[142:145], v[218:221], v[112:115]
	v_mfma_f32_16x16x32_bf16 v[84:87], v[150:153], v[218:221], v[84:87]
	v_mfma_f32_16x16x32_bf16 v[124:127], v[146:149], v[198:201], v[124:127]
	v_mfma_f32_16x16x32_bf16 v[108:111], v[154:157], v[198:201], v[108:111]
	v_mfma_f32_16x16x32_bf16 v[120:123], v[146:149], v[206:209], v[120:123]
	v_mfma_f32_16x16x32_bf16 v[96:99], v[154:157], v[206:209], v[96:99]
	v_mfma_f32_16x16x32_bf16 v[116:119], v[146:149], v[214:217], v[116:119]
	v_mfma_f32_16x16x32_bf16 v[88:91], v[154:157], v[214:217], v[88:91]
	v_mfma_f32_16x16x32_bf16 v[112:115], v[146:149], v[224:227], v[112:115]
	v_mfma_f32_16x16x32_bf16 v[84:87], v[154:157], v[224:227], v[84:87]
	v_mfma_f32_16x16x32_bf16 v[68:71], v[158:161], v[194:197], v[68:71]
	v_mfma_f32_16x16x32_bf16 v[40:43], v[166:169], v[194:197], v[40:43]
	v_mfma_f32_16x16x32_bf16 v[60:63], v[158:161], v[202:205], v[60:63]
	v_mfma_f32_16x16x32_bf16 v[32:35], v[166:169], v[202:205], v[32:35]
	v_mfma_f32_16x16x32_bf16 v[52:55], v[158:161], v[210:213], v[52:55]
	v_mfma_f32_16x16x32_bf16 v[24:27], v[166:169], v[210:213], v[24:27]
	v_mfma_f32_16x16x32_bf16 v[48:51], v[158:161], v[218:221], v[48:51]
	v_mfma_f32_16x16x32_bf16 v[16:19], v[166:169], v[218:221], v[16:19]
	v_mfma_f32_16x16x32_bf16 v[68:71], v[162:165], v[198:201], v[68:71]
	v_mfma_f32_16x16x32_bf16 v[40:43], v[190:193], v[198:201], v[40:43]
	v_mfma_f32_16x16x32_bf16 v[60:63], v[162:165], v[206:209], v[60:63]
	v_mfma_f32_16x16x32_bf16 v[32:35], v[190:193], v[206:209], v[32:35]
	v_mfma_f32_16x16x32_bf16 v[52:55], v[162:165], v[214:217], v[52:55]
	v_mfma_f32_16x16x32_bf16 v[24:27], v[190:193], v[214:217], v[24:27]
	v_mfma_f32_16x16x32_bf16 v[48:51], v[162:165], v[224:227], v[48:51]
	v_mfma_f32_16x16x32_bf16 v[16:19], v[190:193], v[224:227], v[16:19]
	s_setprio 0
	s_barrier
	s_mov_b32 m0, s12
	v_lshl_add_u64 v[170:171], s[62:63], 0, v[128:129]
	s_add_u32 s58, s62, 0xb0000
	ds_read_b128 v[194:197], v172 offset:16384
	ds_read_b128 v[198:201], v172 offset:17408
	ds_read_b128 v[202:205], v172 offset:18432
	ds_read_b128 v[206:209], v172 offset:19456
	ds_read_b128 v[210:213], v172 offset:20480
	ds_read_b128 v[214:217], v172 offset:21504
	ds_read_b128 v[218:221], v172 offset:22528
	ds_read_b128 v[224:227], v172 offset:23552
	global_load_lds_dwordx4 v[170:171], off
	v_lshl_add_u64 v[228:229], s[62:63], 0, v[130:131]
	s_mov_b32 m0, s13
	s_addc_u32 s59, s63, 0
	global_load_lds_dwordx4 v[228:229], off
	v_lshl_add_u64 v[230:231], s[58:59], 0, v[128:129]
	s_mov_b32 m0, s14
	v_lshl_add_u64 v[232:233], s[64:65], 0, v[130:131]
	global_load_lds_dwordx4 v[230:231], off
	v_lshl_add_u64 v[230:231], s[58:59], 0, v[130:131]
	s_mov_b32 m0, s15
	s_nop 0
	global_load_lds_dwordx4 v[230:231], off
	v_lshl_add_u64 v[230:231], s[64:65], 0, v[128:129]
	s_mov_b32 m0, s5
	s_nop 0
	global_load_lds_dwordx4 v[230:231], off
	s_mov_b32 m0, s39
	s_nop 0
	global_load_lds_dwordx4 v[232:233], off
	s_waitcnt vmcnt(8)
	s_waitcnt lgkmcnt(0)
	s_barrier
	s_setprio 1
	v_mfma_f32_16x16x32_bf16 v[104:107], v[142:145], v[194:197], v[104:107]
	v_mfma_f32_16x16x32_bf16 v[76:79], v[150:153], v[194:197], v[76:79]
	v_mfma_f32_16x16x32_bf16 v[100:103], v[142:145], v[202:205], v[100:103]
	v_mfma_f32_16x16x32_bf16 v[72:75], v[150:153], v[202:205], v[72:75]
	v_mfma_f32_16x16x32_bf16 v[92:95], v[142:145], v[210:213], v[92:95]
	v_mfma_f32_16x16x32_bf16 v[64:67], v[150:153], v[210:213], v[64:67]
	v_mfma_f32_16x16x32_bf16 v[80:83], v[142:145], v[218:221], v[80:83]
	v_mfma_f32_16x16x32_bf16 v[56:59], v[150:153], v[218:221], v[56:59]
	v_mfma_f32_16x16x32_bf16 v[104:107], v[146:149], v[198:201], v[104:107]
	v_mfma_f32_16x16x32_bf16 v[76:79], v[154:157], v[198:201], v[76:79]
	v_mfma_f32_16x16x32_bf16 v[100:103], v[146:149], v[206:209], v[100:103]
	v_mfma_f32_16x16x32_bf16 v[72:75], v[154:157], v[206:209], v[72:75]
	v_mfma_f32_16x16x32_bf16 v[92:95], v[146:149], v[214:217], v[92:95]
	v_mfma_f32_16x16x32_bf16 v[64:67], v[154:157], v[214:217], v[64:67]
	v_mfma_f32_16x16x32_bf16 v[80:83], v[146:149], v[224:227], v[80:83]
	v_mfma_f32_16x16x32_bf16 v[56:59], v[154:157], v[224:227], v[56:59]
	v_mfma_f32_16x16x32_bf16 v[44:47], v[158:161], v[194:197], v[44:47]
	v_mfma_f32_16x16x32_bf16 v[12:15], v[166:169], v[194:197], v[12:15]
	v_mfma_f32_16x16x32_bf16 v[36:39], v[158:161], v[202:205], v[36:39]
	v_mfma_f32_16x16x32_bf16 v[8:11], v[166:169], v[202:205], v[8:11]
	v_mfma_f32_16x16x32_bf16 v[28:31], v[158:161], v[210:213], v[28:31]
	v_mfma_f32_16x16x32_bf16 v[4:7], v[166:169], v[210:213], v[4:7]
	v_mfma_f32_16x16x32_bf16 v[20:23], v[158:161], v[218:221], v[20:23]
	v_mfma_f32_16x16x32_bf16 v[0:3], v[166:169], v[218:221], v[0:3]
	v_mfma_f32_16x16x32_bf16 v[44:47], v[162:165], v[198:201], v[44:47]
	v_mfma_f32_16x16x32_bf16 v[12:15], v[190:193], v[198:201], v[12:15]
	v_mfma_f32_16x16x32_bf16 v[36:39], v[162:165], v[206:209], v[36:39]
	v_mfma_f32_16x16x32_bf16 v[8:11], v[190:193], v[206:209], v[8:11]
	v_mfma_f32_16x16x32_bf16 v[28:31], v[162:165], v[214:217], v[28:31]
	v_mfma_f32_16x16x32_bf16 v[4:7], v[190:193], v[214:217], v[4:7]
	v_mfma_f32_16x16x32_bf16 v[20:23], v[162:165], v[224:227], v[20:23]
	v_mfma_f32_16x16x32_bf16 v[0:3], v[190:193], v[224:227], v[0:3]
	s_setprio 0
	s_barrier
; #define PG8_STAGE(bufoff, gbase, voff) do { _Pragma("unroll") for (int _i = 0; _i < 2; ++_i) \
;         __builtin_amdgcn_global_load_lds((const unsigned*)((const char*)(gbase) + (voff)[_i]), (PG8_LAS unsigned*)(lds + (bufoff) + ldsw + _i * 8192), 16, 0, 0); } while (0)
; #define PG8_LDA(dst, b, h) do { _Pragma("unroll") for (int m = 0; m < 4; ++m) _Pragma("unroll") for (int k = 0; k < 2; ++k) dst[m][k] = *(const PG8_LAS bf16x8*)(lds + PG8_SA(b, h) + aoff + m * 2048 + k * 1024); } while (0)
; #define PG8_LDB(dst, b, h) do { _Pragma("unroll") for (int n = 0; n < 2; ++n) _Pragma("unroll") for (int k = 0; k < 2; ++k) dst[n][k] = *(const PG8_LAS bf16x8*)(lds + PG8_SB(b, h) + boff + n * 2048 + k * 1024); } while (0)
; #define PG8_MMA(ai, bj, At, Bt) do { __builtin_amdgcn_s_setprio(1); _Pragma("unroll") for (int m = 0; m < 4; ++m) _Pragma("unroll") for (int n = 0; n < 2; ++n) _Pragma("unroll") for (int k = 0; k < 2; ++k) \
;         acc[ai][bj][m][n] = __builtin_amdgcn_mfma_f32_16x16x32_bf16(Bt[n][k], At[m][k], acc[ai][bj][m][n], 0, 0, 0); __builtin_amdgcn_s_setprio(0); } while (0)
; #define PG8_WAIT_V(n) asm volatile("s_waitcnt vmcnt(" #n ")" ::: "memory")
; #define PG8_WAIT_L(n) asm volatile("s_waitcnt lgkmcnt(" #n ")" ::: "memory")
; #define PG8_BAR __builtin_amdgcn_s_barrier()
; #define PG8_SCHED __builtin_amdgcn_sched_barrier(0)
; template <class Epi, class Sched, bool ALIGN_EPI = false, bool SP2 = false>
; __device__ __forceinline__ void gemm_phase(PG8_LAS unsigned char* lds, const Gemm g, const Sched& S, const Epi& E) {
;     ...
;         for (int t = 0; t < nt; t += 2) {
;     ...
;             PG8_LDB(B0, 1, 0); PG8_LDB(B1, 1, 1); PG8_SCHED; PG8_LDA(At, 1, 0); PG8_STAGE(PG8_SA(0, 1), a2 + hstep, voffA);
;             PG8_WAIT_V(8); PG8_WAIT_L(0); PG8_BAR; PG8_MMA(0, 0, At, B0); PG8_MMA(0, 1, At, B1); PG8_BAR; PG8_SCHED;
;             PG8_LDA(At, 1, 1); PG8_STAGE(PG8_SB(1, 0), b3, voffB); PG8_STAGE(PG8_SB(1, 1), b3 + hstep, voffB); PG8_STAGE(PG8_SA(1, 0), a3, voffA);
;             PG8_WAIT_V(8); PG8_WAIT_L(0); PG8_BAR; PG8_MMA(1, 0, At, B0); PG8_MMA(1, 1, At, B1); PG8_BAR; PG8_SCHED;
	ds_read_b128 v[142:145], v182
	ds_read_b128 v[146:149], v183
	ds_read_b128 v[150:153], v184
	ds_read_b128 v[154:157], v185
	ds_read_b128 v[158:161], v186
	ds_read_b128 v[162:165], v187
	ds_read_b128 v[166:169], v188
	ds_read_b128 v[190:193], v189
	s_add_u32 s58, s64, 0xb0000
	s_addc_u32 s59, s65, 0
	s_mov_b32 m0, s43
	v_lshl_add_u64 v[234:235], s[58:59], 0, v[128:129]
	ds_read_b128 v[194:197], v172 offset:32768
	ds_read_b128 v[198:201], v172 offset:33792
	ds_read_b128 v[202:205], v172 offset:34816
	ds_read_b128 v[206:209], v172 offset:35840
	ds_read_b128 v[210:213], v172 offset:36864
	ds_read_b128 v[214:217], v172 offset:37888
	ds_read_b128 v[218:221], v172 offset:38912
	ds_read_b128 v[224:227], v172 offset:39936
	global_load_lds_dwordx4 v[234:235], off
	v_lshl_add_u64 v[234:235], s[58:59], 0, v[130:131]
	s_mov_b32 m0, s66
	s_nop 0
	global_load_lds_dwordx4 v[234:235], off
	s_waitcnt vmcnt(8)
	s_waitcnt lgkmcnt(0)
	s_barrier
	s_setprio 1
	v_mfma_f32_16x16x32_bf16 v[124:127], v[142:145], v[194:197], v[124:127]
	v_mfma_f32_16x16x32_bf16 v[108:111], v[150:153], v[194:197], v[108:111]
	v_mfma_f32_16x16x32_bf16 v[120:123], v[142:145], v[202:205], v[120:123]
	v_mfma_f32_16x16x32_bf16 v[96:99], v[150:153], v[202:205], v[96:99]
	v_mfma_f32_16x16x32_bf16 v[116:119], v[142:145], v[210:213], v[116:119]
	v_mfma_f32_16x16x32_bf16 v[88:91], v[150:153], v[210:213], v[88:91]
	v_mfma_f32_16x16x32_bf16 v[112:115], v[142:145], v[218:221], v[112:115]
	v_mfma_f32_16x16x32_bf16 v[84:87], v[150:153], v[218:221], v[84:87]
	v_mfma_f32_16x16x32_bf16 v[124:127], v[146:149], v[198:201], v[124:127]
	v_mfma_f32_16x16x32_bf16 v[108:111], v[154:157], v[198:201], v[108:111]
	v_mfma_f32_16x16x32_bf16 v[120:123], v[146:149], v[206:209], v[120:123]
	v_mfma_f32_16x16x32_bf16 v[96:99], v[154:157], v[206:209], v[96:99]
	v_mfma_f32_16x16x32_bf16 v[116:119], v[146:149], v[214:217], v[116:119]
	v_mfma_f32_16x16x32_bf16 v[88:91], v[154:157], v[214:217], v[88:91]
	v_mfma_f32_16x16x32_bf16 v[112:115], v[146:149], v[224:227], v[112:115]
	v_mfma_f32_16x16x32_bf16 v[84:87], v[154:157], v[224:227], v[84:87]
	v_mfma_f32_16x16x32_bf16 v[68:71], v[158:161], v[194:197], v[68:71]
	v_mfma_f32_16x16x32_bf16 v[40:43], v[166:169], v[194:197], v[40:43]
	v_mfma_f32_16x16x32_bf16 v[60:63], v[158:161], v[202:205], v[60:63]
	v_mfma_f32_16x16x32_bf16 v[32:35], v[166:169], v[202:205], v[32:35]
	v_mfma_f32_16x16x32_bf16 v[52:55], v[158:161], v[210:213], v[52:55]
	v_mfma_f32_16x16x32_bf16 v[24:27], v[166:169], v[210:213], v[24:27]
	v_mfma_f32_16x16x32_bf16 v[48:51], v[158:161], v[218:221], v[48:51]
	v_mfma_f32_16x16x32_bf16 v[16:19], v[166:169], v[218:221], v[16:19]
	v_mfma_f32_16x16x32_bf16 v[68:71], v[162:165], v[198:201], v[68:71]
	v_mfma_f32_16x16x32_bf16 v[40:43], v[190:193], v[198:201], v[40:43]
	v_mfma_f32_16x16x32_bf16 v[60:63], v[162:165], v[206:209], v[60:63]
	v_mfma_f32_16x16x32_bf16 v[32:35], v[190:193], v[206:209], v[32:35]
	v_mfma_f32_16x16x32_bf16 v[52:55], v[162:165], v[214:217], v[52:55]
	v_mfma_f32_16x16x32_bf16 v[24:27], v[190:193], v[214:217], v[24:27]
	v_mfma_f32_16x16x32_bf16 v[48:51], v[162:165], v[224:227], v[48:51]
	v_mfma_f32_16x16x32_bf16 v[16:19], v[190:193], v[224:227], v[16:19]
	s_setprio 0
	s_barrier
	s_mov_b32 m0, s70
	v_lshl_add_u64 v[170:171], v[170:171], 0, s[40:41]
	s_add_u32 s58, s62, 0xb0080
	ds_read_b128 v[194:197], v172 offset:49152
	ds_read_b128 v[198:201], v172 offset:50176
	ds_read_b128 v[202:205], v172 offset:51200
	ds_read_b128 v[206:209], v172 offset:52224
	ds_read_b128 v[210:213], v172 offset:53248
	ds_read_b128 v[214:217], v172 offset:54272
	ds_read_b128 v[218:221], v172 offset:55296
	ds_read_b128 v[224:227], v172 offset:56320
	global_load_lds_dwordx4 v[170:171], off
	v_lshl_add_u64 v[170:171], v[228:229], 0, s[40:41]
	s_mov_b32 m0, s71
	s_addc_u32 s59, s63, 0
	global_load_lds_dwordx4 v[170:171], off
	v_lshl_add_u64 v[170:171], s[58:59], 0, v[128:129]
	s_mov_b32 m0, s74
	s_nop 0
	global_load_lds_dwordx4 v[170:171], off
	v_lshl_add_u64 v[170:171], s[58:59], 0, v[130:131]
	s_mov_b32 m0, s75
	s_nop 0
	global_load_lds_dwordx4 v[170:171], off
	v_lshl_add_u64 v[170:171], v[230:231], 0, s[40:41]
	s_mov_b32 m0, s72
	s_nop 0
	global_load_lds_dwordx4 v[170:171], off
	v_lshl_add_u64 v[170:171], v[232:233], 0, s[40:41]
	s_mov_b32 m0, s73
	s_nop 0
	global_load_lds_dwordx4 v[170:171], off
	s_waitcnt vmcnt(8)
	s_waitcnt lgkmcnt(0)
	s_barrier
	s_setprio 1
	v_mfma_f32_16x16x32_bf16 v[104:107], v[142:145], v[194:197], v[104:107]
	v_mfma_f32_16x16x32_bf16 v[76:79], v[150:153], v[194:197], v[76:79]
	v_mfma_f32_16x16x32_bf16 v[100:103], v[142:145], v[202:205], v[100:103]
	v_mfma_f32_16x16x32_bf16 v[72:75], v[150:153], v[202:205], v[72:75]
	v_mfma_f32_16x16x32_bf16 v[92:95], v[142:145], v[210:213], v[92:95]
	v_mfma_f32_16x16x32_bf16 v[64:67], v[150:153], v[210:213], v[64:67]
	v_mfma_f32_16x16x32_bf16 v[80:83], v[142:145], v[218:221], v[80:83]
	v_mfma_f32_16x16x32_bf16 v[56:59], v[150:153], v[218:221], v[56:59]
	v_mfma_f32_16x16x32_bf16 v[104:107], v[146:149], v[198:201], v[104:107]
	v_mfma_f32_16x16x32_bf16 v[76:79], v[154:157], v[198:201], v[76:79]
	v_mfma_f32_16x16x32_bf16 v[100:103], v[146:149], v[206:209], v[100:103]
	v_mfma_f32_16x16x32_bf16 v[72:75], v[154:157], v[206:209], v[72:75]
	v_mfma_f32_16x16x32_bf16 v[92:95], v[146:149], v[214:217], v[92:95]
	v_mfma_f32_16x16x32_bf16 v[64:67], v[154:157], v[214:217], v[64:67]
	v_mfma_f32_16x16x32_bf16 v[80:83], v[146:149], v[224:227], v[80:83]
	v_mfma_f32_16x16x32_bf16 v[56:59], v[154:157], v[224:227], v[56:59]
	v_mfma_f32_16x16x32_bf16 v[44:47], v[158:161], v[194:197], v[44:47]
	v_mfma_f32_16x16x32_bf16 v[12:15], v[166:169], v[194:197], v[12:15]
	v_mfma_f32_16x16x32_bf16 v[36:39], v[158:161], v[202:205], v[36:39]
	v_mfma_f32_16x16x32_bf16 v[8:11], v[166:169], v[202:205], v[8:11]
	v_mfma_f32_16x16x32_bf16 v[28:31], v[158:161], v[210:213], v[28:31]
	v_mfma_f32_16x16x32_bf16 v[4:7], v[166:169], v[210:213], v[4:7]
	v_mfma_f32_16x16x32_bf16 v[20:23], v[158:161], v[218:221], v[20:23]
	v_mfma_f32_16x16x32_bf16 v[0:3], v[166:169], v[218:221], v[0:3]
	v_mfma_f32_16x16x32_bf16 v[44:47], v[162:165], v[198:201], v[44:47]
	v_mfma_f32_16x16x32_bf16 v[12:15], v[190:193], v[198:201], v[12:15]
	v_mfma_f32_16x16x32_bf16 v[36:39], v[162:165], v[206:209], v[36:39]
	v_mfma_f32_16x16x32_bf16 v[8:11], v[190:193], v[206:209], v[8:11]
	v_mfma_f32_16x16x32_bf16 v[28:31], v[162:165], v[214:217], v[28:31]
	v_mfma_f32_16x16x32_bf16 v[4:7], v[190:193], v[214:217], v[4:7]
	v_mfma_f32_16x16x32_bf16 v[20:23], v[162:165], v[224:227], v[20:23]
	v_mfma_f32_16x16x32_bf16 v[0:3], v[190:193], v[224:227], v[0:3]
	s_setprio 0
	s_barrier
	s_add_i32 s89, s89, 2
	s_add_u32 s57, s57, 0x100
	s_addc_u32 s88, s88, 0
	s_cmp_gt_u32 s89, 41
	s_mov_b64 s[58:59], s[60:61]
	s_cbranch_scc0 .LBB0_873
	s_and_b64 vcc, exec, s[52:53]
	s_cbranch_vccz .LBB0_876
	s_barrier

;     __host__ __device__ bool next(int i, Unit& u) const { const int L = i * G + c; if (L >= 16 * nkc) return false; u.kc = L % nkc; const int t = L / nkc; u.pn = t & 3; u.pm = 33 * (t >> 2); return true; }
; #define PG8_STAGE(bufoff, gbase, voff) do { _Pragma("unroll") for (int _i = 0; _i < 2; ++_i) \
;         __builtin_amdgcn_global_load_lds((const unsigned*)((const char*)(gbase) + (voff)[_i]), (PG8_LAS unsigned*)(lds + (bufoff) + ldsw + _i * 8192), 16, 0, 0); } while (0)
; #define PG8_LDA(dst, b, h) do { _Pragma("unroll") for (int m = 0; m < 4; ++m) _Pragma("unroll") for (int k = 0; k < 2; ++k) dst[m][k] = *(const PG8_LAS bf16x8*)(lds + PG8_SA(b, h) + aoff + m * 2048 + k * 1024); } while (0)
; #define PG8_LDB(dst, b, h) do { _Pragma("unroll") for (int n = 0; n < 2; ++n) _Pragma("unroll") for (int k = 0; k < 2; ++k) dst[n][k] = *(const PG8_LAS bf16x8*)(lds + PG8_SB(b, h) + boff + n * 2048 + k * 1024); } while (0)
; #define PG8_BAR __builtin_amdgcn_s_barrier()
; template <class Epi, class Sched, bool ALIGN_EPI = false, bool SP2 = false>
; __device__ __forceinline__ void gemm_phase(PG8_LAS unsigned char* lds, const Gemm g, const Sched& S, const Epi& E) {
;     ...
;         const bool has_next = S.next(ui + 1, nxt);
;         const char* nA = has_next ? (const char*)g.A + (size_t)nxt.pm * tstep + (size_t)nxt.kc * cstep : cA; const char* nB = has_next ? (const char*)g.Bt + (size_t)nxt.pn * tstep + (size_t)nxt.kc * cstep : cB;
;         for (int t = 0; t < nt; t += 2) {
;             const bool last = (t == nt - 2);
;             const char* a1 = cA + (size_t)(t + 1) * kstep;
;             const char* a2 = last ? nA : cA + (size_t)(t + 2) * kstep; const char* b2 = last ? nB : cB + (size_t)(t + 2) * kstep;
;             const char* a3 = a2 + kstep; const char* b3 = b2 + kstep;
;             if (last && has_next) S.a_ready(nxt);
;             if constexpr (SP2) {
;             PG8_LDB(B0, 0, 0); PG8_LDB(B1, 0, 1); PG8_SCHED; PG8_LDA(At, 0, 0); PG8_STAGE(PG8_SA(1, 1), a1 + hstep, voffA);
;             PG8_WAIT_V(8); PG8_WAIT_L(0); PG8_BAR; PG8_MMA(0, 0, At, B0); PG8_MMA(0, 1, At, B1); PG8_BAR; PG8_SCHED;
;             PG8_LDA(At, 0, 1); PG8_STAGE(PG8_SB(0, 0), b2, voffB); PG8_STAGE(PG8_SB(0, 1), b2 + hstep, voffB); PG8_STAGE(PG8_SA(0, 0), a2, voffA);
;             PG8_WAIT_V(8); PG8_WAIT_L(0); PG8_BAR; PG8_MMA(1, 0, At, B0); PG8_MMA(1, 1, At, B1); PG8_BAR; PG8_SCHED;
.LBB0_895:
	s_add_u32 s33, s64, 0x100
	s_addc_u32 s55, s65, 0
	s_mov_b32 s57, 0
	ds_read_b128 v[156:159], v140
	ds_read_b128 v[160:163], v141
	ds_read_b128 v[164:167], v142
	ds_read_b128 v[168:171], v143
	ds_read_b128 v[172:175], v144
	ds_read_b128 v[176:179], v145
	ds_read_b128 v[180:183], v146
	ds_read_b128 v[184:187], v147
	s_add_i32 s86, s57, 2
	s_add_u32 s64, s62, 0x100
	s_addc_u32 s65, s63, 0
	s_cmp_eq_u32 s78, s57
	s_cselect_b32 s69, s59, s65
	s_cselect_b32 s68, s58, s64
	s_cselect_b32 s67, s61, s55
	s_cselect_b32 s66, s60, s33
	s_mov_b32 m0, s79
	v_lshl_add_u64 v[220:221], s[62:63], 0, v[134:135]
	ds_read_b128 v[188:191], v138
	ds_read_b128 v[192:195], v138 offset:1024
	ds_read_b128 v[196:199], v138 offset:2048
	ds_read_b128 v[200:203], v138 offset:3072
	ds_read_b128 v[204:207], v138 offset:4096
	ds_read_b128 v[208:211], v138 offset:5120
	ds_read_b128 v[212:215], v138 offset:6144
	ds_read_b128 v[216:219], v138 offset:7168
	global_load_lds_dwordx4 v[220:221], off
	v_lshl_add_u64 v[220:221], s[62:63], 0, v[136:137]
	s_mov_b32 m0, s80
	s_nop 0
	global_load_lds_dwordx4 v[220:221], off
	s_waitcnt vmcnt(8)
	s_waitcnt lgkmcnt(0)
	s_barrier
	s_setprio 1
	v_mfma_f32_16x16x32_bf16 v[124:127], v[156:159], v[188:191], 0
	v_mfma_f32_16x16x32_bf16 v[120:123], v[164:167], v[188:191], 0
	v_mfma_f32_16x16x32_bf16 v[108:111], v[156:159], v[196:199], 0
	v_mfma_f32_16x16x32_bf16 v[104:107], v[164:167], v[196:199], 0
	v_mfma_f32_16x16x32_bf16 v[92:95], v[156:159], v[204:207], 0
	v_mfma_f32_16x16x32_bf16 v[88:91], v[164:167], v[204:207], 0
	v_mfma_f32_16x16x32_bf16 v[76:79], v[156:159], v[212:215], 0
	v_mfma_f32_16x16x32_bf16 v[72:75], v[164:167], v[212:215], 0
	v_mfma_f32_16x16x32_bf16 v[124:127], v[160:163], v[192:195], v[124:127]
	v_mfma_f32_16x16x32_bf16 v[120:123], v[168:171], v[192:195], v[120:123]
	v_mfma_f32_16x16x32_bf16 v[108:111], v[160:163], v[200:203], v[108:111]
	v_mfma_f32_16x16x32_bf16 v[104:107], v[168:171], v[200:203], v[104:107]
	v_mfma_f32_16x16x32_bf16 v[92:95], v[160:163], v[208:211], v[92:95]
	v_mfma_f32_16x16x32_bf16 v[88:91], v[168:171], v[208:211], v[88:91]
	v_mfma_f32_16x16x32_bf16 v[76:79], v[160:163], v[216:219], v[76:79]
	v_mfma_f32_16x16x32_bf16 v[72:75], v[168:171], v[216:219], v[72:75]
	v_mfma_f32_16x16x32_bf16 v[116:119], v[172:175], v[188:191], 0
	v_mfma_f32_16x16x32_bf16 v[112:115], v[180:183], v[188:191], 0
	v_mfma_f32_16x16x32_bf16 v[100:103], v[172:175], v[196:199], 0
	v_mfma_f32_16x16x32_bf16 v[96:99], v[180:183], v[196:199], 0
	v_mfma_f32_16x16x32_bf16 v[84:87], v[172:175], v[204:207], 0
	v_mfma_f32_16x16x32_bf16 v[80:83], v[180:183], v[204:207], 0
	v_mfma_f32_16x16x32_bf16 v[68:71], v[172:175], v[212:215], 0
	v_mfma_f32_16x16x32_bf16 v[64:67], v[180:183], v[212:215], 0
	v_mfma_f32_16x16x32_bf16 v[116:119], v[176:179], v[192:195], v[116:119]
	v_mfma_f32_16x16x32_bf16 v[112:115], v[184:187], v[192:195], v[112:115]
	v_mfma_f32_16x16x32_bf16 v[100:103], v[176:179], v[200:203], v[100:103]
	v_mfma_f32_16x16x32_bf16 v[96:99], v[184:187], v[200:203], v[96:99]
	v_mfma_f32_16x16x32_bf16 v[84:87], v[176:179], v[208:211], v[84:87]
	v_mfma_f32_16x16x32_bf16 v[80:83], v[184:187], v[208:211], v[80:83]
	v_mfma_f32_16x16x32_bf16 v[68:71], v[176:179], v[216:219], v[68:71]
	v_mfma_f32_16x16x32_bf16 v[64:67], v[184:187], v[216:219], v[64:67]
	s_setprio 0
	s_barrier
	s_mov_b32 m0, s12
	v_lshl_add_u64 v[220:221], s[66:67], 0, v[130:131]
	s_add_u32 s62, s66, 0xb0000
	ds_read_b128 v[188:191], v138 offset:16384
	ds_read_b128 v[192:195], v138 offset:17408
	ds_read_b128 v[196:199], v138 offset:18432
	ds_read_b128 v[200:203], v138 offset:19456
	ds_read_b128 v[204:207], v138 offset:20480
	ds_read_b128 v[208:211], v138 offset:21504
	ds_read_b128 v[212:215], v138 offset:22528
	ds_read_b128 v[216:219], v138 offset:23552
	global_load_lds_dwordx4 v[220:221], off
	v_lshl_add_u64 v[224:225], s[66:67], 0, v[128:129]
	s_mov_b32 m0, s13
	s_addc_u32 s63, s67, 0
	global_load_lds_dwordx4 v[224:225], off
	v_lshl_add_u64 v[226:227], s[62:63], 0, v[130:131]
	s_mov_b32 m0, s14
	v_lshl_add_u64 v[228:229], s[68:69], 0, v[128:129]
	global_load_lds_dwordx4 v[226:227], off
	v_lshl_add_u64 v[226:227], s[62:63], 0, v[128:129]
	s_mov_b32 m0, s15
	s_nop 0
	global_load_lds_dwordx4 v[226:227], off
	v_lshl_add_u64 v[226:227], s[68:69], 0, v[130:131]
	s_mov_b32 m0, s5
	s_nop 0
	global_load_lds_dwordx4 v[226:227], off
	s_mov_b32 m0, s39
	s_nop 0
	global_load_lds_dwordx4 v[228:229], off
	s_waitcnt vmcnt(8)
	s_waitcnt lgkmcnt(0)
	s_barrier
	s_setprio 1
	v_mfma_f32_16x16x32_bf16 v[60:63], v[156:159], v[188:191], 0
	v_mfma_f32_16x16x32_bf16 v[56:59], v[164:167], v[188:191], 0
	v_mfma_f32_16x16x32_bf16 v[44:47], v[156:159], v[196:199], 0
	v_mfma_f32_16x16x32_bf16 v[40:43], v[164:167], v[196:199], 0
	v_mfma_f32_16x16x32_bf16 v[28:31], v[156:159], v[204:207], 0
	v_mfma_f32_16x16x32_bf16 v[24:27], v[164:167], v[204:207], 0
	v_mfma_f32_16x16x32_bf16 v[12:15], v[156:159], v[212:215], 0
	v_mfma_f32_16x16x32_bf16 v[8:11], v[164:167], v[212:215], 0
	v_mfma_f32_16x16x32_bf16 v[60:63], v[160:163], v[192:195], v[60:63]
	v_mfma_f32_16x16x32_bf16 v[56:59], v[168:171], v[192:195], v[56:59]
	v_mfma_f32_16x16x32_bf16 v[44:47], v[160:163], v[200:203], v[44:47]
	v_mfma_f32_16x16x32_bf16 v[40:43], v[168:171], v[200:203], v[40:43]
	v_mfma_f32_16x16x32_bf16 v[28:31], v[160:163], v[208:211], v[28:31]
	v_mfma_f32_16x16x32_bf16 v[24:27], v[168:171], v[208:211], v[24:27]
	v_mfma_f32_16x16x32_bf16 v[12:15], v[160:163], v[216:219], v[12:15]
	v_mfma_f32_16x16x32_bf16 v[8:11], v[168:171], v[216:219], v[8:11]
	v_mfma_f32_16x16x32_bf16 v[52:55], v[172:175], v[188:191], 0
	v_mfma_f32_16x16x32_bf16 v[48:51], v[180:183], v[188:191], 0
	v_mfma_f32_16x16x32_bf16 v[36:39], v[172:175], v[196:199], 0
	v_mfma_f32_16x16x32_bf16 v[32:35], v[180:183], v[196:199], 0
	v_mfma_f32_16x16x32_bf16 v[20:23], v[172:175], v[204:207], 0
	v_mfma_f32_16x16x32_bf16 v[16:19], v[180:183], v[204:207], 0
	v_mfma_f32_16x16x32_bf16 v[4:7], v[172:175], v[212:215], 0
	v_mfma_f32_16x16x32_bf16 v[0:3], v[180:183], v[212:215], 0
	v_mfma_f32_16x16x32_bf16 v[52:55], v[176:179], v[192:195], v[52:55]
	v_mfma_f32_16x16x32_bf16 v[48:51], v[184:187], v[192:195], v[48:51]
	v_mfma_f32_16x16x32_bf16 v[36:39], v[176:179], v[200:203], v[36:39]
	v_mfma_f32_16x16x32_bf16 v[32:35], v[184:187], v[200:203], v[32:35]
	v_mfma_f32_16x16x32_bf16 v[20:23], v[176:179], v[208:211], v[20:23]
	v_mfma_f32_16x16x32_bf16 v[16:19], v[184:187], v[208:211], v[16:19]
	v_mfma_f32_16x16x32_bf16 v[4:7], v[176:179], v[216:219], v[4:7]
	v_mfma_f32_16x16x32_bf16 v[0:3], v[184:187], v[216:219], v[0:3]
	s_setprio 0
	s_barrier
; #define PG8_STAGE(bufoff, gbase, voff) do { _Pragma("unroll") for (int _i = 0; _i < 2; ++_i) \
;         __builtin_amdgcn_global_load_lds((const unsigned*)((const char*)(gbase) + (voff)[_i]), (PG8_LAS unsigned*)(lds + (bufoff) + ldsw + _i * 8192), 16, 0, 0); } while (0)
; #define PG8_LDA(dst, b, h) do { _Pragma("unroll") for (int m = 0; m < 4; ++m) _Pragma("unroll") for (int k = 0; k < 2; ++k) dst[m][k] = *(const PG8_LAS bf16x8*)(lds + PG8_SA(b, h) + aoff + m * 2048 + k * 1024); } while (0)
; #define PG8_LDB(dst, b, h) do { _Pragma("unroll") for (int n = 0; n < 2; ++n) _Pragma("unroll") for (int k = 0; k < 2; ++k) dst[n][k] = *(const PG8_LAS bf16x8*)(lds + PG8_SB(b, h) + boff + n * 2048 + k * 1024); } while (0)
; #define PG8_MMA(ai, bj, At, Bt) do { __builtin_amdgcn_s_setprio(1); _Pragma("unroll") for (int m = 0; m < 4; ++m) _Pragma("unroll") for (int n = 0; n < 2; ++n) _Pragma("unroll") for (int k = 0; k < 2; ++k) \
;         acc[ai][bj][m][n] = __builtin_amdgcn_mfma_f32_16x16x32_bf16(Bt[n][k], At[m][k], acc[ai][bj][m][n], 0, 0, 0); __builtin_amdgcn_s_setprio(0); } while (0)
; #define PG8_WAIT_V(n) asm volatile("s_waitcnt vmcnt(" #n ")" ::: "memory")
; #define PG8_WAIT_L(n) asm volatile("s_waitcnt lgkmcnt(" #n ")" ::: "memory")
; #define PG8_BAR __builtin_amdgcn_s_barrier()
; #define PG8_SCHED __builtin_amdgcn_sched_barrier(0)
; template <class Epi, class Sched, bool ALIGN_EPI = false, bool SP2 = false>
; __device__ __forceinline__ void gemm_phase(PG8_LAS unsigned char* lds, const Gemm g, const Sched& S, const Epi& E) {
;     ...
;             PG8_LDB(B0, 1, 0); PG8_LDB(B1, 1, 1); PG8_SCHED; PG8_LDA(At, 1, 0); PG8_STAGE(PG8_SA(0, 1), a2 + hstep, voffA);
;             PG8_WAIT_V(8); PG8_WAIT_L(0); PG8_BAR; PG8_MMA(0, 0, At, B0); PG8_MMA(0, 1, At, B1); PG8_BAR; PG8_SCHED;
;             PG8_LDA(At, 1, 1); PG8_STAGE(PG8_SB(1, 0), b3, voffB); PG8_STAGE(PG8_SB(1, 1), b3 + hstep, voffB); PG8_STAGE(PG8_SA(1, 0), a3, voffA);
;             PG8_WAIT_V(8); PG8_WAIT_L(0); PG8_BAR; PG8_MMA(1, 0, At, B0); PG8_MMA(1, 1, At, B1); PG8_BAR; PG8_SCHED;
	ds_read_b128 v[156:159], v148
	ds_read_b128 v[160:163], v149
	ds_read_b128 v[164:167], v150
	ds_read_b128 v[168:171], v151
	ds_read_b128 v[172:175], v152
	ds_read_b128 v[176:179], v153
	ds_read_b128 v[180:183], v154
	ds_read_b128 v[184:187], v155
	s_add_u32 s62, s68, 0xb0000
	s_addc_u32 s63, s69, 0
	s_mov_b32 m0, s43
	v_lshl_add_u64 v[230:231], s[62:63], 0, v[130:131]
	ds_read_b128 v[188:191], v138 offset:32768
	ds_read_b128 v[192:195], v138 offset:33792
	ds_read_b128 v[196:199], v138 offset:34816
	ds_read_b128 v[200:203], v138 offset:35840
	ds_read_b128 v[204:207], v138 offset:36864
	ds_read_b128 v[208:211], v138 offset:37888
	ds_read_b128 v[212:215], v138 offset:38912
	ds_read_b128 v[216:219], v138 offset:39936
	global_load_lds_dwordx4 v[230:231], off
	v_lshl_add_u64 v[230:231], s[62:63], 0, v[128:129]
	s_mov_b32 m0, s70
	s_nop 0
	global_load_lds_dwordx4 v[230:231], off
	s_waitcnt vmcnt(8)
	s_waitcnt lgkmcnt(0)
	s_barrier
	s_setprio 1
	v_mfma_f32_16x16x32_bf16 v[124:127], v[156:159], v[188:191], v[124:127]
	v_mfma_f32_16x16x32_bf16 v[120:123], v[164:167], v[188:191], v[120:123]
	v_mfma_f32_16x16x32_bf16 v[108:111], v[156:159], v[196:199], v[108:111]
	v_mfma_f32_16x16x32_bf16 v[104:107], v[164:167], v[196:199], v[104:107]
	v_mfma_f32_16x16x32_bf16 v[92:95], v[156:159], v[204:207], v[92:95]
	v_mfma_f32_16x16x32_bf16 v[88:91], v[164:167], v[204:207], v[88:91]
	v_mfma_f32_16x16x32_bf16 v[76:79], v[156:159], v[212:215], v[76:79]
	v_mfma_f32_16x16x32_bf16 v[72:75], v[164:167], v[212:215], v[72:75]
	v_mfma_f32_16x16x32_bf16 v[124:127], v[160:163], v[192:195], v[124:127]
	v_mfma_f32_16x16x32_bf16 v[120:123], v[168:171], v[192:195], v[120:123]
	v_mfma_f32_16x16x32_bf16 v[108:111], v[160:163], v[200:203], v[108:111]
	v_mfma_f32_16x16x32_bf16 v[104:107], v[168:171], v[200:203], v[104:107]
	v_mfma_f32_16x16x32_bf16 v[92:95], v[160:163], v[208:211], v[92:95]
	v_mfma_f32_16x16x32_bf16 v[88:91], v[168:171], v[208:211], v[88:91]
	v_mfma_f32_16x16x32_bf16 v[76:79], v[160:163], v[216:219], v[76:79]
	v_mfma_f32_16x16x32_bf16 v[72:75], v[168:171], v[216:219], v[72:75]
	v_mfma_f32_16x16x32_bf16 v[116:119], v[172:175], v[188:191], v[116:119]
	v_mfma_f32_16x16x32_bf16 v[112:115], v[180:183], v[188:191], v[112:115]
	v_mfma_f32_16x16x32_bf16 v[100:103], v[172:175], v[196:199], v[100:103]
	v_mfma_f32_16x16x32_bf16 v[96:99], v[180:183], v[196:199], v[96:99]
	v_mfma_f32_16x16x32_bf16 v[84:87], v[172:175], v[204:207], v[84:87]
	v_mfma_f32_16x16x32_bf16 v[80:83], v[180:183], v[204:207], v[80:83]
	v_mfma_f32_16x16x32_bf16 v[68:71], v[172:175], v[212:215], v[68:71]
	v_mfma_f32_16x16x32_bf16 v[64:67], v[180:183], v[212:215], v[64:67]
	v_mfma_f32_16x16x32_bf16 v[116:119], v[176:179], v[192:195], v[116:119]
	v_mfma_f32_16x16x32_bf16 v[112:115], v[184:187], v[192:195], v[112:115]
	v_mfma_f32_16x16x32_bf16 v[100:103], v[176:179], v[200:203], v[100:103]
	v_mfma_f32_16x16x32_bf16 v[96:99], v[184:187], v[200:203], v[96:99]
	v_mfma_f32_16x16x32_bf16 v[84:87], v[176:179], v[208:211], v[84:87]
	v_mfma_f32_16x16x32_bf16 v[80:83], v[184:187], v[208:211], v[80:83]
	v_mfma_f32_16x16x32_bf16 v[68:71], v[176:179], v[216:219], v[68:71]
	v_mfma_f32_16x16x32_bf16 v[64:67], v[184:187], v[216:219], v[64:67]
	s_setprio 0
	s_barrier
	s_mov_b32 m0, s72
	v_lshl_add_u64 v[220:221], v[220:221], 0, s[40:41]
	s_add_u32 s62, s66, 0xb0080
	ds_read_b128 v[188:191], v138 offset:49152
	ds_read_b128 v[192:195], v138 offset:50176
	ds_read_b128 v[196:199], v138 offset:51200
	ds_read_b128 v[200:203], v138 offset:52224
	ds_read_b128 v[204:207], v138 offset:53248
	ds_read_b128 v[208:211], v138 offset:54272
	ds_read_b128 v[212:215], v138 offset:55296
	ds_read_b128 v[216:219], v138 offset:56320
	global_load_lds_dwordx4 v[220:221], off
	v_lshl_add_u64 v[220:221], v[224:225], 0, s[40:41]
	s_mov_b32 m0, s73
	s_addc_u32 s63, s67, 0
	global_load_lds_dwordx4 v[220:221], off
	v_lshl_add_u64 v[220:221], s[62:63], 0, v[130:131]
	s_mov_b32 m0, s76
	s_nop 0
	global_load_lds_dwordx4 v[220:221], off
	v_lshl_add_u64 v[220:221], s[62:63], 0, v[128:129]
	s_mov_b32 m0, s77
	s_nop 0
	global_load_lds_dwordx4 v[220:221], off
	v_lshl_add_u64 v[220:221], v[226:227], 0, s[40:41]
	s_mov_b32 m0, s74
	s_nop 0
	global_load_lds_dwordx4 v[220:221], off
	v_lshl_add_u64 v[220:221], v[228:229], 0, s[40:41]
	s_mov_b32 m0, s75
	s_nop 0
	global_load_lds_dwordx4 v[220:221], off
	s_waitcnt vmcnt(8)
	s_waitcnt lgkmcnt(0)
	s_barrier
	s_setprio 1
	v_mfma_f32_16x16x32_bf16 v[60:63], v[156:159], v[188:191], v[60:63]
	v_mfma_f32_16x16x32_bf16 v[56:59], v[164:167], v[188:191], v[56:59]
	v_mfma_f32_16x16x32_bf16 v[44:47], v[156:159], v[196:199], v[44:47]
	v_mfma_f32_16x16x32_bf16 v[40:43], v[164:167], v[196:199], v[40:43]
	v_mfma_f32_16x16x32_bf16 v[28:31], v[156:159], v[204:207], v[28:31]
	v_mfma_f32_16x16x32_bf16 v[24:27], v[164:167], v[204:207], v[24:27]
	v_mfma_f32_16x16x32_bf16 v[12:15], v[156:159], v[212:215], v[12:15]
	v_mfma_f32_16x16x32_bf16 v[8:11], v[164:167], v[212:215], v[8:11]
	v_mfma_f32_16x16x32_bf16 v[60:63], v[160:163], v[192:195], v[60:63]
	v_mfma_f32_16x16x32_bf16 v[56:59], v[168:171], v[192:195], v[56:59]
	v_mfma_f32_16x16x32_bf16 v[44:47], v[160:163], v[200:203], v[44:47]
	v_mfma_f32_16x16x32_bf16 v[40:43], v[168:171], v[200:203], v[40:43]
	v_mfma_f32_16x16x32_bf16 v[28:31], v[160:163], v[208:211], v[28:31]
	v_mfma_f32_16x16x32_bf16 v[24:27], v[168:171], v[208:211], v[24:27]
	v_mfma_f32_16x16x32_bf16 v[12:15], v[160:163], v[216:219], v[12:15]
	v_mfma_f32_16x16x32_bf16 v[8:11], v[168:171], v[216:219], v[8:11]
	v_mfma_f32_16x16x32_bf16 v[52:55], v[172:175], v[188:191], v[52:55]
	v_mfma_f32_16x16x32_bf16 v[48:51], v[180:183], v[188:191], v[48:51]
	v_mfma_f32_16x16x32_bf16 v[36:39], v[172:175], v[196:199], v[36:39]
	v_mfma_f32_16x16x32_bf16 v[32:35], v[180:183], v[196:199], v[32:35]
	v_mfma_f32_16x16x32_bf16 v[20:23], v[172:175], v[204:207], v[20:23]
	v_mfma_f32_16x16x32_bf16 v[16:19], v[180:183], v[204:207], v[16:19]
	v_mfma_f32_16x16x32_bf16 v[4:7], v[172:175], v[212:215], v[4:7]
	v_mfma_f32_16x16x32_bf16 v[0:3], v[180:183], v[212:215], v[0:3]
	v_mfma_f32_16x16x32_bf16 v[52:55], v[176:179], v[192:195], v[52:55]
	v_mfma_f32_16x16x32_bf16 v[48:51], v[184:187], v[192:195], v[48:51]
	v_mfma_f32_16x16x32_bf16 v[36:39], v[176:179], v[200:203], v[36:39]
	v_mfma_f32_16x16x32_bf16 v[32:35], v[184:187], v[200:203], v[32:35]
	v_mfma_f32_16x16x32_bf16 v[20:23], v[176:179], v[208:211], v[20:23]
	v_mfma_f32_16x16x32_bf16 v[16:19], v[184:187], v[208:211], v[16:19]
	v_mfma_f32_16x16x32_bf16 v[4:7], v[176:179], v[216:219], v[4:7]
	v_mfma_f32_16x16x32_bf16 v[0:3], v[184:187], v[216:219], v[0:3]
	s_setprio 0
	s_barrier
	s_add_u32 s33, s33, 0x100
	s_addc_u32 s55, s55, 0
	s_mov_b64 s[62:63], s[64:65]
	s_mov_b32 s57, s86
; #define PG8_STAGE(bufoff, gbase, voff) do { _Pragma("unroll") for (int _i = 0; _i < 2; ++_i) \
;         __builtin_amdgcn_global_load_lds((const unsigned*)((const char*)(gbase) + (voff)[_i]), (PG8_LAS unsigned*)(lds + (bufoff) + ldsw + _i * 8192), 16, 0, 0); } while (0)
; #define PG8_LDA(dst, b, h) do { _Pragma("unroll") for (int m = 0; m < 4; ++m) _Pragma("unroll") for (int k = 0; k < 2; ++k) dst[m][k] = *(const PG8_LAS bf16x8*)(lds + PG8_SA(b, h) + aoff + m * 2048 + k * 1024); } while (0)
; #define PG8_LDB(dst, b, h) do { _Pragma("unroll") for (int n = 0; n < 2; ++n) _Pragma("unroll") for (int k = 0; k < 2; ++k) dst[n][k] = *(const PG8_LAS bf16x8*)(lds + PG8_SB(b, h) + boff + n * 2048 + k * 1024); } while (0)
; #define PG8_MMA(ai, bj, At, Bt) do { __builtin_amdgcn_s_setprio(1); _Pragma("unroll") for (int m = 0; m < 4; ++m) _Pragma("unroll") for (int n = 0; n < 2; ++n) _Pragma("unroll") for (int k = 0; k < 2; ++k) \
;         acc[ai][bj][m][n] = __builtin_amdgcn_mfma_f32_16x16x32_bf16(Bt[n][k], At[m][k], acc[ai][bj][m][n], 0, 0, 0); __builtin_amdgcn_s_setprio(0); } while (0)
; #define PG8_WAIT_V(n) asm volatile("s_waitcnt vmcnt(" #n ")" ::: "memory")
; #define PG8_WAIT_L(n) asm volatile("s_waitcnt lgkmcnt(" #n ")" ::: "memory")
; #define PG8_BAR __builtin_amdgcn_s_barrier()
; #define PG8_SCHED __builtin_amdgcn_sched_barrier(0)
; template <class Epi, class Sched, bool ALIGN_EPI = false, bool SP2 = false>
; __device__ __forceinline__ void gemm_phase(PG8_LAS unsigned char* lds, const Gemm g, const Sched& S, const Epi& E) {
;     ...
;             PG8_LDB(B0, 0, 0); PG8_LDB(B1, 0, 1); PG8_SCHED; PG8_LDA(At, 0, 0); PG8_STAGE(PG8_SA(1, 1), a1 + hstep, voffA);
;             PG8_WAIT_V(8); PG8_WAIT_L(0); PG8_BAR; PG8_MMA(0, 0, At, B0); PG8_MMA(0, 1, At, B1); PG8_BAR; PG8_SCHED;
;             PG8_LDA(At, 0, 1); PG8_STAGE(PG8_SB(0, 0), b2, voffB); PG8_STAGE(PG8_SB(0, 1), b2 + hstep, voffB); PG8_STAGE(PG8_SA(0, 0), a2, voffA);
.LBB0_896:
	ds_read_b128 v[156:159], v140
	ds_read_b128 v[160:163], v141
	ds_read_b128 v[164:167], v142
	ds_read_b128 v[168:171], v143
	ds_read_b128 v[172:175], v144
	ds_read_b128 v[176:179], v145
	ds_read_b128 v[180:183], v146
	ds_read_b128 v[184:187], v147
	s_add_i32 s86, s57, 2
	s_add_u32 s64, s62, 0x100
	s_addc_u32 s65, s63, 0
	s_cmp_eq_u32 s78, s57
	s_cselect_b32 s69, s59, s65
	s_cselect_b32 s68, s58, s64
	s_cselect_b32 s67, s61, s55
	s_cselect_b32 s66, s60, s33
	s_mov_b32 m0, s79
	v_lshl_add_u64 v[220:221], s[62:63], 0, v[134:135]
	ds_read_b128 v[188:191], v138
	ds_read_b128 v[192:195], v138 offset:1024
	ds_read_b128 v[196:199], v138 offset:2048
	ds_read_b128 v[200:203], v138 offset:3072
	ds_read_b128 v[204:207], v138 offset:4096
	ds_read_b128 v[208:211], v138 offset:5120
	ds_read_b128 v[212:215], v138 offset:6144
	ds_read_b128 v[216:219], v138 offset:7168
	global_load_lds_dwordx4 v[220:221], off
	v_lshl_add_u64 v[220:221], s[62:63], 0, v[136:137]
	s_mov_b32 m0, s80
	s_nop 0
	global_load_lds_dwordx4 v[220:221], off
	s_waitcnt vmcnt(8)
	s_waitcnt lgkmcnt(0)
	s_barrier
	s_setprio 1
	v_mfma_f32_16x16x32_bf16 v[124:127], v[156:159], v[188:191], v[124:127]
	v_mfma_f32_16x16x32_bf16 v[120:123], v[164:167], v[188:191], v[120:123]
	v_mfma_f32_16x16x32_bf16 v[108:111], v[156:159], v[196:199], v[108:111]
	v_mfma_f32_16x16x32_bf16 v[104:107], v[164:167], v[196:199], v[104:107]
	v_mfma_f32_16x16x32_bf16 v[92:95], v[156:159], v[204:207], v[92:95]
	v_mfma_f32_16x16x32_bf16 v[88:91], v[164:167], v[204:207], v[88:91]
	v_mfma_f32_16x16x32_bf16 v[76:79], v[156:159], v[212:215], v[76:79]
	v_mfma_f32_16x16x32_bf16 v[72:75], v[164:167], v[212:215], v[72:75]
	v_mfma_f32_16x16x32_bf16 v[124:127], v[160:163], v[192:195], v[124:127]
	v_mfma_f32_16x16x32_bf16 v[120:123], v[168:171], v[192:195], v[120:123]
	v_mfma_f32_16x16x32_bf16 v[108:111], v[160:163], v[200:203], v[108:111]
	v_mfma_f32_16x16x32_bf16 v[104:107], v[168:171], v[200:203], v[104:107]
	v_mfma_f32_16x16x32_bf16 v[92:95], v[160:163], v[208:211], v[92:95]
	v_mfma_f32_16x16x32_bf16 v[88:91], v[168:171], v[208:211], v[88:91]
	v_mfma_f32_16x16x32_bf16 v[76:79], v[160:163], v[216:219], v[76:79]
	v_mfma_f32_16x16x32_bf16 v[72:75], v[168:171], v[216:219], v[72:75]
	v_mfma_f32_16x16x32_bf16 v[116:119], v[172:175], v[188:191], v[116:119]
	v_mfma_f32_16x16x32_bf16 v[112:115], v[180:183], v[188:191], v[112:115]
	v_mfma_f32_16x16x32_bf16 v[100:103], v[172:175], v[196:199], v[100:103]
	v_mfma_f32_16x16x32_bf16 v[96:99], v[180:183], v[196:199], v[96:99]
	v_mfma_f32_16x16x32_bf16 v[84:87], v[172:175], v[204:207], v[84:87]
	v_mfma_f32_16x16x32_bf16 v[80:83], v[180:183], v[204:207], v[80:83]
	v_mfma_f32_16x16x32_bf16 v[68:71], v[172:175], v[212:215], v[68:71]
	v_mfma_f32_16x16x32_bf16 v[64:67], v[180:183], v[212:215], v[64:67]
	v_mfma_f32_16x16x32_bf16 v[116:119], v[176:179], v[192:195], v[116:119]
	v_mfma_f32_16x16x32_bf16 v[112:115], v[184:187], v[192:195], v[112:115]
	v_mfma_f32_16x16x32_bf16 v[100:103], v[176:179], v[200:203], v[100:103]
	v_mfma_f32_16x16x32_bf16 v[96:99], v[184:187], v[200:203], v[96:99]
	v_mfma_f32_16x16x32_bf16 v[84:87], v[176:179], v[208:211], v[84:87]
	v_mfma_f32_16x16x32_bf16 v[80:83], v[184:187], v[208:211], v[80:83]
	v_mfma_f32_16x16x32_bf16 v[68:71], v[176:179], v[216:219], v[68:71]
	v_mfma_f32_16x16x32_bf16 v[64:67], v[184:187], v[216:219], v[64:67]
	s_setprio 0
	s_barrier
	s_mov_b32 m0, s12
	v_lshl_add_u64 v[220:221], s[66:67], 0, v[130:131]
	s_add_u32 s62, s66, 0xb0000
	ds_read_b128 v[188:191], v138 offset:16384
	ds_read_b128 v[192:195], v138 offset:17408
	ds_read_b128 v[196:199], v138 offset:18432
	ds_read_b128 v[200:203], v138 offset:19456
	ds_read_b128 v[204:207], v138 offset:20480
	ds_read_b128 v[208:211], v138 offset:21504
	ds_read_b128 v[212:215], v138 offset:22528
	ds_read_b128 v[216:219], v138 offset:23552
	global_load_lds_dwordx4 v[220:221], off
	v_lshl_add_u64 v[224:225], s[66:67], 0, v[128:129]
	s_mov_b32 m0, s13
	s_addc_u32 s63, s67, 0
	global_load_lds_dwordx4 v[224:225], off
	v_lshl_add_u64 v[226:227], s[62:63], 0, v[130:131]
	s_mov_b32 m0, s14
	v_lshl_add_u64 v[228:229], s[68:69], 0, v[128:129]
	global_load_lds_dwordx4 v[226:227], off
	v_lshl_add_u64 v[226:227], s[62:63], 0, v[128:129]
	s_mov_b32 m0, s15
	s_nop 0
	global_load_lds_dwordx4 v[226:227], off
	v_lshl_add_u64 v[226:227], s[68:69], 0, v[130:131]
	s_mov_b32 m0, s5
	s_nop 0
	global_load_lds_dwordx4 v[226:227], off
	s_mov_b32 m0, s39
	s_nop 0
	global_load_lds_dwordx4 v[228:229], off
	s_waitcnt vmcnt(8)
	s_waitcnt lgkmcnt(0)
	s_barrier
; #define PG8_STAGE(bufoff, gbase, voff) do { _Pragma("unroll") for (int _i = 0; _i < 2; ++_i) \
;         __builtin_amdgcn_global_load_lds((const unsigned*)((const char*)(gbase) + (voff)[_i]), (PG8_LAS unsigned*)(lds + (bufoff) + ldsw + _i * 8192), 16, 0, 0); } while (0)
; #define PG8_LDA(dst, b, h) do { _Pragma("unroll") for (int m = 0; m < 4; ++m) _Pragma("unroll") for (int k = 0; k < 2; ++k) dst[m][k] = *(const PG8_LAS bf16x8*)(lds + PG8_SA(b, h) + aoff + m * 2048 + k * 1024); } while (0)
; #define PG8_LDB(dst, b, h) do { _Pragma("unroll") for (int n = 0; n < 2; ++n) _Pragma("unroll") for (int k = 0; k < 2; ++k) dst[n][k] = *(const PG8_LAS bf16x8*)(lds + PG8_SB(b, h) + boff + n * 2048 + k * 1024); } while (0)
; #define PG8_MMA(ai, bj, At, Bt) do { __builtin_amdgcn_s_setprio(1); _Pragma("unroll") for (int m = 0; m < 4; ++m) _Pragma("unroll") for (int n = 0; n < 2; ++n) _Pragma("unroll") for (int k = 0; k < 2; ++k) \
;         acc[ai][bj][m][n] = __builtin_amdgcn_mfma_f32_16x16x32_bf16(Bt[n][k], At[m][k], acc[ai][bj][m][n], 0, 0, 0); __builtin_amdgcn_s_setprio(0); } while (0)
; #define PG8_WAIT_V(n) asm volatile("s_waitcnt vmcnt(" #n ")" ::: "memory")
; #define PG8_WAIT_L(n) asm volatile("s_waitcnt lgkmcnt(" #n ")" ::: "memory")
; #define PG8_BAR __builtin_amdgcn_s_barrier()
; #define PG8_SCHED __builtin_amdgcn_sched_barrier(0)
; template <class Epi, class Sched, bool ALIGN_EPI = false, bool SP2 = false>
; __device__ __forceinline__ void gemm_phase(PG8_LAS unsigned char* lds, const Gemm g, const Sched& S, const Epi& E) {
;     ...
;             PG8_WAIT_V(8); PG8_WAIT_L(0); PG8_BAR; PG8_MMA(1, 0, At, B0); PG8_MMA(1, 1, At, B1); PG8_BAR; PG8_SCHED;
;             PG8_LDB(B0, 1, 0); PG8_LDB(B1, 1, 1); PG8_SCHED; PG8_LDA(At, 1, 0); PG8_STAGE(PG8_SA(0, 1), a2 + hstep, voffA);
;             PG8_WAIT_V(8); PG8_WAIT_L(0); PG8_BAR; PG8_MMA(0, 0, At, B0); PG8_MMA(0, 1, At, B1); PG8_BAR; PG8_SCHED;
	s_setprio 1
	v_mfma_f32_16x16x32_bf16 v[60:63], v[156:159], v[188:191], v[60:63]
	v_mfma_f32_16x16x32_bf16 v[56:59], v[164:167], v[188:191], v[56:59]
	v_mfma_f32_16x16x32_bf16 v[44:47], v[156:159], v[196:199], v[44:47]
	v_mfma_f32_16x16x32_bf16 v[40:43], v[164:167], v[196:199], v[40:43]
	v_mfma_f32_16x16x32_bf16 v[28:31], v[156:159], v[204:207], v[28:31]
	v_mfma_f32_16x16x32_bf16 v[24:27], v[164:167], v[204:207], v[24:27]
	v_mfma_f32_16x16x32_bf16 v[12:15], v[156:159], v[212:215], v[12:15]
	v_mfma_f32_16x16x32_bf16 v[8:11], v[164:167], v[212:215], v[8:11]
	v_mfma_f32_16x16x32_bf16 v[60:63], v[160:163], v[192:195], v[60:63]
	v_mfma_f32_16x16x32_bf16 v[56:59], v[168:171], v[192:195], v[56:59]
	v_mfma_f32_16x16x32_bf16 v[44:47], v[160:163], v[200:203], v[44:47]
	v_mfma_f32_16x16x32_bf16 v[40:43], v[168:171], v[200:203], v[40:43]
	v_mfma_f32_16x16x32_bf16 v[28:31], v[160:163], v[208:211], v[28:31]
	v_mfma_f32_16x16x32_bf16 v[24:27], v[168:171], v[208:211], v[24:27]
	v_mfma_f32_16x16x32_bf16 v[12:15], v[160:163], v[216:219], v[12:15]
	v_mfma_f32_16x16x32_bf16 v[8:11], v[168:171], v[216:219], v[8:11]
	v_mfma_f32_16x16x32_bf16 v[52:55], v[172:175], v[188:191], v[52:55]
	v_mfma_f32_16x16x32_bf16 v[48:51], v[180:183], v[188:191], v[48:51]
	v_mfma_f32_16x16x32_bf16 v[36:39], v[172:175], v[196:199], v[36:39]
	v_mfma_f32_16x16x32_bf16 v[32:35], v[180:183], v[196:199], v[32:35]
	v_mfma_f32_16x16x32_bf16 v[20:23], v[172:175], v[204:207], v[20:23]
	v_mfma_f32_16x16x32_bf16 v[16:19], v[180:183], v[204:207], v[16:19]
	v_mfma_f32_16x16x32_bf16 v[4:7], v[172:175], v[212:215], v[4:7]
	v_mfma_f32_16x16x32_bf16 v[0:3], v[180:183], v[212:215], v[0:3]
	v_mfma_f32_16x16x32_bf16 v[52:55], v[176:179], v[192:195], v[52:55]
	v_mfma_f32_16x16x32_bf16 v[48:51], v[184:187], v[192:195], v[48:51]
	v_mfma_f32_16x16x32_bf16 v[36:39], v[176:179], v[200:203], v[36:39]
	v_mfma_f32_16x16x32_bf16 v[32:35], v[184:187], v[200:203], v[32:35]
	v_mfma_f32_16x16x32_bf16 v[20:23], v[176:179], v[208:211], v[20:23]
	v_mfma_f32_16x16x32_bf16 v[16:19], v[184:187], v[208:211], v[16:19]
	v_mfma_f32_16x16x32_bf16 v[4:7], v[176:179], v[216:219], v[4:7]
	v_mfma_f32_16x16x32_bf16 v[0:3], v[184:187], v[216:219], v[0:3]
	s_setprio 0
	s_barrier
	ds_read_b128 v[156:159], v148
	ds_read_b128 v[160:163], v149
	ds_read_b128 v[164:167], v150
	ds_read_b128 v[168:171], v151
	ds_read_b128 v[172:175], v152
	ds_read_b128 v[176:179], v153
	ds_read_b128 v[180:183], v154
	ds_read_b128 v[184:187], v155
	s_add_u32 s62, s68, 0xb0000
	s_addc_u32 s63, s69, 0
	s_mov_b32 m0, s43
	v_lshl_add_u64 v[230:231], s[62:63], 0, v[130:131]
	ds_read_b128 v[188:191], v138 offset:32768
	ds_read_b128 v[192:195], v138 offset:33792
	ds_read_b128 v[196:199], v138 offset:34816
	ds_read_b128 v[200:203], v138 offset:35840
	ds_read_b128 v[204:207], v138 offset:36864
	ds_read_b128 v[208:211], v138 offset:37888
	ds_read_b128 v[212:215], v138 offset:38912
	ds_read_b128 v[216:219], v138 offset:39936
	global_load_lds_dwordx4 v[230:231], off
	v_lshl_add_u64 v[230:231], s[62:63], 0, v[128:129]
	s_mov_b32 m0, s70
	s_nop 0
	global_load_lds_dwordx4 v[230:231], off
	s_waitcnt vmcnt(8)
	s_waitcnt lgkmcnt(0)
	s_barrier
	s_setprio 1
	v_mfma_f32_16x16x32_bf16 v[124:127], v[156:159], v[188:191], v[124:127]
	v_mfma_f32_16x16x32_bf16 v[120:123], v[164:167], v[188:191], v[120:123]
	v_mfma_f32_16x16x32_bf16 v[108:111], v[156:159], v[196:199], v[108:111]
	v_mfma_f32_16x16x32_bf16 v[104:107], v[164:167], v[196:199], v[104:107]
	v_mfma_f32_16x16x32_bf16 v[92:95], v[156:159], v[204:207], v[92:95]
	v_mfma_f32_16x16x32_bf16 v[88:91], v[164:167], v[204:207], v[88:91]
	v_mfma_f32_16x16x32_bf16 v[76:79], v[156:159], v[212:215], v[76:79]
	v_mfma_f32_16x16x32_bf16 v[72:75], v[164:167], v[212:215], v[72:75]
	v_mfma_f32_16x16x32_bf16 v[124:127], v[160:163], v[192:195], v[124:127]
	v_mfma_f32_16x16x32_bf16 v[120:123], v[168:171], v[192:195], v[120:123]
	v_mfma_f32_16x16x32_bf16 v[108:111], v[160:163], v[200:203], v[108:111]
	v_mfma_f32_16x16x32_bf16 v[104:107], v[168:171], v[200:203], v[104:107]
	v_mfma_f32_16x16x32_bf16 v[92:95], v[160:163], v[208:211], v[92:95]
	v_mfma_f32_16x16x32_bf16 v[88:91], v[168:171], v[208:211], v[88:91]
	v_mfma_f32_16x16x32_bf16 v[76:79], v[160:163], v[216:219], v[76:79]
	v_mfma_f32_16x16x32_bf16 v[72:75], v[168:171], v[216:219], v[72:75]
	v_mfma_f32_16x16x32_bf16 v[116:119], v[172:175], v[188:191], v[116:119]
	v_mfma_f32_16x16x32_bf16 v[112:115], v[180:183], v[188:191], v[112:115]
	v_mfma_f32_16x16x32_bf16 v[100:103], v[172:175], v[196:199], v[100:103]
	v_mfma_f32_16x16x32_bf16 v[96:99], v[180:183], v[196:199], v[96:99]
	v_mfma_f32_16x16x32_bf16 v[84:87], v[172:175], v[204:207], v[84:87]
	v_mfma_f32_16x16x32_bf16 v[80:83], v[180:183], v[204:207], v[80:83]
	v_mfma_f32_16x16x32_bf16 v[68:71], v[172:175], v[212:215], v[68:71]
	v_mfma_f32_16x16x32_bf16 v[64:67], v[180:183], v[212:215], v[64:67]
	v_mfma_f32_16x16x32_bf16 v[116:119], v[176:179], v[192:195], v[116:119]
	v_mfma_f32_16x16x32_bf16 v[112:115], v[184:187], v[192:195], v[112:115]
	v_mfma_f32_16x16x32_bf16 v[100:103], v[176:179], v[200:203], v[100:103]
	v_mfma_f32_16x16x32_bf16 v[96:99], v[184:187], v[200:203], v[96:99]
	v_mfma_f32_16x16x32_bf16 v[84:87], v[176:179], v[208:211], v[84:87]
	v_mfma_f32_16x16x32_bf16 v[80:83], v[184:187], v[208:211], v[80:83]
	v_mfma_f32_16x16x32_bf16 v[68:71], v[176:179], v[216:219], v[68:71]
	v_mfma_f32_16x16x32_bf16 v[64:67], v[184:187], v[216:219], v[64:67]
	s_setprio 0
	s_barrier
; #define PG8_STAGE(bufoff, gbase, voff) do { _Pragma("unroll") for (int _i = 0; _i < 2; ++_i) \
;         __builtin_amdgcn_global_load_lds((const unsigned*)((const char*)(gbase) + (voff)[_i]), (PG8_LAS unsigned*)(lds + (bufoff) + ldsw + _i * 8192), 16, 0, 0); } while (0)
; #define PG8_LDA(dst, b, h) do { _Pragma("unroll") for (int m = 0; m < 4; ++m) _Pragma("unroll") for (int k = 0; k < 2; ++k) dst[m][k] = *(const PG8_LAS bf16x8*)(lds + PG8_SA(b, h) + aoff + m * 2048 + k * 1024); } while (0)
; #define PG8_MMA(ai, bj, At, Bt) do { __builtin_amdgcn_s_setprio(1); _Pragma("unroll") for (int m = 0; m < 4; ++m) _Pragma("unroll") for (int n = 0; n < 2; ++n) _Pragma("unroll") for (int k = 0; k < 2; ++k) \
;         acc[ai][bj][m][n] = __builtin_amdgcn_mfma_f32_16x16x32_bf16(Bt[n][k], At[m][k], acc[ai][bj][m][n], 0, 0, 0); __builtin_amdgcn_s_setprio(0); } while (0)
; #define PG8_WAIT_V(n) asm volatile("s_waitcnt vmcnt(" #n ")" ::: "memory")
; #define PG8_WAIT_L(n) asm volatile("s_waitcnt lgkmcnt(" #n ")" ::: "memory")
; #define PG8_BAR __builtin_amdgcn_s_barrier()
; #define PG8_SCHED __builtin_amdgcn_sched_barrier(0)
; template <class Epi, class Sched, bool ALIGN_EPI = false, bool SP2 = false>
; __device__ __forceinline__ void gemm_phase(PG8_LAS unsigned char* lds, const Gemm g, const Sched& S, const Epi& E) {
;     ...
;         for (int t = 0; t < nt; t += 2) {
;     ...
;             PG8_LDA(At, 1, 1); PG8_STAGE(PG8_SB(1, 0), b3, voffB); PG8_STAGE(PG8_SB(1, 1), b3 + hstep, voffB); PG8_STAGE(PG8_SA(1, 0), a3, voffA);
;             PG8_WAIT_V(8); PG8_WAIT_L(0); PG8_BAR; PG8_MMA(1, 0, At, B0); PG8_MMA(1, 1, At, B1); PG8_BAR; PG8_SCHED;
	s_mov_b32 m0, s72
	v_lshl_add_u64 v[220:221], v[220:221], 0, s[40:41]
	s_add_u32 s62, s66, 0xb0080
	ds_read_b128 v[188:191], v138 offset:49152
	ds_read_b128 v[192:195], v138 offset:50176
	ds_read_b128 v[196:199], v138 offset:51200
	ds_read_b128 v[200:203], v138 offset:52224
	ds_read_b128 v[204:207], v138 offset:53248
	ds_read_b128 v[208:211], v138 offset:54272
	ds_read_b128 v[212:215], v138 offset:55296
	ds_read_b128 v[216:219], v138 offset:56320
	global_load_lds_dwordx4 v[220:221], off
	v_lshl_add_u64 v[220:221], v[224:225], 0, s[40:41]
	s_mov_b32 m0, s73
	s_addc_u32 s63, s67, 0
	global_load_lds_dwordx4 v[220:221], off
	v_lshl_add_u64 v[220:221], s[62:63], 0, v[130:131]
	s_mov_b32 m0, s76
	s_nop 0
	global_load_lds_dwordx4 v[220:221], off
	v_lshl_add_u64 v[220:221], s[62:63], 0, v[128:129]
	s_mov_b32 m0, s77
	s_nop 0
	global_load_lds_dwordx4 v[220:221], off
	v_lshl_add_u64 v[220:221], v[226:227], 0, s[40:41]
	s_mov_b32 m0, s74
	s_nop 0
	global_load_lds_dwordx4 v[220:221], off
	v_lshl_add_u64 v[220:221], v[228:229], 0, s[40:41]
	s_mov_b32 m0, s75
	s_nop 0
	global_load_lds_dwordx4 v[220:221], off
	s_waitcnt vmcnt(8)
	s_waitcnt lgkmcnt(0)
	s_barrier
	s_setprio 1
	v_mfma_f32_16x16x32_bf16 v[60:63], v[156:159], v[188:191], v[60:63]
	v_mfma_f32_16x16x32_bf16 v[56:59], v[164:167], v[188:191], v[56:59]
	v_mfma_f32_16x16x32_bf16 v[44:47], v[156:159], v[196:199], v[44:47]
	v_mfma_f32_16x16x32_bf16 v[40:43], v[164:167], v[196:199], v[40:43]
	v_mfma_f32_16x16x32_bf16 v[28:31], v[156:159], v[204:207], v[28:31]
	v_mfma_f32_16x16x32_bf16 v[24:27], v[164:167], v[204:207], v[24:27]
	v_mfma_f32_16x16x32_bf16 v[12:15], v[156:159], v[212:215], v[12:15]
	v_mfma_f32_16x16x32_bf16 v[8:11], v[164:167], v[212:215], v[8:11]
	v_mfma_f32_16x16x32_bf16 v[60:63], v[160:163], v[192:195], v[60:63]
	v_mfma_f32_16x16x32_bf16 v[56:59], v[168:171], v[192:195], v[56:59]
	v_mfma_f32_16x16x32_bf16 v[44:47], v[160:163], v[200:203], v[44:47]
	v_mfma_f32_16x16x32_bf16 v[40:43], v[168:171], v[200:203], v[40:43]
	v_mfma_f32_16x16x32_bf16 v[28:31], v[160:163], v[208:211], v[28:31]
	v_mfma_f32_16x16x32_bf16 v[24:27], v[168:171], v[208:211], v[24:27]
	v_mfma_f32_16x16x32_bf16 v[12:15], v[160:163], v[216:219], v[12:15]
	v_mfma_f32_16x16x32_bf16 v[8:11], v[168:171], v[216:219], v[8:11]
	v_mfma_f32_16x16x32_bf16 v[52:55], v[172:175], v[188:191], v[52:55]
	v_mfma_f32_16x16x32_bf16 v[48:51], v[180:183], v[188:191], v[48:51]
	v_mfma_f32_16x16x32_bf16 v[36:39], v[172:175], v[196:199], v[36:39]
	v_mfma_f32_16x16x32_bf16 v[32:35], v[180:183], v[196:199], v[32:35]
	v_mfma_f32_16x16x32_bf16 v[20:23], v[172:175], v[204:207], v[20:23]
	v_mfma_f32_16x16x32_bf16 v[16:19], v[180:183], v[204:207], v[16:19]
	v_mfma_f32_16x16x32_bf16 v[4:7], v[172:175], v[212:215], v[4:7]
	v_mfma_f32_16x16x32_bf16 v[0:3], v[180:183], v[212:215], v[0:3]
	v_mfma_f32_16x16x32_bf16 v[52:55], v[176:179], v[192:195], v[52:55]
	v_mfma_f32_16x16x32_bf16 v[48:51], v[184:187], v[192:195], v[48:51]
	v_mfma_f32_16x16x32_bf16 v[36:39], v[176:179], v[200:203], v[36:39]
	v_mfma_f32_16x16x32_bf16 v[32:35], v[184:187], v[200:203], v[32:35]
	v_mfma_f32_16x16x32_bf16 v[20:23], v[176:179], v[208:211], v[20:23]
	v_mfma_f32_16x16x32_bf16 v[16:19], v[184:187], v[208:211], v[16:19]
	v_mfma_f32_16x16x32_bf16 v[4:7], v[176:179], v[216:219], v[4:7]
	v_mfma_f32_16x16x32_bf16 v[0:3], v[184:187], v[216:219], v[0:3]
	s_setprio 0
	s_barrier
	s_add_u32 s33, s33, 0x100
	s_addc_u32 s55, s55, 0
	s_cmp_ge_i32 s86, s4
	s_mov_b64 s[62:63], s[64:65]
	s_mov_b32 s57, s86
	s_cbranch_scc0 .LBB0_896
	s_and_b64 vcc, exec, s[52:53]
	s_cbranch_vccz .LBB0_899

;     __host__ __device__ bool next(int i, Unit& u) const { const int L = i * G + c; if (L >= 16 * nkc) return false; u.kc = L % nkc; const int t = L / nkc; u.pn = t & 3; u.pm = 33 * (t >> 2); return true; }
; #define PG8_STAGE(bufoff, gbase, voff) do { _Pragma("unroll") for (int _i = 0; _i < 2; ++_i) \
;         __builtin_amdgcn_global_load_lds((const unsigned*)((const char*)(gbase) + (voff)[_i]), (PG8_LAS unsigned*)(lds + (bufoff) + ldsw + _i * 8192), 16, 0, 0); } while (0)
; #define PG8_LDA(dst, b, h) do { _Pragma("unroll") for (int m = 0; m < 4; ++m) _Pragma("unroll") for (int k = 0; k < 2; ++k) dst[m][k] = *(const PG8_LAS bf16x8*)(lds + PG8_SA(b, h) + aoff + m * 2048 + k * 1024); } while (0)
; #define PG8_LDB(dst, b, h) do { _Pragma("unroll") for (int n = 0; n < 2; ++n) _Pragma("unroll") for (int k = 0; k < 2; ++k) dst[n][k] = *(const PG8_LAS bf16x8*)(lds + PG8_SB(b, h) + boff + n * 2048 + k * 1024); } while (0)
; #define PG8_BAR __builtin_amdgcn_s_barrier()
; template <class Epi, class Sched, bool ALIGN_EPI = false, bool SP2 = false>
; __device__ __forceinline__ void gemm_phase(PG8_LAS unsigned char* lds, const Gemm g, const Sched& S, const Epi& E) {
;     ...
;         const bool has_next = S.next(ui + 1, nxt);
;         const char* nA = has_next ? (const char*)g.A + (size_t)nxt.pm * tstep + (size_t)nxt.kc * cstep : cA; const char* nB = has_next ? (const char*)g.Bt + (size_t)nxt.pn * tstep + (size_t)nxt.kc * cstep : cB;
;         for (int t = 0; t < nt; t += 2) {
;             const bool last = (t == nt - 2);
;             const char* a1 = cA + (size_t)(t + 1) * kstep;
;             const char* a2 = last ? nA : cA + (size_t)(t + 2) * kstep; const char* b2 = last ? nB : cB + (size_t)(t + 2) * kstep;
;             const char* a3 = a2 + kstep; const char* b3 = b2 + kstep;
;             if (last && has_next) S.a_ready(nxt);
;             if constexpr (SP2) {
;             PG8_LDB(B0, 0, 0); PG8_LDB(B1, 0, 1); PG8_SCHED; PG8_LDA(At, 0, 0); PG8_STAGE(PG8_SA(1, 1), a1 + hstep, voffA);
;             PG8_WAIT_V(8); PG8_WAIT_L(0); PG8_BAR; PG8_MMA(0, 0, At, B0); PG8_MMA(0, 1, At, B1); PG8_BAR; PG8_SCHED;
;             PG8_LDA(At, 0, 1); PG8_STAGE(PG8_SB(0, 0), b2, voffB); PG8_STAGE(PG8_SB(0, 1), b2 + hstep, voffB); PG8_STAGE(PG8_SA(0, 0), a2, voffA);
;             PG8_WAIT_V(8); PG8_WAIT_L(0); PG8_BAR; PG8_MMA(1, 0, At, B0); PG8_MMA(1, 1, At, B1); PG8_BAR; PG8_SCHED;
.LBB0_1029:
	s_ashr_i32 s57, s56, 31
	s_lshl_b64 s[58:59], s[56:57], 19
	s_add_u32 s58, s46, s58
	s_addc_u32 s59, s47, s59
	s_and_b64 s[60:61], s[8:9], exec
	s_cselect_b32 s33, s59, s11
	s_cselect_b32 s57, s58, s10
	s_ashr_i32 s55, s54, 31
	s_lshl_b64 s[60:61], s[54:55], 19
	s_add_u32 s60, s1, s60
	s_addc_u32 s61, s3, s61
	s_and_b64 s[68:69], s[8:9], exec
	s_cselect_b32 s55, s61, s67
	s_cselect_b32 s80, s60, s66
	s_add_u32 s10, s10, 0x40080
	s_addc_u32 s11, s11, 0
	s_add_u32 s81, s66, 0x100
	s_addc_u32 s82, s67, 0
	s_mov_b32 s83, -2
	ds_read_b128 v[128:131], v171
	ds_read_b128 v[132:135], v172
	ds_read_b128 v[188:191], v173
	ds_read_b128 v[192:195], v174
	ds_read_b128 v[196:199], v175
	ds_read_b128 v[200:203], v176
	ds_read_b128 v[204:207], v177
	ds_read_b128 v[208:211], v178
	s_add_u32 s66, s10, 0xfffc0080
	s_addc_u32 s67, s11, -1
	s_cmp_eq_u32 s83, 12
	s_cselect_b32 s69, s33, s67
	s_cselect_b32 s68, s57, s66
	s_cselect_b32 s67, s55, s82
	s_cselect_b32 s66, s80, s81
	s_mov_b32 m0, s77
	v_lshl_add_u64 v[136:137], s[10:11], 0, v[146:147]
	ds_read_b128 v[212:215], v159
	ds_read_b128 v[216:219], v159 offset:1024
	ds_read_b128 v[224:227], v159 offset:2048
	ds_read_b128 v[228:231], v159 offset:3072
	ds_read_b128 v[232:235], v159 offset:4096
	ds_read_b128 v[236:239], v159 offset:5120
	ds_read_b128 v[240:243], v159 offset:6144
	ds_read_b128 v[244:247], v159 offset:7168
	global_load_lds_dwordx4 v[136:137], off
	v_lshl_add_u64 v[136:137], s[10:11], 0, v[148:149]
	s_mov_b32 m0, s78
	s_nop 0
	global_load_lds_dwordx4 v[136:137], off
	s_waitcnt vmcnt(8)
	s_waitcnt lgkmcnt(0)
	s_barrier
	s_setprio 1
	v_mfma_f32_16x16x32_bf16 v[124:127], v[128:131], v[212:215], 0
	v_mfma_f32_16x16x32_bf16 v[120:123], v[188:191], v[212:215], 0
	v_mfma_f32_16x16x32_bf16 v[108:111], v[128:131], v[224:227], 0
	v_mfma_f32_16x16x32_bf16 v[104:107], v[188:191], v[224:227], 0
	v_mfma_f32_16x16x32_bf16 v[92:95], v[128:131], v[232:235], 0
	v_mfma_f32_16x16x32_bf16 v[88:91], v[188:191], v[232:235], 0
	v_mfma_f32_16x16x32_bf16 v[76:79], v[128:131], v[240:243], 0
	v_mfma_f32_16x16x32_bf16 v[72:75], v[188:191], v[240:243], 0
	v_mfma_f32_16x16x32_bf16 v[124:127], v[132:135], v[216:219], v[124:127]
	v_mfma_f32_16x16x32_bf16 v[120:123], v[192:195], v[216:219], v[120:123]
	v_mfma_f32_16x16x32_bf16 v[108:111], v[132:135], v[228:231], v[108:111]
	v_mfma_f32_16x16x32_bf16 v[104:107], v[192:195], v[228:231], v[104:107]
	v_mfma_f32_16x16x32_bf16 v[92:95], v[132:135], v[236:239], v[92:95]
	v_mfma_f32_16x16x32_bf16 v[88:91], v[192:195], v[236:239], v[88:91]
	v_mfma_f32_16x16x32_bf16 v[76:79], v[132:135], v[244:247], v[76:79]
	v_mfma_f32_16x16x32_bf16 v[72:75], v[192:195], v[244:247], v[72:75]
	v_mfma_f32_16x16x32_bf16 v[116:119], v[196:199], v[212:215], 0
	v_mfma_f32_16x16x32_bf16 v[112:115], v[204:207], v[212:215], 0
	v_mfma_f32_16x16x32_bf16 v[100:103], v[196:199], v[224:227], 0
	v_mfma_f32_16x16x32_bf16 v[96:99], v[204:207], v[224:227], 0
	v_mfma_f32_16x16x32_bf16 v[84:87], v[196:199], v[232:235], 0
	v_mfma_f32_16x16x32_bf16 v[80:83], v[204:207], v[232:235], 0
	v_mfma_f32_16x16x32_bf16 v[68:71], v[196:199], v[240:243], 0
	v_mfma_f32_16x16x32_bf16 v[64:67], v[204:207], v[240:243], 0
	v_mfma_f32_16x16x32_bf16 v[116:119], v[200:203], v[216:219], v[116:119]
	v_mfma_f32_16x16x32_bf16 v[112:115], v[208:211], v[216:219], v[112:115]
	v_mfma_f32_16x16x32_bf16 v[100:103], v[200:203], v[228:231], v[100:103]
	v_mfma_f32_16x16x32_bf16 v[96:99], v[208:211], v[228:231], v[96:99]
	v_mfma_f32_16x16x32_bf16 v[84:87], v[200:203], v[236:239], v[84:87]
	v_mfma_f32_16x16x32_bf16 v[80:83], v[208:211], v[236:239], v[80:83]
	v_mfma_f32_16x16x32_bf16 v[68:71], v[200:203], v[244:247], v[68:71]
	v_mfma_f32_16x16x32_bf16 v[64:67], v[208:211], v[244:247], v[64:67]
	s_setprio 0
	s_barrier
	s_mov_b32 m0, s5
	v_lshl_add_u64 v[136:137], s[66:67], 0, v[140:141]
	s_add_u32 s84, s66, 0x40000
	ds_read_b128 v[212:215], v159 offset:16384
	ds_read_b128 v[216:219], v159 offset:17408
	ds_read_b128 v[224:227], v159 offset:18432
	ds_read_b128 v[228:231], v159 offset:19456
	ds_read_b128 v[232:235], v159 offset:20480
	ds_read_b128 v[236:239], v159 offset:21504
	ds_read_b128 v[240:243], v159 offset:22528
	ds_read_b128 v[244:247], v159 offset:23552
	global_load_lds_dwordx4 v[136:137], off
	v_lshl_add_u64 v[154:155], s[66:67], 0, v[144:145]
	s_mov_b32 m0, s12
	s_addc_u32 s85, s67, 0
	global_load_lds_dwordx4 v[154:155], off
	v_lshl_add_u64 v[220:221], s[84:85], 0, v[140:141]
	s_mov_b32 m0, s13
	v_lshl_add_u64 v[248:249], s[68:69], 0, v[142:143]
	global_load_lds_dwordx4 v[220:221], off
	v_lshl_add_u64 v[220:221], s[84:85], 0, v[144:145]
	s_mov_b32 m0, s14
	s_nop 0
	global_load_lds_dwordx4 v[220:221], off
	v_lshl_add_u64 v[220:221], s[68:69], 0, v[138:139]
	s_mov_b32 m0, s4
	s_nop 0
	global_load_lds_dwordx4 v[220:221], off
	s_mov_b32 m0, s15
	s_nop 0
	global_load_lds_dwordx4 v[248:249], off
	s_waitcnt vmcnt(8)
	s_waitcnt lgkmcnt(0)
	s_barrier
; #define PG8_STAGE(bufoff, gbase, voff) do { _Pragma("unroll") for (int _i = 0; _i < 2; ++_i) \
;         __builtin_amdgcn_global_load_lds((const unsigned*)((const char*)(gbase) + (voff)[_i]), (PG8_LAS unsigned*)(lds + (bufoff) + ldsw + _i * 8192), 16, 0, 0); } while (0)
; #define PG8_LDA(dst, b, h) do { _Pragma("unroll") for (int m = 0; m < 4; ++m) _Pragma("unroll") for (int k = 0; k < 2; ++k) dst[m][k] = *(const PG8_LAS bf16x8*)(lds + PG8_SA(b, h) + aoff + m * 2048 + k * 1024); } while (0)
; #define PG8_LDB(dst, b, h) do { _Pragma("unroll") for (int n = 0; n < 2; ++n) _Pragma("unroll") for (int k = 0; k < 2; ++k) dst[n][k] = *(const PG8_LAS bf16x8*)(lds + PG8_SB(b, h) + boff + n * 2048 + k * 1024); } while (0)
; #define PG8_MMA(ai, bj, At, Bt) do { __builtin_amdgcn_s_setprio(1); _Pragma("unroll") for (int m = 0; m < 4; ++m) _Pragma("unroll") for (int n = 0; n < 2; ++n) _Pragma("unroll") for (int k = 0; k < 2; ++k) \
;         acc[ai][bj][m][n] = __builtin_amdgcn_mfma_f32_16x16x32_bf16(Bt[n][k], At[m][k], acc[ai][bj][m][n], 0, 0, 0); __builtin_amdgcn_s_setprio(0); } while (0)
; #define PG8_WAIT_V(n) asm volatile("s_waitcnt vmcnt(" #n ")" ::: "memory")
; #define PG8_WAIT_L(n) asm volatile("s_waitcnt lgkmcnt(" #n ")" ::: "memory")
; #define PG8_BAR __builtin_amdgcn_s_barrier()
; #define PG8_SCHED __builtin_amdgcn_sched_barrier(0)
; template <class Epi, class Sched, bool ALIGN_EPI = false, bool SP2 = false>
; __device__ __forceinline__ void gemm_phase(PG8_LAS unsigned char* lds, const Gemm g, const Sched& S, const Epi& E) {
;     ...
;             PG8_WAIT_V(8); PG8_WAIT_L(0); PG8_BAR; PG8_MMA(1, 0, At, B0); PG8_MMA(1, 1, At, B1); PG8_BAR; PG8_SCHED;
;             PG8_LDB(B0, 1, 0); PG8_LDB(B1, 1, 1); PG8_SCHED; PG8_LDA(At, 1, 0); PG8_STAGE(PG8_SA(0, 1), a2 + hstep, voffA);
;             PG8_WAIT_V(8); PG8_WAIT_L(0); PG8_BAR; PG8_MMA(0, 0, At, B0); PG8_MMA(0, 1, At, B1); PG8_BAR; PG8_SCHED;
	s_setprio 1
	v_mfma_f32_16x16x32_bf16 v[60:63], v[128:131], v[212:215], 0
	v_mfma_f32_16x16x32_bf16 v[56:59], v[188:191], v[212:215], 0
	v_mfma_f32_16x16x32_bf16 v[44:47], v[128:131], v[224:227], 0
	v_mfma_f32_16x16x32_bf16 v[40:43], v[188:191], v[224:227], 0
	v_mfma_f32_16x16x32_bf16 v[28:31], v[128:131], v[232:235], 0
	v_mfma_f32_16x16x32_bf16 v[24:27], v[188:191], v[232:235], 0
	v_mfma_f32_16x16x32_bf16 v[12:15], v[128:131], v[240:243], 0
	v_mfma_f32_16x16x32_bf16 v[8:11], v[188:191], v[240:243], 0
	v_mfma_f32_16x16x32_bf16 v[60:63], v[132:135], v[216:219], v[60:63]
	v_mfma_f32_16x16x32_bf16 v[56:59], v[192:195], v[216:219], v[56:59]
	v_mfma_f32_16x16x32_bf16 v[44:47], v[132:135], v[228:231], v[44:47]
	v_mfma_f32_16x16x32_bf16 v[40:43], v[192:195], v[228:231], v[40:43]
	v_mfma_f32_16x16x32_bf16 v[28:31], v[132:135], v[236:239], v[28:31]
	v_mfma_f32_16x16x32_bf16 v[24:27], v[192:195], v[236:239], v[24:27]
	v_mfma_f32_16x16x32_bf16 v[12:15], v[132:135], v[244:247], v[12:15]
	v_mfma_f32_16x16x32_bf16 v[8:11], v[192:195], v[244:247], v[8:11]
	v_mfma_f32_16x16x32_bf16 v[52:55], v[196:199], v[212:215], 0
	v_mfma_f32_16x16x32_bf16 v[48:51], v[204:207], v[212:215], 0
	v_mfma_f32_16x16x32_bf16 v[36:39], v[196:199], v[224:227], 0
	v_mfma_f32_16x16x32_bf16 v[32:35], v[204:207], v[224:227], 0
	v_mfma_f32_16x16x32_bf16 v[20:23], v[196:199], v[232:235], 0
	v_mfma_f32_16x16x32_bf16 v[16:19], v[204:207], v[232:235], 0
	v_mfma_f32_16x16x32_bf16 v[4:7], v[196:199], v[240:243], 0
	v_mfma_f32_16x16x32_bf16 v[0:3], v[204:207], v[240:243], 0
	v_mfma_f32_16x16x32_bf16 v[52:55], v[200:203], v[216:219], v[52:55]
	v_mfma_f32_16x16x32_bf16 v[48:51], v[208:211], v[216:219], v[48:51]
	v_mfma_f32_16x16x32_bf16 v[36:39], v[200:203], v[228:231], v[36:39]
	v_mfma_f32_16x16x32_bf16 v[32:35], v[208:211], v[228:231], v[32:35]
	v_mfma_f32_16x16x32_bf16 v[20:23], v[200:203], v[236:239], v[20:23]
	v_mfma_f32_16x16x32_bf16 v[16:19], v[208:211], v[236:239], v[16:19]
	v_mfma_f32_16x16x32_bf16 v[4:7], v[200:203], v[244:247], v[4:7]
	v_mfma_f32_16x16x32_bf16 v[0:3], v[208:211], v[244:247], v[0:3]
	s_setprio 0
	s_barrier
	ds_read_b128 v[128:131], v179
	ds_read_b128 v[132:135], v180
	ds_read_b128 v[188:191], v181
	ds_read_b128 v[192:195], v182
	ds_read_b128 v[196:199], v183
	ds_read_b128 v[200:203], v184
	ds_read_b128 v[204:207], v185
	ds_read_b128 v[208:211], v186
	s_add_u32 s68, s68, 0x40000
	s_addc_u32 s69, s69, 0
	s_mov_b32 m0, s39
	v_lshl_add_u64 v[250:251], s[68:69], 0, v[138:139]
	ds_read_b128 v[212:215], v159 offset:32768
	ds_read_b128 v[216:219], v159 offset:33792
	ds_read_b128 v[224:227], v159 offset:34816
	ds_read_b128 v[228:231], v159 offset:35840
	ds_read_b128 v[232:235], v159 offset:36864
	ds_read_b128 v[236:239], v159 offset:37888
	ds_read_b128 v[240:243], v159 offset:38912
	ds_read_b128 v[244:247], v159 offset:39936
	global_load_lds_dwordx4 v[250:251], off
	v_lshl_add_u64 v[250:251], s[68:69], 0, v[142:143]
	s_mov_b32 m0, s43
	s_nop 0
	global_load_lds_dwordx4 v[250:251], off
	s_waitcnt vmcnt(8)
	s_waitcnt lgkmcnt(0)
	s_barrier
	s_setprio 1
	v_mfma_f32_16x16x32_bf16 v[124:127], v[128:131], v[212:215], v[124:127]
	v_mfma_f32_16x16x32_bf16 v[120:123], v[188:191], v[212:215], v[120:123]
	v_mfma_f32_16x16x32_bf16 v[108:111], v[128:131], v[224:227], v[108:111]
	v_mfma_f32_16x16x32_bf16 v[104:107], v[188:191], v[224:227], v[104:107]
	v_mfma_f32_16x16x32_bf16 v[92:95], v[128:131], v[232:235], v[92:95]
	v_mfma_f32_16x16x32_bf16 v[88:91], v[188:191], v[232:235], v[88:91]
	v_mfma_f32_16x16x32_bf16 v[76:79], v[128:131], v[240:243], v[76:79]
	v_mfma_f32_16x16x32_bf16 v[72:75], v[188:191], v[240:243], v[72:75]
	v_mfma_f32_16x16x32_bf16 v[124:127], v[132:135], v[216:219], v[124:127]
	v_mfma_f32_16x16x32_bf16 v[120:123], v[192:195], v[216:219], v[120:123]
	v_mfma_f32_16x16x32_bf16 v[108:111], v[132:135], v[228:231], v[108:111]
	v_mfma_f32_16x16x32_bf16 v[104:107], v[192:195], v[228:231], v[104:107]
	v_mfma_f32_16x16x32_bf16 v[92:95], v[132:135], v[236:239], v[92:95]
	v_mfma_f32_16x16x32_bf16 v[88:91], v[192:195], v[236:239], v[88:91]
	v_mfma_f32_16x16x32_bf16 v[76:79], v[132:135], v[244:247], v[76:79]
	v_mfma_f32_16x16x32_bf16 v[72:75], v[192:195], v[244:247], v[72:75]
	v_mfma_f32_16x16x32_bf16 v[116:119], v[196:199], v[212:215], v[116:119]
	v_mfma_f32_16x16x32_bf16 v[112:115], v[204:207], v[212:215], v[112:115]
	v_mfma_f32_16x16x32_bf16 v[100:103], v[196:199], v[224:227], v[100:103]
	v_mfma_f32_16x16x32_bf16 v[96:99], v[204:207], v[224:227], v[96:99]
	v_mfma_f32_16x16x32_bf16 v[84:87], v[196:199], v[232:235], v[84:87]
	v_mfma_f32_16x16x32_bf16 v[80:83], v[204:207], v[232:235], v[80:83]
	v_mfma_f32_16x16x32_bf16 v[68:71], v[196:199], v[240:243], v[68:71]
	v_mfma_f32_16x16x32_bf16 v[64:67], v[204:207], v[240:243], v[64:67]
	v_mfma_f32_16x16x32_bf16 v[116:119], v[200:203], v[216:219], v[116:119]
	v_mfma_f32_16x16x32_bf16 v[112:115], v[208:211], v[216:219], v[112:115]
	v_mfma_f32_16x16x32_bf16 v[100:103], v[200:203], v[228:231], v[100:103]
	v_mfma_f32_16x16x32_bf16 v[96:99], v[208:211], v[228:231], v[96:99]
	v_mfma_f32_16x16x32_bf16 v[84:87], v[200:203], v[236:239], v[84:87]
	v_mfma_f32_16x16x32_bf16 v[80:83], v[208:211], v[236:239], v[80:83]
	v_mfma_f32_16x16x32_bf16 v[68:71], v[200:203], v[244:247], v[68:71]
	v_mfma_f32_16x16x32_bf16 v[64:67], v[208:211], v[244:247], v[64:67]
	s_setprio 0
	s_barrier
; #define PG8_STAGE(bufoff, gbase, voff) do { _Pragma("unroll") for (int _i = 0; _i < 2; ++_i) \
;         __builtin_amdgcn_global_load_lds((const unsigned*)((const char*)(gbase) + (voff)[_i]), (PG8_LAS unsigned*)(lds + (bufoff) + ldsw + _i * 8192), 16, 0, 0); } while (0)
; #define PG8_LDA(dst, b, h) do { _Pragma("unroll") for (int m = 0; m < 4; ++m) _Pragma("unroll") for (int k = 0; k < 2; ++k) dst[m][k] = *(const PG8_LAS bf16x8*)(lds + PG8_SA(b, h) + aoff + m * 2048 + k * 1024); } while (0)
; #define PG8_LDB(dst, b, h) do { _Pragma("unroll") for (int n = 0; n < 2; ++n) _Pragma("unroll") for (int k = 0; k < 2; ++k) dst[n][k] = *(const PG8_LAS bf16x8*)(lds + PG8_SB(b, h) + boff + n * 2048 + k * 1024); } while (0)
; #define PG8_WAIT_V(n) asm volatile("s_waitcnt vmcnt(" #n ")" ::: "memory")
; #define PG8_WAIT_L(n) asm volatile("s_waitcnt lgkmcnt(" #n ")" ::: "memory")
; #define PG8_BAR __builtin_amdgcn_s_barrier()
; template <class Epi, class Sched, bool ALIGN_EPI = false, bool SP2 = false>
; __device__ __forceinline__ void gemm_phase(PG8_LAS unsigned char* lds, const Gemm g, const Sched& S, const Epi& E) {
;     ...
;         for (int t = 0; t < nt; t += 2) {
;             const bool last = (t == nt - 2);
;             const char* a1 = cA + (size_t)(t + 1) * kstep;
;             const char* a2 = last ? nA : cA + (size_t)(t + 2) * kstep; const char* b2 = last ? nB : cB + (size_t)(t + 2) * kstep;
;             const char* a3 = a2 + kstep; const char* b3 = b2 + kstep;
;             if (last && has_next) S.a_ready(nxt);
;             if constexpr (SP2) {
;             PG8_LDB(B0, 0, 0); PG8_LDB(B1, 0, 1); PG8_SCHED; PG8_LDA(At, 0, 0); PG8_STAGE(PG8_SA(1, 1), a1 + hstep, voffA);
;             PG8_WAIT_V(8); PG8_WAIT_L(0); PG8_BAR; PG8_MMA(0, 0, At, B0); PG8_MMA(0, 1, At, B1); PG8_BAR; PG8_SCHED;
;             PG8_LDA(At, 0, 1); PG8_STAGE(PG8_SB(0, 0), b2, voffB); PG8_STAGE(PG8_SB(0, 1), b2 + hstep, voffB); PG8_STAGE(PG8_SA(0, 0), a2, voffA);
;             PG8_WAIT_V(8); PG8_WAIT_L(0); PG8_BAR; PG8_MMA(1, 0, At, B0); PG8_MMA(1, 1, At, B1); PG8_BAR; PG8_SCHED;
;     ...
;             PG8_LDA(At, 1, 1); PG8_STAGE(PG8_SB(1, 0), b3, voffB); PG8_STAGE(PG8_SB(1, 1), b3 + hstep, voffB); PG8_STAGE(PG8_SA(1, 0), a3, voffA);
;             PG8_WAIT_V(8); PG8_WAIT_L(0); PG8_BAR; PG8_MMA(1, 0, At, B0); PG8_MMA(1, 1, At, B1); PG8_BAR; PG8_SCHED;
	s_mov_b32 m0, s63
	v_lshl_add_u64 v[136:137], v[136:137], 0, s[40:41]
	s_add_u32 s66, s66, 0x40080
	ds_read_b128 v[212:215], v159 offset:49152
	ds_read_b128 v[216:219], v159 offset:50176
	ds_read_b128 v[224:227], v159 offset:51200
	ds_read_b128 v[228:231], v159 offset:52224
	ds_read_b128 v[232:235], v159 offset:53248
	ds_read_b128 v[236:239], v159 offset:54272
	ds_read_b128 v[240:243], v159 offset:55296
	ds_read_b128 v[244:247], v159 offset:56320
	global_load_lds_dwordx4 v[136:137], off
	v_lshl_add_u64 v[136:137], v[154:155], 0, s[40:41]
	s_mov_b32 m0, s65
	s_addc_u32 s67, s67, 0
	global_load_lds_dwordx4 v[136:137], off
	v_lshl_add_u64 v[136:137], s[66:67], 0, v[140:141]
	s_mov_b32 m0, s72
	s_nop 0
	global_load_lds_dwordx4 v[136:137], off
	v_lshl_add_u64 v[136:137], s[66:67], 0, v[144:145]
	s_mov_b32 m0, s73
	s_nop 0
	global_load_lds_dwordx4 v[136:137], off
	v_lshl_add_u64 v[136:137], v[220:221], 0, s[40:41]
	s_mov_b32 m0, s70
	s_nop 0
	global_load_lds_dwordx4 v[136:137], off
	v_lshl_add_u64 v[136:137], v[248:249], 0, s[40:41]
	s_mov_b32 m0, s71
	s_nop 0
	global_load_lds_dwordx4 v[136:137], off
	s_waitcnt vmcnt(8)
	s_waitcnt lgkmcnt(0)
	s_barrier
	s_setprio 1
	v_mfma_f32_16x16x32_bf16 v[60:63], v[128:131], v[212:215], v[60:63]
	v_mfma_f32_16x16x32_bf16 v[56:59], v[188:191], v[212:215], v[56:59]
	v_mfma_f32_16x16x32_bf16 v[44:47], v[128:131], v[224:227], v[44:47]
	v_mfma_f32_16x16x32_bf16 v[40:43], v[188:191], v[224:227], v[40:43]
	v_mfma_f32_16x16x32_bf16 v[28:31], v[128:131], v[232:235], v[28:31]
	v_mfma_f32_16x16x32_bf16 v[24:27], v[188:191], v[232:235], v[24:27]
	v_mfma_f32_16x16x32_bf16 v[12:15], v[128:131], v[240:243], v[12:15]
	v_mfma_f32_16x16x32_bf16 v[8:11], v[188:191], v[240:243], v[8:11]
	v_mfma_f32_16x16x32_bf16 v[60:63], v[132:135], v[216:219], v[60:63]
	v_mfma_f32_16x16x32_bf16 v[56:59], v[192:195], v[216:219], v[56:59]
	v_mfma_f32_16x16x32_bf16 v[44:47], v[132:135], v[228:231], v[44:47]
	v_mfma_f32_16x16x32_bf16 v[40:43], v[192:195], v[228:231], v[40:43]
	v_mfma_f32_16x16x32_bf16 v[28:31], v[132:135], v[236:239], v[28:31]
	v_mfma_f32_16x16x32_bf16 v[24:27], v[192:195], v[236:239], v[24:27]
	v_mfma_f32_16x16x32_bf16 v[12:15], v[132:135], v[244:247], v[12:15]
	v_mfma_f32_16x16x32_bf16 v[8:11], v[192:195], v[244:247], v[8:11]
	v_mfma_f32_16x16x32_bf16 v[52:55], v[196:199], v[212:215], v[52:55]
	v_mfma_f32_16x16x32_bf16 v[48:51], v[204:207], v[212:215], v[48:51]
	v_mfma_f32_16x16x32_bf16 v[36:39], v[196:199], v[224:227], v[36:39]
	v_mfma_f32_16x16x32_bf16 v[32:35], v[204:207], v[224:227], v[32:35]
	v_mfma_f32_16x16x32_bf16 v[20:23], v[196:199], v[232:235], v[20:23]
	v_mfma_f32_16x16x32_bf16 v[16:19], v[204:207], v[232:235], v[16:19]
	v_mfma_f32_16x16x32_bf16 v[4:7], v[196:199], v[240:243], v[4:7]
	v_mfma_f32_16x16x32_bf16 v[0:3], v[204:207], v[240:243], v[0:3]
	v_mfma_f32_16x16x32_bf16 v[52:55], v[200:203], v[216:219], v[52:55]
	v_mfma_f32_16x16x32_bf16 v[48:51], v[208:211], v[216:219], v[48:51]
	v_mfma_f32_16x16x32_bf16 v[36:39], v[200:203], v[228:231], v[36:39]
	v_mfma_f32_16x16x32_bf16 v[32:35], v[208:211], v[228:231], v[32:35]
	v_mfma_f32_16x16x32_bf16 v[20:23], v[200:203], v[236:239], v[20:23]
	v_mfma_f32_16x16x32_bf16 v[16:19], v[208:211], v[236:239], v[16:19]
	v_mfma_f32_16x16x32_bf16 v[4:7], v[200:203], v[244:247], v[4:7]
	v_mfma_f32_16x16x32_bf16 v[0:3], v[208:211], v[244:247], v[0:3]
	s_setprio 0
	s_barrier
	s_add_i32 s83, s83, 2
	s_add_u32 s10, s10, 0x100
	s_addc_u32 s11, s11, 0
	s_add_u32 s81, s81, 0x100
	s_addc_u32 s82, s82, 0
.LBB0_1030:
	ds_read_b128 v[128:131], v171
	ds_read_b128 v[132:135], v172
	ds_read_b128 v[188:191], v173
	ds_read_b128 v[192:195], v174
	ds_read_b128 v[196:199], v175
	ds_read_b128 v[200:203], v176
	ds_read_b128 v[204:207], v177
	ds_read_b128 v[208:211], v178
	s_add_u32 s66, s10, 0xfffc0080
	s_addc_u32 s67, s11, -1
	s_cmp_eq_u32 s83, 12
	s_cselect_b32 s69, s33, s67
	s_cselect_b32 s68, s57, s66
	s_cselect_b32 s67, s55, s82
	s_cselect_b32 s66, s80, s81
	s_mov_b32 m0, s77
	v_lshl_add_u64 v[136:137], s[10:11], 0, v[146:147]
	ds_read_b128 v[212:215], v159
	ds_read_b128 v[216:219], v159 offset:1024
	ds_read_b128 v[224:227], v159 offset:2048
	ds_read_b128 v[228:231], v159 offset:3072
	ds_read_b128 v[232:235], v159 offset:4096
	ds_read_b128 v[236:239], v159 offset:5120
	ds_read_b128 v[240:243], v159 offset:6144
	ds_read_b128 v[244:247], v159 offset:7168
	global_load_lds_dwordx4 v[136:137], off
	v_lshl_add_u64 v[136:137], s[10:11], 0, v[148:149]
	s_mov_b32 m0, s78
	s_nop 0
	global_load_lds_dwordx4 v[136:137], off
	s_waitcnt vmcnt(8)
	s_waitcnt lgkmcnt(0)
	s_barrier
; #define PG8_STAGE(bufoff, gbase, voff) do { _Pragma("unroll") for (int _i = 0; _i < 2; ++_i) \
;         __builtin_amdgcn_global_load_lds((const unsigned*)((const char*)(gbase) + (voff)[_i]), (PG8_LAS unsigned*)(lds + (bufoff) + ldsw + _i * 8192), 16, 0, 0); } while (0)
; #define PG8_LDA(dst, b, h) do { _Pragma("unroll") for (int m = 0; m < 4; ++m) _Pragma("unroll") for (int k = 0; k < 2; ++k) dst[m][k] = *(const PG8_LAS bf16x8*)(lds + PG8_SA(b, h) + aoff + m * 2048 + k * 1024); } while (0)
; #define PG8_MMA(ai, bj, At, Bt) do { __builtin_amdgcn_s_setprio(1); _Pragma("unroll") for (int m = 0; m < 4; ++m) _Pragma("unroll") for (int n = 0; n < 2; ++n) _Pragma("unroll") for (int k = 0; k < 2; ++k) \
;         acc[ai][bj][m][n] = __builtin_amdgcn_mfma_f32_16x16x32_bf16(Bt[n][k], At[m][k], acc[ai][bj][m][n], 0, 0, 0); __builtin_amdgcn_s_setprio(0); } while (0)
; #define PG8_WAIT_V(n) asm volatile("s_waitcnt vmcnt(" #n ")" ::: "memory")
; #define PG8_WAIT_L(n) asm volatile("s_waitcnt lgkmcnt(" #n ")" ::: "memory")
; #define PG8_BAR __builtin_amdgcn_s_barrier()
; #define PG8_SCHED __builtin_amdgcn_sched_barrier(0)
; template <class Epi, class Sched, bool ALIGN_EPI = false, bool SP2 = false>
; __device__ __forceinline__ void gemm_phase(PG8_LAS unsigned char* lds, const Gemm g, const Sched& S, const Epi& E) {
;     ...
;             PG8_WAIT_V(8); PG8_WAIT_L(0); PG8_BAR; PG8_MMA(0, 0, At, B0); PG8_MMA(0, 1, At, B1); PG8_BAR; PG8_SCHED;
;             PG8_LDA(At, 0, 1); PG8_STAGE(PG8_SB(0, 0), b2, voffB); PG8_STAGE(PG8_SB(0, 1), b2 + hstep, voffB); PG8_STAGE(PG8_SA(0, 0), a2, voffA);
;             PG8_WAIT_V(8); PG8_WAIT_L(0); PG8_BAR; PG8_MMA(1, 0, At, B0); PG8_MMA(1, 1, At, B1); PG8_BAR; PG8_SCHED;
	s_setprio 1
	v_mfma_f32_16x16x32_bf16 v[124:127], v[128:131], v[212:215], v[124:127]
	v_mfma_f32_16x16x32_bf16 v[120:123], v[188:191], v[212:215], v[120:123]
	v_mfma_f32_16x16x32_bf16 v[108:111], v[128:131], v[224:227], v[108:111]
	v_mfma_f32_16x16x32_bf16 v[104:107], v[188:191], v[224:227], v[104:107]
	v_mfma_f32_16x16x32_bf16 v[92:95], v[128:131], v[232:235], v[92:95]
	v_mfma_f32_16x16x32_bf16 v[88:91], v[188:191], v[232:235], v[88:91]
	v_mfma_f32_16x16x32_bf16 v[76:79], v[128:131], v[240:243], v[76:79]
	v_mfma_f32_16x16x32_bf16 v[72:75], v[188:191], v[240:243], v[72:75]
	v_mfma_f32_16x16x32_bf16 v[124:127], v[132:135], v[216:219], v[124:127]
	v_mfma_f32_16x16x32_bf16 v[120:123], v[192:195], v[216:219], v[120:123]
	v_mfma_f32_16x16x32_bf16 v[108:111], v[132:135], v[228:231], v[108:111]
	v_mfma_f32_16x16x32_bf16 v[104:107], v[192:195], v[228:231], v[104:107]
	v_mfma_f32_16x16x32_bf16 v[92:95], v[132:135], v[236:239], v[92:95]
	v_mfma_f32_16x16x32_bf16 v[88:91], v[192:195], v[236:239], v[88:91]
	v_mfma_f32_16x16x32_bf16 v[76:79], v[132:135], v[244:247], v[76:79]
	v_mfma_f32_16x16x32_bf16 v[72:75], v[192:195], v[244:247], v[72:75]
	v_mfma_f32_16x16x32_bf16 v[116:119], v[196:199], v[212:215], v[116:119]
	v_mfma_f32_16x16x32_bf16 v[112:115], v[204:207], v[212:215], v[112:115]
	v_mfma_f32_16x16x32_bf16 v[100:103], v[196:199], v[224:227], v[100:103]
	v_mfma_f32_16x16x32_bf16 v[96:99], v[204:207], v[224:227], v[96:99]
	v_mfma_f32_16x16x32_bf16 v[84:87], v[196:199], v[232:235], v[84:87]
	v_mfma_f32_16x16x32_bf16 v[80:83], v[204:207], v[232:235], v[80:83]
	v_mfma_f32_16x16x32_bf16 v[68:71], v[196:199], v[240:243], v[68:71]
	v_mfma_f32_16x16x32_bf16 v[64:67], v[204:207], v[240:243], v[64:67]
	v_mfma_f32_16x16x32_bf16 v[116:119], v[200:203], v[216:219], v[116:119]
	v_mfma_f32_16x16x32_bf16 v[112:115], v[208:211], v[216:219], v[112:115]
	v_mfma_f32_16x16x32_bf16 v[100:103], v[200:203], v[228:231], v[100:103]
	v_mfma_f32_16x16x32_bf16 v[96:99], v[208:211], v[228:231], v[96:99]
	v_mfma_f32_16x16x32_bf16 v[84:87], v[200:203], v[236:239], v[84:87]
	v_mfma_f32_16x16x32_bf16 v[80:83], v[208:211], v[236:239], v[80:83]
	v_mfma_f32_16x16x32_bf16 v[68:71], v[200:203], v[244:247], v[68:71]
	v_mfma_f32_16x16x32_bf16 v[64:67], v[208:211], v[244:247], v[64:67]
	s_setprio 0
	s_barrier
	s_mov_b32 m0, s5
	v_lshl_add_u64 v[136:137], s[66:67], 0, v[140:141]
	s_add_u32 s84, s66, 0x40000
	ds_read_b128 v[212:215], v159 offset:16384
	ds_read_b128 v[216:219], v159 offset:17408
	ds_read_b128 v[224:227], v159 offset:18432
	ds_read_b128 v[228:231], v159 offset:19456
	ds_read_b128 v[232:235], v159 offset:20480
	ds_read_b128 v[236:239], v159 offset:21504
	ds_read_b128 v[240:243], v159 offset:22528
	ds_read_b128 v[244:247], v159 offset:23552
	global_load_lds_dwordx4 v[136:137], off
	v_lshl_add_u64 v[154:155], s[66:67], 0, v[144:145]
	s_mov_b32 m0, s12
	s_addc_u32 s85, s67, 0
	global_load_lds_dwordx4 v[154:155], off
	v_lshl_add_u64 v[220:221], s[84:85], 0, v[140:141]
	s_mov_b32 m0, s13
	v_lshl_add_u64 v[248:249], s[68:69], 0, v[142:143]
	global_load_lds_dwordx4 v[220:221], off
	v_lshl_add_u64 v[220:221], s[84:85], 0, v[144:145]
	s_mov_b32 m0, s14
	s_nop 0
	global_load_lds_dwordx4 v[220:221], off
	v_lshl_add_u64 v[220:221], s[68:69], 0, v[138:139]
	s_mov_b32 m0, s4
	s_nop 0
	global_load_lds_dwordx4 v[220:221], off
	s_mov_b32 m0, s15
	s_nop 0
	global_load_lds_dwordx4 v[248:249], off
	s_waitcnt vmcnt(8)
	s_waitcnt lgkmcnt(0)
	s_barrier
	s_setprio 1
	v_mfma_f32_16x16x32_bf16 v[60:63], v[128:131], v[212:215], v[60:63]
	v_mfma_f32_16x16x32_bf16 v[56:59], v[188:191], v[212:215], v[56:59]
	v_mfma_f32_16x16x32_bf16 v[44:47], v[128:131], v[224:227], v[44:47]
	v_mfma_f32_16x16x32_bf16 v[40:43], v[188:191], v[224:227], v[40:43]
	v_mfma_f32_16x16x32_bf16 v[28:31], v[128:131], v[232:235], v[28:31]
	v_mfma_f32_16x16x32_bf16 v[24:27], v[188:191], v[232:235], v[24:27]
	v_mfma_f32_16x16x32_bf16 v[12:15], v[128:131], v[240:243], v[12:15]
	v_mfma_f32_16x16x32_bf16 v[8:11], v[188:191], v[240:243], v[8:11]
	v_mfma_f32_16x16x32_bf16 v[60:63], v[132:135], v[216:219], v[60:63]
	v_mfma_f32_16x16x32_bf16 v[56:59], v[192:195], v[216:219], v[56:59]
	v_mfma_f32_16x16x32_bf16 v[44:47], v[132:135], v[228:231], v[44:47]
	v_mfma_f32_16x16x32_bf16 v[40:43], v[192:195], v[228:231], v[40:43]
	v_mfma_f32_16x16x32_bf16 v[28:31], v[132:135], v[236:239], v[28:31]
	v_mfma_f32_16x16x32_bf16 v[24:27], v[192:195], v[236:239], v[24:27]
	v_mfma_f32_16x16x32_bf16 v[12:15], v[132:135], v[244:247], v[12:15]
	v_mfma_f32_16x16x32_bf16 v[8:11], v[192:195], v[244:247], v[8:11]
	v_mfma_f32_16x16x32_bf16 v[52:55], v[196:199], v[212:215], v[52:55]
	v_mfma_f32_16x16x32_bf16 v[48:51], v[204:207], v[212:215], v[48:51]
	v_mfma_f32_16x16x32_bf16 v[36:39], v[196:199], v[224:227], v[36:39]
	v_mfma_f32_16x16x32_bf16 v[32:35], v[204:207], v[224:227], v[32:35]
	v_mfma_f32_16x16x32_bf16 v[20:23], v[196:199], v[232:235], v[20:23]
	v_mfma_f32_16x16x32_bf16 v[16:19], v[204:207], v[232:235], v[16:19]
	v_mfma_f32_16x16x32_bf16 v[4:7], v[196:199], v[240:243], v[4:7]
	v_mfma_f32_16x16x32_bf16 v[0:3], v[204:207], v[240:243], v[0:3]
	v_mfma_f32_16x16x32_bf16 v[52:55], v[200:203], v[216:219], v[52:55]
	v_mfma_f32_16x16x32_bf16 v[48:51], v[208:211], v[216:219], v[48:51]
	v_mfma_f32_16x16x32_bf16 v[36:39], v[200:203], v[228:231], v[36:39]
	v_mfma_f32_16x16x32_bf16 v[32:35], v[208:211], v[228:231], v[32:35]
	v_mfma_f32_16x16x32_bf16 v[20:23], v[200:203], v[236:239], v[20:23]
	v_mfma_f32_16x16x32_bf16 v[16:19], v[208:211], v[236:239], v[16:19]
	v_mfma_f32_16x16x32_bf16 v[4:7], v[200:203], v[244:247], v[4:7]
	v_mfma_f32_16x16x32_bf16 v[0:3], v[208:211], v[244:247], v[0:3]
	s_setprio 0
	s_barrier
; #define PG8_STAGE(bufoff, gbase, voff) do { _Pragma("unroll") for (int _i = 0; _i < 2; ++_i) \
;         __builtin_amdgcn_global_load_lds((const unsigned*)((const char*)(gbase) + (voff)[_i]), (PG8_LAS unsigned*)(lds + (bufoff) + ldsw + _i * 8192), 16, 0, 0); } while (0)
; #define PG8_LDA(dst, b, h) do { _Pragma("unroll") for (int m = 0; m < 4; ++m) _Pragma("unroll") for (int k = 0; k < 2; ++k) dst[m][k] = *(const PG8_LAS bf16x8*)(lds + PG8_SA(b, h) + aoff + m * 2048 + k * 1024); } while (0)
; #define PG8_LDB(dst, b, h) do { _Pragma("unroll") for (int n = 0; n < 2; ++n) _Pragma("unroll") for (int k = 0; k < 2; ++k) dst[n][k] = *(const PG8_LAS bf16x8*)(lds + PG8_SB(b, h) + boff + n * 2048 + k * 1024); } while (0)
; #define PG8_MMA(ai, bj, At, Bt) do { __builtin_amdgcn_s_setprio(1); _Pragma("unroll") for (int m = 0; m < 4; ++m) _Pragma("unroll") for (int n = 0; n < 2; ++n) _Pragma("unroll") for (int k = 0; k < 2; ++k) \
;         acc[ai][bj][m][n] = __builtin_amdgcn_mfma_f32_16x16x32_bf16(Bt[n][k], At[m][k], acc[ai][bj][m][n], 0, 0, 0); __builtin_amdgcn_s_setprio(0); } while (0)
; #define PG8_WAIT_V(n) asm volatile("s_waitcnt vmcnt(" #n ")" ::: "memory")
; #define PG8_WAIT_L(n) asm volatile("s_waitcnt lgkmcnt(" #n ")" ::: "memory")
; #define PG8_BAR __builtin_amdgcn_s_barrier()
; #define PG8_SCHED __builtin_amdgcn_sched_barrier(0)
; template <class Epi, class Sched, bool ALIGN_EPI = false, bool SP2 = false>
; __device__ __forceinline__ void gemm_phase(PG8_LAS unsigned char* lds, const Gemm g, const Sched& S, const Epi& E) {
;     ...
;         for (int t = 0; t < nt; t += 2) {
;     ...
;             PG8_LDB(B0, 1, 0); PG8_LDB(B1, 1, 1); PG8_SCHED; PG8_LDA(At, 1, 0); PG8_STAGE(PG8_SA(0, 1), a2 + hstep, voffA);
;             PG8_WAIT_V(8); PG8_WAIT_L(0); PG8_BAR; PG8_MMA(0, 0, At, B0); PG8_MMA(0, 1, At, B1); PG8_BAR; PG8_SCHED;
;             PG8_LDA(At, 1, 1); PG8_STAGE(PG8_SB(1, 0), b3, voffB); PG8_STAGE(PG8_SB(1, 1), b3 + hstep, voffB); PG8_STAGE(PG8_SA(1, 0), a3, voffA);
;             PG8_WAIT_V(8); PG8_WAIT_L(0); PG8_BAR; PG8_MMA(1, 0, At, B0); PG8_MMA(1, 1, At, B1); PG8_BAR; PG8_SCHED;
	ds_read_b128 v[128:131], v179
	ds_read_b128 v[132:135], v180
	ds_read_b128 v[188:191], v181
	ds_read_b128 v[192:195], v182
	ds_read_b128 v[196:199], v183
	ds_read_b128 v[200:203], v184
	ds_read_b128 v[204:207], v185
	ds_read_b128 v[208:211], v186
	s_add_u32 s68, s68, 0x40000
	s_addc_u32 s69, s69, 0
	s_mov_b32 m0, s39
	v_lshl_add_u64 v[250:251], s[68:69], 0, v[138:139]
	ds_read_b128 v[212:215], v159 offset:32768
	ds_read_b128 v[216:219], v159 offset:33792
	ds_read_b128 v[224:227], v159 offset:34816
	ds_read_b128 v[228:231], v159 offset:35840
	ds_read_b128 v[232:235], v159 offset:36864
	ds_read_b128 v[236:239], v159 offset:37888
	ds_read_b128 v[240:243], v159 offset:38912
	ds_read_b128 v[244:247], v159 offset:39936
	global_load_lds_dwordx4 v[250:251], off
	v_lshl_add_u64 v[250:251], s[68:69], 0, v[142:143]
	s_mov_b32 m0, s43
	s_nop 0
	global_load_lds_dwordx4 v[250:251], off
	s_waitcnt vmcnt(8)
	s_waitcnt lgkmcnt(0)
	s_barrier
	s_setprio 1
	v_mfma_f32_16x16x32_bf16 v[124:127], v[128:131], v[212:215], v[124:127]
	v_mfma_f32_16x16x32_bf16 v[120:123], v[188:191], v[212:215], v[120:123]
	v_mfma_f32_16x16x32_bf16 v[108:111], v[128:131], v[224:227], v[108:111]
	v_mfma_f32_16x16x32_bf16 v[104:107], v[188:191], v[224:227], v[104:107]
	v_mfma_f32_16x16x32_bf16 v[92:95], v[128:131], v[232:235], v[92:95]
	v_mfma_f32_16x16x32_bf16 v[88:91], v[188:191], v[232:235], v[88:91]
	v_mfma_f32_16x16x32_bf16 v[76:79], v[128:131], v[240:243], v[76:79]
	v_mfma_f32_16x16x32_bf16 v[72:75], v[188:191], v[240:243], v[72:75]
	v_mfma_f32_16x16x32_bf16 v[124:127], v[132:135], v[216:219], v[124:127]
	v_mfma_f32_16x16x32_bf16 v[120:123], v[192:195], v[216:219], v[120:123]
	v_mfma_f32_16x16x32_bf16 v[108:111], v[132:135], v[228:231], v[108:111]
	v_mfma_f32_16x16x32_bf16 v[104:107], v[192:195], v[228:231], v[104:107]
	v_mfma_f32_16x16x32_bf16 v[92:95], v[132:135], v[236:239], v[92:95]
	v_mfma_f32_16x16x32_bf16 v[88:91], v[192:195], v[236:239], v[88:91]
	v_mfma_f32_16x16x32_bf16 v[76:79], v[132:135], v[244:247], v[76:79]
	v_mfma_f32_16x16x32_bf16 v[72:75], v[192:195], v[244:247], v[72:75]
	v_mfma_f32_16x16x32_bf16 v[116:119], v[196:199], v[212:215], v[116:119]
	v_mfma_f32_16x16x32_bf16 v[112:115], v[204:207], v[212:215], v[112:115]
	v_mfma_f32_16x16x32_bf16 v[100:103], v[196:199], v[224:227], v[100:103]
	v_mfma_f32_16x16x32_bf16 v[96:99], v[204:207], v[224:227], v[96:99]
	v_mfma_f32_16x16x32_bf16 v[84:87], v[196:199], v[232:235], v[84:87]
	v_mfma_f32_16x16x32_bf16 v[80:83], v[204:207], v[232:235], v[80:83]
	v_mfma_f32_16x16x32_bf16 v[68:71], v[196:199], v[240:243], v[68:71]
	v_mfma_f32_16x16x32_bf16 v[64:67], v[204:207], v[240:243], v[64:67]
	v_mfma_f32_16x16x32_bf16 v[116:119], v[200:203], v[216:219], v[116:119]
	v_mfma_f32_16x16x32_bf16 v[112:115], v[208:211], v[216:219], v[112:115]
	v_mfma_f32_16x16x32_bf16 v[100:103], v[200:203], v[228:231], v[100:103]
	v_mfma_f32_16x16x32_bf16 v[96:99], v[208:211], v[228:231], v[96:99]
	v_mfma_f32_16x16x32_bf16 v[84:87], v[200:203], v[236:239], v[84:87]
	v_mfma_f32_16x16x32_bf16 v[80:83], v[208:211], v[236:239], v[80:83]
	v_mfma_f32_16x16x32_bf16 v[68:71], v[200:203], v[244:247], v[68:71]
	v_mfma_f32_16x16x32_bf16 v[64:67], v[208:211], v[244:247], v[64:67]
	s_setprio 0
	s_barrier
	s_mov_b32 m0, s63
	v_lshl_add_u64 v[136:137], v[136:137], 0, s[40:41]
	s_add_u32 s66, s66, 0x40080
	ds_read_b128 v[212:215], v159 offset:49152
	ds_read_b128 v[216:219], v159 offset:50176
	ds_read_b128 v[224:227], v159 offset:51200
	ds_read_b128 v[228:231], v159 offset:52224
	ds_read_b128 v[232:235], v159 offset:53248
	ds_read_b128 v[236:239], v159 offset:54272
	ds_read_b128 v[240:243], v159 offset:55296
	ds_read_b128 v[244:247], v159 offset:56320
	global_load_lds_dwordx4 v[136:137], off
	v_lshl_add_u64 v[136:137], v[154:155], 0, s[40:41]
	s_mov_b32 m0, s65
	s_addc_u32 s67, s67, 0
	global_load_lds_dwordx4 v[136:137], off
	v_lshl_add_u64 v[136:137], s[66:67], 0, v[140:141]
	s_mov_b32 m0, s72
	s_nop 0
	global_load_lds_dwordx4 v[136:137], off
	v_lshl_add_u64 v[136:137], s[66:67], 0, v[144:145]
	s_mov_b32 m0, s73
	s_nop 0
	global_load_lds_dwordx4 v[136:137], off
	v_lshl_add_u64 v[136:137], v[220:221], 0, s[40:41]
	s_mov_b32 m0, s70
	s_nop 0
	global_load_lds_dwordx4 v[136:137], off
	v_lshl_add_u64 v[136:137], v[248:249], 0, s[40:41]
	s_mov_b32 m0, s71
	s_nop 0
	global_load_lds_dwordx4 v[136:137], off
	s_waitcnt vmcnt(8)
	s_waitcnt lgkmcnt(0)
	s_barrier
	s_setprio 1
	v_mfma_f32_16x16x32_bf16 v[60:63], v[128:131], v[212:215], v[60:63]
	v_mfma_f32_16x16x32_bf16 v[56:59], v[188:191], v[212:215], v[56:59]
	v_mfma_f32_16x16x32_bf16 v[44:47], v[128:131], v[224:227], v[44:47]
	v_mfma_f32_16x16x32_bf16 v[40:43], v[188:191], v[224:227], v[40:43]
	v_mfma_f32_16x16x32_bf16 v[28:31], v[128:131], v[232:235], v[28:31]
	v_mfma_f32_16x16x32_bf16 v[24:27], v[188:191], v[232:235], v[24:27]
	v_mfma_f32_16x16x32_bf16 v[12:15], v[128:131], v[240:243], v[12:15]
	v_mfma_f32_16x16x32_bf16 v[8:11], v[188:191], v[240:243], v[8:11]
	v_mfma_f32_16x16x32_bf16 v[60:63], v[132:135], v[216:219], v[60:63]
	v_mfma_f32_16x16x32_bf16 v[56:59], v[192:195], v[216:219], v[56:59]
	v_mfma_f32_16x16x32_bf16 v[44:47], v[132:135], v[228:231], v[44:47]
	v_mfma_f32_16x16x32_bf16 v[40:43], v[192:195], v[228:231], v[40:43]
	v_mfma_f32_16x16x32_bf16 v[28:31], v[132:135], v[236:239], v[28:31]
	v_mfma_f32_16x16x32_bf16 v[24:27], v[192:195], v[236:239], v[24:27]
	v_mfma_f32_16x16x32_bf16 v[12:15], v[132:135], v[244:247], v[12:15]
	v_mfma_f32_16x16x32_bf16 v[8:11], v[192:195], v[244:247], v[8:11]
	v_mfma_f32_16x16x32_bf16 v[52:55], v[196:199], v[212:215], v[52:55]
	v_mfma_f32_16x16x32_bf16 v[48:51], v[204:207], v[212:215], v[48:51]
	v_mfma_f32_16x16x32_bf16 v[36:39], v[196:199], v[224:227], v[36:39]
	v_mfma_f32_16x16x32_bf16 v[32:35], v[204:207], v[224:227], v[32:35]
	v_mfma_f32_16x16x32_bf16 v[20:23], v[196:199], v[232:235], v[20:23]
	v_mfma_f32_16x16x32_bf16 v[16:19], v[204:207], v[232:235], v[16:19]
	v_mfma_f32_16x16x32_bf16 v[4:7], v[196:199], v[240:243], v[4:7]
	v_mfma_f32_16x16x32_bf16 v[0:3], v[204:207], v[240:243], v[0:3]
	v_mfma_f32_16x16x32_bf16 v[52:55], v[200:203], v[216:219], v[52:55]
	v_mfma_f32_16x16x32_bf16 v[48:51], v[208:211], v[216:219], v[48:51]
	v_mfma_f32_16x16x32_bf16 v[36:39], v[200:203], v[228:231], v[36:39]
	v_mfma_f32_16x16x32_bf16 v[32:35], v[208:211], v[228:231], v[32:35]
	v_mfma_f32_16x16x32_bf16 v[20:23], v[200:203], v[236:239], v[20:23]
	v_mfma_f32_16x16x32_bf16 v[16:19], v[208:211], v[236:239], v[16:19]
	v_mfma_f32_16x16x32_bf16 v[4:7], v[200:203], v[244:247], v[4:7]
	v_mfma_f32_16x16x32_bf16 v[0:3], v[208:211], v[244:247], v[0:3]
	s_setprio 0
	s_barrier
	s_add_i32 s83, s83, 2
	s_add_u32 s10, s10, 0x100
	s_addc_u32 s11, s11, 0
	s_add_u32 s81, s81, 0x100
	s_addc_u32 s82, s82, 0
	s_cmp_gt_u32 s83, 13
	s_cbranch_scc0 .LBB0_1030
	s_and_b64 vcc, exec, s[52:53]
	s_cbranch_vccz .LBB0_1033
	s_barrier

;     __host__ __device__ bool next(int i, Unit& u) const { const int L = i * G + c; if (L >= 16 * nkc) return false; u.kc = L % nkc; const int t = L / nkc; u.pn = t & 3; u.pm = 33 * (t >> 2); return true; }
; #define PG8_STAGE(bufoff, gbase, voff) do { _Pragma("unroll") for (int _i = 0; _i < 2; ++_i) \
;         __builtin_amdgcn_global_load_lds((const unsigned*)((const char*)(gbase) + (voff)[_i]), (PG8_LAS unsigned*)(lds + (bufoff) + ldsw + _i * 8192), 16, 0, 0); } while (0)
; #define PG8_LDA(dst, b, h) do { _Pragma("unroll") for (int m = 0; m < 4; ++m) _Pragma("unroll") for (int k = 0; k < 2; ++k) dst[m][k] = *(const PG8_LAS bf16x8*)(lds + PG8_SA(b, h) + aoff + m * 2048 + k * 1024); } while (0)
; #define PG8_LDB(dst, b, h) do { _Pragma("unroll") for (int n = 0; n < 2; ++n) _Pragma("unroll") for (int k = 0; k < 2; ++k) dst[n][k] = *(const PG8_LAS bf16x8*)(lds + PG8_SB(b, h) + boff + n * 2048 + k * 1024); } while (0)
; #define PG8_BAR __builtin_amdgcn_s_barrier()
; template <class Epi, class Sched, bool ALIGN_EPI = false, bool SP2 = false>
; __device__ __forceinline__ void gemm_phase(PG8_LAS unsigned char* lds, const Gemm g, const Sched& S, const Epi& E) {
;     ...
;         const bool has_next = S.next(ui + 1, nxt);
;         const char* nA = has_next ? (const char*)g.A + (size_t)nxt.pm * tstep + (size_t)nxt.kc * cstep : cA; const char* nB = has_next ? (const char*)g.Bt + (size_t)nxt.pn * tstep + (size_t)nxt.kc * cstep : cB;
;         for (int t = 0; t < nt; t += 2) {
;             const bool last = (t == nt - 2);
;             const char* a1 = cA + (size_t)(t + 1) * kstep;
;             const char* a2 = last ? nA : cA + (size_t)(t + 2) * kstep; const char* b2 = last ? nB : cB + (size_t)(t + 2) * kstep;
;             const char* a3 = a2 + kstep; const char* b3 = b2 + kstep;
;             if (last && has_next) S.a_ready(nxt);
;             if constexpr (SP2) {
;             PG8_LDB(B0, 0, 0); PG8_LDB(B1, 0, 1); PG8_SCHED; PG8_LDA(At, 0, 0); PG8_STAGE(PG8_SA(1, 1), a1 + hstep, voffA);
;             PG8_WAIT_V(8); PG8_WAIT_L(0); PG8_BAR; PG8_MMA(0, 0, At, B0); PG8_MMA(0, 1, At, B1); PG8_BAR; PG8_SCHED;
;             PG8_LDA(At, 0, 1); PG8_STAGE(PG8_SB(0, 0), b2, voffB); PG8_STAGE(PG8_SB(0, 1), b2 + hstep, voffB); PG8_STAGE(PG8_SA(0, 0), a2, voffA);
;             PG8_WAIT_V(8); PG8_WAIT_L(0); PG8_BAR; PG8_MMA(1, 0, At, B0); PG8_MMA(1, 1, At, B1); PG8_BAR; PG8_SCHED;
.LBB0_1306:
	s_ashr_i32 s21, s20, 31
	s_lshl_b64 s[22:23], s[20:21], 19
	s_add_u32 s22, s46, s22
	s_addc_u32 s23, s47, s23
	s_and_b64 s[24:25], s[6:7], exec
	s_cselect_b32 s21, s23, s41
	s_cselect_b32 s37, s22, s40
	s_ashr_i32 s19, s18, 31
	s_lshl_b64 s[24:25], s[18:19], 19
	s_add_u32 s24, s3, s24
	s_addc_u32 s25, s4, s25
	s_and_b64 s[52:53], s[6:7], exec
	s_cselect_b32 s19, s25, s51
	s_cselect_b32 s76, s24, s50
	s_add_u32 s77, s50, 0x100
	s_addc_u32 s78, s51, 0
	s_mov_b32 s79, -2
	ds_read_b128 v[142:145], v174
	ds_read_b128 v[146:149], v175
	ds_read_b128 v[150:153], v176
	ds_read_b128 v[154:157], v177
	ds_read_b128 v[158:161], v178
	ds_read_b128 v[162:165], v179
	ds_read_b128 v[166:169], v180
	ds_read_b128 v[190:193], v181
	s_add_u32 s50, s40, 0x100
	s_addc_u32 s51, s41, 0
	s_cmp_eq_u32 s79, 12
	s_cselect_b32 s55, s21, s51
	s_cselect_b32 s54, s37, s50
	s_cselect_b32 s53, s19, s78
	s_cselect_b32 s52, s76, s77
	s_mov_b32 m0, s68
	v_lshl_add_u64 v[170:171], s[40:41], 0, v[134:135]
	ds_read_b128 v[194:197], v172
	ds_read_b128 v[198:201], v172 offset:1024
	ds_read_b128 v[202:205], v172 offset:2048
	ds_read_b128 v[206:209], v172 offset:3072
	ds_read_b128 v[210:213], v172 offset:4096
	ds_read_b128 v[214:217], v172 offset:5120
	ds_read_b128 v[218:221], v172 offset:6144
	ds_read_b128 v[224:227], v172 offset:7168
	global_load_lds_dwordx4 v[170:171], off
	v_lshl_add_u64 v[170:171], s[40:41], 0, v[136:137]
	s_mov_b32 m0, s69
	s_nop 0
	global_load_lds_dwordx4 v[170:171], off
	s_waitcnt vmcnt(8)
	s_waitcnt lgkmcnt(0)
	s_barrier
	s_setprio 1
	v_mfma_f32_16x16x32_bf16 v[124:127], v[142:145], v[194:197], 0
	v_mfma_f32_16x16x32_bf16 v[108:111], v[150:153], v[194:197], 0
	v_mfma_f32_16x16x32_bf16 v[120:123], v[142:145], v[202:205], 0
	v_mfma_f32_16x16x32_bf16 v[96:99], v[150:153], v[202:205], 0
	v_mfma_f32_16x16x32_bf16 v[116:119], v[142:145], v[210:213], 0
	v_mfma_f32_16x16x32_bf16 v[88:91], v[150:153], v[210:213], 0
	v_mfma_f32_16x16x32_bf16 v[112:115], v[142:145], v[218:221], 0
	v_mfma_f32_16x16x32_bf16 v[84:87], v[150:153], v[218:221], 0
	v_mfma_f32_16x16x32_bf16 v[124:127], v[146:149], v[198:201], v[124:127]
	v_mfma_f32_16x16x32_bf16 v[108:111], v[154:157], v[198:201], v[108:111]
	v_mfma_f32_16x16x32_bf16 v[120:123], v[146:149], v[206:209], v[120:123]
	v_mfma_f32_16x16x32_bf16 v[96:99], v[154:157], v[206:209], v[96:99]
	v_mfma_f32_16x16x32_bf16 v[116:119], v[146:149], v[214:217], v[116:119]
	v_mfma_f32_16x16x32_bf16 v[88:91], v[154:157], v[214:217], v[88:91]
	v_mfma_f32_16x16x32_bf16 v[112:115], v[146:149], v[224:227], v[112:115]
	v_mfma_f32_16x16x32_bf16 v[84:87], v[154:157], v[224:227], v[84:87]
	v_mfma_f32_16x16x32_bf16 v[68:71], v[158:161], v[194:197], 0
	v_mfma_f32_16x16x32_bf16 v[40:43], v[166:169], v[194:197], 0
	v_mfma_f32_16x16x32_bf16 v[60:63], v[158:161], v[202:205], 0
	v_mfma_f32_16x16x32_bf16 v[32:35], v[166:169], v[202:205], 0
	v_mfma_f32_16x16x32_bf16 v[52:55], v[158:161], v[210:213], 0
	v_mfma_f32_16x16x32_bf16 v[24:27], v[166:169], v[210:213], 0
	v_mfma_f32_16x16x32_bf16 v[48:51], v[158:161], v[218:221], 0
	v_mfma_f32_16x16x32_bf16 v[16:19], v[166:169], v[218:221], 0
	v_mfma_f32_16x16x32_bf16 v[68:71], v[162:165], v[198:201], v[68:71]
	v_mfma_f32_16x16x32_bf16 v[40:43], v[190:193], v[198:201], v[40:43]
	v_mfma_f32_16x16x32_bf16 v[60:63], v[162:165], v[206:209], v[60:63]
	v_mfma_f32_16x16x32_bf16 v[32:35], v[190:193], v[206:209], v[32:35]
	v_mfma_f32_16x16x32_bf16 v[52:55], v[162:165], v[214:217], v[52:55]
	v_mfma_f32_16x16x32_bf16 v[24:27], v[190:193], v[214:217], v[24:27]
	v_mfma_f32_16x16x32_bf16 v[48:51], v[162:165], v[224:227], v[48:51]
	v_mfma_f32_16x16x32_bf16 v[16:19], v[190:193], v[224:227], v[16:19]
	s_setprio 0
	s_barrier
	s_mov_b32 m0, s12
	v_lshl_add_u64 v[170:171], s[52:53], 0, v[128:129]
	s_add_u32 s40, s52, 0x40000
	ds_read_b128 v[194:197], v172 offset:16384
	ds_read_b128 v[198:201], v172 offset:17408
	ds_read_b128 v[202:205], v172 offset:18432
	ds_read_b128 v[206:209], v172 offset:19456
	ds_read_b128 v[210:213], v172 offset:20480
	ds_read_b128 v[214:217], v172 offset:21504
	ds_read_b128 v[218:221], v172 offset:22528
	ds_read_b128 v[224:227], v172 offset:23552
	global_load_lds_dwordx4 v[170:171], off
	v_lshl_add_u64 v[228:229], s[52:53], 0, v[130:131]
	s_mov_b32 m0, s13
	s_addc_u32 s41, s53, 0
	global_load_lds_dwordx4 v[228:229], off
	v_lshl_add_u64 v[236:237], s[40:41], 0, v[128:129]
	s_mov_b32 m0, s14
	v_lshl_add_u64 v[238:239], s[54:55], 0, v[130:131]
	global_load_lds_dwordx4 v[236:237], off
	v_lshl_add_u64 v[236:237], s[40:41], 0, v[130:131]
	s_mov_b32 m0, s15
	s_nop 0
	global_load_lds_dwordx4 v[236:237], off
	v_lshl_add_u64 v[236:237], s[54:55], 0, v[128:129]
	s_mov_b32 m0, s5
	s_nop 0
	global_load_lds_dwordx4 v[236:237], off
	s_mov_b32 m0, s39
	s_nop 0
	global_load_lds_dwordx4 v[238:239], off
	s_waitcnt vmcnt(8)
	s_waitcnt lgkmcnt(0)
	s_barrier
; #define PG8_STAGE(bufoff, gbase, voff) do { _Pragma("unroll") for (int _i = 0; _i < 2; ++_i) \
;         __builtin_amdgcn_global_load_lds((const unsigned*)((const char*)(gbase) + (voff)[_i]), (PG8_LAS unsigned*)(lds + (bufoff) + ldsw + _i * 8192), 16, 0, 0); } while (0)
; #define PG8_LDA(dst, b, h) do { _Pragma("unroll") for (int m = 0; m < 4; ++m) _Pragma("unroll") for (int k = 0; k < 2; ++k) dst[m][k] = *(const PG8_LAS bf16x8*)(lds + PG8_SA(b, h) + aoff + m * 2048 + k * 1024); } while (0)
; #define PG8_LDB(dst, b, h) do { _Pragma("unroll") for (int n = 0; n < 2; ++n) _Pragma("unroll") for (int k = 0; k < 2; ++k) dst[n][k] = *(const PG8_LAS bf16x8*)(lds + PG8_SB(b, h) + boff + n * 2048 + k * 1024); } while (0)
; #define PG8_MMA(ai, bj, At, Bt) do { __builtin_amdgcn_s_setprio(1); _Pragma("unroll") for (int m = 0; m < 4; ++m) _Pragma("unroll") for (int n = 0; n < 2; ++n) _Pragma("unroll") for (int k = 0; k < 2; ++k) \
;         acc[ai][bj][m][n] = __builtin_amdgcn_mfma_f32_16x16x32_bf16(Bt[n][k], At[m][k], acc[ai][bj][m][n], 0, 0, 0); __builtin_amdgcn_s_setprio(0); } while (0)
; #define PG8_WAIT_V(n) asm volatile("s_waitcnt vmcnt(" #n ")" ::: "memory")
; #define PG8_WAIT_L(n) asm volatile("s_waitcnt lgkmcnt(" #n ")" ::: "memory")
; #define PG8_BAR __builtin_amdgcn_s_barrier()
; #define PG8_SCHED __builtin_amdgcn_sched_barrier(0)
; template <class Epi, class Sched, bool ALIGN_EPI = false, bool SP2 = false>
; __device__ __forceinline__ void gemm_phase(PG8_LAS unsigned char* lds, const Gemm g, const Sched& S, const Epi& E) {
;     ...
;             PG8_WAIT_V(8); PG8_WAIT_L(0); PG8_BAR; PG8_MMA(1, 0, At, B0); PG8_MMA(1, 1, At, B1); PG8_BAR; PG8_SCHED;
;             PG8_LDB(B0, 1, 0); PG8_LDB(B1, 1, 1); PG8_SCHED; PG8_LDA(At, 1, 0); PG8_STAGE(PG8_SA(0, 1), a2 + hstep, voffA);
;             PG8_WAIT_V(8); PG8_WAIT_L(0); PG8_BAR; PG8_MMA(0, 0, At, B0); PG8_MMA(0, 1, At, B1); PG8_BAR; PG8_SCHED;
	s_setprio 1
	v_mfma_f32_16x16x32_bf16 v[104:107], v[142:145], v[194:197], 0
	v_mfma_f32_16x16x32_bf16 v[76:79], v[150:153], v[194:197], 0
	v_mfma_f32_16x16x32_bf16 v[100:103], v[142:145], v[202:205], 0
	v_mfma_f32_16x16x32_bf16 v[72:75], v[150:153], v[202:205], 0
	v_mfma_f32_16x16x32_bf16 v[92:95], v[142:145], v[210:213], 0
	v_mfma_f32_16x16x32_bf16 v[64:67], v[150:153], v[210:213], 0
	v_mfma_f32_16x16x32_bf16 v[80:83], v[142:145], v[218:221], 0
	v_mfma_f32_16x16x32_bf16 v[56:59], v[150:153], v[218:221], 0
	v_mfma_f32_16x16x32_bf16 v[104:107], v[146:149], v[198:201], v[104:107]
	v_mfma_f32_16x16x32_bf16 v[76:79], v[154:157], v[198:201], v[76:79]
	v_mfma_f32_16x16x32_bf16 v[100:103], v[146:149], v[206:209], v[100:103]
	v_mfma_f32_16x16x32_bf16 v[72:75], v[154:157], v[206:209], v[72:75]
	v_mfma_f32_16x16x32_bf16 v[92:95], v[146:149], v[214:217], v[92:95]
	v_mfma_f32_16x16x32_bf16 v[64:67], v[154:157], v[214:217], v[64:67]
	v_mfma_f32_16x16x32_bf16 v[80:83], v[146:149], v[224:227], v[80:83]
	v_mfma_f32_16x16x32_bf16 v[56:59], v[154:157], v[224:227], v[56:59]
	v_mfma_f32_16x16x32_bf16 v[44:47], v[158:161], v[194:197], 0
	v_mfma_f32_16x16x32_bf16 v[12:15], v[166:169], v[194:197], 0
	v_mfma_f32_16x16x32_bf16 v[36:39], v[158:161], v[202:205], 0
	v_mfma_f32_16x16x32_bf16 v[8:11], v[166:169], v[202:205], 0
	v_mfma_f32_16x16x32_bf16 v[28:31], v[158:161], v[210:213], 0
	v_mfma_f32_16x16x32_bf16 v[4:7], v[166:169], v[210:213], 0
	v_mfma_f32_16x16x32_bf16 v[20:23], v[158:161], v[218:221], 0
	v_mfma_f32_16x16x32_bf16 v[0:3], v[166:169], v[218:221], 0
	v_mfma_f32_16x16x32_bf16 v[44:47], v[162:165], v[198:201], v[44:47]
	v_mfma_f32_16x16x32_bf16 v[12:15], v[190:193], v[198:201], v[12:15]
	v_mfma_f32_16x16x32_bf16 v[36:39], v[162:165], v[206:209], v[36:39]
	v_mfma_f32_16x16x32_bf16 v[8:11], v[190:193], v[206:209], v[8:11]
	v_mfma_f32_16x16x32_bf16 v[28:31], v[162:165], v[214:217], v[28:31]
	v_mfma_f32_16x16x32_bf16 v[4:7], v[190:193], v[214:217], v[4:7]
	v_mfma_f32_16x16x32_bf16 v[20:23], v[162:165], v[224:227], v[20:23]
	v_mfma_f32_16x16x32_bf16 v[0:3], v[190:193], v[224:227], v[0:3]
	s_setprio 0
	s_barrier
	ds_read_b128 v[142:145], v182
	ds_read_b128 v[146:149], v183
	ds_read_b128 v[150:153], v184
	ds_read_b128 v[154:157], v185
	ds_read_b128 v[158:161], v186
	ds_read_b128 v[162:165], v187
	ds_read_b128 v[166:169], v188
	ds_read_b128 v[190:193], v189
	s_add_u32 s40, s54, 0x40000
	s_addc_u32 s41, s55, 0
	s_mov_b32 m0, s43
	v_lshl_add_u64 v[240:241], s[40:41], 0, v[128:129]
	ds_read_b128 v[194:197], v172 offset:32768
	ds_read_b128 v[198:201], v172 offset:33792
	ds_read_b128 v[202:205], v172 offset:34816
	ds_read_b128 v[206:209], v172 offset:35840
	ds_read_b128 v[210:213], v172 offset:36864
	ds_read_b128 v[214:217], v172 offset:37888
	ds_read_b128 v[218:221], v172 offset:38912
	ds_read_b128 v[224:227], v172 offset:39936
	global_load_lds_dwordx4 v[240:241], off
	v_lshl_add_u64 v[240:241], s[40:41], 0, v[130:131]
	s_mov_b32 m0, s56
	s_nop 0
	global_load_lds_dwordx4 v[240:241], off
	s_waitcnt vmcnt(8)
	s_waitcnt lgkmcnt(0)
	s_barrier
	s_setprio 1
	v_mfma_f32_16x16x32_bf16 v[124:127], v[142:145], v[194:197], v[124:127]
	v_mfma_f32_16x16x32_bf16 v[108:111], v[150:153], v[194:197], v[108:111]
	v_mfma_f32_16x16x32_bf16 v[120:123], v[142:145], v[202:205], v[120:123]
	v_mfma_f32_16x16x32_bf16 v[96:99], v[150:153], v[202:205], v[96:99]
	v_mfma_f32_16x16x32_bf16 v[116:119], v[142:145], v[210:213], v[116:119]
	v_mfma_f32_16x16x32_bf16 v[88:91], v[150:153], v[210:213], v[88:91]
	v_mfma_f32_16x16x32_bf16 v[112:115], v[142:145], v[218:221], v[112:115]
	v_mfma_f32_16x16x32_bf16 v[84:87], v[150:153], v[218:221], v[84:87]
	v_mfma_f32_16x16x32_bf16 v[124:127], v[146:149], v[198:201], v[124:127]
	v_mfma_f32_16x16x32_bf16 v[108:111], v[154:157], v[198:201], v[108:111]
	v_mfma_f32_16x16x32_bf16 v[120:123], v[146:149], v[206:209], v[120:123]
	v_mfma_f32_16x16x32_bf16 v[96:99], v[154:157], v[206:209], v[96:99]
	v_mfma_f32_16x16x32_bf16 v[116:119], v[146:149], v[214:217], v[116:119]
	v_mfma_f32_16x16x32_bf16 v[88:91], v[154:157], v[214:217], v[88:91]
	v_mfma_f32_16x16x32_bf16 v[112:115], v[146:149], v[224:227], v[112:115]
	v_mfma_f32_16x16x32_bf16 v[84:87], v[154:157], v[224:227], v[84:87]
	v_mfma_f32_16x16x32_bf16 v[68:71], v[158:161], v[194:197], v[68:71]
	v_mfma_f32_16x16x32_bf16 v[40:43], v[166:169], v[194:197], v[40:43]
	v_mfma_f32_16x16x32_bf16 v[60:63], v[158:161], v[202:205], v[60:63]
	v_mfma_f32_16x16x32_bf16 v[32:35], v[166:169], v[202:205], v[32:35]
	v_mfma_f32_16x16x32_bf16 v[52:55], v[158:161], v[210:213], v[52:55]
	v_mfma_f32_16x16x32_bf16 v[24:27], v[166:169], v[210:213], v[24:27]
	v_mfma_f32_16x16x32_bf16 v[48:51], v[158:161], v[218:221], v[48:51]
	v_mfma_f32_16x16x32_bf16 v[16:19], v[166:169], v[218:221], v[16:19]
	v_mfma_f32_16x16x32_bf16 v[68:71], v[162:165], v[198:201], v[68:71]
	v_mfma_f32_16x16x32_bf16 v[40:43], v[190:193], v[198:201], v[40:43]
	v_mfma_f32_16x16x32_bf16 v[60:63], v[162:165], v[206:209], v[60:63]
	v_mfma_f32_16x16x32_bf16 v[32:35], v[190:193], v[206:209], v[32:35]
	v_mfma_f32_16x16x32_bf16 v[52:55], v[162:165], v[214:217], v[52:55]
	v_mfma_f32_16x16x32_bf16 v[24:27], v[190:193], v[214:217], v[24:27]
	v_mfma_f32_16x16x32_bf16 v[48:51], v[162:165], v[224:227], v[48:51]
	v_mfma_f32_16x16x32_bf16 v[16:19], v[190:193], v[224:227], v[16:19]
	s_setprio 0
	s_barrier
; #define PG8_STAGE(bufoff, gbase, voff) do { _Pragma("unroll") for (int _i = 0; _i < 2; ++_i) \
;         __builtin_amdgcn_global_load_lds((const unsigned*)((const char*)(gbase) + (voff)[_i]), (PG8_LAS unsigned*)(lds + (bufoff) + ldsw + _i * 8192), 16, 0, 0); } while (0)
; #define PG8_LDA(dst, b, h) do { _Pragma("unroll") for (int m = 0; m < 4; ++m) _Pragma("unroll") for (int k = 0; k < 2; ++k) dst[m][k] = *(const PG8_LAS bf16x8*)(lds + PG8_SA(b, h) + aoff + m * 2048 + k * 1024); } while (0)
; #define PG8_LDB(dst, b, h) do { _Pragma("unroll") for (int n = 0; n < 2; ++n) _Pragma("unroll") for (int k = 0; k < 2; ++k) dst[n][k] = *(const PG8_LAS bf16x8*)(lds + PG8_SB(b, h) + boff + n * 2048 + k * 1024); } while (0)
; #define PG8_WAIT_V(n) asm volatile("s_waitcnt vmcnt(" #n ")" ::: "memory")
; #define PG8_WAIT_L(n) asm volatile("s_waitcnt lgkmcnt(" #n ")" ::: "memory")
; #define PG8_BAR __builtin_amdgcn_s_barrier()
; template <class Epi, class Sched, bool ALIGN_EPI = false, bool SP2 = false>
; __device__ __forceinline__ void gemm_phase(PG8_LAS unsigned char* lds, const Gemm g, const Sched& S, const Epi& E) {
;     ...
;         for (int t = 0; t < nt; t += 2) {
;             const bool last = (t == nt - 2);
;             const char* a1 = cA + (size_t)(t + 1) * kstep;
;             const char* a2 = last ? nA : cA + (size_t)(t + 2) * kstep; const char* b2 = last ? nB : cB + (size_t)(t + 2) * kstep;
;             const char* a3 = a2 + kstep; const char* b3 = b2 + kstep;
;             if (last && has_next) S.a_ready(nxt);
;             if constexpr (SP2) {
;             PG8_LDB(B0, 0, 0); PG8_LDB(B1, 0, 1); PG8_SCHED; PG8_LDA(At, 0, 0); PG8_STAGE(PG8_SA(1, 1), a1 + hstep, voffA);
;             PG8_WAIT_V(8); PG8_WAIT_L(0); PG8_BAR; PG8_MMA(0, 0, At, B0); PG8_MMA(0, 1, At, B1); PG8_BAR; PG8_SCHED;
;             PG8_LDA(At, 0, 1); PG8_STAGE(PG8_SB(0, 0), b2, voffB); PG8_STAGE(PG8_SB(0, 1), b2 + hstep, voffB); PG8_STAGE(PG8_SA(0, 0), a2, voffA);
;             PG8_WAIT_V(8); PG8_WAIT_L(0); PG8_BAR; PG8_MMA(1, 0, At, B0); PG8_MMA(1, 1, At, B1); PG8_BAR; PG8_SCHED;
;     ...
;             PG8_LDA(At, 1, 1); PG8_STAGE(PG8_SB(1, 0), b3, voffB); PG8_STAGE(PG8_SB(1, 1), b3 + hstep, voffB); PG8_STAGE(PG8_SA(1, 0), a3, voffA);
;             PG8_WAIT_V(8); PG8_WAIT_L(0); PG8_BAR; PG8_MMA(1, 0, At, B0); PG8_MMA(1, 1, At, B1); PG8_BAR; PG8_SCHED;
	s_mov_b32 m0, s60
	v_lshl_add_u64 v[170:171], v[170:171], 0, s[10:11]
	s_add_u32 s40, s52, 0x40080
	ds_read_b128 v[194:197], v172 offset:49152
	ds_read_b128 v[198:201], v172 offset:50176
	ds_read_b128 v[202:205], v172 offset:51200
	ds_read_b128 v[206:209], v172 offset:52224
	ds_read_b128 v[210:213], v172 offset:53248
	ds_read_b128 v[214:217], v172 offset:54272
	ds_read_b128 v[218:221], v172 offset:55296
	ds_read_b128 v[224:227], v172 offset:56320
	global_load_lds_dwordx4 v[170:171], off
	v_lshl_add_u64 v[170:171], v[228:229], 0, s[10:11]
	s_mov_b32 m0, s61
	s_addc_u32 s41, s53, 0
	global_load_lds_dwordx4 v[170:171], off
	v_lshl_add_u64 v[170:171], s[40:41], 0, v[128:129]
	s_mov_b32 m0, s64
	s_nop 0
	global_load_lds_dwordx4 v[170:171], off
	v_lshl_add_u64 v[170:171], s[40:41], 0, v[130:131]
	s_mov_b32 m0, s65
	s_nop 0
	global_load_lds_dwordx4 v[170:171], off
	v_lshl_add_u64 v[170:171], v[236:237], 0, s[10:11]
	s_mov_b32 m0, s62
	s_nop 0
	global_load_lds_dwordx4 v[170:171], off
	v_lshl_add_u64 v[170:171], v[238:239], 0, s[10:11]
	s_mov_b32 m0, s63
	s_nop 0
	global_load_lds_dwordx4 v[170:171], off
	s_waitcnt vmcnt(8)
	s_waitcnt lgkmcnt(0)
	s_barrier
	s_setprio 1
	v_mfma_f32_16x16x32_bf16 v[104:107], v[142:145], v[194:197], v[104:107]
	v_mfma_f32_16x16x32_bf16 v[76:79], v[150:153], v[194:197], v[76:79]
	v_mfma_f32_16x16x32_bf16 v[100:103], v[142:145], v[202:205], v[100:103]
	v_mfma_f32_16x16x32_bf16 v[72:75], v[150:153], v[202:205], v[72:75]
	v_mfma_f32_16x16x32_bf16 v[92:95], v[142:145], v[210:213], v[92:95]
	v_mfma_f32_16x16x32_bf16 v[64:67], v[150:153], v[210:213], v[64:67]
	v_mfma_f32_16x16x32_bf16 v[80:83], v[142:145], v[218:221], v[80:83]
	v_mfma_f32_16x16x32_bf16 v[56:59], v[150:153], v[218:221], v[56:59]
	v_mfma_f32_16x16x32_bf16 v[104:107], v[146:149], v[198:201], v[104:107]
	v_mfma_f32_16x16x32_bf16 v[76:79], v[154:157], v[198:201], v[76:79]
	v_mfma_f32_16x16x32_bf16 v[100:103], v[146:149], v[206:209], v[100:103]
	v_mfma_f32_16x16x32_bf16 v[72:75], v[154:157], v[206:209], v[72:75]
	v_mfma_f32_16x16x32_bf16 v[92:95], v[146:149], v[214:217], v[92:95]
	v_mfma_f32_16x16x32_bf16 v[64:67], v[154:157], v[214:217], v[64:67]
	v_mfma_f32_16x16x32_bf16 v[80:83], v[146:149], v[224:227], v[80:83]
	v_mfma_f32_16x16x32_bf16 v[56:59], v[154:157], v[224:227], v[56:59]
	v_mfma_f32_16x16x32_bf16 v[44:47], v[158:161], v[194:197], v[44:47]
	v_mfma_f32_16x16x32_bf16 v[12:15], v[166:169], v[194:197], v[12:15]
	v_mfma_f32_16x16x32_bf16 v[36:39], v[158:161], v[202:205], v[36:39]
	v_mfma_f32_16x16x32_bf16 v[8:11], v[166:169], v[202:205], v[8:11]
	v_mfma_f32_16x16x32_bf16 v[28:31], v[158:161], v[210:213], v[28:31]
	v_mfma_f32_16x16x32_bf16 v[4:7], v[166:169], v[210:213], v[4:7]
	v_mfma_f32_16x16x32_bf16 v[20:23], v[158:161], v[218:221], v[20:23]
	v_mfma_f32_16x16x32_bf16 v[0:3], v[166:169], v[218:221], v[0:3]
	v_mfma_f32_16x16x32_bf16 v[44:47], v[162:165], v[198:201], v[44:47]
	v_mfma_f32_16x16x32_bf16 v[12:15], v[190:193], v[198:201], v[12:15]
	v_mfma_f32_16x16x32_bf16 v[36:39], v[162:165], v[206:209], v[36:39]
	v_mfma_f32_16x16x32_bf16 v[8:11], v[190:193], v[206:209], v[8:11]
	v_mfma_f32_16x16x32_bf16 v[28:31], v[162:165], v[214:217], v[28:31]
	v_mfma_f32_16x16x32_bf16 v[4:7], v[190:193], v[214:217], v[4:7]
	v_mfma_f32_16x16x32_bf16 v[20:23], v[162:165], v[224:227], v[20:23]
	v_mfma_f32_16x16x32_bf16 v[0:3], v[190:193], v[224:227], v[0:3]
	s_setprio 0
	s_barrier
	s_add_i32 s79, s79, 2
	s_add_u32 s77, s77, 0x100
	s_addc_u32 s78, s78, 0
	s_mov_b64 s[40:41], s[50:51]
.LBB0_1307:
	ds_read_b128 v[142:145], v174
	ds_read_b128 v[146:149], v175
	ds_read_b128 v[150:153], v176
	ds_read_b128 v[154:157], v177
	ds_read_b128 v[158:161], v178
	ds_read_b128 v[162:165], v179
	ds_read_b128 v[166:169], v180
	ds_read_b128 v[190:193], v181
	s_add_u32 s50, s40, 0x100
	s_addc_u32 s51, s41, 0
	s_cmp_eq_u32 s79, 12
	s_cselect_b32 s55, s21, s51
	s_cselect_b32 s54, s37, s50
	s_cselect_b32 s53, s19, s78
	s_cselect_b32 s52, s76, s77
	s_mov_b32 m0, s68
	v_lshl_add_u64 v[170:171], s[40:41], 0, v[134:135]
	ds_read_b128 v[194:197], v172
	ds_read_b128 v[198:201], v172 offset:1024
	ds_read_b128 v[202:205], v172 offset:2048
	ds_read_b128 v[206:209], v172 offset:3072
	ds_read_b128 v[210:213], v172 offset:4096
	ds_read_b128 v[214:217], v172 offset:5120
	ds_read_b128 v[218:221], v172 offset:6144
	ds_read_b128 v[224:227], v172 offset:7168
	global_load_lds_dwordx4 v[170:171], off
	v_lshl_add_u64 v[170:171], s[40:41], 0, v[136:137]
	s_mov_b32 m0, s69
	s_nop 0
	global_load_lds_dwordx4 v[170:171], off
	s_waitcnt vmcnt(8)
	s_waitcnt lgkmcnt(0)
	s_barrier
; #define PG8_STAGE(bufoff, gbase, voff) do { _Pragma("unroll") for (int _i = 0; _i < 2; ++_i) \
;         __builtin_amdgcn_global_load_lds((const unsigned*)((const char*)(gbase) + (voff)[_i]), (PG8_LAS unsigned*)(lds + (bufoff) + ldsw + _i * 8192), 16, 0, 0); } while (0)
; #define PG8_LDA(dst, b, h) do { _Pragma("unroll") for (int m = 0; m < 4; ++m) _Pragma("unroll") for (int k = 0; k < 2; ++k) dst[m][k] = *(const PG8_LAS bf16x8*)(lds + PG8_SA(b, h) + aoff + m * 2048 + k * 1024); } while (0)
; #define PG8_MMA(ai, bj, At, Bt) do { __builtin_amdgcn_s_setprio(1); _Pragma("unroll") for (int m = 0; m < 4; ++m) _Pragma("unroll") for (int n = 0; n < 2; ++n) _Pragma("unroll") for (int k = 0; k < 2; ++k) \
;         acc[ai][bj][m][n] = __builtin_amdgcn_mfma_f32_16x16x32_bf16(Bt[n][k], At[m][k], acc[ai][bj][m][n], 0, 0, 0); __builtin_amdgcn_s_setprio(0); } while (0)
; #define PG8_WAIT_V(n) asm volatile("s_waitcnt vmcnt(" #n ")" ::: "memory")
; #define PG8_WAIT_L(n) asm volatile("s_waitcnt lgkmcnt(" #n ")" ::: "memory")
; #define PG8_BAR __builtin_amdgcn_s_barrier()
; #define PG8_SCHED __builtin_amdgcn_sched_barrier(0)
; template <class Epi, class Sched, bool ALIGN_EPI = false, bool SP2 = false>
; __device__ __forceinline__ void gemm_phase(PG8_LAS unsigned char* lds, const Gemm g, const Sched& S, const Epi& E) {
;     ...
;             PG8_WAIT_V(8); PG8_WAIT_L(0); PG8_BAR; PG8_MMA(0, 0, At, B0); PG8_MMA(0, 1, At, B1); PG8_BAR; PG8_SCHED;
;             PG8_LDA(At, 0, 1); PG8_STAGE(PG8_SB(0, 0), b2, voffB); PG8_STAGE(PG8_SB(0, 1), b2 + hstep, voffB); PG8_STAGE(PG8_SA(0, 0), a2, voffA);
;             PG8_WAIT_V(8); PG8_WAIT_L(0); PG8_BAR; PG8_MMA(1, 0, At, B0); PG8_MMA(1, 1, At, B1); PG8_BAR; PG8_SCHED;
	s_setprio 1
	v_mfma_f32_16x16x32_bf16 v[124:127], v[142:145], v[194:197], v[124:127]
	v_mfma_f32_16x16x32_bf16 v[108:111], v[150:153], v[194:197], v[108:111]
	v_mfma_f32_16x16x32_bf16 v[120:123], v[142:145], v[202:205], v[120:123]
	v_mfma_f32_16x16x32_bf16 v[96:99], v[150:153], v[202:205], v[96:99]
	v_mfma_f32_16x16x32_bf16 v[116:119], v[142:145], v[210:213], v[116:119]
	v_mfma_f32_16x16x32_bf16 v[88:91], v[150:153], v[210:213], v[88:91]
	v_mfma_f32_16x16x32_bf16 v[112:115], v[142:145], v[218:221], v[112:115]
	v_mfma_f32_16x16x32_bf16 v[84:87], v[150:153], v[218:221], v[84:87]
	v_mfma_f32_16x16x32_bf16 v[124:127], v[146:149], v[198:201], v[124:127]
	v_mfma_f32_16x16x32_bf16 v[108:111], v[154:157], v[198:201], v[108:111]
	v_mfma_f32_16x16x32_bf16 v[120:123], v[146:149], v[206:209], v[120:123]
	v_mfma_f32_16x16x32_bf16 v[96:99], v[154:157], v[206:209], v[96:99]
	v_mfma_f32_16x16x32_bf16 v[116:119], v[146:149], v[214:217], v[116:119]
	v_mfma_f32_16x16x32_bf16 v[88:91], v[154:157], v[214:217], v[88:91]
	v_mfma_f32_16x16x32_bf16 v[112:115], v[146:149], v[224:227], v[112:115]
	v_mfma_f32_16x16x32_bf16 v[84:87], v[154:157], v[224:227], v[84:87]
	v_mfma_f32_16x16x32_bf16 v[68:71], v[158:161], v[194:197], v[68:71]
	v_mfma_f32_16x16x32_bf16 v[40:43], v[166:169], v[194:197], v[40:43]
	v_mfma_f32_16x16x32_bf16 v[60:63], v[158:161], v[202:205], v[60:63]
	v_mfma_f32_16x16x32_bf16 v[32:35], v[166:169], v[202:205], v[32:35]
	v_mfma_f32_16x16x32_bf16 v[52:55], v[158:161], v[210:213], v[52:55]
	v_mfma_f32_16x16x32_bf16 v[24:27], v[166:169], v[210:213], v[24:27]
	v_mfma_f32_16x16x32_bf16 v[48:51], v[158:161], v[218:221], v[48:51]
	v_mfma_f32_16x16x32_bf16 v[16:19], v[166:169], v[218:221], v[16:19]
	v_mfma_f32_16x16x32_bf16 v[68:71], v[162:165], v[198:201], v[68:71]
	v_mfma_f32_16x16x32_bf16 v[40:43], v[190:193], v[198:201], v[40:43]
	v_mfma_f32_16x16x32_bf16 v[60:63], v[162:165], v[206:209], v[60:63]
	v_mfma_f32_16x16x32_bf16 v[32:35], v[190:193], v[206:209], v[32:35]
	v_mfma_f32_16x16x32_bf16 v[52:55], v[162:165], v[214:217], v[52:55]
	v_mfma_f32_16x16x32_bf16 v[24:27], v[190:193], v[214:217], v[24:27]
	v_mfma_f32_16x16x32_bf16 v[48:51], v[162:165], v[224:227], v[48:51]
	v_mfma_f32_16x16x32_bf16 v[16:19], v[190:193], v[224:227], v[16:19]
	s_setprio 0
	s_barrier
	s_mov_b32 m0, s12
	v_lshl_add_u64 v[170:171], s[52:53], 0, v[128:129]
	s_add_u32 s40, s52, 0x40000
	ds_read_b128 v[194:197], v172 offset:16384
	ds_read_b128 v[198:201], v172 offset:17408
	ds_read_b128 v[202:205], v172 offset:18432
	ds_read_b128 v[206:209], v172 offset:19456
	ds_read_b128 v[210:213], v172 offset:20480
	ds_read_b128 v[214:217], v172 offset:21504
	ds_read_b128 v[218:221], v172 offset:22528
	ds_read_b128 v[224:227], v172 offset:23552
	global_load_lds_dwordx4 v[170:171], off
	v_lshl_add_u64 v[228:229], s[52:53], 0, v[130:131]
	s_mov_b32 m0, s13
	s_addc_u32 s41, s53, 0
	global_load_lds_dwordx4 v[228:229], off
	v_lshl_add_u64 v[236:237], s[40:41], 0, v[128:129]
	s_mov_b32 m0, s14
	v_lshl_add_u64 v[238:239], s[54:55], 0, v[130:131]
	global_load_lds_dwordx4 v[236:237], off
	v_lshl_add_u64 v[236:237], s[40:41], 0, v[130:131]
	s_mov_b32 m0, s15
	s_nop 0
	global_load_lds_dwordx4 v[236:237], off
	v_lshl_add_u64 v[236:237], s[54:55], 0, v[128:129]
	s_mov_b32 m0, s5
	s_nop 0
	global_load_lds_dwordx4 v[236:237], off
	s_mov_b32 m0, s39
	s_nop 0
	global_load_lds_dwordx4 v[238:239], off
	s_waitcnt vmcnt(8)
	s_waitcnt lgkmcnt(0)
	s_barrier
	s_setprio 1
	v_mfma_f32_16x16x32_bf16 v[104:107], v[142:145], v[194:197], v[104:107]
	v_mfma_f32_16x16x32_bf16 v[76:79], v[150:153], v[194:197], v[76:79]
	v_mfma_f32_16x16x32_bf16 v[100:103], v[142:145], v[202:205], v[100:103]
	v_mfma_f32_16x16x32_bf16 v[72:75], v[150:153], v[202:205], v[72:75]
	v_mfma_f32_16x16x32_bf16 v[92:95], v[142:145], v[210:213], v[92:95]
	v_mfma_f32_16x16x32_bf16 v[64:67], v[150:153], v[210:213], v[64:67]
	v_mfma_f32_16x16x32_bf16 v[80:83], v[142:145], v[218:221], v[80:83]
	v_mfma_f32_16x16x32_bf16 v[56:59], v[150:153], v[218:221], v[56:59]
	v_mfma_f32_16x16x32_bf16 v[104:107], v[146:149], v[198:201], v[104:107]
	v_mfma_f32_16x16x32_bf16 v[76:79], v[154:157], v[198:201], v[76:79]
	v_mfma_f32_16x16x32_bf16 v[100:103], v[146:149], v[206:209], v[100:103]
	v_mfma_f32_16x16x32_bf16 v[72:75], v[154:157], v[206:209], v[72:75]
	v_mfma_f32_16x16x32_bf16 v[92:95], v[146:149], v[214:217], v[92:95]
	v_mfma_f32_16x16x32_bf16 v[64:67], v[154:157], v[214:217], v[64:67]
	v_mfma_f32_16x16x32_bf16 v[80:83], v[146:149], v[224:227], v[80:83]
	v_mfma_f32_16x16x32_bf16 v[56:59], v[154:157], v[224:227], v[56:59]
	v_mfma_f32_16x16x32_bf16 v[44:47], v[158:161], v[194:197], v[44:47]
	v_mfma_f32_16x16x32_bf16 v[12:15], v[166:169], v[194:197], v[12:15]
	v_mfma_f32_16x16x32_bf16 v[36:39], v[158:161], v[202:205], v[36:39]
	v_mfma_f32_16x16x32_bf16 v[8:11], v[166:169], v[202:205], v[8:11]
	v_mfma_f32_16x16x32_bf16 v[28:31], v[158:161], v[210:213], v[28:31]
	v_mfma_f32_16x16x32_bf16 v[4:7], v[166:169], v[210:213], v[4:7]
	v_mfma_f32_16x16x32_bf16 v[20:23], v[158:161], v[218:221], v[20:23]
	v_mfma_f32_16x16x32_bf16 v[0:3], v[166:169], v[218:221], v[0:3]
	v_mfma_f32_16x16x32_bf16 v[44:47], v[162:165], v[198:201], v[44:47]
	v_mfma_f32_16x16x32_bf16 v[12:15], v[190:193], v[198:201], v[12:15]
	v_mfma_f32_16x16x32_bf16 v[36:39], v[162:165], v[206:209], v[36:39]
	v_mfma_f32_16x16x32_bf16 v[8:11], v[190:193], v[206:209], v[8:11]
	v_mfma_f32_16x16x32_bf16 v[28:31], v[162:165], v[214:217], v[28:31]
	v_mfma_f32_16x16x32_bf16 v[4:7], v[190:193], v[214:217], v[4:7]
	v_mfma_f32_16x16x32_bf16 v[20:23], v[162:165], v[224:227], v[20:23]
	v_mfma_f32_16x16x32_bf16 v[0:3], v[190:193], v[224:227], v[0:3]
	s_setprio 0
	s_barrier
; #define PG8_STAGE(bufoff, gbase, voff) do { _Pragma("unroll") for (int _i = 0; _i < 2; ++_i) \
;         __builtin_amdgcn_global_load_lds((const unsigned*)((const char*)(gbase) + (voff)[_i]), (PG8_LAS unsigned*)(lds + (bufoff) + ldsw + _i * 8192), 16, 0, 0); } while (0)
; #define PG8_LDA(dst, b, h) do { _Pragma("unroll") for (int m = 0; m < 4; ++m) _Pragma("unroll") for (int k = 0; k < 2; ++k) dst[m][k] = *(const PG8_LAS bf16x8*)(lds + PG8_SA(b, h) + aoff + m * 2048 + k * 1024); } while (0)
; #define PG8_LDB(dst, b, h) do { _Pragma("unroll") for (int n = 0; n < 2; ++n) _Pragma("unroll") for (int k = 0; k < 2; ++k) dst[n][k] = *(const PG8_LAS bf16x8*)(lds + PG8_SB(b, h) + boff + n * 2048 + k * 1024); } while (0)
; #define PG8_MMA(ai, bj, At, Bt) do { __builtin_amdgcn_s_setprio(1); _Pragma("unroll") for (int m = 0; m < 4; ++m) _Pragma("unroll") for (int n = 0; n < 2; ++n) _Pragma("unroll") for (int k = 0; k < 2; ++k) \
;         acc[ai][bj][m][n] = __builtin_amdgcn_mfma_f32_16x16x32_bf16(Bt[n][k], At[m][k], acc[ai][bj][m][n], 0, 0, 0); __builtin_amdgcn_s_setprio(0); } while (0)
; #define PG8_WAIT_V(n) asm volatile("s_waitcnt vmcnt(" #n ")" ::: "memory")
; #define PG8_WAIT_L(n) asm volatile("s_waitcnt lgkmcnt(" #n ")" ::: "memory")
; #define PG8_BAR __builtin_amdgcn_s_barrier()
; #define PG8_SCHED __builtin_amdgcn_sched_barrier(0)
; template <class Epi, class Sched, bool ALIGN_EPI = false, bool SP2 = false>
; __device__ __forceinline__ void gemm_phase(PG8_LAS unsigned char* lds, const Gemm g, const Sched& S, const Epi& E) {
;     ...
;         for (int t = 0; t < nt; t += 2) {
;     ...
;             PG8_LDB(B0, 1, 0); PG8_LDB(B1, 1, 1); PG8_SCHED; PG8_LDA(At, 1, 0); PG8_STAGE(PG8_SA(0, 1), a2 + hstep, voffA);
;             PG8_WAIT_V(8); PG8_WAIT_L(0); PG8_BAR; PG8_MMA(0, 0, At, B0); PG8_MMA(0, 1, At, B1); PG8_BAR; PG8_SCHED;
;             PG8_LDA(At, 1, 1); PG8_STAGE(PG8_SB(1, 0), b3, voffB); PG8_STAGE(PG8_SB(1, 1), b3 + hstep, voffB); PG8_STAGE(PG8_SA(1, 0), a3, voffA);
;             PG8_WAIT_V(8); PG8_WAIT_L(0); PG8_BAR; PG8_MMA(1, 0, At, B0); PG8_MMA(1, 1, At, B1); PG8_BAR; PG8_SCHED;
	ds_read_b128 v[142:145], v182
	ds_read_b128 v[146:149], v183
	ds_read_b128 v[150:153], v184
	ds_read_b128 v[154:157], v185
	ds_read_b128 v[158:161], v186
	ds_read_b128 v[162:165], v187
	ds_read_b128 v[166:169], v188
	ds_read_b128 v[190:193], v189
	s_add_u32 s40, s54, 0x40000
	s_addc_u32 s41, s55, 0
	s_mov_b32 m0, s43
	v_lshl_add_u64 v[240:241], s[40:41], 0, v[128:129]
	ds_read_b128 v[194:197], v172 offset:32768
	ds_read_b128 v[198:201], v172 offset:33792
	ds_read_b128 v[202:205], v172 offset:34816
	ds_read_b128 v[206:209], v172 offset:35840
	ds_read_b128 v[210:213], v172 offset:36864
	ds_read_b128 v[214:217], v172 offset:37888
	ds_read_b128 v[218:221], v172 offset:38912
	ds_read_b128 v[224:227], v172 offset:39936
	global_load_lds_dwordx4 v[240:241], off
	v_lshl_add_u64 v[240:241], s[40:41], 0, v[130:131]
	s_mov_b32 m0, s56
	s_nop 0
	global_load_lds_dwordx4 v[240:241], off
	s_waitcnt vmcnt(8)
	s_waitcnt lgkmcnt(0)
	s_barrier
	s_setprio 1
	v_mfma_f32_16x16x32_bf16 v[124:127], v[142:145], v[194:197], v[124:127]
	v_mfma_f32_16x16x32_bf16 v[108:111], v[150:153], v[194:197], v[108:111]
	v_mfma_f32_16x16x32_bf16 v[120:123], v[142:145], v[202:205], v[120:123]
	v_mfma_f32_16x16x32_bf16 v[96:99], v[150:153], v[202:205], v[96:99]
	v_mfma_f32_16x16x32_bf16 v[116:119], v[142:145], v[210:213], v[116:119]
	v_mfma_f32_16x16x32_bf16 v[88:91], v[150:153], v[210:213], v[88:91]
	v_mfma_f32_16x16x32_bf16 v[112:115], v[142:145], v[218:221], v[112:115]
	v_mfma_f32_16x16x32_bf16 v[84:87], v[150:153], v[218:221], v[84:87]
	v_mfma_f32_16x16x32_bf16 v[124:127], v[146:149], v[198:201], v[124:127]
	v_mfma_f32_16x16x32_bf16 v[108:111], v[154:157], v[198:201], v[108:111]
	v_mfma_f32_16x16x32_bf16 v[120:123], v[146:149], v[206:209], v[120:123]
	v_mfma_f32_16x16x32_bf16 v[96:99], v[154:157], v[206:209], v[96:99]
	v_mfma_f32_16x16x32_bf16 v[116:119], v[146:149], v[214:217], v[116:119]
	v_mfma_f32_16x16x32_bf16 v[88:91], v[154:157], v[214:217], v[88:91]
	v_mfma_f32_16x16x32_bf16 v[112:115], v[146:149], v[224:227], v[112:115]
	v_mfma_f32_16x16x32_bf16 v[84:87], v[154:157], v[224:227], v[84:87]
	v_mfma_f32_16x16x32_bf16 v[68:71], v[158:161], v[194:197], v[68:71]
	v_mfma_f32_16x16x32_bf16 v[40:43], v[166:169], v[194:197], v[40:43]
	v_mfma_f32_16x16x32_bf16 v[60:63], v[158:161], v[202:205], v[60:63]
	v_mfma_f32_16x16x32_bf16 v[32:35], v[166:169], v[202:205], v[32:35]
	v_mfma_f32_16x16x32_bf16 v[52:55], v[158:161], v[210:213], v[52:55]
	v_mfma_f32_16x16x32_bf16 v[24:27], v[166:169], v[210:213], v[24:27]
	v_mfma_f32_16x16x32_bf16 v[48:51], v[158:161], v[218:221], v[48:51]
	v_mfma_f32_16x16x32_bf16 v[16:19], v[166:169], v[218:221], v[16:19]
	v_mfma_f32_16x16x32_bf16 v[68:71], v[162:165], v[198:201], v[68:71]
	v_mfma_f32_16x16x32_bf16 v[40:43], v[190:193], v[198:201], v[40:43]
	v_mfma_f32_16x16x32_bf16 v[60:63], v[162:165], v[206:209], v[60:63]
	v_mfma_f32_16x16x32_bf16 v[32:35], v[190:193], v[206:209], v[32:35]
	v_mfma_f32_16x16x32_bf16 v[52:55], v[162:165], v[214:217], v[52:55]
	v_mfma_f32_16x16x32_bf16 v[24:27], v[190:193], v[214:217], v[24:27]
	v_mfma_f32_16x16x32_bf16 v[48:51], v[162:165], v[224:227], v[48:51]
	v_mfma_f32_16x16x32_bf16 v[16:19], v[190:193], v[224:227], v[16:19]
	s_setprio 0
	s_barrier
	s_mov_b32 m0, s60
	v_lshl_add_u64 v[170:171], v[170:171], 0, s[10:11]
	s_add_u32 s40, s52, 0x40080
	ds_read_b128 v[194:197], v172 offset:49152
	ds_read_b128 v[198:201], v172 offset:50176
	ds_read_b128 v[202:205], v172 offset:51200
	ds_read_b128 v[206:209], v172 offset:52224
	ds_read_b128 v[210:213], v172 offset:53248
	ds_read_b128 v[214:217], v172 offset:54272
	ds_read_b128 v[218:221], v172 offset:55296
	ds_read_b128 v[224:227], v172 offset:56320
	global_load_lds_dwordx4 v[170:171], off
	v_lshl_add_u64 v[170:171], v[228:229], 0, s[10:11]
	s_mov_b32 m0, s61
	s_addc_u32 s41, s53, 0
	global_load_lds_dwordx4 v[170:171], off
	v_lshl_add_u64 v[170:171], s[40:41], 0, v[128:129]
	s_mov_b32 m0, s64
	s_nop 0
	global_load_lds_dwordx4 v[170:171], off
	v_lshl_add_u64 v[170:171], s[40:41], 0, v[130:131]
	s_mov_b32 m0, s65
	s_nop 0
	global_load_lds_dwordx4 v[170:171], off
	v_lshl_add_u64 v[170:171], v[236:237], 0, s[10:11]
	s_mov_b32 m0, s62
	s_nop 0
	global_load_lds_dwordx4 v[170:171], off
	v_lshl_add_u64 v[170:171], v[238:239], 0, s[10:11]
	s_mov_b32 m0, s63
	s_nop 0
	global_load_lds_dwordx4 v[170:171], off
	s_waitcnt vmcnt(8)
	s_waitcnt lgkmcnt(0)
	s_barrier
	s_setprio 1
	v_mfma_f32_16x16x32_bf16 v[104:107], v[142:145], v[194:197], v[104:107]
	v_mfma_f32_16x16x32_bf16 v[76:79], v[150:153], v[194:197], v[76:79]
	v_mfma_f32_16x16x32_bf16 v[100:103], v[142:145], v[202:205], v[100:103]
	v_mfma_f32_16x16x32_bf16 v[72:75], v[150:153], v[202:205], v[72:75]
	v_mfma_f32_16x16x32_bf16 v[92:95], v[142:145], v[210:213], v[92:95]
	v_mfma_f32_16x16x32_bf16 v[64:67], v[150:153], v[210:213], v[64:67]
	v_mfma_f32_16x16x32_bf16 v[80:83], v[142:145], v[218:221], v[80:83]
	v_mfma_f32_16x16x32_bf16 v[56:59], v[150:153], v[218:221], v[56:59]
	v_mfma_f32_16x16x32_bf16 v[104:107], v[146:149], v[198:201], v[104:107]
	v_mfma_f32_16x16x32_bf16 v[76:79], v[154:157], v[198:201], v[76:79]
	v_mfma_f32_16x16x32_bf16 v[100:103], v[146:149], v[206:209], v[100:103]
	v_mfma_f32_16x16x32_bf16 v[72:75], v[154:157], v[206:209], v[72:75]
	v_mfma_f32_16x16x32_bf16 v[92:95], v[146:149], v[214:217], v[92:95]
	v_mfma_f32_16x16x32_bf16 v[64:67], v[154:157], v[214:217], v[64:67]
	v_mfma_f32_16x16x32_bf16 v[80:83], v[146:149], v[224:227], v[80:83]
	v_mfma_f32_16x16x32_bf16 v[56:59], v[154:157], v[224:227], v[56:59]
	v_mfma_f32_16x16x32_bf16 v[44:47], v[158:161], v[194:197], v[44:47]
	v_mfma_f32_16x16x32_bf16 v[12:15], v[166:169], v[194:197], v[12:15]
	v_mfma_f32_16x16x32_bf16 v[36:39], v[158:161], v[202:205], v[36:39]
	v_mfma_f32_16x16x32_bf16 v[8:11], v[166:169], v[202:205], v[8:11]
	v_mfma_f32_16x16x32_bf16 v[28:31], v[158:161], v[210:213], v[28:31]
	v_mfma_f32_16x16x32_bf16 v[4:7], v[166:169], v[210:213], v[4:7]
	v_mfma_f32_16x16x32_bf16 v[20:23], v[158:161], v[218:221], v[20:23]
	v_mfma_f32_16x16x32_bf16 v[0:3], v[166:169], v[218:221], v[0:3]
	v_mfma_f32_16x16x32_bf16 v[44:47], v[162:165], v[198:201], v[44:47]
	v_mfma_f32_16x16x32_bf16 v[12:15], v[190:193], v[198:201], v[12:15]
	v_mfma_f32_16x16x32_bf16 v[36:39], v[162:165], v[206:209], v[36:39]
	v_mfma_f32_16x16x32_bf16 v[8:11], v[190:193], v[206:209], v[8:11]
	v_mfma_f32_16x16x32_bf16 v[28:31], v[162:165], v[214:217], v[28:31]
	v_mfma_f32_16x16x32_bf16 v[4:7], v[190:193], v[214:217], v[4:7]
	v_mfma_f32_16x16x32_bf16 v[20:23], v[162:165], v[224:227], v[20:23]
	v_mfma_f32_16x16x32_bf16 v[0:3], v[190:193], v[224:227], v[0:3]
	s_setprio 0
	s_barrier
	s_add_i32 s79, s79, 2
	s_add_u32 s77, s77, 0x100
	s_addc_u32 s78, s78, 0
	s_cmp_gt_u32 s79, 13
	s_mov_b64 s[40:41], s[50:51]
	s_cbranch_scc0 .LBB0_1307
	s_and_b64 vcc, exec, s[16:17]
	s_cbranch_vccz .LBB0_1310
	s_barrier

;     __host__ __device__ bool next(int i, Unit& u) const { const int L = i * G + c; if (L >= 16 * nkc) return false; u.kc = L % nkc; const int t = L / nkc; u.pn = t & 3; u.pm = 33 * (t >> 2); return true; }
; #define PG8_STAGE(bufoff, gbase, voff) do { _Pragma("unroll") for (int _i = 0; _i < 2; ++_i) \
;         __builtin_amdgcn_global_load_lds((const unsigned*)((const char*)(gbase) + (voff)[_i]), (PG8_LAS unsigned*)(lds + (bufoff) + ldsw + _i * 8192), 16, 0, 0); } while (0)
; #define PG8_LDA(dst, b, h) do { _Pragma("unroll") for (int m = 0; m < 4; ++m) _Pragma("unroll") for (int k = 0; k < 2; ++k) dst[m][k] = *(const PG8_LAS bf16x8*)(lds + PG8_SA(b, h) + aoff + m * 2048 + k * 1024); } while (0)
; #define PG8_LDB(dst, b, h) do { _Pragma("unroll") for (int n = 0; n < 2; ++n) _Pragma("unroll") for (int k = 0; k < 2; ++k) dst[n][k] = *(const PG8_LAS bf16x8*)(lds + PG8_SB(b, h) + boff + n * 2048 + k * 1024); } while (0)
; #define PG8_BAR __builtin_amdgcn_s_barrier()
; template <class Epi, class Sched, bool ALIGN_EPI = false, bool SP2 = false>
; __device__ __forceinline__ void gemm_phase(PG8_LAS unsigned char* lds, const Gemm g, const Sched& S, const Epi& E) {
;     ...
;         const bool has_next = S.next(ui + 1, nxt);
;         const char* nA = has_next ? (const char*)g.A + (size_t)nxt.pm * tstep + (size_t)nxt.kc * cstep : cA; const char* nB = has_next ? (const char*)g.Bt + (size_t)nxt.pn * tstep + (size_t)nxt.kc * cstep : cB;
;         for (int t = 0; t < nt; t += 2) {
;             const bool last = (t == nt - 2);
;             const char* a1 = cA + (size_t)(t + 1) * kstep;
;             const char* a2 = last ? nA : cA + (size_t)(t + 2) * kstep; const char* b2 = last ? nB : cB + (size_t)(t + 2) * kstep;
;             const char* a3 = a2 + kstep; const char* b3 = b2 + kstep;
;             if (last && has_next) S.a_ready(nxt);
;             if constexpr (SP2) {
;             PG8_LDB(B0, 0, 0); PG8_LDB(B1, 0, 1); PG8_SCHED; PG8_LDA(At, 0, 0); PG8_STAGE(PG8_SA(1, 1), a1 + hstep, voffA);
;             PG8_WAIT_V(8); PG8_WAIT_L(0); PG8_BAR; PG8_MMA(0, 0, At, B0); PG8_MMA(0, 1, At, B1); PG8_BAR; PG8_SCHED;
;             PG8_LDA(At, 0, 1); PG8_STAGE(PG8_SB(0, 0), b2, voffB); PG8_STAGE(PG8_SB(0, 1), b2 + hstep, voffB); PG8_STAGE(PG8_SA(0, 0), a2, voffA);
;             PG8_WAIT_V(8); PG8_WAIT_L(0); PG8_BAR; PG8_MMA(1, 0, At, B0); PG8_MMA(1, 1, At, B1); PG8_BAR; PG8_SCHED;
.LBB0_1437:
	s_ashr_i32 s19, s18, 31
	s_lshl_b64 s[20:21], s[18:19], 19
	s_add_u32 s20, s46, s20
	s_addc_u32 s21, s47, s21
	s_and_b64 s[22:23], s[6:7], exec
	s_cselect_b32 s19, s21, s37
	s_cselect_b32 s66, s20, s36
	s_ashr_i32 s17, s16, 31
	s_lshl_b64 s[22:23], s[16:17], 19
	s_add_u32 s22, s1, s22
	s_addc_u32 s23, s3, s23
	s_and_b64 s[50:51], s[6:7], exec
	s_cselect_b32 s17, s23, s41
	s_cselect_b32 s67, s22, s40
	s_add_u32 s36, s36, 0x40080
	s_addc_u32 s37, s37, 0
	s_add_u32 s68, s40, 0x100
	s_addc_u32 s69, s41, 0
	s_mov_b32 s70, -2
	ds_read_b128 v[166:169], v149
	ds_read_b128 v[170:173], v150
	ds_read_b128 v[174:177], v151
	ds_read_b128 v[178:181], v152
	ds_read_b128 v[182:185], v153
	ds_read_b128 v[186:189], v154
	ds_read_b128 v[190:193], v155
	ds_read_b128 v[194:197], v156
	s_add_u32 s40, s36, 0xfffc0080
	s_addc_u32 s41, s37, -1
	s_cmp_eq_u32 s70, 12
	s_cselect_b32 s51, s19, s41
	s_cselect_b32 s50, s66, s40
	s_cselect_b32 s41, s17, s69
	s_cselect_b32 s40, s67, s68
	s_mov_b32 m0, s63
	v_lshl_add_u64 v[144:145], s[36:37], 0, v[136:137]
	ds_read_b128 v[198:201], v147
	ds_read_b128 v[202:205], v147 offset:1024
	ds_read_b128 v[206:209], v147 offset:2048
	ds_read_b128 v[210:213], v147 offset:3072
	ds_read_b128 v[214:217], v147 offset:4096
	ds_read_b128 v[218:221], v147 offset:5120
	ds_read_b128 v[224:227], v147 offset:6144
	ds_read_b128 v[236:239], v147 offset:7168
	global_load_lds_dwordx4 v[144:145], off
	v_lshl_add_u64 v[144:145], s[36:37], 0, v[138:139]
	s_mov_b32 m0, s64
	s_nop 0
	global_load_lds_dwordx4 v[144:145], off
	s_waitcnt vmcnt(8)
	s_waitcnt lgkmcnt(0)
	s_barrier
	s_setprio 1
	v_mfma_f32_16x16x32_bf16 v[124:127], v[166:169], v[198:201], 0
	v_mfma_f32_16x16x32_bf16 v[120:123], v[174:177], v[198:201], 0
	v_mfma_f32_16x16x32_bf16 v[108:111], v[166:169], v[206:209], 0
	v_mfma_f32_16x16x32_bf16 v[104:107], v[174:177], v[206:209], 0
	v_mfma_f32_16x16x32_bf16 v[92:95], v[166:169], v[214:217], 0
	v_mfma_f32_16x16x32_bf16 v[88:91], v[174:177], v[214:217], 0
	v_mfma_f32_16x16x32_bf16 v[76:79], v[166:169], v[224:227], 0
	v_mfma_f32_16x16x32_bf16 v[72:75], v[174:177], v[224:227], 0
	v_mfma_f32_16x16x32_bf16 v[124:127], v[170:173], v[202:205], v[124:127]
	v_mfma_f32_16x16x32_bf16 v[120:123], v[178:181], v[202:205], v[120:123]
	v_mfma_f32_16x16x32_bf16 v[108:111], v[170:173], v[210:213], v[108:111]
	v_mfma_f32_16x16x32_bf16 v[104:107], v[178:181], v[210:213], v[104:107]
	v_mfma_f32_16x16x32_bf16 v[92:95], v[170:173], v[218:221], v[92:95]
	v_mfma_f32_16x16x32_bf16 v[88:91], v[178:181], v[218:221], v[88:91]
	v_mfma_f32_16x16x32_bf16 v[76:79], v[170:173], v[236:239], v[76:79]
	v_mfma_f32_16x16x32_bf16 v[72:75], v[178:181], v[236:239], v[72:75]
	v_mfma_f32_16x16x32_bf16 v[116:119], v[182:185], v[198:201], 0
	v_mfma_f32_16x16x32_bf16 v[112:115], v[190:193], v[198:201], 0
	v_mfma_f32_16x16x32_bf16 v[100:103], v[182:185], v[206:209], 0
	v_mfma_f32_16x16x32_bf16 v[96:99], v[190:193], v[206:209], 0
	v_mfma_f32_16x16x32_bf16 v[84:87], v[182:185], v[214:217], 0
	v_mfma_f32_16x16x32_bf16 v[80:83], v[190:193], v[214:217], 0
	v_mfma_f32_16x16x32_bf16 v[68:71], v[182:185], v[224:227], 0
	v_mfma_f32_16x16x32_bf16 v[64:67], v[190:193], v[224:227], 0
	v_mfma_f32_16x16x32_bf16 v[116:119], v[186:189], v[202:205], v[116:119]
	v_mfma_f32_16x16x32_bf16 v[112:115], v[194:197], v[202:205], v[112:115]
	v_mfma_f32_16x16x32_bf16 v[100:103], v[186:189], v[210:213], v[100:103]
	v_mfma_f32_16x16x32_bf16 v[96:99], v[194:197], v[210:213], v[96:99]
	v_mfma_f32_16x16x32_bf16 v[84:87], v[186:189], v[218:221], v[84:87]
	v_mfma_f32_16x16x32_bf16 v[80:83], v[194:197], v[218:221], v[80:83]
	v_mfma_f32_16x16x32_bf16 v[68:71], v[186:189], v[236:239], v[68:71]
	v_mfma_f32_16x16x32_bf16 v[64:67], v[194:197], v[236:239], v[64:67]
	s_setprio 0
	s_barrier
	s_mov_b32 m0, s15
	v_lshl_add_u64 v[144:145], s[40:41], 0, v[132:133]
	s_add_u32 s72, s40, 0x40000
	ds_read_b128 v[198:201], v147 offset:16384
	ds_read_b128 v[202:205], v147 offset:17408
	ds_read_b128 v[206:209], v147 offset:18432
	ds_read_b128 v[210:213], v147 offset:19456
	ds_read_b128 v[214:217], v147 offset:20480
	ds_read_b128 v[218:221], v147 offset:21504
	ds_read_b128 v[224:227], v147 offset:22528
	ds_read_b128 v[236:239], v147 offset:23552
	global_load_lds_dwordx4 v[144:145], off
	v_lshl_add_u64 v[228:229], s[40:41], 0, v[128:129]
	s_mov_b32 m0, s25
	s_addc_u32 s73, s41, 0
	global_load_lds_dwordx4 v[228:229], off
	v_lshl_add_u64 v[240:241], s[72:73], 0, v[132:133]
	s_mov_b32 m0, s39
	v_lshl_add_u64 v[242:243], s[50:51], 0, v[130:131]
	global_load_lds_dwordx4 v[240:241], off
	v_lshl_add_u64 v[240:241], s[72:73], 0, v[128:129]
	s_mov_b32 m0, s43
	s_nop 0
	global_load_lds_dwordx4 v[240:241], off
	v_lshl_add_u64 v[240:241], s[50:51], 0, v[134:135]
	s_mov_b32 m0, s4
	s_nop 0
	global_load_lds_dwordx4 v[240:241], off
	s_mov_b32 m0, s52
	s_nop 0
	global_load_lds_dwordx4 v[242:243], off
	s_waitcnt vmcnt(8)
	s_waitcnt lgkmcnt(0)
	s_barrier
; #define PG8_STAGE(bufoff, gbase, voff) do { _Pragma("unroll") for (int _i = 0; _i < 2; ++_i) \
;         __builtin_amdgcn_global_load_lds((const unsigned*)((const char*)(gbase) + (voff)[_i]), (PG8_LAS unsigned*)(lds + (bufoff) + ldsw + _i * 8192), 16, 0, 0); } while (0)
; #define PG8_LDA(dst, b, h) do { _Pragma("unroll") for (int m = 0; m < 4; ++m) _Pragma("unroll") for (int k = 0; k < 2; ++k) dst[m][k] = *(const PG8_LAS bf16x8*)(lds + PG8_SA(b, h) + aoff + m * 2048 + k * 1024); } while (0)
; #define PG8_LDB(dst, b, h) do { _Pragma("unroll") for (int n = 0; n < 2; ++n) _Pragma("unroll") for (int k = 0; k < 2; ++k) dst[n][k] = *(const PG8_LAS bf16x8*)(lds + PG8_SB(b, h) + boff + n * 2048 + k * 1024); } while (0)
; #define PG8_MMA(ai, bj, At, Bt) do { __builtin_amdgcn_s_setprio(1); _Pragma("unroll") for (int m = 0; m < 4; ++m) _Pragma("unroll") for (int n = 0; n < 2; ++n) _Pragma("unroll") for (int k = 0; k < 2; ++k) \
;         acc[ai][bj][m][n] = __builtin_amdgcn_mfma_f32_16x16x32_bf16(Bt[n][k], At[m][k], acc[ai][bj][m][n], 0, 0, 0); __builtin_amdgcn_s_setprio(0); } while (0)
; #define PG8_WAIT_V(n) asm volatile("s_waitcnt vmcnt(" #n ")" ::: "memory")
; template <class Epi, class Sched, bool ALIGN_EPI = false, bool SP2 = false>
; __device__ __forceinline__ void gemm_phase(PG8_LAS unsigned char* lds, const Gemm g, const Sched& S, const Epi& E) {
;     ...
;             PG8_LDB(B0, 0, 0); PG8_LDB(B1, 0, 1); PG8_SCHED; PG8_LDA(At, 0, 0); PG8_STAGE(PG8_SA(1, 1), a1 + hstep, voffA);
;             PG8_WAIT_V(8); PG8_WAIT_L(0); PG8_BAR; PG8_MMA(0, 0, At, B0); PG8_MMA(0, 1, At, B1); PG8_BAR; PG8_SCHED;
;             PG8_LDA(At, 0, 1); PG8_STAGE(PG8_SB(0, 0), b2, voffB); PG8_STAGE(PG8_SB(0, 1), b2 + hstep, voffB); PG8_STAGE(PG8_SA(0, 0), a2, voffA);
;             PG8_WAIT_V(8); PG8_WAIT_L(0); PG8_BAR; PG8_MMA(1, 0, At, B0); PG8_MMA(1, 1, At, B1); PG8_BAR; PG8_SCHED;
;             PG8_LDB(B0, 1, 0); PG8_LDB(B1, 1, 1); PG8_SCHED; PG8_LDA(At, 1, 0); PG8_STAGE(PG8_SA(0, 1), a2 + hstep, voffA);
;             PG8_WAIT_V(8); PG8_WAIT_L(0); PG8_BAR; PG8_MMA(0, 0, At, B0); PG8_MMA(0, 1, At, B1); PG8_BAR; PG8_SCHED;
;             PG8_LDA(At, 1, 1); PG8_STAGE(PG8_SB(1, 0), b3, voffB); PG8_STAGE(PG8_SB(1, 1), b3 + hstep, voffB); PG8_STAGE(PG8_SA(1, 0), a3, voffA);
;             PG8_WAIT_V(8); PG8_WAIT_L(0); PG8_BAR; PG8_MMA(1, 0, At, B0); PG8_MMA(1, 1, At, B1); PG8_BAR; PG8_SCHED;
	s_setprio 1
	v_mfma_f32_16x16x32_bf16 v[60:63], v[166:169], v[198:201], 0
	v_mfma_f32_16x16x32_bf16 v[56:59], v[174:177], v[198:201], 0
	v_mfma_f32_16x16x32_bf16 v[44:47], v[166:169], v[206:209], 0
	v_mfma_f32_16x16x32_bf16 v[40:43], v[174:177], v[206:209], 0
	v_mfma_f32_16x16x32_bf16 v[28:31], v[166:169], v[214:217], 0
	v_mfma_f32_16x16x32_bf16 v[24:27], v[174:177], v[214:217], 0
	v_mfma_f32_16x16x32_bf16 v[12:15], v[166:169], v[224:227], 0
	v_mfma_f32_16x16x32_bf16 v[8:11], v[174:177], v[224:227], 0
	v_mfma_f32_16x16x32_bf16 v[60:63], v[170:173], v[202:205], v[60:63]
	v_mfma_f32_16x16x32_bf16 v[56:59], v[178:181], v[202:205], v[56:59]
	v_mfma_f32_16x16x32_bf16 v[44:47], v[170:173], v[210:213], v[44:47]
	v_mfma_f32_16x16x32_bf16 v[40:43], v[178:181], v[210:213], v[40:43]
	v_mfma_f32_16x16x32_bf16 v[28:31], v[170:173], v[218:221], v[28:31]
	v_mfma_f32_16x16x32_bf16 v[24:27], v[178:181], v[218:221], v[24:27]
	v_mfma_f32_16x16x32_bf16 v[12:15], v[170:173], v[236:239], v[12:15]
	v_mfma_f32_16x16x32_bf16 v[8:11], v[178:181], v[236:239], v[8:11]
	v_mfma_f32_16x16x32_bf16 v[52:55], v[182:185], v[198:201], 0
	v_mfma_f32_16x16x32_bf16 v[48:51], v[190:193], v[198:201], 0
	v_mfma_f32_16x16x32_bf16 v[36:39], v[182:185], v[206:209], 0
	v_mfma_f32_16x16x32_bf16 v[32:35], v[190:193], v[206:209], 0
	v_mfma_f32_16x16x32_bf16 v[20:23], v[182:185], v[214:217], 0
	v_mfma_f32_16x16x32_bf16 v[16:19], v[190:193], v[214:217], 0
	v_mfma_f32_16x16x32_bf16 v[4:7], v[182:185], v[224:227], 0
	v_mfma_f32_16x16x32_bf16 v[0:3], v[190:193], v[224:227], 0
	v_mfma_f32_16x16x32_bf16 v[52:55], v[186:189], v[202:205], v[52:55]
	v_mfma_f32_16x16x32_bf16 v[48:51], v[194:197], v[202:205], v[48:51]
	v_mfma_f32_16x16x32_bf16 v[36:39], v[186:189], v[210:213], v[36:39]
	v_mfma_f32_16x16x32_bf16 v[32:35], v[194:197], v[210:213], v[32:35]
	v_mfma_f32_16x16x32_bf16 v[20:23], v[186:189], v[218:221], v[20:23]
	v_mfma_f32_16x16x32_bf16 v[16:19], v[194:197], v[218:221], v[16:19]
	v_mfma_f32_16x16x32_bf16 v[4:7], v[186:189], v[236:239], v[4:7]
	v_mfma_f32_16x16x32_bf16 v[0:3], v[194:197], v[236:239], v[0:3]
	s_setprio 0
	s_barrier
	ds_read_b128 v[166:169], v157
	ds_read_b128 v[170:173], v158
	ds_read_b128 v[174:177], v159
	ds_read_b128 v[178:181], v160
	ds_read_b128 v[182:185], v161
	ds_read_b128 v[186:189], v162
	ds_read_b128 v[190:193], v163
	ds_read_b128 v[194:197], v164
	s_add_u32 s50, s50, 0x40000
	s_addc_u32 s51, s51, 0
	s_mov_b32 m0, s53
	v_lshl_add_u64 v[244:245], s[50:51], 0, v[134:135]
	ds_read_b128 v[198:201], v147 offset:32768
	ds_read_b128 v[202:205], v147 offset:33792
	ds_read_b128 v[206:209], v147 offset:34816
	ds_read_b128 v[210:213], v147 offset:35840
	ds_read_b128 v[214:217], v147 offset:36864
	ds_read_b128 v[218:221], v147 offset:37888
	ds_read_b128 v[224:227], v147 offset:38912
	ds_read_b128 v[236:239], v147 offset:39936
	global_load_lds_dwordx4 v[244:245], off
	v_lshl_add_u64 v[244:245], s[50:51], 0, v[130:131]
	s_mov_b32 m0, s54
	s_nop 0
	global_load_lds_dwordx4 v[244:245], off
	s_waitcnt vmcnt(8)
	s_waitcnt lgkmcnt(0)
	s_barrier
	s_setprio 1
	v_mfma_f32_16x16x32_bf16 v[124:127], v[166:169], v[198:201], v[124:127]
	v_mfma_f32_16x16x32_bf16 v[120:123], v[174:177], v[198:201], v[120:123]
	v_mfma_f32_16x16x32_bf16 v[108:111], v[166:169], v[206:209], v[108:111]
	v_mfma_f32_16x16x32_bf16 v[104:107], v[174:177], v[206:209], v[104:107]
	v_mfma_f32_16x16x32_bf16 v[92:95], v[166:169], v[214:217], v[92:95]
	v_mfma_f32_16x16x32_bf16 v[88:91], v[174:177], v[214:217], v[88:91]
	v_mfma_f32_16x16x32_bf16 v[76:79], v[166:169], v[224:227], v[76:79]
	v_mfma_f32_16x16x32_bf16 v[72:75], v[174:177], v[224:227], v[72:75]
	v_mfma_f32_16x16x32_bf16 v[124:127], v[170:173], v[202:205], v[124:127]
	v_mfma_f32_16x16x32_bf16 v[120:123], v[178:181], v[202:205], v[120:123]
	v_mfma_f32_16x16x32_bf16 v[108:111], v[170:173], v[210:213], v[108:111]
	v_mfma_f32_16x16x32_bf16 v[104:107], v[178:181], v[210:213], v[104:107]
	v_mfma_f32_16x16x32_bf16 v[92:95], v[170:173], v[218:221], v[92:95]
	v_mfma_f32_16x16x32_bf16 v[88:91], v[178:181], v[218:221], v[88:91]
	v_mfma_f32_16x16x32_bf16 v[76:79], v[170:173], v[236:239], v[76:79]
	v_mfma_f32_16x16x32_bf16 v[72:75], v[178:181], v[236:239], v[72:75]
	v_mfma_f32_16x16x32_bf16 v[116:119], v[182:185], v[198:201], v[116:119]
	v_mfma_f32_16x16x32_bf16 v[112:115], v[190:193], v[198:201], v[112:115]
	v_mfma_f32_16x16x32_bf16 v[100:103], v[182:185], v[206:209], v[100:103]
	v_mfma_f32_16x16x32_bf16 v[96:99], v[190:193], v[206:209], v[96:99]
	v_mfma_f32_16x16x32_bf16 v[84:87], v[182:185], v[214:217], v[84:87]
	v_mfma_f32_16x16x32_bf16 v[80:83], v[190:193], v[214:217], v[80:83]
	v_mfma_f32_16x16x32_bf16 v[68:71], v[182:185], v[224:227], v[68:71]
	v_mfma_f32_16x16x32_bf16 v[64:67], v[190:193], v[224:227], v[64:67]
	v_mfma_f32_16x16x32_bf16 v[116:119], v[186:189], v[202:205], v[116:119]
	v_mfma_f32_16x16x32_bf16 v[112:115], v[194:197], v[202:205], v[112:115]
	v_mfma_f32_16x16x32_bf16 v[100:103], v[186:189], v[210:213], v[100:103]
	v_mfma_f32_16x16x32_bf16 v[96:99], v[194:197], v[210:213], v[96:99]
	v_mfma_f32_16x16x32_bf16 v[84:87], v[186:189], v[218:221], v[84:87]
	v_mfma_f32_16x16x32_bf16 v[80:83], v[194:197], v[218:221], v[80:83]
	v_mfma_f32_16x16x32_bf16 v[68:71], v[186:189], v[236:239], v[68:71]
	v_mfma_f32_16x16x32_bf16 v[64:67], v[194:197], v[236:239], v[64:67]
	s_setprio 0
	s_barrier
; #define PG8_STAGE(bufoff, gbase, voff) do { _Pragma("unroll") for (int _i = 0; _i < 2; ++_i) \
;         __builtin_amdgcn_global_load_lds((const unsigned*)((const char*)(gbase) + (voff)[_i]), (PG8_LAS unsigned*)(lds + (bufoff) + ldsw + _i * 8192), 16, 0, 0); } while (0)
; #define PG8_LDA(dst, b, h) do { _Pragma("unroll") for (int m = 0; m < 4; ++m) _Pragma("unroll") for (int k = 0; k < 2; ++k) dst[m][k] = *(const PG8_LAS bf16x8*)(lds + PG8_SA(b, h) + aoff + m * 2048 + k * 1024); } while (0)
; #define PG8_LDB(dst, b, h) do { _Pragma("unroll") for (int n = 0; n < 2; ++n) _Pragma("unroll") for (int k = 0; k < 2; ++k) dst[n][k] = *(const PG8_LAS bf16x8*)(lds + PG8_SB(b, h) + boff + n * 2048 + k * 1024); } while (0)
; template <class Epi, class Sched, bool ALIGN_EPI = false, bool SP2 = false>
; __device__ __forceinline__ void gemm_phase(PG8_LAS unsigned char* lds, const Gemm g, const Sched& S, const Epi& E) {
;     ...
;         for (int t = 0; t < nt; t += 2) {
;             const bool last = (t == nt - 2);
;             const char* a1 = cA + (size_t)(t + 1) * kstep;
;             const char* a2 = last ? nA : cA + (size_t)(t + 2) * kstep; const char* b2 = last ? nB : cB + (size_t)(t + 2) * kstep;
;             const char* a3 = a2 + kstep; const char* b3 = b2 + kstep;
;             if (last && has_next) S.a_ready(nxt);
;             if constexpr (SP2) {
;             PG8_LDB(B0, 0, 0); PG8_LDB(B1, 0, 1); PG8_SCHED; PG8_LDA(At, 0, 0); PG8_STAGE(PG8_SA(1, 1), a1 + hstep, voffA);
;             PG8_WAIT_V(8); PG8_WAIT_L(0); PG8_BAR; PG8_MMA(0, 0, At, B0); PG8_MMA(0, 1, At, B1); PG8_BAR; PG8_SCHED;
;             PG8_LDA(At, 0, 1); PG8_STAGE(PG8_SB(0, 0), b2, voffB); PG8_STAGE(PG8_SB(0, 1), b2 + hstep, voffB); PG8_STAGE(PG8_SA(0, 0), a2, voffA);
;             PG8_WAIT_V(8); PG8_WAIT_L(0); PG8_BAR; PG8_MMA(1, 0, At, B0); PG8_MMA(1, 1, At, B1); PG8_BAR; PG8_SCHED;
;             PG8_LDB(B0, 1, 0); PG8_LDB(B1, 1, 1); PG8_SCHED; PG8_LDA(At, 1, 0); PG8_STAGE(PG8_SA(0, 1), a2 + hstep, voffA);
;             PG8_WAIT_V(8); PG8_WAIT_L(0); PG8_BAR; PG8_MMA(0, 0, At, B0); PG8_MMA(0, 1, At, B1); PG8_BAR; PG8_SCHED;
;             PG8_LDA(At, 1, 1); PG8_STAGE(PG8_SB(1, 0), b3, voffB); PG8_STAGE(PG8_SB(1, 1), b3 + hstep, voffB); PG8_STAGE(PG8_SA(1, 0), a3, voffA);
;             PG8_WAIT_V(8); PG8_WAIT_L(0); PG8_BAR; PG8_MMA(1, 0, At, B0); PG8_MMA(1, 1, At, B1); PG8_BAR; PG8_SCHED;
	s_mov_b32 m0, s56
	v_lshl_add_u64 v[144:145], v[144:145], 0, s[10:11]
	s_add_u32 s40, s40, 0x40080
	ds_read_b128 v[198:201], v147 offset:49152
	ds_read_b128 v[202:205], v147 offset:50176
	ds_read_b128 v[206:209], v147 offset:51200
	ds_read_b128 v[210:213], v147 offset:52224
	ds_read_b128 v[214:217], v147 offset:53248
	ds_read_b128 v[218:221], v147 offset:54272
	ds_read_b128 v[224:227], v147 offset:55296
	ds_read_b128 v[236:239], v147 offset:56320
	global_load_lds_dwordx4 v[144:145], off
	v_lshl_add_u64 v[144:145], v[228:229], 0, s[10:11]
	s_mov_b32 m0, s57
	s_addc_u32 s41, s41, 0
	global_load_lds_dwordx4 v[144:145], off
	v_lshl_add_u64 v[144:145], s[40:41], 0, v[132:133]
	s_mov_b32 m0, s60
	s_nop 0
	global_load_lds_dwordx4 v[144:145], off
	v_lshl_add_u64 v[144:145], s[40:41], 0, v[128:129]
	s_mov_b32 m0, s61
	s_nop 0
	global_load_lds_dwordx4 v[144:145], off
	v_lshl_add_u64 v[144:145], v[240:241], 0, s[10:11]
	s_mov_b32 m0, s58
	s_nop 0
	global_load_lds_dwordx4 v[144:145], off
	v_lshl_add_u64 v[144:145], v[242:243], 0, s[10:11]
	s_mov_b32 m0, s59
	s_nop 0
	global_load_lds_dwordx4 v[144:145], off
	s_waitcnt vmcnt(8)
	s_waitcnt lgkmcnt(0)
	s_barrier
	s_setprio 1
	v_mfma_f32_16x16x32_bf16 v[60:63], v[166:169], v[198:201], v[60:63]
	v_mfma_f32_16x16x32_bf16 v[56:59], v[174:177], v[198:201], v[56:59]
	v_mfma_f32_16x16x32_bf16 v[44:47], v[166:169], v[206:209], v[44:47]
	v_mfma_f32_16x16x32_bf16 v[40:43], v[174:177], v[206:209], v[40:43]
	v_mfma_f32_16x16x32_bf16 v[28:31], v[166:169], v[214:217], v[28:31]
	v_mfma_f32_16x16x32_bf16 v[24:27], v[174:177], v[214:217], v[24:27]
	v_mfma_f32_16x16x32_bf16 v[12:15], v[166:169], v[224:227], v[12:15]
	v_mfma_f32_16x16x32_bf16 v[8:11], v[174:177], v[224:227], v[8:11]
	v_mfma_f32_16x16x32_bf16 v[60:63], v[170:173], v[202:205], v[60:63]
	v_mfma_f32_16x16x32_bf16 v[56:59], v[178:181], v[202:205], v[56:59]
	v_mfma_f32_16x16x32_bf16 v[44:47], v[170:173], v[210:213], v[44:47]
	v_mfma_f32_16x16x32_bf16 v[40:43], v[178:181], v[210:213], v[40:43]
	v_mfma_f32_16x16x32_bf16 v[28:31], v[170:173], v[218:221], v[28:31]
	v_mfma_f32_16x16x32_bf16 v[24:27], v[178:181], v[218:221], v[24:27]
	v_mfma_f32_16x16x32_bf16 v[12:15], v[170:173], v[236:239], v[12:15]
	v_mfma_f32_16x16x32_bf16 v[8:11], v[178:181], v[236:239], v[8:11]
	v_mfma_f32_16x16x32_bf16 v[52:55], v[182:185], v[198:201], v[52:55]
	v_mfma_f32_16x16x32_bf16 v[48:51], v[190:193], v[198:201], v[48:51]
	v_mfma_f32_16x16x32_bf16 v[36:39], v[182:185], v[206:209], v[36:39]
	v_mfma_f32_16x16x32_bf16 v[32:35], v[190:193], v[206:209], v[32:35]
	v_mfma_f32_16x16x32_bf16 v[20:23], v[182:185], v[214:217], v[20:23]
	v_mfma_f32_16x16x32_bf16 v[16:19], v[190:193], v[214:217], v[16:19]
	v_mfma_f32_16x16x32_bf16 v[4:7], v[182:185], v[224:227], v[4:7]
	v_mfma_f32_16x16x32_bf16 v[0:3], v[190:193], v[224:227], v[0:3]
	v_mfma_f32_16x16x32_bf16 v[52:55], v[186:189], v[202:205], v[52:55]
	v_mfma_f32_16x16x32_bf16 v[48:51], v[194:197], v[202:205], v[48:51]
	v_mfma_f32_16x16x32_bf16 v[36:39], v[186:189], v[210:213], v[36:39]
	v_mfma_f32_16x16x32_bf16 v[32:35], v[194:197], v[210:213], v[32:35]
	v_mfma_f32_16x16x32_bf16 v[20:23], v[186:189], v[218:221], v[20:23]
	v_mfma_f32_16x16x32_bf16 v[16:19], v[194:197], v[218:221], v[16:19]
	v_mfma_f32_16x16x32_bf16 v[4:7], v[186:189], v[236:239], v[4:7]
	v_mfma_f32_16x16x32_bf16 v[0:3], v[194:197], v[236:239], v[0:3]
	s_setprio 0
	s_barrier
	s_add_i32 s70, s70, 2
	s_add_u32 s36, s36, 0x100
	s_addc_u32 s37, s37, 0
	s_add_u32 s68, s68, 0x100
	s_addc_u32 s69, s69, 0
.LBB0_1438:
	ds_read_b128 v[166:169], v149
	ds_read_b128 v[170:173], v150
	ds_read_b128 v[174:177], v151
	ds_read_b128 v[178:181], v152
	ds_read_b128 v[182:185], v153
	ds_read_b128 v[186:189], v154
	ds_read_b128 v[190:193], v155
	ds_read_b128 v[194:197], v156
	s_add_u32 s40, s36, 0xfffc0080
	s_addc_u32 s41, s37, -1
	s_cmp_eq_u32 s70, 12
	s_cselect_b32 s51, s19, s41
	s_cselect_b32 s50, s66, s40
	s_cselect_b32 s41, s17, s69
	s_cselect_b32 s40, s67, s68
	s_mov_b32 m0, s63
	v_lshl_add_u64 v[144:145], s[36:37], 0, v[136:137]
	ds_read_b128 v[198:201], v147
	ds_read_b128 v[202:205], v147 offset:1024
	ds_read_b128 v[206:209], v147 offset:2048
	ds_read_b128 v[210:213], v147 offset:3072
	ds_read_b128 v[214:217], v147 offset:4096
	ds_read_b128 v[218:221], v147 offset:5120
	ds_read_b128 v[224:227], v147 offset:6144
	ds_read_b128 v[236:239], v147 offset:7168
	global_load_lds_dwordx4 v[144:145], off
	v_lshl_add_u64 v[144:145], s[36:37], 0, v[138:139]
	s_mov_b32 m0, s64
	s_nop 0
	global_load_lds_dwordx4 v[144:145], off
	s_waitcnt vmcnt(8)
	s_waitcnt lgkmcnt(0)
	s_barrier
; #define PG8_STAGE(bufoff, gbase, voff) do { _Pragma("unroll") for (int _i = 0; _i < 2; ++_i) \
;         __builtin_amdgcn_global_load_lds((const unsigned*)((const char*)(gbase) + (voff)[_i]), (PG8_LAS unsigned*)(lds + (bufoff) + ldsw + _i * 8192), 16, 0, 0); } while (0)
; #define PG8_LDA(dst, b, h) do { _Pragma("unroll") for (int m = 0; m < 4; ++m) _Pragma("unroll") for (int k = 0; k < 2; ++k) dst[m][k] = *(const PG8_LAS bf16x8*)(lds + PG8_SA(b, h) + aoff + m * 2048 + k * 1024); } while (0)
; #define PG8_LDB(dst, b, h) do { _Pragma("unroll") for (int n = 0; n < 2; ++n) _Pragma("unroll") for (int k = 0; k < 2; ++k) dst[n][k] = *(const PG8_LAS bf16x8*)(lds + PG8_SB(b, h) + boff + n * 2048 + k * 1024); } while (0)
; #define PG8_MMA(ai, bj, At, Bt) do { __builtin_amdgcn_s_setprio(1); _Pragma("unroll") for (int m = 0; m < 4; ++m) _Pragma("unroll") for (int n = 0; n < 2; ++n) _Pragma("unroll") for (int k = 0; k < 2; ++k) \
;         acc[ai][bj][m][n] = __builtin_amdgcn_mfma_f32_16x16x32_bf16(Bt[n][k], At[m][k], acc[ai][bj][m][n], 0, 0, 0); __builtin_amdgcn_s_setprio(0); } while (0)
; #define PG8_WAIT_V(n) asm volatile("s_waitcnt vmcnt(" #n ")" ::: "memory")
; template <class Epi, class Sched, bool ALIGN_EPI = false, bool SP2 = false>
; __device__ __forceinline__ void gemm_phase(PG8_LAS unsigned char* lds, const Gemm g, const Sched& S, const Epi& E) {
;     ...
;             PG8_LDB(B0, 0, 0); PG8_LDB(B1, 0, 1); PG8_SCHED; PG8_LDA(At, 0, 0); PG8_STAGE(PG8_SA(1, 1), a1 + hstep, voffA);
;             PG8_WAIT_V(8); PG8_WAIT_L(0); PG8_BAR; PG8_MMA(0, 0, At, B0); PG8_MMA(0, 1, At, B1); PG8_BAR; PG8_SCHED;
;             PG8_LDA(At, 0, 1); PG8_STAGE(PG8_SB(0, 0), b2, voffB); PG8_STAGE(PG8_SB(0, 1), b2 + hstep, voffB); PG8_STAGE(PG8_SA(0, 0), a2, voffA);
;             PG8_WAIT_V(8); PG8_WAIT_L(0); PG8_BAR; PG8_MMA(1, 0, At, B0); PG8_MMA(1, 1, At, B1); PG8_BAR; PG8_SCHED;
;             PG8_LDB(B0, 1, 0); PG8_LDB(B1, 1, 1); PG8_SCHED; PG8_LDA(At, 1, 0); PG8_STAGE(PG8_SA(0, 1), a2 + hstep, voffA);
;             PG8_WAIT_V(8); PG8_WAIT_L(0); PG8_BAR; PG8_MMA(0, 0, At, B0); PG8_MMA(0, 1, At, B1); PG8_BAR; PG8_SCHED;
;             PG8_LDA(At, 1, 1); PG8_STAGE(PG8_SB(1, 0), b3, voffB); PG8_STAGE(PG8_SB(1, 1), b3 + hstep, voffB); PG8_STAGE(PG8_SA(1, 0), a3, voffA);
;             PG8_WAIT_V(8); PG8_WAIT_L(0); PG8_BAR; PG8_MMA(1, 0, At, B0); PG8_MMA(1, 1, At, B1); PG8_BAR; PG8_SCHED;
	s_setprio 1
	v_mfma_f32_16x16x32_bf16 v[124:127], v[166:169], v[198:201], v[124:127]
	v_mfma_f32_16x16x32_bf16 v[120:123], v[174:177], v[198:201], v[120:123]
	v_mfma_f32_16x16x32_bf16 v[108:111], v[166:169], v[206:209], v[108:111]
	v_mfma_f32_16x16x32_bf16 v[104:107], v[174:177], v[206:209], v[104:107]
	v_mfma_f32_16x16x32_bf16 v[92:95], v[166:169], v[214:217], v[92:95]
	v_mfma_f32_16x16x32_bf16 v[88:91], v[174:177], v[214:217], v[88:91]
	v_mfma_f32_16x16x32_bf16 v[76:79], v[166:169], v[224:227], v[76:79]
	v_mfma_f32_16x16x32_bf16 v[72:75], v[174:177], v[224:227], v[72:75]
	v_mfma_f32_16x16x32_bf16 v[124:127], v[170:173], v[202:205], v[124:127]
	v_mfma_f32_16x16x32_bf16 v[120:123], v[178:181], v[202:205], v[120:123]
	v_mfma_f32_16x16x32_bf16 v[108:111], v[170:173], v[210:213], v[108:111]
	v_mfma_f32_16x16x32_bf16 v[104:107], v[178:181], v[210:213], v[104:107]
	v_mfma_f32_16x16x32_bf16 v[92:95], v[170:173], v[218:221], v[92:95]
	v_mfma_f32_16x16x32_bf16 v[88:91], v[178:181], v[218:221], v[88:91]
	v_mfma_f32_16x16x32_bf16 v[76:79], v[170:173], v[236:239], v[76:79]
	v_mfma_f32_16x16x32_bf16 v[72:75], v[178:181], v[236:239], v[72:75]
	v_mfma_f32_16x16x32_bf16 v[116:119], v[182:185], v[198:201], v[116:119]
	v_mfma_f32_16x16x32_bf16 v[112:115], v[190:193], v[198:201], v[112:115]
	v_mfma_f32_16x16x32_bf16 v[100:103], v[182:185], v[206:209], v[100:103]
	v_mfma_f32_16x16x32_bf16 v[96:99], v[190:193], v[206:209], v[96:99]
	v_mfma_f32_16x16x32_bf16 v[84:87], v[182:185], v[214:217], v[84:87]
	v_mfma_f32_16x16x32_bf16 v[80:83], v[190:193], v[214:217], v[80:83]
	v_mfma_f32_16x16x32_bf16 v[68:71], v[182:185], v[224:227], v[68:71]
	v_mfma_f32_16x16x32_bf16 v[64:67], v[190:193], v[224:227], v[64:67]
	v_mfma_f32_16x16x32_bf16 v[116:119], v[186:189], v[202:205], v[116:119]
	v_mfma_f32_16x16x32_bf16 v[112:115], v[194:197], v[202:205], v[112:115]
	v_mfma_f32_16x16x32_bf16 v[100:103], v[186:189], v[210:213], v[100:103]
	v_mfma_f32_16x16x32_bf16 v[96:99], v[194:197], v[210:213], v[96:99]
	v_mfma_f32_16x16x32_bf16 v[84:87], v[186:189], v[218:221], v[84:87]
	v_mfma_f32_16x16x32_bf16 v[80:83], v[194:197], v[218:221], v[80:83]
	v_mfma_f32_16x16x32_bf16 v[68:71], v[186:189], v[236:239], v[68:71]
	v_mfma_f32_16x16x32_bf16 v[64:67], v[194:197], v[236:239], v[64:67]
	s_setprio 0
	s_barrier
	s_mov_b32 m0, s15
	v_lshl_add_u64 v[144:145], s[40:41], 0, v[132:133]
	s_add_u32 s72, s40, 0x40000
	ds_read_b128 v[198:201], v147 offset:16384
	ds_read_b128 v[202:205], v147 offset:17408
	ds_read_b128 v[206:209], v147 offset:18432
	ds_read_b128 v[210:213], v147 offset:19456
	ds_read_b128 v[214:217], v147 offset:20480
	ds_read_b128 v[218:221], v147 offset:21504
	ds_read_b128 v[224:227], v147 offset:22528
	ds_read_b128 v[236:239], v147 offset:23552
	global_load_lds_dwordx4 v[144:145], off
	v_lshl_add_u64 v[228:229], s[40:41], 0, v[128:129]
	s_mov_b32 m0, s25
	s_addc_u32 s73, s41, 0
	global_load_lds_dwordx4 v[228:229], off
	v_lshl_add_u64 v[240:241], s[72:73], 0, v[132:133]
	s_mov_b32 m0, s39
	v_lshl_add_u64 v[242:243], s[50:51], 0, v[130:131]
	global_load_lds_dwordx4 v[240:241], off
	v_lshl_add_u64 v[240:241], s[72:73], 0, v[128:129]
	s_mov_b32 m0, s43
	s_nop 0
	global_load_lds_dwordx4 v[240:241], off
	v_lshl_add_u64 v[240:241], s[50:51], 0, v[134:135]
	s_mov_b32 m0, s4
	s_nop 0
	global_load_lds_dwordx4 v[240:241], off
	s_mov_b32 m0, s52
	s_nop 0
	global_load_lds_dwordx4 v[242:243], off
	s_waitcnt vmcnt(8)
	s_waitcnt lgkmcnt(0)
	s_barrier
	s_setprio 1
	v_mfma_f32_16x16x32_bf16 v[60:63], v[166:169], v[198:201], v[60:63]
	v_mfma_f32_16x16x32_bf16 v[56:59], v[174:177], v[198:201], v[56:59]
	v_mfma_f32_16x16x32_bf16 v[44:47], v[166:169], v[206:209], v[44:47]
	v_mfma_f32_16x16x32_bf16 v[40:43], v[174:177], v[206:209], v[40:43]
	v_mfma_f32_16x16x32_bf16 v[28:31], v[166:169], v[214:217], v[28:31]
	v_mfma_f32_16x16x32_bf16 v[24:27], v[174:177], v[214:217], v[24:27]
	v_mfma_f32_16x16x32_bf16 v[12:15], v[166:169], v[224:227], v[12:15]
	v_mfma_f32_16x16x32_bf16 v[8:11], v[174:177], v[224:227], v[8:11]
	v_mfma_f32_16x16x32_bf16 v[60:63], v[170:173], v[202:205], v[60:63]
	v_mfma_f32_16x16x32_bf16 v[56:59], v[178:181], v[202:205], v[56:59]
	v_mfma_f32_16x16x32_bf16 v[44:47], v[170:173], v[210:213], v[44:47]
	v_mfma_f32_16x16x32_bf16 v[40:43], v[178:181], v[210:213], v[40:43]
	v_mfma_f32_16x16x32_bf16 v[28:31], v[170:173], v[218:221], v[28:31]
	v_mfma_f32_16x16x32_bf16 v[24:27], v[178:181], v[218:221], v[24:27]
	v_mfma_f32_16x16x32_bf16 v[12:15], v[170:173], v[236:239], v[12:15]
	v_mfma_f32_16x16x32_bf16 v[8:11], v[178:181], v[236:239], v[8:11]
	v_mfma_f32_16x16x32_bf16 v[52:55], v[182:185], v[198:201], v[52:55]
	v_mfma_f32_16x16x32_bf16 v[48:51], v[190:193], v[198:201], v[48:51]
	v_mfma_f32_16x16x32_bf16 v[36:39], v[182:185], v[206:209], v[36:39]
	v_mfma_f32_16x16x32_bf16 v[32:35], v[190:193], v[206:209], v[32:35]
	v_mfma_f32_16x16x32_bf16 v[20:23], v[182:185], v[214:217], v[20:23]
	v_mfma_f32_16x16x32_bf16 v[16:19], v[190:193], v[214:217], v[16:19]
	v_mfma_f32_16x16x32_bf16 v[4:7], v[182:185], v[224:227], v[4:7]
	v_mfma_f32_16x16x32_bf16 v[0:3], v[190:193], v[224:227], v[0:3]
	v_mfma_f32_16x16x32_bf16 v[52:55], v[186:189], v[202:205], v[52:55]
	v_mfma_f32_16x16x32_bf16 v[48:51], v[194:197], v[202:205], v[48:51]
	v_mfma_f32_16x16x32_bf16 v[36:39], v[186:189], v[210:213], v[36:39]
	v_mfma_f32_16x16x32_bf16 v[32:35], v[194:197], v[210:213], v[32:35]
	v_mfma_f32_16x16x32_bf16 v[20:23], v[186:189], v[218:221], v[20:23]
	v_mfma_f32_16x16x32_bf16 v[16:19], v[194:197], v[218:221], v[16:19]
	v_mfma_f32_16x16x32_bf16 v[4:7], v[186:189], v[236:239], v[4:7]
	v_mfma_f32_16x16x32_bf16 v[0:3], v[194:197], v[236:239], v[0:3]
	s_setprio 0
	s_barrier
; #define PG8_STAGE(bufoff, gbase, voff) do { _Pragma("unroll") for (int _i = 0; _i < 2; ++_i) \
;         __builtin_amdgcn_global_load_lds((const unsigned*)((const char*)(gbase) + (voff)[_i]), (PG8_LAS unsigned*)(lds + (bufoff) + ldsw + _i * 8192), 16, 0, 0); } while (0)
; #define PG8_LDA(dst, b, h) do { _Pragma("unroll") for (int m = 0; m < 4; ++m) _Pragma("unroll") for (int k = 0; k < 2; ++k) dst[m][k] = *(const PG8_LAS bf16x8*)(lds + PG8_SA(b, h) + aoff + m * 2048 + k * 1024); } while (0)
; #define PG8_LDB(dst, b, h) do { _Pragma("unroll") for (int n = 0; n < 2; ++n) _Pragma("unroll") for (int k = 0; k < 2; ++k) dst[n][k] = *(const PG8_LAS bf16x8*)(lds + PG8_SB(b, h) + boff + n * 2048 + k * 1024); } while (0)
; #define PG8_MMA(ai, bj, At, Bt) do { __builtin_amdgcn_s_setprio(1); _Pragma("unroll") for (int m = 0; m < 4; ++m) _Pragma("unroll") for (int n = 0; n < 2; ++n) _Pragma("unroll") for (int k = 0; k < 2; ++k) \
;         acc[ai][bj][m][n] = __builtin_amdgcn_mfma_f32_16x16x32_bf16(Bt[n][k], At[m][k], acc[ai][bj][m][n], 0, 0, 0); __builtin_amdgcn_s_setprio(0); } while (0)
; template <class Epi, class Sched, bool ALIGN_EPI = false, bool SP2 = false>
; __device__ __forceinline__ void gemm_phase(PG8_LAS unsigned char* lds, const Gemm g, const Sched& S, const Epi& E) {
;     ...
;             PG8_LDB(B0, 0, 0); PG8_LDB(B1, 0, 1); PG8_SCHED; PG8_LDA(At, 0, 0); PG8_STAGE(PG8_SA(1, 1), a1 + hstep, voffA);
;             PG8_WAIT_V(8); PG8_WAIT_L(0); PG8_BAR; PG8_MMA(0, 0, At, B0); PG8_MMA(0, 1, At, B1); PG8_BAR; PG8_SCHED;
;             PG8_LDA(At, 0, 1); PG8_STAGE(PG8_SB(0, 0), b2, voffB); PG8_STAGE(PG8_SB(0, 1), b2 + hstep, voffB); PG8_STAGE(PG8_SA(0, 0), a2, voffA);
;             PG8_WAIT_V(8); PG8_WAIT_L(0); PG8_BAR; PG8_MMA(1, 0, At, B0); PG8_MMA(1, 1, At, B1); PG8_BAR; PG8_SCHED;
;             PG8_LDB(B0, 1, 0); PG8_LDB(B1, 1, 1); PG8_SCHED; PG8_LDA(At, 1, 0); PG8_STAGE(PG8_SA(0, 1), a2 + hstep, voffA);
;             PG8_WAIT_V(8); PG8_WAIT_L(0); PG8_BAR; PG8_MMA(0, 0, At, B0); PG8_MMA(0, 1, At, B1); PG8_BAR; PG8_SCHED;
;             PG8_LDA(At, 1, 1); PG8_STAGE(PG8_SB(1, 0), b3, voffB); PG8_STAGE(PG8_SB(1, 1), b3 + hstep, voffB); PG8_STAGE(PG8_SA(1, 0), a3, voffA);
;             PG8_WAIT_V(8); PG8_WAIT_L(0); PG8_BAR; PG8_MMA(1, 0, At, B0); PG8_MMA(1, 1, At, B1); PG8_BAR; PG8_SCHED;
;     ...
;         if constexpr (ALIGN_EPI) { if (wr == 0) PG8_BAR; }
	ds_read_b128 v[166:169], v157
	ds_read_b128 v[170:173], v158
	ds_read_b128 v[174:177], v159
	ds_read_b128 v[178:181], v160
	ds_read_b128 v[182:185], v161
	ds_read_b128 v[186:189], v162
	ds_read_b128 v[190:193], v163
	ds_read_b128 v[194:197], v164
	s_add_u32 s50, s50, 0x40000
	s_addc_u32 s51, s51, 0
	s_mov_b32 m0, s53
	v_lshl_add_u64 v[244:245], s[50:51], 0, v[134:135]
	ds_read_b128 v[198:201], v147 offset:32768
	ds_read_b128 v[202:205], v147 offset:33792
	ds_read_b128 v[206:209], v147 offset:34816
	ds_read_b128 v[210:213], v147 offset:35840
	ds_read_b128 v[214:217], v147 offset:36864
	ds_read_b128 v[218:221], v147 offset:37888
	ds_read_b128 v[224:227], v147 offset:38912
	ds_read_b128 v[236:239], v147 offset:39936
	global_load_lds_dwordx4 v[244:245], off
	v_lshl_add_u64 v[244:245], s[50:51], 0, v[130:131]
	s_mov_b32 m0, s54
	s_nop 0
	global_load_lds_dwordx4 v[244:245], off
	s_waitcnt vmcnt(8)
	s_waitcnt lgkmcnt(0)
	s_barrier
	s_setprio 1
	v_mfma_f32_16x16x32_bf16 v[124:127], v[166:169], v[198:201], v[124:127]
	v_mfma_f32_16x16x32_bf16 v[120:123], v[174:177], v[198:201], v[120:123]
	v_mfma_f32_16x16x32_bf16 v[108:111], v[166:169], v[206:209], v[108:111]
	v_mfma_f32_16x16x32_bf16 v[104:107], v[174:177], v[206:209], v[104:107]
	v_mfma_f32_16x16x32_bf16 v[92:95], v[166:169], v[214:217], v[92:95]
	v_mfma_f32_16x16x32_bf16 v[88:91], v[174:177], v[214:217], v[88:91]
	v_mfma_f32_16x16x32_bf16 v[76:79], v[166:169], v[224:227], v[76:79]
	v_mfma_f32_16x16x32_bf16 v[72:75], v[174:177], v[224:227], v[72:75]
	v_mfma_f32_16x16x32_bf16 v[124:127], v[170:173], v[202:205], v[124:127]
	v_mfma_f32_16x16x32_bf16 v[120:123], v[178:181], v[202:205], v[120:123]
	v_mfma_f32_16x16x32_bf16 v[108:111], v[170:173], v[210:213], v[108:111]
	v_mfma_f32_16x16x32_bf16 v[104:107], v[178:181], v[210:213], v[104:107]
	v_mfma_f32_16x16x32_bf16 v[92:95], v[170:173], v[218:221], v[92:95]
	v_mfma_f32_16x16x32_bf16 v[88:91], v[178:181], v[218:221], v[88:91]
	v_mfma_f32_16x16x32_bf16 v[76:79], v[170:173], v[236:239], v[76:79]
	v_mfma_f32_16x16x32_bf16 v[72:75], v[178:181], v[236:239], v[72:75]
	v_mfma_f32_16x16x32_bf16 v[116:119], v[182:185], v[198:201], v[116:119]
	v_mfma_f32_16x16x32_bf16 v[112:115], v[190:193], v[198:201], v[112:115]
	v_mfma_f32_16x16x32_bf16 v[100:103], v[182:185], v[206:209], v[100:103]
	v_mfma_f32_16x16x32_bf16 v[96:99], v[190:193], v[206:209], v[96:99]
	v_mfma_f32_16x16x32_bf16 v[84:87], v[182:185], v[214:217], v[84:87]
	v_mfma_f32_16x16x32_bf16 v[80:83], v[190:193], v[214:217], v[80:83]
	v_mfma_f32_16x16x32_bf16 v[68:71], v[182:185], v[224:227], v[68:71]
	v_mfma_f32_16x16x32_bf16 v[64:67], v[190:193], v[224:227], v[64:67]
	v_mfma_f32_16x16x32_bf16 v[116:119], v[186:189], v[202:205], v[116:119]
	v_mfma_f32_16x16x32_bf16 v[112:115], v[194:197], v[202:205], v[112:115]
	v_mfma_f32_16x16x32_bf16 v[100:103], v[186:189], v[210:213], v[100:103]
	v_mfma_f32_16x16x32_bf16 v[96:99], v[194:197], v[210:213], v[96:99]
	v_mfma_f32_16x16x32_bf16 v[84:87], v[186:189], v[218:221], v[84:87]
	v_mfma_f32_16x16x32_bf16 v[80:83], v[194:197], v[218:221], v[80:83]
	v_mfma_f32_16x16x32_bf16 v[68:71], v[186:189], v[236:239], v[68:71]
	v_mfma_f32_16x16x32_bf16 v[64:67], v[194:197], v[236:239], v[64:67]
	s_setprio 0
	s_barrier
	s_mov_b32 m0, s56
	v_lshl_add_u64 v[144:145], v[144:145], 0, s[10:11]
	s_add_u32 s40, s40, 0x40080
	ds_read_b128 v[198:201], v147 offset:49152
	ds_read_b128 v[202:205], v147 offset:50176
	ds_read_b128 v[206:209], v147 offset:51200
	ds_read_b128 v[210:213], v147 offset:52224
	ds_read_b128 v[214:217], v147 offset:53248
	ds_read_b128 v[218:221], v147 offset:54272
	ds_read_b128 v[224:227], v147 offset:55296
	ds_read_b128 v[236:239], v147 offset:56320
	global_load_lds_dwordx4 v[144:145], off
	v_lshl_add_u64 v[144:145], v[228:229], 0, s[10:11]
	s_mov_b32 m0, s57
	s_addc_u32 s41, s41, 0
	global_load_lds_dwordx4 v[144:145], off
	v_lshl_add_u64 v[144:145], s[40:41], 0, v[132:133]
	s_mov_b32 m0, s60
	s_nop 0
	global_load_lds_dwordx4 v[144:145], off
	v_lshl_add_u64 v[144:145], s[40:41], 0, v[128:129]
	s_mov_b32 m0, s61
	s_nop 0
	global_load_lds_dwordx4 v[144:145], off
	v_lshl_add_u64 v[144:145], v[240:241], 0, s[10:11]
	s_mov_b32 m0, s58
	s_nop 0
	global_load_lds_dwordx4 v[144:145], off
	v_lshl_add_u64 v[144:145], v[242:243], 0, s[10:11]
	s_mov_b32 m0, s59
	s_nop 0
	global_load_lds_dwordx4 v[144:145], off
	s_waitcnt vmcnt(8)
	s_waitcnt lgkmcnt(0)
	s_barrier
	s_setprio 1
	v_mfma_f32_16x16x32_bf16 v[60:63], v[166:169], v[198:201], v[60:63]
	v_mfma_f32_16x16x32_bf16 v[56:59], v[174:177], v[198:201], v[56:59]
	v_mfma_f32_16x16x32_bf16 v[44:47], v[166:169], v[206:209], v[44:47]
	v_mfma_f32_16x16x32_bf16 v[40:43], v[174:177], v[206:209], v[40:43]
	v_mfma_f32_16x16x32_bf16 v[28:31], v[166:169], v[214:217], v[28:31]
	v_mfma_f32_16x16x32_bf16 v[24:27], v[174:177], v[214:217], v[24:27]
	v_mfma_f32_16x16x32_bf16 v[12:15], v[166:169], v[224:227], v[12:15]
	v_mfma_f32_16x16x32_bf16 v[8:11], v[174:177], v[224:227], v[8:11]
	v_mfma_f32_16x16x32_bf16 v[60:63], v[170:173], v[202:205], v[60:63]
	v_mfma_f32_16x16x32_bf16 v[56:59], v[178:181], v[202:205], v[56:59]
	v_mfma_f32_16x16x32_bf16 v[44:47], v[170:173], v[210:213], v[44:47]
	v_mfma_f32_16x16x32_bf16 v[40:43], v[178:181], v[210:213], v[40:43]
	v_mfma_f32_16x16x32_bf16 v[28:31], v[170:173], v[218:221], v[28:31]
	v_mfma_f32_16x16x32_bf16 v[24:27], v[178:181], v[218:221], v[24:27]
	v_mfma_f32_16x16x32_bf16 v[12:15], v[170:173], v[236:239], v[12:15]
	v_mfma_f32_16x16x32_bf16 v[8:11], v[178:181], v[236:239], v[8:11]
	v_mfma_f32_16x16x32_bf16 v[52:55], v[182:185], v[198:201], v[52:55]
	v_mfma_f32_16x16x32_bf16 v[48:51], v[190:193], v[198:201], v[48:51]
	v_mfma_f32_16x16x32_bf16 v[36:39], v[182:185], v[206:209], v[36:39]
	v_mfma_f32_16x16x32_bf16 v[32:35], v[190:193], v[206:209], v[32:35]
	v_mfma_f32_16x16x32_bf16 v[20:23], v[182:185], v[214:217], v[20:23]
	v_mfma_f32_16x16x32_bf16 v[16:19], v[190:193], v[214:217], v[16:19]
	v_mfma_f32_16x16x32_bf16 v[4:7], v[182:185], v[224:227], v[4:7]
	v_mfma_f32_16x16x32_bf16 v[0:3], v[190:193], v[224:227], v[0:3]
	v_mfma_f32_16x16x32_bf16 v[52:55], v[186:189], v[202:205], v[52:55]
	v_mfma_f32_16x16x32_bf16 v[48:51], v[194:197], v[202:205], v[48:51]
	v_mfma_f32_16x16x32_bf16 v[36:39], v[186:189], v[210:213], v[36:39]
	v_mfma_f32_16x16x32_bf16 v[32:35], v[194:197], v[210:213], v[32:35]
	v_mfma_f32_16x16x32_bf16 v[20:23], v[186:189], v[218:221], v[20:23]
	v_mfma_f32_16x16x32_bf16 v[16:19], v[194:197], v[218:221], v[16:19]
	v_mfma_f32_16x16x32_bf16 v[4:7], v[186:189], v[236:239], v[4:7]
	v_mfma_f32_16x16x32_bf16 v[0:3], v[194:197], v[236:239], v[0:3]
	s_setprio 0
	s_barrier
	s_add_i32 s70, s70, 2
	s_add_u32 s36, s36, 0x100
	s_addc_u32 s37, s37, 0
	s_add_u32 s68, s68, 0x100
	s_addc_u32 s69, s69, 0
	s_cmp_gt_u32 s70, 13
	s_cbranch_scc0 .LBB0_1438
	s_and_b64 vcc, exec, s[12:13]
	s_cbranch_vccz .LBB0_1441
	s_barrier

;     __host__ __device__ bool next(int i, Unit& u) const { const int L = i * G + c; if (L >= 16 * nkc) return false; u.kc = L % nkc; const int t = L / nkc; u.pn = t & 3; u.pm = 33 * (t >> 2); return true; }
; #define PG8_LDA(dst, b, h) do { _Pragma("unroll") for (int m = 0; m < 4; ++m) _Pragma("unroll") for (int k = 0; k < 2; ++k) dst[m][k] = *(const PG8_LAS bf16x8*)(lds + PG8_SA(b, h) + aoff + m * 2048 + k * 1024); } while (0)
; template <class Epi, class Sched, bool ALIGN_EPI = false, bool SP2 = false>
; __device__ __forceinline__ void gemm_phase(PG8_LAS unsigned char* lds, const Gemm g, const Sched& S, const Epi& E) {
;     ...
;         const bool has_next = S.next(ui + 1, nxt);
;         const char* nA = has_next ? (const char*)g.A + (size_t)nxt.pm * tstep + (size_t)nxt.kc * cstep : cA; const char* nB = has_next ? (const char*)g.Bt + (size_t)nxt.pn * tstep + (size_t)nxt.kc * cstep : cB;
;         for (int t = 0; t < nt; t += 2) {
;             const bool last = (t == nt - 2);
;             const char* a1 = cA + (size_t)(t + 1) * kstep;
;             const char* a2 = last ? nA : cA + (size_t)(t + 2) * kstep; const char* b2 = last ? nB : cB + (size_t)(t + 2) * kstep;
;             const char* a3 = a2 + kstep; const char* b3 = b2 + kstep;
;             if (last && has_next) S.a_ready(nxt);
;             if constexpr (SP2) {
;             PG8_LDB(B0, 0, 0); PG8_LDB(B1, 0, 1); PG8_SCHED; PG8_LDA(At, 0, 0); PG8_STAGE(PG8_SA(1, 1), a1 + hstep, voffA);
;             PG8_WAIT_V(8); PG8_WAIT_L(0); PG8_BAR; PG8_MMA(0, 0, At, B0); PG8_MMA(0, 1, At, B1); PG8_BAR; PG8_SCHED;
;             PG8_LDA(At, 0, 1); PG8_STAGE(PG8_SB(0, 0), b2, voffB); PG8_STAGE(PG8_SB(0, 1), b2 + hstep, voffB); PG8_STAGE(PG8_SA(0, 0), a2, voffA);
;             PG8_WAIT_V(8); PG8_WAIT_L(0); PG8_BAR; PG8_MMA(1, 0, At, B0); PG8_MMA(1, 1, At, B1); PG8_BAR; PG8_SCHED;
;             PG8_LDB(B0, 1, 0); PG8_LDB(B1, 1, 1); PG8_SCHED; PG8_LDA(At, 1, 0); PG8_STAGE(PG8_SA(0, 1), a2 + hstep, voffA);
;             PG8_WAIT_V(8); PG8_WAIT_L(0); PG8_BAR; PG8_MMA(0, 0, At, B0); PG8_MMA(0, 1, At, B1); PG8_BAR; PG8_SCHED;
;             PG8_LDA(At, 1, 1); PG8_STAGE(PG8_SB(1, 0), b3, voffB); PG8_STAGE(PG8_SB(1, 1), b3 + hstep, voffB); PG8_STAGE(PG8_SA(1, 0), a3, voffA);
;             PG8_WAIT_V(8); PG8_WAIT_L(0); PG8_BAR; PG8_MMA(1, 0, At, B0); PG8_MMA(1, 1, At, B1); PG8_BAR; PG8_SCHED;
.LBB0_1517:
	s_add_u32 s33, s22, 0x100
	s_addc_u32 s72, s23, 0
	s_mov_b32 s73, -2
	ds_read_b128 v[142:145], v174
	ds_read_b128 v[146:149], v175
	ds_read_b128 v[150:153], v176
	ds_read_b128 v[154:157], v177
	ds_read_b128 v[158:161], v178
	ds_read_b128 v[162:165], v179
	ds_read_b128 v[166:169], v180
	ds_read_b128 v[190:193], v181
	s_add_u32 s22, s20, 0x100
	s_addc_u32 s23, s21, 0
	s_cmp_eq_u32 s73, 40
	s_cselect_b32 s37, s5, s23
	s_cselect_b32 s36, s4, s22
	s_cselect_b32 s25, s17, s72
	s_cselect_b32 s24, s16, s33
	s_mov_b32 m0, s62
	v_lshl_add_u64 v[170:171], s[20:21], 0, v[134:135]
	ds_read_b128 v[194:197], v172
	ds_read_b128 v[198:201], v172 offset:1024
	ds_read_b128 v[202:205], v172 offset:2048
	ds_read_b128 v[206:209], v172 offset:3072
	ds_read_b128 v[210:213], v172 offset:4096
	ds_read_b128 v[214:217], v172 offset:5120
	ds_read_b128 v[218:221], v172 offset:6144
	ds_read_b128 v[224:227], v172 offset:7168
	global_load_lds_dwordx4 v[170:171], off
	v_lshl_add_u64 v[170:171], s[20:21], 0, v[136:137]
	s_mov_b32 m0, s63
	s_nop 0
	global_load_lds_dwordx4 v[170:171], off
	s_waitcnt vmcnt(8)
	s_waitcnt lgkmcnt(0)
	s_barrier
	s_setprio 1
	v_mfma_f32_16x16x32_bf16 v[124:127], v[142:145], v[194:197], 0
	v_mfma_f32_16x16x32_bf16 v[108:111], v[150:153], v[194:197], 0
	v_mfma_f32_16x16x32_bf16 v[120:123], v[142:145], v[202:205], 0
	v_mfma_f32_16x16x32_bf16 v[96:99], v[150:153], v[202:205], 0
	v_mfma_f32_16x16x32_bf16 v[116:119], v[142:145], v[210:213], 0
	v_mfma_f32_16x16x32_bf16 v[88:91], v[150:153], v[210:213], 0
	v_mfma_f32_16x16x32_bf16 v[112:115], v[142:145], v[218:221], 0
	v_mfma_f32_16x16x32_bf16 v[84:87], v[150:153], v[218:221], 0
	v_mfma_f32_16x16x32_bf16 v[124:127], v[146:149], v[198:201], v[124:127]
	v_mfma_f32_16x16x32_bf16 v[108:111], v[154:157], v[198:201], v[108:111]
	v_mfma_f32_16x16x32_bf16 v[120:123], v[146:149], v[206:209], v[120:123]
	v_mfma_f32_16x16x32_bf16 v[96:99], v[154:157], v[206:209], v[96:99]
	v_mfma_f32_16x16x32_bf16 v[116:119], v[146:149], v[214:217], v[116:119]
	v_mfma_f32_16x16x32_bf16 v[88:91], v[154:157], v[214:217], v[88:91]
	v_mfma_f32_16x16x32_bf16 v[112:115], v[146:149], v[224:227], v[112:115]
	v_mfma_f32_16x16x32_bf16 v[84:87], v[154:157], v[224:227], v[84:87]
	v_mfma_f32_16x16x32_bf16 v[68:71], v[158:161], v[194:197], 0
	v_mfma_f32_16x16x32_bf16 v[40:43], v[166:169], v[194:197], 0
	v_mfma_f32_16x16x32_bf16 v[60:63], v[158:161], v[202:205], 0
	v_mfma_f32_16x16x32_bf16 v[32:35], v[166:169], v[202:205], 0
	v_mfma_f32_16x16x32_bf16 v[52:55], v[158:161], v[210:213], 0
	v_mfma_f32_16x16x32_bf16 v[24:27], v[166:169], v[210:213], 0
	v_mfma_f32_16x16x32_bf16 v[48:51], v[158:161], v[218:221], 0
	v_mfma_f32_16x16x32_bf16 v[16:19], v[166:169], v[218:221], 0
	v_mfma_f32_16x16x32_bf16 v[68:71], v[162:165], v[198:201], v[68:71]
	v_mfma_f32_16x16x32_bf16 v[40:43], v[190:193], v[198:201], v[40:43]
	v_mfma_f32_16x16x32_bf16 v[60:63], v[162:165], v[206:209], v[60:63]
	v_mfma_f32_16x16x32_bf16 v[32:35], v[190:193], v[206:209], v[32:35]
	v_mfma_f32_16x16x32_bf16 v[52:55], v[162:165], v[214:217], v[52:55]
	v_mfma_f32_16x16x32_bf16 v[24:27], v[190:193], v[214:217], v[24:27]
	v_mfma_f32_16x16x32_bf16 v[48:51], v[162:165], v[224:227], v[48:51]
	v_mfma_f32_16x16x32_bf16 v[16:19], v[190:193], v[224:227], v[16:19]
	s_setprio 0
	s_barrier
	s_mov_b32 m0, s39
	v_lshl_add_u64 v[170:171], s[24:25], 0, v[128:129]
	s_add_u32 s20, s24, 0xb0000
	ds_read_b128 v[194:197], v172 offset:16384
	ds_read_b128 v[198:201], v172 offset:17408
	ds_read_b128 v[202:205], v172 offset:18432
	ds_read_b128 v[206:209], v172 offset:19456
	ds_read_b128 v[210:213], v172 offset:20480
	ds_read_b128 v[214:217], v172 offset:21504
	ds_read_b128 v[218:221], v172 offset:22528
	ds_read_b128 v[224:227], v172 offset:23552
	global_load_lds_dwordx4 v[170:171], off
	v_lshl_add_u64 v[228:229], s[24:25], 0, v[130:131]
	s_mov_b32 m0, s40
	s_addc_u32 s21, s25, 0
	global_load_lds_dwordx4 v[228:229], off
	v_lshl_add_u64 v[236:237], s[20:21], 0, v[128:129]
	s_mov_b32 m0, s41
	v_lshl_add_u64 v[238:239], s[36:37], 0, v[130:131]
	global_load_lds_dwordx4 v[236:237], off
	v_lshl_add_u64 v[236:237], s[20:21], 0, v[130:131]
	s_mov_b32 m0, s43
	s_nop 0
	global_load_lds_dwordx4 v[236:237], off
	v_lshl_add_u64 v[236:237], s[36:37], 0, v[128:129]
	s_mov_b32 m0, s15
	s_nop 0
	global_load_lds_dwordx4 v[236:237], off
	s_mov_b32 m0, s46
	s_nop 0
	global_load_lds_dwordx4 v[238:239], off
	s_waitcnt vmcnt(8)
	s_waitcnt lgkmcnt(0)
	s_barrier
	s_setprio 1
	v_mfma_f32_16x16x32_bf16 v[104:107], v[142:145], v[194:197], 0
	v_mfma_f32_16x16x32_bf16 v[76:79], v[150:153], v[194:197], 0
	v_mfma_f32_16x16x32_bf16 v[100:103], v[142:145], v[202:205], 0
	v_mfma_f32_16x16x32_bf16 v[72:75], v[150:153], v[202:205], 0
	v_mfma_f32_16x16x32_bf16 v[92:95], v[142:145], v[210:213], 0
	v_mfma_f32_16x16x32_bf16 v[64:67], v[150:153], v[210:213], 0
	v_mfma_f32_16x16x32_bf16 v[80:83], v[142:145], v[218:221], 0
	v_mfma_f32_16x16x32_bf16 v[56:59], v[150:153], v[218:221], 0
	v_mfma_f32_16x16x32_bf16 v[104:107], v[146:149], v[198:201], v[104:107]
	v_mfma_f32_16x16x32_bf16 v[76:79], v[154:157], v[198:201], v[76:79]
	v_mfma_f32_16x16x32_bf16 v[100:103], v[146:149], v[206:209], v[100:103]
	v_mfma_f32_16x16x32_bf16 v[72:75], v[154:157], v[206:209], v[72:75]
	v_mfma_f32_16x16x32_bf16 v[92:95], v[146:149], v[214:217], v[92:95]
	v_mfma_f32_16x16x32_bf16 v[64:67], v[154:157], v[214:217], v[64:67]
	v_mfma_f32_16x16x32_bf16 v[80:83], v[146:149], v[224:227], v[80:83]
	v_mfma_f32_16x16x32_bf16 v[56:59], v[154:157], v[224:227], v[56:59]
	v_mfma_f32_16x16x32_bf16 v[44:47], v[158:161], v[194:197], 0
	v_mfma_f32_16x16x32_bf16 v[12:15], v[166:169], v[194:197], 0
	v_mfma_f32_16x16x32_bf16 v[36:39], v[158:161], v[202:205], 0
	v_mfma_f32_16x16x32_bf16 v[8:11], v[166:169], v[202:205], 0
	v_mfma_f32_16x16x32_bf16 v[28:31], v[158:161], v[210:213], 0
	v_mfma_f32_16x16x32_bf16 v[4:7], v[166:169], v[210:213], 0
	v_mfma_f32_16x16x32_bf16 v[20:23], v[158:161], v[218:221], 0
	v_mfma_f32_16x16x32_bf16 v[0:3], v[166:169], v[218:221], 0
	v_mfma_f32_16x16x32_bf16 v[44:47], v[162:165], v[198:201], v[44:47]
	v_mfma_f32_16x16x32_bf16 v[12:15], v[190:193], v[198:201], v[12:15]
	v_mfma_f32_16x16x32_bf16 v[36:39], v[162:165], v[206:209], v[36:39]
	v_mfma_f32_16x16x32_bf16 v[8:11], v[190:193], v[206:209], v[8:11]
	v_mfma_f32_16x16x32_bf16 v[28:31], v[162:165], v[214:217], v[28:31]
	v_mfma_f32_16x16x32_bf16 v[4:7], v[190:193], v[214:217], v[4:7]
	v_mfma_f32_16x16x32_bf16 v[20:23], v[162:165], v[224:227], v[20:23]
	v_mfma_f32_16x16x32_bf16 v[0:3], v[190:193], v[224:227], v[0:3]
	s_setprio 0
	s_barrier
; #define PG8_STAGE(bufoff, gbase, voff) do { _Pragma("unroll") for (int _i = 0; _i < 2; ++_i) \
;         __builtin_amdgcn_global_load_lds((const unsigned*)((const char*)(gbase) + (voff)[_i]), (PG8_LAS unsigned*)(lds + (bufoff) + ldsw + _i * 8192), 16, 0, 0); } while (0)
; #define PG8_LDA(dst, b, h) do { _Pragma("unroll") for (int m = 0; m < 4; ++m) _Pragma("unroll") for (int k = 0; k < 2; ++k) dst[m][k] = *(const PG8_LAS bf16x8*)(lds + PG8_SA(b, h) + aoff + m * 2048 + k * 1024); } while (0)
; #define PG8_LDB(dst, b, h) do { _Pragma("unroll") for (int n = 0; n < 2; ++n) _Pragma("unroll") for (int k = 0; k < 2; ++k) dst[n][k] = *(const PG8_LAS bf16x8*)(lds + PG8_SB(b, h) + boff + n * 2048 + k * 1024); } while (0)
; #define PG8_MMA(ai, bj, At, Bt) do { __builtin_amdgcn_s_setprio(1); _Pragma("unroll") for (int m = 0; m < 4; ++m) _Pragma("unroll") for (int n = 0; n < 2; ++n) _Pragma("unroll") for (int k = 0; k < 2; ++k) \
;         acc[ai][bj][m][n] = __builtin_amdgcn_mfma_f32_16x16x32_bf16(Bt[n][k], At[m][k], acc[ai][bj][m][n], 0, 0, 0); __builtin_amdgcn_s_setprio(0); } while (0)
; #define PG8_WAIT_V(n) asm volatile("s_waitcnt vmcnt(" #n ")" ::: "memory")
; template <class Epi, class Sched, bool ALIGN_EPI = false, bool SP2 = false>
; __device__ __forceinline__ void gemm_phase(PG8_LAS unsigned char* lds, const Gemm g, const Sched& S, const Epi& E) {
;     ...
;             PG8_LDB(B0, 0, 0); PG8_LDB(B1, 0, 1); PG8_SCHED; PG8_LDA(At, 0, 0); PG8_STAGE(PG8_SA(1, 1), a1 + hstep, voffA);
;             PG8_WAIT_V(8); PG8_WAIT_L(0); PG8_BAR; PG8_MMA(0, 0, At, B0); PG8_MMA(0, 1, At, B1); PG8_BAR; PG8_SCHED;
;             PG8_LDA(At, 0, 1); PG8_STAGE(PG8_SB(0, 0), b2, voffB); PG8_STAGE(PG8_SB(0, 1), b2 + hstep, voffB); PG8_STAGE(PG8_SA(0, 0), a2, voffA);
;             PG8_WAIT_V(8); PG8_WAIT_L(0); PG8_BAR; PG8_MMA(1, 0, At, B0); PG8_MMA(1, 1, At, B1); PG8_BAR; PG8_SCHED;
;             PG8_LDB(B0, 1, 0); PG8_LDB(B1, 1, 1); PG8_SCHED; PG8_LDA(At, 1, 0); PG8_STAGE(PG8_SA(0, 1), a2 + hstep, voffA);
;             PG8_WAIT_V(8); PG8_WAIT_L(0); PG8_BAR; PG8_MMA(0, 0, At, B0); PG8_MMA(0, 1, At, B1); PG8_BAR; PG8_SCHED;
;             PG8_LDA(At, 1, 1); PG8_STAGE(PG8_SB(1, 0), b3, voffB); PG8_STAGE(PG8_SB(1, 1), b3 + hstep, voffB); PG8_STAGE(PG8_SA(1, 0), a3, voffA);
;             PG8_WAIT_V(8); PG8_WAIT_L(0); PG8_BAR; PG8_MMA(1, 0, At, B0); PG8_MMA(1, 1, At, B1); PG8_BAR; PG8_SCHED;
	ds_read_b128 v[142:145], v182
	ds_read_b128 v[146:149], v183
	ds_read_b128 v[150:153], v184
	ds_read_b128 v[154:157], v185
	ds_read_b128 v[158:161], v186
	ds_read_b128 v[162:165], v187
	ds_read_b128 v[166:169], v188
	ds_read_b128 v[190:193], v189
	s_add_u32 s20, s36, 0xb0000
	s_addc_u32 s21, s37, 0
	s_mov_b32 m0, s47
	v_lshl_add_u64 v[240:241], s[20:21], 0, v[128:129]
	ds_read_b128 v[194:197], v172 offset:32768
	ds_read_b128 v[198:201], v172 offset:33792
	ds_read_b128 v[202:205], v172 offset:34816
	ds_read_b128 v[206:209], v172 offset:35840
	ds_read_b128 v[210:213], v172 offset:36864
	ds_read_b128 v[214:217], v172 offset:37888
	ds_read_b128 v[218:221], v172 offset:38912
	ds_read_b128 v[224:227], v172 offset:39936
	global_load_lds_dwordx4 v[240:241], off
	v_lshl_add_u64 v[240:241], s[20:21], 0, v[130:131]
	s_mov_b32 m0, s50
	s_nop 0
	global_load_lds_dwordx4 v[240:241], off
	s_waitcnt vmcnt(8)
	s_waitcnt lgkmcnt(0)
	s_barrier
	s_setprio 1
	v_mfma_f32_16x16x32_bf16 v[124:127], v[142:145], v[194:197], v[124:127]
	v_mfma_f32_16x16x32_bf16 v[108:111], v[150:153], v[194:197], v[108:111]
	v_mfma_f32_16x16x32_bf16 v[120:123], v[142:145], v[202:205], v[120:123]
	v_mfma_f32_16x16x32_bf16 v[96:99], v[150:153], v[202:205], v[96:99]
	v_mfma_f32_16x16x32_bf16 v[116:119], v[142:145], v[210:213], v[116:119]
	v_mfma_f32_16x16x32_bf16 v[88:91], v[150:153], v[210:213], v[88:91]
	v_mfma_f32_16x16x32_bf16 v[112:115], v[142:145], v[218:221], v[112:115]
	v_mfma_f32_16x16x32_bf16 v[84:87], v[150:153], v[218:221], v[84:87]
	v_mfma_f32_16x16x32_bf16 v[124:127], v[146:149], v[198:201], v[124:127]
	v_mfma_f32_16x16x32_bf16 v[108:111], v[154:157], v[198:201], v[108:111]
	v_mfma_f32_16x16x32_bf16 v[120:123], v[146:149], v[206:209], v[120:123]
	v_mfma_f32_16x16x32_bf16 v[96:99], v[154:157], v[206:209], v[96:99]
	v_mfma_f32_16x16x32_bf16 v[116:119], v[146:149], v[214:217], v[116:119]
	v_mfma_f32_16x16x32_bf16 v[88:91], v[154:157], v[214:217], v[88:91]
	v_mfma_f32_16x16x32_bf16 v[112:115], v[146:149], v[224:227], v[112:115]
	v_mfma_f32_16x16x32_bf16 v[84:87], v[154:157], v[224:227], v[84:87]
	v_mfma_f32_16x16x32_bf16 v[68:71], v[158:161], v[194:197], v[68:71]
	v_mfma_f32_16x16x32_bf16 v[40:43], v[166:169], v[194:197], v[40:43]
	v_mfma_f32_16x16x32_bf16 v[60:63], v[158:161], v[202:205], v[60:63]
	v_mfma_f32_16x16x32_bf16 v[32:35], v[166:169], v[202:205], v[32:35]
	v_mfma_f32_16x16x32_bf16 v[52:55], v[158:161], v[210:213], v[52:55]
	v_mfma_f32_16x16x32_bf16 v[24:27], v[166:169], v[210:213], v[24:27]
	v_mfma_f32_16x16x32_bf16 v[48:51], v[158:161], v[218:221], v[48:51]
	v_mfma_f32_16x16x32_bf16 v[16:19], v[166:169], v[218:221], v[16:19]
	v_mfma_f32_16x16x32_bf16 v[68:71], v[162:165], v[198:201], v[68:71]
	v_mfma_f32_16x16x32_bf16 v[40:43], v[190:193], v[198:201], v[40:43]
	v_mfma_f32_16x16x32_bf16 v[60:63], v[162:165], v[206:209], v[60:63]
	v_mfma_f32_16x16x32_bf16 v[32:35], v[190:193], v[206:209], v[32:35]
	v_mfma_f32_16x16x32_bf16 v[52:55], v[162:165], v[214:217], v[52:55]
	v_mfma_f32_16x16x32_bf16 v[24:27], v[190:193], v[214:217], v[24:27]
	v_mfma_f32_16x16x32_bf16 v[48:51], v[162:165], v[224:227], v[48:51]
	v_mfma_f32_16x16x32_bf16 v[16:19], v[190:193], v[224:227], v[16:19]
	s_setprio 0
	s_barrier
	s_mov_b32 m0, s54
	v_lshl_add_u64 v[170:171], v[170:171], 0, s[10:11]
	s_add_u32 s20, s24, 0xb0080
	ds_read_b128 v[194:197], v172 offset:49152
	ds_read_b128 v[198:201], v172 offset:50176
	ds_read_b128 v[202:205], v172 offset:51200
	ds_read_b128 v[206:209], v172 offset:52224
	ds_read_b128 v[210:213], v172 offset:53248
	ds_read_b128 v[214:217], v172 offset:54272
	ds_read_b128 v[218:221], v172 offset:55296
	ds_read_b128 v[224:227], v172 offset:56320
	global_load_lds_dwordx4 v[170:171], off
	v_lshl_add_u64 v[170:171], v[228:229], 0, s[10:11]
	s_mov_b32 m0, s55
	s_addc_u32 s21, s25, 0
	global_load_lds_dwordx4 v[170:171], off
	v_lshl_add_u64 v[170:171], s[20:21], 0, v[128:129]
	s_mov_b32 m0, s58
	s_nop 0
	global_load_lds_dwordx4 v[170:171], off
	v_lshl_add_u64 v[170:171], s[20:21], 0, v[130:131]
	s_mov_b32 m0, s59
	s_nop 0
	global_load_lds_dwordx4 v[170:171], off
	v_lshl_add_u64 v[170:171], v[236:237], 0, s[10:11]
	s_mov_b32 m0, s56
	s_nop 0
	global_load_lds_dwordx4 v[170:171], off
	v_lshl_add_u64 v[170:171], v[238:239], 0, s[10:11]
	s_mov_b32 m0, s57
	s_nop 0
	global_load_lds_dwordx4 v[170:171], off
	s_waitcnt vmcnt(8)
	s_waitcnt lgkmcnt(0)
	s_barrier
	s_setprio 1
	v_mfma_f32_16x16x32_bf16 v[104:107], v[142:145], v[194:197], v[104:107]
	v_mfma_f32_16x16x32_bf16 v[76:79], v[150:153], v[194:197], v[76:79]
	v_mfma_f32_16x16x32_bf16 v[100:103], v[142:145], v[202:205], v[100:103]
	v_mfma_f32_16x16x32_bf16 v[72:75], v[150:153], v[202:205], v[72:75]
	v_mfma_f32_16x16x32_bf16 v[92:95], v[142:145], v[210:213], v[92:95]
	v_mfma_f32_16x16x32_bf16 v[64:67], v[150:153], v[210:213], v[64:67]
	v_mfma_f32_16x16x32_bf16 v[80:83], v[142:145], v[218:221], v[80:83]
	v_mfma_f32_16x16x32_bf16 v[56:59], v[150:153], v[218:221], v[56:59]
	v_mfma_f32_16x16x32_bf16 v[104:107], v[146:149], v[198:201], v[104:107]
	v_mfma_f32_16x16x32_bf16 v[76:79], v[154:157], v[198:201], v[76:79]
	v_mfma_f32_16x16x32_bf16 v[100:103], v[146:149], v[206:209], v[100:103]
	v_mfma_f32_16x16x32_bf16 v[72:75], v[154:157], v[206:209], v[72:75]
	v_mfma_f32_16x16x32_bf16 v[92:95], v[146:149], v[214:217], v[92:95]
	v_mfma_f32_16x16x32_bf16 v[64:67], v[154:157], v[214:217], v[64:67]
	v_mfma_f32_16x16x32_bf16 v[80:83], v[146:149], v[224:227], v[80:83]
	v_mfma_f32_16x16x32_bf16 v[56:59], v[154:157], v[224:227], v[56:59]
	v_mfma_f32_16x16x32_bf16 v[44:47], v[158:161], v[194:197], v[44:47]
	v_mfma_f32_16x16x32_bf16 v[12:15], v[166:169], v[194:197], v[12:15]
	v_mfma_f32_16x16x32_bf16 v[36:39], v[158:161], v[202:205], v[36:39]
	v_mfma_f32_16x16x32_bf16 v[8:11], v[166:169], v[202:205], v[8:11]
	v_mfma_f32_16x16x32_bf16 v[28:31], v[158:161], v[210:213], v[28:31]
	v_mfma_f32_16x16x32_bf16 v[4:7], v[166:169], v[210:213], v[4:7]
	v_mfma_f32_16x16x32_bf16 v[20:23], v[158:161], v[218:221], v[20:23]
	v_mfma_f32_16x16x32_bf16 v[0:3], v[166:169], v[218:221], v[0:3]
	v_mfma_f32_16x16x32_bf16 v[44:47], v[162:165], v[198:201], v[44:47]
	v_mfma_f32_16x16x32_bf16 v[12:15], v[190:193], v[198:201], v[12:15]
	v_mfma_f32_16x16x32_bf16 v[36:39], v[162:165], v[206:209], v[36:39]
	v_mfma_f32_16x16x32_bf16 v[8:11], v[190:193], v[206:209], v[8:11]
	v_mfma_f32_16x16x32_bf16 v[28:31], v[162:165], v[214:217], v[28:31]
	v_mfma_f32_16x16x32_bf16 v[4:7], v[190:193], v[214:217], v[4:7]
	v_mfma_f32_16x16x32_bf16 v[20:23], v[162:165], v[224:227], v[20:23]
	v_mfma_f32_16x16x32_bf16 v[0:3], v[190:193], v[224:227], v[0:3]
	s_setprio 0
	s_barrier
	s_add_i32 s73, s73, 2
	s_add_u32 s33, s33, 0x100
	s_addc_u32 s72, s72, 0
	s_mov_b64 s[20:21], s[22:23]
; #define PG8_STAGE(bufoff, gbase, voff) do { _Pragma("unroll") for (int _i = 0; _i < 2; ++_i) \
;         __builtin_amdgcn_global_load_lds((const unsigned*)((const char*)(gbase) + (voff)[_i]), (PG8_LAS unsigned*)(lds + (bufoff) + ldsw + _i * 8192), 16, 0, 0); } while (0)
; #define PG8_LDA(dst, b, h) do { _Pragma("unroll") for (int m = 0; m < 4; ++m) _Pragma("unroll") for (int k = 0; k < 2; ++k) dst[m][k] = *(const PG8_LAS bf16x8*)(lds + PG8_SA(b, h) + aoff + m * 2048 + k * 1024); } while (0)
; #define PG8_LDB(dst, b, h) do { _Pragma("unroll") for (int n = 0; n < 2; ++n) _Pragma("unroll") for (int k = 0; k < 2; ++k) dst[n][k] = *(const PG8_LAS bf16x8*)(lds + PG8_SB(b, h) + boff + n * 2048 + k * 1024); } while (0)
; template <class Epi, class Sched, bool ALIGN_EPI = false, bool SP2 = false>
; __device__ __forceinline__ void gemm_phase(PG8_LAS unsigned char* lds, const Gemm g, const Sched& S, const Epi& E) {
;     ...
;         for (int t = 0; t < nt; t += 2) {
;             const bool last = (t == nt - 2);
;             const char* a1 = cA + (size_t)(t + 1) * kstep;
;             const char* a2 = last ? nA : cA + (size_t)(t + 2) * kstep; const char* b2 = last ? nB : cB + (size_t)(t + 2) * kstep;
;             const char* a3 = a2 + kstep; const char* b3 = b2 + kstep;
;             if (last && has_next) S.a_ready(nxt);
;             if constexpr (SP2) {
;             PG8_LDB(B0, 0, 0); PG8_LDB(B1, 0, 1); PG8_SCHED; PG8_LDA(At, 0, 0); PG8_STAGE(PG8_SA(1, 1), a1 + hstep, voffA);
;             PG8_WAIT_V(8); PG8_WAIT_L(0); PG8_BAR; PG8_MMA(0, 0, At, B0); PG8_MMA(0, 1, At, B1); PG8_BAR; PG8_SCHED;
;             PG8_LDA(At, 0, 1); PG8_STAGE(PG8_SB(0, 0), b2, voffB); PG8_STAGE(PG8_SB(0, 1), b2 + hstep, voffB); PG8_STAGE(PG8_SA(0, 0), a2, voffA);
;             PG8_WAIT_V(8); PG8_WAIT_L(0); PG8_BAR; PG8_MMA(1, 0, At, B0); PG8_MMA(1, 1, At, B1); PG8_BAR; PG8_SCHED;
;             PG8_LDB(B0, 1, 0); PG8_LDB(B1, 1, 1); PG8_SCHED; PG8_LDA(At, 1, 0); PG8_STAGE(PG8_SA(0, 1), a2 + hstep, voffA);
;             PG8_WAIT_V(8); PG8_WAIT_L(0); PG8_BAR; PG8_MMA(0, 0, At, B0); PG8_MMA(0, 1, At, B1); PG8_BAR; PG8_SCHED;
;             PG8_LDA(At, 1, 1); PG8_STAGE(PG8_SB(1, 0), b3, voffB); PG8_STAGE(PG8_SB(1, 1), b3 + hstep, voffB); PG8_STAGE(PG8_SA(1, 0), a3, voffA);
;             PG8_WAIT_V(8); PG8_WAIT_L(0); PG8_BAR; PG8_MMA(1, 0, At, B0); PG8_MMA(1, 1, At, B1); PG8_BAR; PG8_SCHED;
.LBB0_1518:
	ds_read_b128 v[142:145], v174
	ds_read_b128 v[146:149], v175
	ds_read_b128 v[150:153], v176
	ds_read_b128 v[154:157], v177
	ds_read_b128 v[158:161], v178
	ds_read_b128 v[162:165], v179
	ds_read_b128 v[166:169], v180
	ds_read_b128 v[190:193], v181
	s_add_u32 s22, s20, 0x100
	s_addc_u32 s23, s21, 0
	s_cmp_eq_u32 s73, 40
	s_cselect_b32 s37, s5, s23
	s_cselect_b32 s36, s4, s22
	s_cselect_b32 s25, s17, s72
	s_cselect_b32 s24, s16, s33
	s_mov_b32 m0, s62
	v_lshl_add_u64 v[170:171], s[20:21], 0, v[134:135]
	ds_read_b128 v[194:197], v172
	ds_read_b128 v[198:201], v172 offset:1024
	ds_read_b128 v[202:205], v172 offset:2048
	ds_read_b128 v[206:209], v172 offset:3072
	ds_read_b128 v[210:213], v172 offset:4096
	ds_read_b128 v[214:217], v172 offset:5120
	ds_read_b128 v[218:221], v172 offset:6144
	ds_read_b128 v[224:227], v172 offset:7168
	global_load_lds_dwordx4 v[170:171], off
	v_lshl_add_u64 v[170:171], s[20:21], 0, v[136:137]
	s_mov_b32 m0, s63
	s_nop 0
	global_load_lds_dwordx4 v[170:171], off
	s_waitcnt vmcnt(8)
	s_waitcnt lgkmcnt(0)
	s_barrier
	s_setprio 1
	v_mfma_f32_16x16x32_bf16 v[124:127], v[142:145], v[194:197], v[124:127]
	v_mfma_f32_16x16x32_bf16 v[108:111], v[150:153], v[194:197], v[108:111]
	v_mfma_f32_16x16x32_bf16 v[120:123], v[142:145], v[202:205], v[120:123]
	v_mfma_f32_16x16x32_bf16 v[96:99], v[150:153], v[202:205], v[96:99]
	v_mfma_f32_16x16x32_bf16 v[116:119], v[142:145], v[210:213], v[116:119]
	v_mfma_f32_16x16x32_bf16 v[88:91], v[150:153], v[210:213], v[88:91]
	v_mfma_f32_16x16x32_bf16 v[112:115], v[142:145], v[218:221], v[112:115]
	v_mfma_f32_16x16x32_bf16 v[84:87], v[150:153], v[218:221], v[84:87]
	v_mfma_f32_16x16x32_bf16 v[124:127], v[146:149], v[198:201], v[124:127]
	v_mfma_f32_16x16x32_bf16 v[108:111], v[154:157], v[198:201], v[108:111]
	v_mfma_f32_16x16x32_bf16 v[120:123], v[146:149], v[206:209], v[120:123]
	v_mfma_f32_16x16x32_bf16 v[96:99], v[154:157], v[206:209], v[96:99]
	v_mfma_f32_16x16x32_bf16 v[116:119], v[146:149], v[214:217], v[116:119]
	v_mfma_f32_16x16x32_bf16 v[88:91], v[154:157], v[214:217], v[88:91]
	v_mfma_f32_16x16x32_bf16 v[112:115], v[146:149], v[224:227], v[112:115]
	v_mfma_f32_16x16x32_bf16 v[84:87], v[154:157], v[224:227], v[84:87]
	v_mfma_f32_16x16x32_bf16 v[68:71], v[158:161], v[194:197], v[68:71]
	v_mfma_f32_16x16x32_bf16 v[40:43], v[166:169], v[194:197], v[40:43]
	v_mfma_f32_16x16x32_bf16 v[60:63], v[158:161], v[202:205], v[60:63]
	v_mfma_f32_16x16x32_bf16 v[32:35], v[166:169], v[202:205], v[32:35]
	v_mfma_f32_16x16x32_bf16 v[52:55], v[158:161], v[210:213], v[52:55]
	v_mfma_f32_16x16x32_bf16 v[24:27], v[166:169], v[210:213], v[24:27]
	v_mfma_f32_16x16x32_bf16 v[48:51], v[158:161], v[218:221], v[48:51]
	v_mfma_f32_16x16x32_bf16 v[16:19], v[166:169], v[218:221], v[16:19]
	v_mfma_f32_16x16x32_bf16 v[68:71], v[162:165], v[198:201], v[68:71]
	v_mfma_f32_16x16x32_bf16 v[40:43], v[190:193], v[198:201], v[40:43]
	v_mfma_f32_16x16x32_bf16 v[60:63], v[162:165], v[206:209], v[60:63]
	v_mfma_f32_16x16x32_bf16 v[32:35], v[190:193], v[206:209], v[32:35]
	v_mfma_f32_16x16x32_bf16 v[52:55], v[162:165], v[214:217], v[52:55]
	v_mfma_f32_16x16x32_bf16 v[24:27], v[190:193], v[214:217], v[24:27]
	v_mfma_f32_16x16x32_bf16 v[48:51], v[162:165], v[224:227], v[48:51]
	v_mfma_f32_16x16x32_bf16 v[16:19], v[190:193], v[224:227], v[16:19]
	s_setprio 0
	s_barrier
	s_mov_b32 m0, s39
	v_lshl_add_u64 v[170:171], s[24:25], 0, v[128:129]
	s_add_u32 s20, s24, 0xb0000
	ds_read_b128 v[194:197], v172 offset:16384
	ds_read_b128 v[198:201], v172 offset:17408
	ds_read_b128 v[202:205], v172 offset:18432
	ds_read_b128 v[206:209], v172 offset:19456
	ds_read_b128 v[210:213], v172 offset:20480
	ds_read_b128 v[214:217], v172 offset:21504
	ds_read_b128 v[218:221], v172 offset:22528
	ds_read_b128 v[224:227], v172 offset:23552
	global_load_lds_dwordx4 v[170:171], off
	v_lshl_add_u64 v[228:229], s[24:25], 0, v[130:131]
	s_mov_b32 m0, s40
	s_addc_u32 s21, s25, 0
	global_load_lds_dwordx4 v[228:229], off
	v_lshl_add_u64 v[236:237], s[20:21], 0, v[128:129]
	s_mov_b32 m0, s41
	v_lshl_add_u64 v[238:239], s[36:37], 0, v[130:131]
	global_load_lds_dwordx4 v[236:237], off
	v_lshl_add_u64 v[236:237], s[20:21], 0, v[130:131]
	s_mov_b32 m0, s43
	s_nop 0
	global_load_lds_dwordx4 v[236:237], off
	v_lshl_add_u64 v[236:237], s[36:37], 0, v[128:129]
	s_mov_b32 m0, s15
	s_nop 0
	global_load_lds_dwordx4 v[236:237], off
	s_mov_b32 m0, s46
	s_nop 0
	global_load_lds_dwordx4 v[238:239], off
	s_waitcnt vmcnt(8)
	s_waitcnt lgkmcnt(0)
	s_barrier
	s_setprio 1
	v_mfma_f32_16x16x32_bf16 v[104:107], v[142:145], v[194:197], v[104:107]
	v_mfma_f32_16x16x32_bf16 v[76:79], v[150:153], v[194:197], v[76:79]
	v_mfma_f32_16x16x32_bf16 v[100:103], v[142:145], v[202:205], v[100:103]
	v_mfma_f32_16x16x32_bf16 v[72:75], v[150:153], v[202:205], v[72:75]
	v_mfma_f32_16x16x32_bf16 v[92:95], v[142:145], v[210:213], v[92:95]
	v_mfma_f32_16x16x32_bf16 v[64:67], v[150:153], v[210:213], v[64:67]
	v_mfma_f32_16x16x32_bf16 v[80:83], v[142:145], v[218:221], v[80:83]
	v_mfma_f32_16x16x32_bf16 v[56:59], v[150:153], v[218:221], v[56:59]
	v_mfma_f32_16x16x32_bf16 v[104:107], v[146:149], v[198:201], v[104:107]
	v_mfma_f32_16x16x32_bf16 v[76:79], v[154:157], v[198:201], v[76:79]
	v_mfma_f32_16x16x32_bf16 v[100:103], v[146:149], v[206:209], v[100:103]
	v_mfma_f32_16x16x32_bf16 v[72:75], v[154:157], v[206:209], v[72:75]
	v_mfma_f32_16x16x32_bf16 v[92:95], v[146:149], v[214:217], v[92:95]
	v_mfma_f32_16x16x32_bf16 v[64:67], v[154:157], v[214:217], v[64:67]
	v_mfma_f32_16x16x32_bf16 v[80:83], v[146:149], v[224:227], v[80:83]
	v_mfma_f32_16x16x32_bf16 v[56:59], v[154:157], v[224:227], v[56:59]
	v_mfma_f32_16x16x32_bf16 v[44:47], v[158:161], v[194:197], v[44:47]
	v_mfma_f32_16x16x32_bf16 v[12:15], v[166:169], v[194:197], v[12:15]
	v_mfma_f32_16x16x32_bf16 v[36:39], v[158:161], v[202:205], v[36:39]
	v_mfma_f32_16x16x32_bf16 v[8:11], v[166:169], v[202:205], v[8:11]
	v_mfma_f32_16x16x32_bf16 v[28:31], v[158:161], v[210:213], v[28:31]
	v_mfma_f32_16x16x32_bf16 v[4:7], v[166:169], v[210:213], v[4:7]
	v_mfma_f32_16x16x32_bf16 v[20:23], v[158:161], v[218:221], v[20:23]
	v_mfma_f32_16x16x32_bf16 v[0:3], v[166:169], v[218:221], v[0:3]
	v_mfma_f32_16x16x32_bf16 v[44:47], v[162:165], v[198:201], v[44:47]
	v_mfma_f32_16x16x32_bf16 v[12:15], v[190:193], v[198:201], v[12:15]
	v_mfma_f32_16x16x32_bf16 v[36:39], v[162:165], v[206:209], v[36:39]
	v_mfma_f32_16x16x32_bf16 v[8:11], v[190:193], v[206:209], v[8:11]
	v_mfma_f32_16x16x32_bf16 v[28:31], v[162:165], v[214:217], v[28:31]
	v_mfma_f32_16x16x32_bf16 v[4:7], v[190:193], v[214:217], v[4:7]
	v_mfma_f32_16x16x32_bf16 v[20:23], v[162:165], v[224:227], v[20:23]
	v_mfma_f32_16x16x32_bf16 v[0:3], v[190:193], v[224:227], v[0:3]
	s_setprio 0
	s_barrier
; #define PG8_STAGE(bufoff, gbase, voff) do { _Pragma("unroll") for (int _i = 0; _i < 2; ++_i) \
;         __builtin_amdgcn_global_load_lds((const unsigned*)((const char*)(gbase) + (voff)[_i]), (PG8_LAS unsigned*)(lds + (bufoff) + ldsw + _i * 8192), 16, 0, 0); } while (0)
; #define PG8_LDA(dst, b, h) do { _Pragma("unroll") for (int m = 0; m < 4; ++m) _Pragma("unroll") for (int k = 0; k < 2; ++k) dst[m][k] = *(const PG8_LAS bf16x8*)(lds + PG8_SA(b, h) + aoff + m * 2048 + k * 1024); } while (0)
; #define PG8_LDB(dst, b, h) do { _Pragma("unroll") for (int n = 0; n < 2; ++n) _Pragma("unroll") for (int k = 0; k < 2; ++k) dst[n][k] = *(const PG8_LAS bf16x8*)(lds + PG8_SB(b, h) + boff + n * 2048 + k * 1024); } while (0)
; #define PG8_MMA(ai, bj, At, Bt) do { __builtin_amdgcn_s_setprio(1); _Pragma("unroll") for (int m = 0; m < 4; ++m) _Pragma("unroll") for (int n = 0; n < 2; ++n) _Pragma("unroll") for (int k = 0; k < 2; ++k) \
;         acc[ai][bj][m][n] = __builtin_amdgcn_mfma_f32_16x16x32_bf16(Bt[n][k], At[m][k], acc[ai][bj][m][n], 0, 0, 0); __builtin_amdgcn_s_setprio(0); } while (0)
; template <class Epi, class Sched, bool ALIGN_EPI = false, bool SP2 = false>
; __device__ __forceinline__ void gemm_phase(PG8_LAS unsigned char* lds, const Gemm g, const Sched& S, const Epi& E) {
;     ...
;             PG8_LDB(B0, 0, 0); PG8_LDB(B1, 0, 1); PG8_SCHED; PG8_LDA(At, 0, 0); PG8_STAGE(PG8_SA(1, 1), a1 + hstep, voffA);
;             PG8_WAIT_V(8); PG8_WAIT_L(0); PG8_BAR; PG8_MMA(0, 0, At, B0); PG8_MMA(0, 1, At, B1); PG8_BAR; PG8_SCHED;
;             PG8_LDA(At, 0, 1); PG8_STAGE(PG8_SB(0, 0), b2, voffB); PG8_STAGE(PG8_SB(0, 1), b2 + hstep, voffB); PG8_STAGE(PG8_SA(0, 0), a2, voffA);
;             PG8_WAIT_V(8); PG8_WAIT_L(0); PG8_BAR; PG8_MMA(1, 0, At, B0); PG8_MMA(1, 1, At, B1); PG8_BAR; PG8_SCHED;
;             PG8_LDB(B0, 1, 0); PG8_LDB(B1, 1, 1); PG8_SCHED; PG8_LDA(At, 1, 0); PG8_STAGE(PG8_SA(0, 1), a2 + hstep, voffA);
;             PG8_WAIT_V(8); PG8_WAIT_L(0); PG8_BAR; PG8_MMA(0, 0, At, B0); PG8_MMA(0, 1, At, B1); PG8_BAR; PG8_SCHED;
;             PG8_LDA(At, 1, 1); PG8_STAGE(PG8_SB(1, 0), b3, voffB); PG8_STAGE(PG8_SB(1, 1), b3 + hstep, voffB); PG8_STAGE(PG8_SA(1, 0), a3, voffA);
;             PG8_WAIT_V(8); PG8_WAIT_L(0); PG8_BAR; PG8_MMA(1, 0, At, B0); PG8_MMA(1, 1, At, B1); PG8_BAR; PG8_SCHED;
;     ...
;         if constexpr (ALIGN_EPI) { if (wr == 0) PG8_BAR; }
	ds_read_b128 v[142:145], v182
	ds_read_b128 v[146:149], v183
	ds_read_b128 v[150:153], v184
	ds_read_b128 v[154:157], v185
	ds_read_b128 v[158:161], v186
	ds_read_b128 v[162:165], v187
	ds_read_b128 v[166:169], v188
	ds_read_b128 v[190:193], v189
	s_add_u32 s20, s36, 0xb0000
	s_addc_u32 s21, s37, 0
	s_mov_b32 m0, s47
	v_lshl_add_u64 v[240:241], s[20:21], 0, v[128:129]
	ds_read_b128 v[194:197], v172 offset:32768
	ds_read_b128 v[198:201], v172 offset:33792
	ds_read_b128 v[202:205], v172 offset:34816
	ds_read_b128 v[206:209], v172 offset:35840
	ds_read_b128 v[210:213], v172 offset:36864
	ds_read_b128 v[214:217], v172 offset:37888
	ds_read_b128 v[218:221], v172 offset:38912
	ds_read_b128 v[224:227], v172 offset:39936
	global_load_lds_dwordx4 v[240:241], off
	v_lshl_add_u64 v[240:241], s[20:21], 0, v[130:131]
	s_mov_b32 m0, s50
	s_nop 0
	global_load_lds_dwordx4 v[240:241], off
	s_waitcnt vmcnt(8)
	s_waitcnt lgkmcnt(0)
	s_barrier
	s_setprio 1
	v_mfma_f32_16x16x32_bf16 v[124:127], v[142:145], v[194:197], v[124:127]
	v_mfma_f32_16x16x32_bf16 v[108:111], v[150:153], v[194:197], v[108:111]
	v_mfma_f32_16x16x32_bf16 v[120:123], v[142:145], v[202:205], v[120:123]
	v_mfma_f32_16x16x32_bf16 v[96:99], v[150:153], v[202:205], v[96:99]
	v_mfma_f32_16x16x32_bf16 v[116:119], v[142:145], v[210:213], v[116:119]
	v_mfma_f32_16x16x32_bf16 v[88:91], v[150:153], v[210:213], v[88:91]
	v_mfma_f32_16x16x32_bf16 v[112:115], v[142:145], v[218:221], v[112:115]
	v_mfma_f32_16x16x32_bf16 v[84:87], v[150:153], v[218:221], v[84:87]
	v_mfma_f32_16x16x32_bf16 v[124:127], v[146:149], v[198:201], v[124:127]
	v_mfma_f32_16x16x32_bf16 v[108:111], v[154:157], v[198:201], v[108:111]
	v_mfma_f32_16x16x32_bf16 v[120:123], v[146:149], v[206:209], v[120:123]
	v_mfma_f32_16x16x32_bf16 v[96:99], v[154:157], v[206:209], v[96:99]
	v_mfma_f32_16x16x32_bf16 v[116:119], v[146:149], v[214:217], v[116:119]
	v_mfma_f32_16x16x32_bf16 v[88:91], v[154:157], v[214:217], v[88:91]
	v_mfma_f32_16x16x32_bf16 v[112:115], v[146:149], v[224:227], v[112:115]
	v_mfma_f32_16x16x32_bf16 v[84:87], v[154:157], v[224:227], v[84:87]
	v_mfma_f32_16x16x32_bf16 v[68:71], v[158:161], v[194:197], v[68:71]
	v_mfma_f32_16x16x32_bf16 v[40:43], v[166:169], v[194:197], v[40:43]
	v_mfma_f32_16x16x32_bf16 v[60:63], v[158:161], v[202:205], v[60:63]
	v_mfma_f32_16x16x32_bf16 v[32:35], v[166:169], v[202:205], v[32:35]
	v_mfma_f32_16x16x32_bf16 v[52:55], v[158:161], v[210:213], v[52:55]
	v_mfma_f32_16x16x32_bf16 v[24:27], v[166:169], v[210:213], v[24:27]
	v_mfma_f32_16x16x32_bf16 v[48:51], v[158:161], v[218:221], v[48:51]
	v_mfma_f32_16x16x32_bf16 v[16:19], v[166:169], v[218:221], v[16:19]
	v_mfma_f32_16x16x32_bf16 v[68:71], v[162:165], v[198:201], v[68:71]
	v_mfma_f32_16x16x32_bf16 v[40:43], v[190:193], v[198:201], v[40:43]
	v_mfma_f32_16x16x32_bf16 v[60:63], v[162:165], v[206:209], v[60:63]
	v_mfma_f32_16x16x32_bf16 v[32:35], v[190:193], v[206:209], v[32:35]
	v_mfma_f32_16x16x32_bf16 v[52:55], v[162:165], v[214:217], v[52:55]
	v_mfma_f32_16x16x32_bf16 v[24:27], v[190:193], v[214:217], v[24:27]
	v_mfma_f32_16x16x32_bf16 v[48:51], v[162:165], v[224:227], v[48:51]
	v_mfma_f32_16x16x32_bf16 v[16:19], v[190:193], v[224:227], v[16:19]
	s_setprio 0
	s_barrier
	s_mov_b32 m0, s54
	v_lshl_add_u64 v[170:171], v[170:171], 0, s[10:11]
	s_add_u32 s20, s24, 0xb0080
	ds_read_b128 v[194:197], v172 offset:49152
	ds_read_b128 v[198:201], v172 offset:50176
	ds_read_b128 v[202:205], v172 offset:51200
	ds_read_b128 v[206:209], v172 offset:52224
	ds_read_b128 v[210:213], v172 offset:53248
	ds_read_b128 v[214:217], v172 offset:54272
	ds_read_b128 v[218:221], v172 offset:55296
	ds_read_b128 v[224:227], v172 offset:56320
	global_load_lds_dwordx4 v[170:171], off
	v_lshl_add_u64 v[170:171], v[228:229], 0, s[10:11]
	s_mov_b32 m0, s55
	s_addc_u32 s21, s25, 0
	global_load_lds_dwordx4 v[170:171], off
	v_lshl_add_u64 v[170:171], s[20:21], 0, v[128:129]
	s_mov_b32 m0, s58
	s_nop 0
	global_load_lds_dwordx4 v[170:171], off
	v_lshl_add_u64 v[170:171], s[20:21], 0, v[130:131]
	s_mov_b32 m0, s59
	s_nop 0
	global_load_lds_dwordx4 v[170:171], off
	v_lshl_add_u64 v[170:171], v[236:237], 0, s[10:11]
	s_mov_b32 m0, s56
	s_nop 0
	global_load_lds_dwordx4 v[170:171], off
	v_lshl_add_u64 v[170:171], v[238:239], 0, s[10:11]
	s_mov_b32 m0, s57
	s_nop 0
	global_load_lds_dwordx4 v[170:171], off
	s_waitcnt vmcnt(8)
	s_waitcnt lgkmcnt(0)
	s_barrier
	s_setprio 1
	v_mfma_f32_16x16x32_bf16 v[104:107], v[142:145], v[194:197], v[104:107]
	v_mfma_f32_16x16x32_bf16 v[76:79], v[150:153], v[194:197], v[76:79]
	v_mfma_f32_16x16x32_bf16 v[100:103], v[142:145], v[202:205], v[100:103]
	v_mfma_f32_16x16x32_bf16 v[72:75], v[150:153], v[202:205], v[72:75]
	v_mfma_f32_16x16x32_bf16 v[92:95], v[142:145], v[210:213], v[92:95]
	v_mfma_f32_16x16x32_bf16 v[64:67], v[150:153], v[210:213], v[64:67]
	v_mfma_f32_16x16x32_bf16 v[80:83], v[142:145], v[218:221], v[80:83]
	v_mfma_f32_16x16x32_bf16 v[56:59], v[150:153], v[218:221], v[56:59]
	v_mfma_f32_16x16x32_bf16 v[104:107], v[146:149], v[198:201], v[104:107]
	v_mfma_f32_16x16x32_bf16 v[76:79], v[154:157], v[198:201], v[76:79]
	v_mfma_f32_16x16x32_bf16 v[100:103], v[146:149], v[206:209], v[100:103]
	v_mfma_f32_16x16x32_bf16 v[72:75], v[154:157], v[206:209], v[72:75]
	v_mfma_f32_16x16x32_bf16 v[92:95], v[146:149], v[214:217], v[92:95]
	v_mfma_f32_16x16x32_bf16 v[64:67], v[154:157], v[214:217], v[64:67]
	v_mfma_f32_16x16x32_bf16 v[80:83], v[146:149], v[224:227], v[80:83]
	v_mfma_f32_16x16x32_bf16 v[56:59], v[154:157], v[224:227], v[56:59]
	v_mfma_f32_16x16x32_bf16 v[44:47], v[158:161], v[194:197], v[44:47]
	v_mfma_f32_16x16x32_bf16 v[12:15], v[166:169], v[194:197], v[12:15]
	v_mfma_f32_16x16x32_bf16 v[36:39], v[158:161], v[202:205], v[36:39]
	v_mfma_f32_16x16x32_bf16 v[8:11], v[166:169], v[202:205], v[8:11]
	v_mfma_f32_16x16x32_bf16 v[28:31], v[158:161], v[210:213], v[28:31]
	v_mfma_f32_16x16x32_bf16 v[4:7], v[166:169], v[210:213], v[4:7]
	v_mfma_f32_16x16x32_bf16 v[20:23], v[158:161], v[218:221], v[20:23]
	v_mfma_f32_16x16x32_bf16 v[0:3], v[166:169], v[218:221], v[0:3]
	v_mfma_f32_16x16x32_bf16 v[44:47], v[162:165], v[198:201], v[44:47]
	v_mfma_f32_16x16x32_bf16 v[12:15], v[190:193], v[198:201], v[12:15]
	v_mfma_f32_16x16x32_bf16 v[36:39], v[162:165], v[206:209], v[36:39]
	v_mfma_f32_16x16x32_bf16 v[8:11], v[190:193], v[206:209], v[8:11]
	v_mfma_f32_16x16x32_bf16 v[28:31], v[162:165], v[214:217], v[28:31]
	v_mfma_f32_16x16x32_bf16 v[4:7], v[190:193], v[214:217], v[4:7]
	v_mfma_f32_16x16x32_bf16 v[20:23], v[162:165], v[224:227], v[20:23]
	v_mfma_f32_16x16x32_bf16 v[0:3], v[190:193], v[224:227], v[0:3]
	s_setprio 0
	s_barrier
	s_add_i32 s73, s73, 2
	s_add_u32 s33, s33, 0x100
	s_addc_u32 s72, s72, 0
	s_cmp_gt_u32 s73, 41
	s_mov_b64 s[20:21], s[22:23]
	s_cbranch_scc0 .LBB0_1518
	s_and_b64 vcc, exec, s[12:13]
	s_cbranch_vccz .LBB0_1521
	s_barrier
